# grid barriers: acquire invalidate issued at arrival (overlaps the wait) instead of after release
# baseline (speedup 1.0000x reference)
.LBB0_256:
	s_or_b64 exec, exec, s[4:5]
	s_waitcnt vmcnt(0)
	s_waitcnt vmcnt(0)

.LBB0_398:
	s_lshl_b32 s86, s15, 10
	s_lshl_b64 s[2:3], s[86:87], 2
	v_readlane_b32 s6, v254, 35
	v_readlane_b32 s7, v254, 36
	s_add_u32 s2, s6, s2
	v_readlane_b32 s5, v254, 37
	s_addc_u32 s3, s7, s3
	s_add_i32 s5, s5, s18
	v_or_b32_e32 v78, s5, v154
	v_ashrrev_i32_e32 v79, 31, v78
	v_lshlrev_b32_e32 v70, 9, v74
	v_lshl_add_u64 v[74:75], v[78:79], 2, s[2:3]
	v_or_b32_e32 v168, s4, v5
	v_readlane_b32 s2, v254, 39
	v_readlane_b32 s3, v254, 40
	v_ashrrev_i32_e32 v169, 31, v168
	v_add_u32_e32 v70, 0, v70
	v_lshl_add_u64 v[166:167], v[78:79], 1, s[2:3]
	v_lshlrev_b64 v[78:79], 11, v[168:169]
	v_lshl_add_u64 v[176:177], v[166:167], 0, v[78:79]
	v_or_b32_e32 v78, 16, v168
	v_ashrrev_i32_e32 v79, 31, v78
	v_lshlrev_b64 v[78:79], 11, v[78:79]
	v_add3_u32 v70, v70, v138, v150
	v_lshl_add_u64 v[78:79], v[166:167], 0, v[78:79]
	ds_write_b64 v70, v[72:73]
	s_waitcnt lgkmcnt(0)
	s_barrier
	global_load_dwordx4 v[70:73], v[74:75], off offset:16
	s_nop 0
	global_load_dwordx4 v[74:77], v[74:75], off
	v_or_b32_e32 v174, 0x50, v168
	global_load_dwordx4 v[138:141], v[176:177], off
	global_load_dwordx4 v[122:125], v[78:79], off
	v_or_b32_e32 v78, 32, v168
	v_ashrrev_i32_e32 v79, 31, v78
	v_lshlrev_b64 v[78:79], 11, v[78:79]
	v_lshl_add_u64 v[78:79], v[166:167], 0, v[78:79]
	global_load_dwordx4 v[106:109], v[78:79], off
	v_or_b32_e32 v78, 48, v168
	v_ashrrev_i32_e32 v79, 31, v78
	v_lshlrev_b64 v[78:79], 11, v[78:79]
	v_lshl_add_u64 v[78:79], v[166:167], 0, v[78:79]
	global_load_dwordx4 v[94:97], v[78:79], off
	v_or_b32_e32 v78, 64, v168
	v_ashrrev_i32_e32 v79, 31, v78
	v_lshlrev_b64 v[78:79], 11, v[78:79]
	v_lshl_add_u64 v[78:79], v[166:167], 0, v[78:79]
	v_ashrrev_i32_e32 v175, 31, v174
	global_load_dwordx4 v[90:93], v[78:79], off
	v_lshlrev_b64 v[78:79], 11, v[174:175]
	v_or_b32_e32 v172, 0x60, v168
	v_lshl_add_u64 v[78:79], v[166:167], 0, v[78:79]
	v_ashrrev_i32_e32 v173, 31, v172
	global_load_dwordx4 v[86:89], v[78:79], off
	v_lshlrev_b64 v[78:79], 11, v[172:173]
	v_or_b32_e32 v170, 0x70, v168
	v_lshl_add_u64 v[78:79], v[166:167], 0, v[78:79]
	v_ashrrev_i32_e32 v171, 31, v170
	global_load_dwordx4 v[82:85], v[78:79], off
	v_lshlrev_b64 v[78:79], 11, v[170:171]
	v_lshl_add_u64 v[78:79], v[166:167], 0, v[78:79]
	global_load_dwordx4 v[78:81], v[78:79], off
	v_xor_b32_e32 v98, v152, v5
	v_bitop3_b32 v102, v152, v5, 4 bitop3:0x36
	v_bitop3_b32 v110, v152, v5, 8 bitop3:0x36
	v_bitop3_b32 v114, v152, v5, 12 bitop3:0x36
	v_bitop3_b32 v118, v152, v5, 16 bitop3:0x36
	v_bitop3_b32 v126, v152, v5, 20 bitop3:0x36
	v_bitop3_b32 v130, v152, v5, 24 bitop3:0x36
	v_bitop3_b32 v134, v152, v5, 28 bitop3:0x36
	v_lshl_add_u32 v183, v5, 9, 0
	v_lshlrev_b32_e32 v184, 4, v98
	v_lshlrev_b32_e32 v185, 4, v102
	v_lshlrev_b32_e32 v187, 4, v110
	v_lshlrev_b32_e32 v189, 4, v114
	v_lshlrev_b32_e32 v186, 4, v118
	v_lshlrev_b32_e32 v188, 4, v126
	v_lshlrev_b32_e32 v190, 4, v130
	v_lshlrev_b32_e32 v191, 4, v134
	v_add_u32_e32 v169, v183, v184
	v_add_u32_e32 v182, v183, v185
	v_add_u32_e32 v216, v183, v187
	v_add_u32_e32 v217, v183, v189
	v_add_u32_e32 v220, v183, v186
	v_add_u32_e32 v221, v183, v188
	v_add_u32_e32 v222, v183, v190
	v_add_u32_e32 v223, v183, v191
	ds_read_b128 v[98:101], v169
	ds_read_b128 v[102:105], v182
	ds_read_b128 v[110:113], v216
	ds_read_b128 v[114:117], v217
	ds_read_b128 v[118:121], v220
	ds_read_b128 v[126:129], v221
	ds_read_b128 v[130:133], v222
	ds_read_b128 v[134:137], v223
	s_lshl_b32 s2, s52, 10
	s_add_i32 s2, s2, 0
	v_cmp_gt_u32_e32 vcc, 16, v153
	s_add_i32 s2, s2, 0x21000
	s_setprio 1
	s_waitcnt vmcnt(25) lgkmcnt(7)
	v_mfma_f32_16x16x32_bf16 v[142:145], v[34:37], v[98:101], 0
	s_waitcnt vmcnt(17)
	v_mfma_f32_16x16x32_bf16 v[98:101], v[66:69], v[98:101], 0
	s_waitcnt lgkmcnt(6)
	v_mfma_f32_16x16x32_bf16 v[142:145], v[30:33], v[102:105], v[142:145]
	s_waitcnt vmcnt(16)
	v_mfma_f32_16x16x32_bf16 v[98:101], v[62:65], v[102:105], v[98:101]
	s_waitcnt lgkmcnt(5)
	v_mfma_f32_16x16x32_bf16 v[102:105], v[26:29], v[110:113], v[142:145]
	s_waitcnt vmcnt(15)
	v_mfma_f32_16x16x32_bf16 v[98:101], v[58:61], v[110:113], v[98:101]
	s_waitcnt lgkmcnt(4)
	v_mfma_f32_16x16x32_bf16 v[102:105], v[22:25], v[114:117], v[102:105]
	s_waitcnt vmcnt(14)
	v_mfma_f32_16x16x32_bf16 v[98:101], v[54:57], v[114:117], v[98:101]
	s_setprio 0
	ds_read_b128 v[110:113], v169 offset:8192
	ds_read_b128 v[114:117], v182 offset:8192
	ds_read_b128 v[142:145], v216 offset:8192
	ds_read_b128 v[146:149], v217 offset:8192
	s_setprio 1
	s_waitcnt lgkmcnt(7)
	v_mfma_f32_16x16x32_bf16 v[102:105], v[18:21], v[118:121], v[102:105]
	s_waitcnt vmcnt(13)
	v_mfma_f32_16x16x32_bf16 v[98:101], v[50:53], v[118:121], v[98:101]
	s_waitcnt lgkmcnt(6)
	v_mfma_f32_16x16x32_bf16 v[102:105], v[14:17], v[126:129], v[102:105]
	s_waitcnt vmcnt(12)
	v_mfma_f32_16x16x32_bf16 v[98:101], v[46:49], v[126:129], v[98:101]
	s_waitcnt lgkmcnt(5)
	v_mfma_f32_16x16x32_bf16 v[102:105], v[10:13], v[130:133], v[102:105]
	s_waitcnt vmcnt(11)
	v_mfma_f32_16x16x32_bf16 v[98:101], v[42:45], v[130:133], v[98:101]
	s_waitcnt lgkmcnt(4)
	v_mfma_f32_16x16x32_bf16 v[178:181], v[6:9], v[134:137], v[102:105]
	s_waitcnt vmcnt(10)
	v_mfma_f32_16x16x32_bf16 v[192:195], v[38:41], v[134:137], v[98:101]
	s_setprio 0
	s_nop 2
	ds_read_b128 v[98:101], v220 offset:8192
	ds_read_b128 v[102:105], v221 offset:8192
	ds_read_b128 v[118:121], v222 offset:8192
	ds_read_b128 v[126:129], v223 offset:8192
	s_setprio 1
	s_waitcnt lgkmcnt(7)
	v_mfma_f32_16x16x32_bf16 v[130:133], v[34:37], v[110:113], 0
	v_mfma_f32_16x16x32_bf16 v[110:113], v[66:69], v[110:113], 0
	s_waitcnt lgkmcnt(6)
	v_mfma_f32_16x16x32_bf16 v[130:133], v[30:33], v[114:117], v[130:133]
	v_mfma_f32_16x16x32_bf16 v[110:113], v[62:65], v[114:117], v[110:113]
	s_waitcnt lgkmcnt(5)
	v_mfma_f32_16x16x32_bf16 v[114:117], v[26:29], v[142:145], v[130:133]
	v_mfma_f32_16x16x32_bf16 v[110:113], v[58:61], v[142:145], v[110:113]
	s_waitcnt lgkmcnt(4)
	v_mfma_f32_16x16x32_bf16 v[114:117], v[22:25], v[146:149], v[114:117]
	v_mfma_f32_16x16x32_bf16 v[110:113], v[54:57], v[146:149], v[110:113]
	s_setprio 0
	ds_read_b128 v[130:133], v169 offset:16384
	ds_read_b128 v[134:137], v182 offset:16384
	ds_read_b128 v[142:145], v216 offset:16384
	ds_read_b128 v[146:149], v217 offset:16384
	s_setprio 1
	s_waitcnt lgkmcnt(7)
	v_mfma_f32_16x16x32_bf16 v[114:117], v[18:21], v[98:101], v[114:117]
	v_mfma_f32_16x16x32_bf16 v[98:101], v[50:53], v[98:101], v[110:113]
	s_waitcnt lgkmcnt(6)
	v_mfma_f32_16x16x32_bf16 v[110:113], v[14:17], v[102:105], v[114:117]
	v_mfma_f32_16x16x32_bf16 v[98:101], v[46:49], v[102:105], v[98:101]
	s_waitcnt lgkmcnt(5)
	v_mfma_f32_16x16x32_bf16 v[102:105], v[10:13], v[118:121], v[110:113]
	v_mfma_f32_16x16x32_bf16 v[98:101], v[42:45], v[118:121], v[98:101]
	s_waitcnt lgkmcnt(4)
	v_mfma_f32_16x16x32_bf16 v[162:165], v[6:9], v[126:129], v[102:105]
	v_mfma_f32_16x16x32_bf16 v[158:161], v[38:41], v[126:129], v[98:101]
	s_setprio 0
	s_nop 3
	ds_read_b128 v[98:101], v220 offset:16384
	ds_read_b128 v[102:105], v221 offset:16384
	ds_read_b128 v[110:113], v222 offset:16384
	ds_read_b128 v[114:117], v223 offset:16384
	s_setprio 1
	s_waitcnt lgkmcnt(7)
	v_mfma_f32_16x16x32_bf16 v[118:121], v[34:37], v[130:133], 0
	v_mfma_f32_16x16x32_bf16 v[126:129], v[66:69], v[130:133], 0
	s_waitcnt lgkmcnt(6)
	v_mfma_f32_16x16x32_bf16 v[118:121], v[30:33], v[134:137], v[118:121]
	v_mfma_f32_16x16x32_bf16 v[126:129], v[62:65], v[134:137], v[126:129]
	s_waitcnt lgkmcnt(5)
	v_mfma_f32_16x16x32_bf16 v[118:121], v[26:29], v[142:145], v[118:121]
	v_mfma_f32_16x16x32_bf16 v[126:129], v[58:61], v[142:145], v[126:129]
	s_waitcnt lgkmcnt(4)
	v_mfma_f32_16x16x32_bf16 v[118:121], v[22:25], v[146:149], v[118:121]
	v_mfma_f32_16x16x32_bf16 v[126:129], v[54:57], v[146:149], v[126:129]
	s_setprio 0
	ds_read_b128 v[130:133], v169 offset:24576
	ds_read_b128 v[134:137], v182 offset:24576
	ds_read_b128 v[142:145], v216 offset:24576
	ds_read_b128 v[146:149], v217 offset:24576
	s_setprio 1
	s_waitcnt lgkmcnt(7)
	v_mfma_f32_16x16x32_bf16 v[118:121], v[18:21], v[98:101], v[118:121]
	v_mfma_f32_16x16x32_bf16 v[98:101], v[50:53], v[98:101], v[126:129]
	s_waitcnt lgkmcnt(6)
	v_mfma_f32_16x16x32_bf16 v[118:121], v[14:17], v[102:105], v[118:121]
	v_mfma_f32_16x16x32_bf16 v[98:101], v[46:49], v[102:105], v[98:101]
	s_waitcnt lgkmcnt(5)
	v_mfma_f32_16x16x32_bf16 v[102:105], v[10:13], v[110:113], v[118:121]
	v_mfma_f32_16x16x32_bf16 v[98:101], v[42:45], v[110:113], v[98:101]
	s_waitcnt lgkmcnt(4)
	v_mfma_f32_16x16x32_bf16 v[154:157], v[6:9], v[114:117], v[102:105]
	v_mfma_f32_16x16x32_bf16 v[150:153], v[38:41], v[114:117], v[98:101]
	s_setprio 0
	s_nop 3
	ds_read_b128 v[98:101], v220 offset:24576
	ds_read_b128 v[102:105], v221 offset:24576
	ds_read_b128 v[110:113], v222 offset:24576
	ds_read_b128 v[114:117], v223 offset:24576
	s_setprio 1
	s_waitcnt lgkmcnt(7)
	v_mfma_f32_16x16x32_bf16 v[118:121], v[34:37], v[130:133], 0
	v_mfma_f32_16x16x32_bf16 v[126:129], v[66:69], v[130:133], 0
	s_waitcnt lgkmcnt(6)
	v_mfma_f32_16x16x32_bf16 v[118:121], v[30:33], v[134:137], v[118:121]
	v_mfma_f32_16x16x32_bf16 v[126:129], v[62:65], v[134:137], v[126:129]
	s_waitcnt lgkmcnt(5)
	v_mfma_f32_16x16x32_bf16 v[118:121], v[26:29], v[142:145], v[118:121]
	v_mfma_f32_16x16x32_bf16 v[126:129], v[58:61], v[142:145], v[126:129]
	s_waitcnt lgkmcnt(4)
	v_mfma_f32_16x16x32_bf16 v[118:121], v[22:25], v[146:149], v[118:121]
	v_mfma_f32_16x16x32_bf16 v[126:129], v[54:57], v[146:149], v[126:129]
	s_setprio 0
	ds_read_b128 v[130:133], v169 offset:32768
	ds_read_b128 v[134:137], v182 offset:32768
	ds_read_b128 v[196:199], v216 offset:32768
	ds_read_b128 v[200:203], v217 offset:32768
	s_setprio 1
	s_waitcnt lgkmcnt(7)
	v_mfma_f32_16x16x32_bf16 v[118:121], v[18:21], v[98:101], v[118:121]
	v_mfma_f32_16x16x32_bf16 v[98:101], v[50:53], v[98:101], v[126:129]
	s_waitcnt lgkmcnt(6)
	v_mfma_f32_16x16x32_bf16 v[118:121], v[14:17], v[102:105], v[118:121]
	v_mfma_f32_16x16x32_bf16 v[98:101], v[46:49], v[102:105], v[98:101]
	s_waitcnt lgkmcnt(5)
	v_mfma_f32_16x16x32_bf16 v[102:105], v[10:13], v[110:113], v[118:121]
	v_mfma_f32_16x16x32_bf16 v[98:101], v[42:45], v[110:113], v[98:101]
	s_waitcnt lgkmcnt(4)
	v_mfma_f32_16x16x32_bf16 v[146:149], v[6:9], v[114:117], v[102:105]
	v_mfma_f32_16x16x32_bf16 v[142:145], v[38:41], v[114:117], v[98:101]
	s_setprio 0
	s_nop 3
	ds_read_b128 v[98:101], v220 offset:32768
	ds_read_b128 v[102:105], v221 offset:32768
	ds_read_b128 v[110:113], v222 offset:32768
	ds_read_b128 v[114:117], v223 offset:32768
	s_setprio 1
	s_waitcnt lgkmcnt(7)
	v_mfma_f32_16x16x32_bf16 v[118:121], v[34:37], v[130:133], 0
	v_mfma_f32_16x16x32_bf16 v[126:129], v[66:69], v[130:133], 0
	s_waitcnt lgkmcnt(6)
	v_mfma_f32_16x16x32_bf16 v[118:121], v[30:33], v[134:137], v[118:121]
	v_mfma_f32_16x16x32_bf16 v[126:129], v[62:65], v[134:137], v[126:129]
	s_waitcnt lgkmcnt(5)
	v_mfma_f32_16x16x32_bf16 v[118:121], v[26:29], v[196:199], v[118:121]
	v_mfma_f32_16x16x32_bf16 v[126:129], v[58:61], v[196:199], v[126:129]
	s_waitcnt lgkmcnt(4)
	v_mfma_f32_16x16x32_bf16 v[118:121], v[22:25], v[200:203], v[118:121]
	v_mfma_f32_16x16x32_bf16 v[126:129], v[54:57], v[200:203], v[126:129]
	s_setprio 0
	ds_read_b128 v[196:199], v169 offset:40960
	ds_read_b128 v[200:203], v182 offset:40960
	ds_read_b128 v[204:207], v216 offset:40960
	ds_read_b128 v[208:211], v217 offset:40960
	s_setprio 1
	s_waitcnt lgkmcnt(7)
	v_mfma_f32_16x16x32_bf16 v[118:121], v[18:21], v[98:101], v[118:121]
	v_mfma_f32_16x16x32_bf16 v[98:101], v[50:53], v[98:101], v[126:129]
	s_waitcnt lgkmcnt(6)
	v_mfma_f32_16x16x32_bf16 v[118:121], v[14:17], v[102:105], v[118:121]
	v_mfma_f32_16x16x32_bf16 v[98:101], v[46:49], v[102:105], v[98:101]
	s_waitcnt lgkmcnt(5)
	v_mfma_f32_16x16x32_bf16 v[102:105], v[10:13], v[110:113], v[118:121]
	v_mfma_f32_16x16x32_bf16 v[98:101], v[42:45], v[110:113], v[98:101]
	s_waitcnt lgkmcnt(4)
	v_mfma_f32_16x16x32_bf16 v[134:137], v[6:9], v[114:117], v[102:105]
	v_mfma_f32_16x16x32_bf16 v[130:133], v[38:41], v[114:117], v[98:101]
	s_setprio 0
	s_nop 3
	ds_read_b128 v[98:101], v220 offset:40960
	ds_read_b128 v[102:105], v221 offset:40960
	ds_read_b128 v[110:113], v222 offset:40960
	ds_read_b128 v[114:117], v223 offset:40960
	s_setprio 1
	s_waitcnt lgkmcnt(7)
	v_mfma_f32_16x16x32_bf16 v[118:121], v[34:37], v[196:199], 0
	v_mfma_f32_16x16x32_bf16 v[126:129], v[66:69], v[196:199], 0
	s_waitcnt lgkmcnt(6)
	v_mfma_f32_16x16x32_bf16 v[118:121], v[30:33], v[200:203], v[118:121]
	v_mfma_f32_16x16x32_bf16 v[126:129], v[62:65], v[200:203], v[126:129]
	s_waitcnt lgkmcnt(5)
	v_mfma_f32_16x16x32_bf16 v[118:121], v[26:29], v[204:207], v[118:121]
	v_mfma_f32_16x16x32_bf16 v[126:129], v[58:61], v[204:207], v[126:129]
	s_waitcnt lgkmcnt(4)
	v_mfma_f32_16x16x32_bf16 v[118:121], v[22:25], v[208:211], v[118:121]
	v_mfma_f32_16x16x32_bf16 v[126:129], v[54:57], v[208:211], v[126:129]
	s_setprio 0
	ds_read_b128 v[196:199], v169 offset:49152
	ds_read_b128 v[200:203], v182 offset:49152
	ds_read_b128 v[204:207], v216 offset:49152
	ds_read_b128 v[208:211], v217 offset:49152
	s_setprio 1
	s_waitcnt lgkmcnt(7)
	v_mfma_f32_16x16x32_bf16 v[118:121], v[18:21], v[98:101], v[118:121]
	v_mfma_f32_16x16x32_bf16 v[98:101], v[50:53], v[98:101], v[126:129]
	s_waitcnt lgkmcnt(6)
	v_mfma_f32_16x16x32_bf16 v[118:121], v[14:17], v[102:105], v[118:121]
	v_mfma_f32_16x16x32_bf16 v[98:101], v[46:49], v[102:105], v[98:101]
	s_waitcnt lgkmcnt(5)
	v_mfma_f32_16x16x32_bf16 v[102:105], v[10:13], v[110:113], v[118:121]
	v_mfma_f32_16x16x32_bf16 v[98:101], v[42:45], v[110:113], v[98:101]
	s_waitcnt lgkmcnt(4)
	v_mfma_f32_16x16x32_bf16 v[126:129], v[6:9], v[114:117], v[102:105]
	v_mfma_f32_16x16x32_bf16 v[118:121], v[38:41], v[114:117], v[98:101]
	s_setprio 0
	s_nop 3
	ds_read_b128 v[98:101], v220 offset:49152
	ds_read_b128 v[102:105], v221 offset:49152
	ds_read_b128 v[110:113], v222 offset:49152
	ds_read_b128 v[212:215], v223 offset:49152
	s_setprio 1
	s_waitcnt lgkmcnt(7)
	v_mfma_f32_16x16x32_bf16 v[114:117], v[34:37], v[196:199], 0
	v_mfma_f32_16x16x32_bf16 v[196:199], v[66:69], v[196:199], 0
	s_waitcnt lgkmcnt(6)
	v_mfma_f32_16x16x32_bf16 v[114:117], v[30:33], v[200:203], v[114:117]
	v_mfma_f32_16x16x32_bf16 v[196:199], v[62:65], v[200:203], v[196:199]
	s_waitcnt lgkmcnt(5)
	v_mfma_f32_16x16x32_bf16 v[114:117], v[26:29], v[204:207], v[114:117]
	v_mfma_f32_16x16x32_bf16 v[196:199], v[58:61], v[204:207], v[196:199]
	s_waitcnt lgkmcnt(4)
	v_mfma_f32_16x16x32_bf16 v[114:117], v[22:25], v[208:211], v[114:117]
	v_mfma_f32_16x16x32_bf16 v[196:199], v[54:57], v[208:211], v[196:199]
	s_setprio 0
	ds_read_b128 v[200:203], v169 offset:57344
	ds_read_b128 v[204:207], v182 offset:57344
	ds_read_b128 v[208:211], v216 offset:57344
	ds_read_b128 v[216:219], v217 offset:57344
	s_setprio 1
	s_waitcnt lgkmcnt(7)
	v_mfma_f32_16x16x32_bf16 v[114:117], v[18:21], v[98:101], v[114:117]
	v_mfma_f32_16x16x32_bf16 v[98:101], v[50:53], v[98:101], v[196:199]
	s_waitcnt lgkmcnt(6)
	v_mfma_f32_16x16x32_bf16 v[114:117], v[14:17], v[102:105], v[114:117]
	v_mfma_f32_16x16x32_bf16 v[98:101], v[46:49], v[102:105], v[98:101]
	s_waitcnt lgkmcnt(5)
	v_mfma_f32_16x16x32_bf16 v[102:105], v[10:13], v[110:113], v[114:117]
	v_mfma_f32_16x16x32_bf16 v[98:101], v[42:45], v[110:113], v[98:101]
	s_waitcnt lgkmcnt(4)
	v_mfma_f32_16x16x32_bf16 v[114:117], v[6:9], v[212:215], v[102:105]
	v_mfma_f32_16x16x32_bf16 v[110:113], v[38:41], v[212:215], v[98:101]
	s_setprio 0
	s_nop 3
	ds_read_b128 v[98:101], v220 offset:57344
	ds_read_b128 v[102:105], v221 offset:57344
	ds_read_b128 v[196:199], v222 offset:57344
	ds_read_b128 v[212:215], v223 offset:57344
	s_setprio 1
	s_waitcnt lgkmcnt(7)
	v_mfma_f32_16x16x32_bf16 v[220:223], v[34:37], v[200:203], 0
	v_mfma_f32_16x16x32_bf16 v[200:203], v[66:69], v[200:203], 0
	s_waitcnt lgkmcnt(6)
	v_mfma_f32_16x16x32_bf16 v[220:223], v[30:33], v[204:207], v[220:223]
	v_mfma_f32_16x16x32_bf16 v[200:203], v[62:65], v[204:207], v[200:203]
	s_waitcnt lgkmcnt(5)
	v_mfma_f32_16x16x32_bf16 v[204:207], v[26:29], v[208:211], v[220:223]
	v_mfma_f32_16x16x32_bf16 v[200:203], v[58:61], v[208:211], v[200:203]
	s_waitcnt lgkmcnt(4)
	v_mfma_f32_16x16x32_bf16 v[204:207], v[22:25], v[216:219], v[204:207]
	v_mfma_f32_16x16x32_bf16 v[200:203], v[54:57], v[216:219], v[200:203]
	s_setprio 0
	s_setprio 1
	s_waitcnt lgkmcnt(3)
	v_mfma_f32_16x16x32_bf16 v[204:207], v[18:21], v[98:101], v[204:207]
	v_mfma_f32_16x16x32_bf16 v[98:101], v[50:53], v[98:101], v[200:203]
	s_waitcnt lgkmcnt(2)
	v_mfma_f32_16x16x32_bf16 v[200:203], v[14:17], v[102:105], v[204:207]
	v_mfma_f32_16x16x32_bf16 v[98:101], v[46:49], v[102:105], v[98:101]
	s_waitcnt lgkmcnt(1)
	v_mfma_f32_16x16x32_bf16 v[102:105], v[10:13], v[196:199], v[200:203]
	v_mfma_f32_16x16x32_bf16 v[98:101], v[42:45], v[196:199], v[98:101]
	s_waitcnt lgkmcnt(0)
	v_mfma_f32_16x16x32_bf16 v[102:105], v[6:9], v[212:215], v[102:105]
	v_mfma_f32_16x16x32_bf16 v[98:101], v[38:41], v[212:215], v[98:101]
	s_setprio 0
	s_waitcnt vmcnt(7)
	v_lshlrev_b32_e32 v196, 16, v138
	v_and_b32_e32 v197, 0xffff0000, v138
	v_lshlrev_b32_e32 v138, 16, v139
	v_and_b32_e32 v139, 0xffff0000, v139
	v_pk_fma_f32 v[180:181], v[76:77], v[180:181], v[138:139]
	v_pk_fma_f32 v[138:139], v[74:75], v[178:179], v[196:197]
	v_lshlrev_b32_e32 v178, 16, v140
	v_and_b32_e32 v179, 0xffff0000, v140
	v_lshlrev_b32_e32 v140, 16, v141
	v_and_b32_e32 v141, 0xffff0000, v141
	v_pk_fma_f32 v[194:195], v[72:73], v[194:195], v[140:141]
	v_pk_fma_f32 v[140:141], v[70:71], v[192:193], v[178:179]
	v_mul_f32_e32 v169, v139, v139
	v_mul_f32_e32 v178, v181, v181
	v_fmac_f32_e32 v169, v138, v138
	v_fmac_f32_e32 v178, v180, v180
	v_add_f32_e32 v169, v169, v178
	v_mul_f32_e32 v178, v141, v141
	v_mul_f32_e32 v179, v195, v195
	v_fmac_f32_e32 v178, v140, v140
	v_fmac_f32_e32 v179, v194, v194
	v_add_f32_e32 v178, v178, v179
	v_add_f32_e32 v169, v169, v178
	v_cvt_pk_bf16_f32 v138, v138, v139
	v_cvt_pk_bf16_f32 v139, v180, v181
	v_cvt_pk_bf16_f32 v140, v140, v141
	v_cvt_pk_bf16_f32 v141, v194, v195
	global_store_dwordx4 v[176:177], v[138:141], off
	v_lshl_add_u32 v182, v5, 2, s2
	s_nop 0
	v_mov_b32_e32 v138, v169
	s_nop 1
	v_permlane16_swap_b32_e32 v169, v138
	v_add_f32_e32 v138, v169, v138
	v_mov_b32_e32 v139, v138
	s_nop 1
	v_permlane32_swap_b32_e32 v138, v139
	s_and_saveexec_b64 s[2:3], vcc
	v_add_f32_e32 v138, v138, v139
	ds_write_b32 v182, v138
	s_or_b64 exec, exec, s[2:3]
	s_waitcnt vmcnt(7)
	v_lshlrev_b32_e32 v138, 16, v122
	v_and_b32_e32 v139, 0xffff0000, v122
	v_lshlrev_b32_e32 v122, 16, v123
	v_and_b32_e32 v123, 0xffff0000, v123
	v_pk_fma_f32 v[140:141], v[76:77], v[164:165], v[122:123]
	v_pk_fma_f32 v[122:123], v[74:75], v[162:163], v[138:139]
	v_lshlrev_b32_e32 v138, 16, v124
	v_and_b32_e32 v139, 0xffff0000, v124
	v_lshlrev_b32_e32 v124, 16, v125
	v_and_b32_e32 v125, 0xffff0000, v125
	v_pk_fma_f32 v[160:161], v[72:73], v[160:161], v[124:125]
	v_pk_fma_f32 v[124:125], v[70:71], v[158:159], v[138:139]
	v_mul_f32_e32 v138, v123, v123
	v_mul_f32_e32 v139, v141, v141
	v_fmac_f32_e32 v138, v122, v122
	v_fmac_f32_e32 v139, v140, v140
	v_add_f32_e32 v138, v138, v139
	v_mul_f32_e32 v139, v125, v125
	v_mul_f32_e32 v158, v161, v161
	v_fmac_f32_e32 v139, v124, v124
	v_fmac_f32_e32 v158, v160, v160
	v_add_f32_e32 v139, v139, v158
	v_add_f32_e32 v158, v138, v139
	v_or3_b32 v138, v5, s4, 16
	v_ashrrev_i32_e32 v139, 31, v138
	v_lshlrev_b64 v[138:139], 11, v[138:139]
	v_lshl_add_u64 v[138:139], v[166:167], 0, v[138:139]
	v_cvt_pk_bf16_f32 v122, v122, v123
	v_cvt_pk_bf16_f32 v123, v140, v141
	v_cvt_pk_bf16_f32 v124, v124, v125
	v_cvt_pk_bf16_f32 v125, v160, v161
	global_store_dwordx4 v[138:139], v[122:125], off
	s_nop 1
	v_mov_b32_e32 v122, v158
	s_nop 1
	v_permlane16_swap_b32_e32 v158, v122
	v_add_f32_e32 v122, v158, v122
	v_mov_b32_e32 v123, v122
	s_nop 1
	v_permlane32_swap_b32_e32 v122, v123
	s_and_saveexec_b64 s[2:3], vcc
	v_readlane_b32 s86, v254, 13
	v_add_f32_e32 v122, v122, v123
	ds_write_b32 v182, v122 offset:64
	s_or_b64 exec, exec, s[2:3]
	s_waitcnt vmcnt(7)
	v_lshlrev_b32_e32 v122, 16, v106
	v_and_b32_e32 v123, 0xffff0000, v106
	v_lshlrev_b32_e32 v106, 16, v107
	v_and_b32_e32 v107, 0xffff0000, v107
	v_pk_fma_f32 v[124:125], v[76:77], v[156:157], v[106:107]
	v_pk_fma_f32 v[106:107], v[74:75], v[154:155], v[122:123]
	v_lshlrev_b32_e32 v122, 16, v108
	v_and_b32_e32 v123, 0xffff0000, v108
	v_lshlrev_b32_e32 v108, 16, v109
	v_and_b32_e32 v109, 0xffff0000, v109
	v_pk_fma_f32 v[138:139], v[72:73], v[152:153], v[108:109]
	v_pk_fma_f32 v[108:109], v[70:71], v[150:151], v[122:123]
	v_mul_f32_e32 v122, v107, v107
	v_mul_f32_e32 v123, v125, v125
	v_fmac_f32_e32 v122, v106, v106
	v_fmac_f32_e32 v123, v124, v124
	v_add_f32_e32 v122, v122, v123
	v_mul_f32_e32 v123, v109, v109
	v_mul_f32_e32 v140, v139, v139
	v_fmac_f32_e32 v123, v108, v108
	v_fmac_f32_e32 v140, v138, v138
	v_add_f32_e32 v123, v123, v140
	v_add_f32_e32 v140, v122, v123
	v_or3_b32 v122, v5, s4, 32
	v_ashrrev_i32_e32 v123, 31, v122
	v_lshlrev_b64 v[122:123], 11, v[122:123]
	v_lshl_add_u64 v[122:123], v[166:167], 0, v[122:123]
	v_cvt_pk_bf16_f32 v106, v106, v107
	v_cvt_pk_bf16_f32 v107, v124, v125
	v_cvt_pk_bf16_f32 v108, v108, v109
	v_cvt_pk_bf16_f32 v109, v138, v139
	global_store_dwordx4 v[122:123], v[106:109], off
	s_nop 1
	v_mov_b32_e32 v106, v140
	s_nop 1
	v_permlane16_swap_b32_e32 v140, v106
	v_add_f32_e32 v106, v140, v106
	v_mov_b32_e32 v107, v106
	s_nop 1
	v_permlane32_swap_b32_e32 v106, v107
	s_and_saveexec_b64 s[2:3], vcc
	v_add_f32_e32 v106, v106, v107
	ds_write_b32 v182, v106 offset:128
	s_or_b64 exec, exec, s[2:3]
	s_waitcnt vmcnt(7)
	v_lshlrev_b32_e32 v106, 16, v94
	v_and_b32_e32 v107, 0xffff0000, v94
	v_lshlrev_b32_e32 v94, 16, v95
	v_and_b32_e32 v95, 0xffff0000, v95
	v_pk_fma_f32 v[108:109], v[76:77], v[148:149], v[94:95]
	v_pk_fma_f32 v[94:95], v[74:75], v[146:147], v[106:107]
	v_lshlrev_b32_e32 v106, 16, v96
	v_and_b32_e32 v107, 0xffff0000, v96
	v_lshlrev_b32_e32 v96, 16, v97
	v_and_b32_e32 v97, 0xffff0000, v97
	v_pk_fma_f32 v[122:123], v[72:73], v[144:145], v[96:97]
	v_pk_fma_f32 v[96:97], v[70:71], v[142:143], v[106:107]
	v_mul_f32_e32 v106, v95, v95
	v_mul_f32_e32 v107, v109, v109
	v_fmac_f32_e32 v106, v94, v94
	v_fmac_f32_e32 v107, v108, v108
	v_add_f32_e32 v106, v106, v107
	v_mul_f32_e32 v107, v97, v97
	v_mul_f32_e32 v124, v123, v123
	v_fmac_f32_e32 v107, v96, v96
	v_fmac_f32_e32 v124, v122, v122
	v_add_f32_e32 v107, v107, v124
	v_add_f32_e32 v124, v106, v107
	v_or3_b32 v106, v5, s4, 48
	v_ashrrev_i32_e32 v107, 31, v106
	v_lshlrev_b64 v[106:107], 11, v[106:107]
	v_lshl_add_u64 v[106:107], v[166:167], 0, v[106:107]
	v_cvt_pk_bf16_f32 v94, v94, v95
	v_cvt_pk_bf16_f32 v95, v108, v109
	v_cvt_pk_bf16_f32 v96, v96, v97
	v_cvt_pk_bf16_f32 v97, v122, v123
	global_store_dwordx4 v[106:107], v[94:97], off
	s_nop 1
	v_mov_b32_e32 v94, v124
	s_nop 1
	v_permlane16_swap_b32_e32 v124, v94
	v_add_f32_e32 v94, v124, v94
	v_mov_b32_e32 v95, v94
	s_nop 1
	v_permlane32_swap_b32_e32 v94, v95
	s_and_saveexec_b64 s[2:3], vcc
	v_add_f32_e32 v94, v94, v95
	ds_write_b32 v182, v94 offset:192
	s_or_b64 exec, exec, s[2:3]
	s_waitcnt vmcnt(7)
	v_lshlrev_b32_e32 v94, 16, v90
	v_and_b32_e32 v95, 0xffff0000, v90
	v_lshlrev_b32_e32 v90, 16, v91
	v_and_b32_e32 v91, 0xffff0000, v91
	v_pk_fma_f32 v[96:97], v[76:77], v[136:137], v[90:91]
	v_pk_fma_f32 v[90:91], v[74:75], v[134:135], v[94:95]
	v_lshlrev_b32_e32 v94, 16, v92
	v_and_b32_e32 v95, 0xffff0000, v92
	v_lshlrev_b32_e32 v92, 16, v93
	v_and_b32_e32 v93, 0xffff0000, v93
	v_pk_fma_f32 v[106:107], v[72:73], v[132:133], v[92:93]
	v_pk_fma_f32 v[92:93], v[70:71], v[130:131], v[94:95]
	v_mul_f32_e32 v94, v91, v91
	v_mul_f32_e32 v95, v97, v97
	v_fmac_f32_e32 v94, v90, v90
	v_fmac_f32_e32 v95, v96, v96
	v_add_f32_e32 v94, v94, v95
	v_mul_f32_e32 v95, v93, v93
	v_mul_f32_e32 v108, v107, v107
	v_fmac_f32_e32 v95, v92, v92
	v_fmac_f32_e32 v108, v106, v106
	v_add_f32_e32 v95, v95, v108
	v_add_f32_e32 v108, v94, v95
	v_or3_b32 v94, v5, s4, 64
	v_ashrrev_i32_e32 v95, 31, v94
	v_lshlrev_b64 v[94:95], 11, v[94:95]
	v_lshl_add_u64 v[94:95], v[166:167], 0, v[94:95]
	v_cvt_pk_bf16_f32 v90, v90, v91
	v_cvt_pk_bf16_f32 v91, v96, v97
	v_cvt_pk_bf16_f32 v92, v92, v93
	v_cvt_pk_bf16_f32 v93, v106, v107
	global_store_dwordx4 v[94:95], v[90:93], off
	s_nop 1
	v_mov_b32_e32 v90, v108
	s_nop 1
	v_permlane16_swap_b32_e32 v108, v90
	v_add_f32_e32 v90, v108, v90
	v_mov_b32_e32 v91, v90
	s_nop 1
	v_permlane32_swap_b32_e32 v90, v91
	s_and_saveexec_b64 s[2:3], vcc
	v_add_f32_e32 v90, v90, v91
	ds_write_b32 v182, v90 offset:256
	s_or_b64 exec, exec, s[2:3]
	s_waitcnt vmcnt(7)
	v_lshlrev_b32_e32 v90, 16, v86
	v_and_b32_e32 v91, 0xffff0000, v86
	v_lshlrev_b32_e32 v86, 16, v87
	v_and_b32_e32 v87, 0xffff0000, v87
	v_pk_fma_f32 v[92:93], v[76:77], v[128:129], v[86:87]
	v_pk_fma_f32 v[86:87], v[74:75], v[126:127], v[90:91]
	v_lshlrev_b32_e32 v90, 16, v88
	v_and_b32_e32 v91, 0xffff0000, v88
	v_lshlrev_b32_e32 v88, 16, v89
	v_and_b32_e32 v89, 0xffff0000, v89
	v_pk_fma_f32 v[94:95], v[72:73], v[120:121], v[88:89]
	v_pk_fma_f32 v[88:89], v[70:71], v[118:119], v[90:91]
	v_mul_f32_e32 v90, v87, v87
	v_mul_f32_e32 v91, v93, v93
	v_fmac_f32_e32 v90, v86, v86
	v_fmac_f32_e32 v91, v92, v92
	v_add_f32_e32 v90, v90, v91
	v_mul_f32_e32 v91, v89, v89
	v_mul_f32_e32 v96, v95, v95
	v_fmac_f32_e32 v91, v88, v88
	v_fmac_f32_e32 v96, v94, v94
	v_add_f32_e32 v91, v91, v96
	v_add_f32_e32 v96, v90, v91
	v_lshlrev_b64 v[90:91], 11, v[174:175]
	v_lshl_add_u64 v[90:91], v[166:167], 0, v[90:91]
	v_cvt_pk_bf16_f32 v86, v86, v87
	v_cvt_pk_bf16_f32 v87, v92, v93
	v_cvt_pk_bf16_f32 v88, v88, v89
	v_cvt_pk_bf16_f32 v89, v94, v95
	global_store_dwordx4 v[90:91], v[86:89], off
	s_nop 1
	v_mov_b32_e32 v86, v96
	s_nop 1
	v_permlane16_swap_b32_e32 v96, v86
	v_add_f32_e32 v86, v96, v86
	v_mov_b32_e32 v87, v86
	s_nop 1
	v_permlane32_swap_b32_e32 v86, v87
	s_and_saveexec_b64 s[2:3], vcc
	v_add_f32_e32 v86, v86, v87
	ds_write_b32 v182, v86 offset:320
	s_or_b64 exec, exec, s[2:3]
	s_waitcnt vmcnt(7)
	v_lshlrev_b32_e32 v86, 16, v82
	v_and_b32_e32 v87, 0xffff0000, v82
	v_lshlrev_b32_e32 v82, 16, v83
	v_and_b32_e32 v83, 0xffff0000, v83
	v_pk_fma_f32 v[88:89], v[76:77], v[116:117], v[82:83]
	v_pk_fma_f32 v[82:83], v[74:75], v[114:115], v[86:87]
	v_lshlrev_b32_e32 v86, 16, v84
	v_and_b32_e32 v87, 0xffff0000, v84
	v_lshlrev_b32_e32 v84, 16, v85
	v_and_b32_e32 v85, 0xffff0000, v85
	v_pk_fma_f32 v[90:91], v[72:73], v[112:113], v[84:85]
	v_pk_fma_f32 v[84:85], v[70:71], v[110:111], v[86:87]
	v_mul_f32_e32 v86, v83, v83
	v_mul_f32_e32 v87, v89, v89
	v_fmac_f32_e32 v86, v82, v82
	v_fmac_f32_e32 v87, v88, v88
	v_add_f32_e32 v86, v86, v87
	v_mul_f32_e32 v87, v85, v85
	v_mul_f32_e32 v92, v91, v91
	v_fmac_f32_e32 v87, v84, v84
	v_fmac_f32_e32 v92, v90, v90
	v_add_f32_e32 v87, v87, v92
	v_add_f32_e32 v92, v86, v87
	v_lshlrev_b64 v[86:87], 11, v[172:173]
	v_lshl_add_u64 v[86:87], v[166:167], 0, v[86:87]
	v_cvt_pk_bf16_f32 v82, v82, v83
	v_cvt_pk_bf16_f32 v83, v88, v89
	v_cvt_pk_bf16_f32 v84, v84, v85
	v_cvt_pk_bf16_f32 v85, v90, v91
	global_store_dwordx4 v[86:87], v[82:85], off
	s_nop 1
	v_mov_b32_e32 v82, v92
	s_nop 1
	v_permlane16_swap_b32_e32 v92, v82
	v_add_f32_e32 v82, v92, v82
	v_mov_b32_e32 v83, v82
	s_nop 1
	v_permlane32_swap_b32_e32 v82, v83
	s_and_saveexec_b64 s[2:3], vcc
	v_add_f32_e32 v82, v82, v83
	ds_write_b32 v182, v82 offset:384
	s_or_b64 exec, exec, s[2:3]
	s_waitcnt vmcnt(7)
	v_lshlrev_b32_e32 v82, 16, v78
	v_and_b32_e32 v83, 0xffff0000, v78
	v_lshlrev_b32_e32 v78, 16, v79
	v_and_b32_e32 v79, 0xffff0000, v79
	v_pk_fma_f32 v[84:85], v[76:77], v[104:105], v[78:79]
	v_pk_fma_f32 v[78:79], v[74:75], v[102:103], v[82:83]
	v_lshlrev_b32_e32 v82, 16, v80
	v_and_b32_e32 v83, 0xffff0000, v80
	v_lshlrev_b32_e32 v80, 16, v81
	v_and_b32_e32 v81, 0xffff0000, v81
	v_pk_fma_f32 v[86:87], v[72:73], v[100:101], v[80:81]
	v_pk_fma_f32 v[80:81], v[70:71], v[98:99], v[82:83]
	v_mul_f32_e32 v82, v79, v79
	v_mul_f32_e32 v83, v85, v85
	v_fmac_f32_e32 v82, v78, v78
	v_fmac_f32_e32 v83, v84, v84
	v_add_f32_e32 v82, v82, v83
	v_mul_f32_e32 v83, v81, v81
	v_mul_f32_e32 v88, v87, v87
	v_fmac_f32_e32 v83, v80, v80
	v_fmac_f32_e32 v88, v86, v86
	v_add_f32_e32 v83, v83, v88
	v_add_f32_e32 v88, v82, v83
	v_lshlrev_b64 v[82:83], 11, v[170:171]
	v_lshl_add_u64 v[82:83], v[166:167], 0, v[82:83]
	v_cvt_pk_bf16_f32 v78, v78, v79
	v_cvt_pk_bf16_f32 v79, v84, v85
	v_cvt_pk_bf16_f32 v80, v80, v81
	v_cvt_pk_bf16_f32 v81, v86, v87
	global_store_dwordx4 v[82:83], v[78:81], off
	s_nop 1
	v_mov_b32_e32 v78, v88
	s_nop 1
	v_permlane16_swap_b32_e32 v88, v78
	v_add_f32_e32 v78, v88, v78
	v_mov_b32_e32 v79, v78
	s_nop 1
	v_permlane32_swap_b32_e32 v78, v79
	s_and_saveexec_b64 s[2:3], vcc
	v_add_f32_e32 v78, v78, v79
	ds_write_b32 v182, v78 offset:448
	s_or_b64 exec, exec, s[2:3]
	v_or_b32_e32 v78, 0x80, v168
	v_ashrrev_i32_e32 v79, 31, v78
	v_or_b32_e32 v80, 0x90, v168
	v_lshlrev_b64 v[78:79], 11, v[78:79]
	v_ashrrev_i32_e32 v81, 31, v80
	v_or_b32_e32 v178, 0xa0, v168
	v_or_b32_e32 v176, 0xb0, v168
	v_lshl_add_u64 v[78:79], v[166:167], 0, v[78:79]
	v_lshlrev_b64 v[80:81], 11, v[80:81]
	v_ashrrev_i32_e32 v179, 31, v178
	v_ashrrev_i32_e32 v177, 31, v176
	v_lshl_add_u64 v[180:181], v[166:167], 0, v[80:81]
	global_load_dwordx4 v[134:137], v[78:79], off
	global_load_dwordx4 v[110:113], v[180:181], off
	v_lshlrev_b64 v[78:79], 11, v[178:179]
	v_lshlrev_b64 v[80:81], 11, v[176:177]
	v_or_b32_e32 v174, 0xc0, v168
	v_or_b32_e32 v172, 0xd0, v168
	v_lshl_add_u64 v[78:79], v[166:167], 0, v[78:79]
	v_lshl_add_u64 v[80:81], v[166:167], 0, v[80:81]
	v_ashrrev_i32_e32 v175, 31, v174
	v_ashrrev_i32_e32 v173, 31, v172
	global_load_dwordx4 v[98:101], v[78:79], off
	global_load_dwordx4 v[94:97], v[80:81], off
	v_lshlrev_b64 v[78:79], 11, v[174:175]
	v_lshlrev_b64 v[80:81], 11, v[172:173]
	v_or_b32_e32 v170, 0xe0, v168
	v_or_b32_e32 v168, 0xf0, v168
	v_lshl_add_u64 v[78:79], v[166:167], 0, v[78:79]
	v_lshl_add_u64 v[80:81], v[166:167], 0, v[80:81]
	v_ashrrev_i32_e32 v171, 31, v170
	v_ashrrev_i32_e32 v169, 31, v168
	global_load_dwordx4 v[90:93], v[78:79], off
	global_load_dwordx4 v[86:89], v[80:81], off
	v_lshlrev_b64 v[78:79], 11, v[170:171]
	v_lshlrev_b64 v[80:81], 11, v[168:169]
	v_lshl_add_u64 v[78:79], v[166:167], 0, v[78:79]
	v_lshl_add_u64 v[80:81], v[166:167], 0, v[80:81]
	global_load_dwordx4 v[82:85], v[78:79], off
	s_nop 0
	global_load_dwordx4 v[78:81], v[80:81], off
	v_or_b32_e32 v5, 0x80, v5
	v_add_u32_e32 v114, 0x10000, v183
	v_lshl_add_u32 v130, v5, 9, 0
	v_add_u32_e32 v102, v114, v184
	v_add_u32_e32 v106, v114, v185
	v_add_u32_e32 v115, v114, v187
	v_add_u32_e32 v118, v114, v189
	v_add_u32_e32 v122, v130, v186
	v_add_u32_e32 v126, v130, v188
	v_add_u32_e32 v131, v130, v190
	v_add_u32_e32 v138, v130, v191
	ds_read_b128 v[102:105], v102
	ds_read_b128 v[106:109], v106
	ds_read_b128 v[114:117], v115
	ds_read_b128 v[118:121], v118
	ds_read_b128 v[122:125], v122
	ds_read_b128 v[126:129], v126
	ds_read_b128 v[130:133], v131
	ds_read_b128 v[138:141], v138
	s_setprio 1
	s_waitcnt lgkmcnt(7)
	v_mfma_f32_16x16x32_bf16 v[142:145], v[34:37], v[102:105], 0
	v_mfma_f32_16x16x32_bf16 v[102:105], v[66:69], v[102:105], 0
	s_waitcnt lgkmcnt(6)
	v_mfma_f32_16x16x32_bf16 v[142:145], v[30:33], v[106:109], v[142:145]
	v_mfma_f32_16x16x32_bf16 v[102:105], v[62:65], v[106:109], v[102:105]
	s_waitcnt lgkmcnt(5)
	v_mfma_f32_16x16x32_bf16 v[106:109], v[26:29], v[114:117], v[142:145]
	v_mfma_f32_16x16x32_bf16 v[102:105], v[58:61], v[114:117], v[102:105]
	s_waitcnt lgkmcnt(4)
	v_mfma_f32_16x16x32_bf16 v[106:109], v[22:25], v[118:121], v[106:109]
	v_mfma_f32_16x16x32_bf16 v[102:105], v[54:57], v[118:121], v[102:105]
	s_setprio 0
	v_add_u32_e32 v150, 0x12000, v183
	v_add_u32_e32 v114, v150, v184
	v_add_u32_e32 v118, v150, v185
	v_add_u32_e32 v142, v150, v187
	v_add_u32_e32 v146, v150, v189
	ds_read_b128 v[114:117], v114
	ds_read_b128 v[118:121], v118
	ds_read_b128 v[142:145], v142
	ds_read_b128 v[146:149], v146
	s_setprio 1
	s_waitcnt lgkmcnt(7)
	v_mfma_f32_16x16x32_bf16 v[106:109], v[18:21], v[122:125], v[106:109]
	v_mfma_f32_16x16x32_bf16 v[102:105], v[50:53], v[122:125], v[102:105]
	s_waitcnt lgkmcnt(6)
	v_mfma_f32_16x16x32_bf16 v[106:109], v[14:17], v[126:129], v[106:109]
	v_mfma_f32_16x16x32_bf16 v[102:105], v[46:49], v[126:129], v[102:105]
	s_waitcnt lgkmcnt(5)
	v_mfma_f32_16x16x32_bf16 v[106:109], v[10:13], v[130:133], v[106:109]
	v_mfma_f32_16x16x32_bf16 v[102:105], v[42:45], v[130:133], v[102:105]
	s_waitcnt lgkmcnt(4)
	v_mfma_f32_16x16x32_bf16 v[162:165], v[6:9], v[138:141], v[106:109]
	v_mfma_f32_16x16x32_bf16 v[158:161], v[38:41], v[138:141], v[102:105]
	s_setprio 0
	s_nop 3
	v_add_u32_e32 v102, v150, v186
	v_add_u32_e32 v106, v150, v188
	v_add_u32_e32 v122, v150, v190
	v_add_u32_e32 v126, v150, v191
	ds_read_b128 v[102:105], v102
	ds_read_b128 v[106:109], v106
	ds_read_b128 v[122:125], v122
	ds_read_b128 v[126:129], v126
	s_setprio 1
	s_waitcnt lgkmcnt(7)
	v_mfma_f32_16x16x32_bf16 v[130:133], v[34:37], v[114:117], 0
	v_mfma_f32_16x16x32_bf16 v[114:117], v[66:69], v[114:117], 0
	s_waitcnt lgkmcnt(6)
	v_mfma_f32_16x16x32_bf16 v[130:133], v[30:33], v[118:121], v[130:133]
	v_mfma_f32_16x16x32_bf16 v[114:117], v[62:65], v[118:121], v[114:117]
	s_waitcnt lgkmcnt(5)
	v_mfma_f32_16x16x32_bf16 v[118:121], v[26:29], v[142:145], v[130:133]
	v_mfma_f32_16x16x32_bf16 v[114:117], v[58:61], v[142:145], v[114:117]
	s_waitcnt lgkmcnt(4)
	v_mfma_f32_16x16x32_bf16 v[118:121], v[22:25], v[146:149], v[118:121]
	v_mfma_f32_16x16x32_bf16 v[114:117], v[54:57], v[146:149], v[114:117]
	s_setprio 0
	v_add_u32_e32 v192, 0x14000, v183
	v_add_u32_e32 v130, v192, v184
	v_add_u32_e32 v138, v192, v185
	v_add_u32_e32 v142, v192, v187
	v_add_u32_e32 v146, v192, v189
	ds_read_b128 v[130:133], v130
	ds_read_b128 v[138:141], v138
	ds_read_b128 v[142:145], v142
	ds_read_b128 v[146:149], v146
	s_setprio 1
	s_waitcnt lgkmcnt(7)
	v_mfma_f32_16x16x32_bf16 v[118:121], v[18:21], v[102:105], v[118:121]
	v_mfma_f32_16x16x32_bf16 v[102:105], v[50:53], v[102:105], v[114:117]
	s_waitcnt lgkmcnt(6)
	v_mfma_f32_16x16x32_bf16 v[114:117], v[14:17], v[106:109], v[118:121]
	v_mfma_f32_16x16x32_bf16 v[102:105], v[46:49], v[106:109], v[102:105]
	s_waitcnt lgkmcnt(5)
	v_mfma_f32_16x16x32_bf16 v[106:109], v[10:13], v[122:125], v[114:117]
	v_mfma_f32_16x16x32_bf16 v[102:105], v[42:45], v[122:125], v[102:105]
	s_waitcnt lgkmcnt(4)
	v_mfma_f32_16x16x32_bf16 v[154:157], v[6:9], v[126:129], v[106:109]
	v_mfma_f32_16x16x32_bf16 v[150:153], v[38:41], v[126:129], v[102:105]
	s_setprio 0
	s_nop 3
	v_add_u32_e32 v102, v192, v186
	v_add_u32_e32 v106, v192, v188
	v_add_u32_e32 v114, v192, v190
	v_add_u32_e32 v118, v192, v191
	ds_read_b128 v[102:105], v102
	ds_read_b128 v[106:109], v106
	ds_read_b128 v[114:117], v114
	ds_read_b128 v[118:121], v118
	s_setprio 1
	s_waitcnt lgkmcnt(7)
	v_mfma_f32_16x16x32_bf16 v[122:125], v[34:37], v[130:133], 0
	v_mfma_f32_16x16x32_bf16 v[126:129], v[66:69], v[130:133], 0
	s_waitcnt lgkmcnt(6)
	v_mfma_f32_16x16x32_bf16 v[122:125], v[30:33], v[138:141], v[122:125]
	v_mfma_f32_16x16x32_bf16 v[126:129], v[62:65], v[138:141], v[126:129]
	s_waitcnt lgkmcnt(5)
	v_mfma_f32_16x16x32_bf16 v[122:125], v[26:29], v[142:145], v[122:125]
	v_mfma_f32_16x16x32_bf16 v[126:129], v[58:61], v[142:145], v[126:129]
	s_waitcnt lgkmcnt(4)
	v_mfma_f32_16x16x32_bf16 v[122:125], v[22:25], v[146:149], v[122:125]
	v_mfma_f32_16x16x32_bf16 v[126:129], v[54:57], v[146:149], v[126:129]
	s_setprio 0
	v_add_u32_e32 v200, 0x16000, v183
	v_add_u32_e32 v130, v200, v184
	v_add_u32_e32 v138, v200, v185
	v_add_u32_e32 v142, v200, v187
	ds_read_b128 v[130:133], v130
	ds_read_b128 v[138:141], v138
	v_add_u32_e32 v143, v200, v189
	ds_read_b128 v[192:195], v142
	ds_read_b128 v[196:199], v143
	s_setprio 1
	s_waitcnt lgkmcnt(7)
	v_mfma_f32_16x16x32_bf16 v[122:125], v[18:21], v[102:105], v[122:125]
	v_mfma_f32_16x16x32_bf16 v[102:105], v[50:53], v[102:105], v[126:129]
	s_waitcnt lgkmcnt(6)
	v_mfma_f32_16x16x32_bf16 v[122:125], v[14:17], v[106:109], v[122:125]
	v_mfma_f32_16x16x32_bf16 v[102:105], v[46:49], v[106:109], v[102:105]
	s_waitcnt lgkmcnt(5)
	v_mfma_f32_16x16x32_bf16 v[106:109], v[10:13], v[114:117], v[122:125]
	v_mfma_f32_16x16x32_bf16 v[102:105], v[42:45], v[114:117], v[102:105]
	s_waitcnt lgkmcnt(4)
	v_mfma_f32_16x16x32_bf16 v[146:149], v[6:9], v[118:121], v[106:109]
	v_mfma_f32_16x16x32_bf16 v[142:145], v[38:41], v[118:121], v[102:105]
	s_setprio 0
	s_nop 3
	v_add_u32_e32 v102, v200, v186
	v_add_u32_e32 v106, v200, v188
	v_add_u32_e32 v114, v200, v190
	v_add_u32_e32 v118, v200, v191
	ds_read_b128 v[102:105], v102
	ds_read_b128 v[106:109], v106
	ds_read_b128 v[114:117], v114
	ds_read_b128 v[118:121], v118
	s_setprio 1
	s_waitcnt lgkmcnt(7)
	v_mfma_f32_16x16x32_bf16 v[122:125], v[34:37], v[130:133], 0
	v_mfma_f32_16x16x32_bf16 v[126:129], v[66:69], v[130:133], 0
	s_waitcnt lgkmcnt(6)
	v_mfma_f32_16x16x32_bf16 v[122:125], v[30:33], v[138:141], v[122:125]
	v_mfma_f32_16x16x32_bf16 v[126:129], v[62:65], v[138:141], v[126:129]
	s_waitcnt lgkmcnt(5)
	v_mfma_f32_16x16x32_bf16 v[122:125], v[26:29], v[192:195], v[122:125]
	v_mfma_f32_16x16x32_bf16 v[126:129], v[58:61], v[192:195], v[126:129]
	s_waitcnt lgkmcnt(4)
	v_mfma_f32_16x16x32_bf16 v[122:125], v[22:25], v[196:199], v[122:125]
	v_mfma_f32_16x16x32_bf16 v[126:129], v[54:57], v[196:199], v[126:129]
	s_setprio 0
	v_add_u32_e32 v208, 0x18000, v183
	v_add_u32_e32 v130, v208, v184
	v_add_u32_e32 v131, v208, v185
	ds_read_b128 v[192:195], v130
	ds_read_b128 v[196:199], v131
	v_add_u32_e32 v130, v208, v187
	v_add_u32_e32 v131, v208, v189
	ds_read_b128 v[200:203], v130
	ds_read_b128 v[204:207], v131
	s_setprio 1
	s_waitcnt lgkmcnt(7)
	v_mfma_f32_16x16x32_bf16 v[122:125], v[18:21], v[102:105], v[122:125]
	v_mfma_f32_16x16x32_bf16 v[102:105], v[50:53], v[102:105], v[126:129]
	s_waitcnt lgkmcnt(6)
	v_mfma_f32_16x16x32_bf16 v[122:125], v[14:17], v[106:109], v[122:125]
	v_mfma_f32_16x16x32_bf16 v[102:105], v[46:49], v[106:109], v[102:105]
	s_waitcnt lgkmcnt(5)
	v_mfma_f32_16x16x32_bf16 v[106:109], v[10:13], v[114:117], v[122:125]
	v_mfma_f32_16x16x32_bf16 v[102:105], v[42:45], v[114:117], v[102:105]
	s_waitcnt lgkmcnt(4)
	v_mfma_f32_16x16x32_bf16 v[138:141], v[6:9], v[118:121], v[106:109]
	v_mfma_f32_16x16x32_bf16 v[130:133], v[38:41], v[118:121], v[102:105]
	s_setprio 0
	s_nop 3
	v_add_u32_e32 v102, v208, v186
	v_add_u32_e32 v106, v208, v188
	v_add_u32_e32 v114, v208, v190
	v_add_u32_e32 v118, v208, v191
	ds_read_b128 v[102:105], v102
	ds_read_b128 v[106:109], v106
	ds_read_b128 v[114:117], v114
	ds_read_b128 v[118:121], v118
	s_setprio 1
	s_waitcnt lgkmcnt(7)
	v_mfma_f32_16x16x32_bf16 v[122:125], v[34:37], v[192:195], 0
	v_mfma_f32_16x16x32_bf16 v[126:129], v[66:69], v[192:195], 0
	s_waitcnt lgkmcnt(6)
	v_mfma_f32_16x16x32_bf16 v[122:125], v[30:33], v[196:199], v[122:125]
	v_mfma_f32_16x16x32_bf16 v[126:129], v[62:65], v[196:199], v[126:129]
	s_waitcnt lgkmcnt(5)
	v_mfma_f32_16x16x32_bf16 v[122:125], v[26:29], v[200:203], v[122:125]
	v_mfma_f32_16x16x32_bf16 v[126:129], v[58:61], v[200:203], v[126:129]
	s_waitcnt lgkmcnt(4)
	v_mfma_f32_16x16x32_bf16 v[122:125], v[22:25], v[204:207], v[122:125]
	v_mfma_f32_16x16x32_bf16 v[126:129], v[54:57], v[204:207], v[126:129]
	s_setprio 0
	v_add_u32_e32 v208, 0x1a000, v183
	v_add_u32_e32 v192, v208, v184
	v_add_u32_e32 v196, v208, v185
	v_add_u32_e32 v200, v208, v187
	v_add_u32_e32 v204, v208, v189
	ds_read_b128 v[192:195], v192
	ds_read_b128 v[196:199], v196
	ds_read_b128 v[200:203], v200
	ds_read_b128 v[204:207], v204
	s_setprio 1
	s_waitcnt lgkmcnt(7)
	v_mfma_f32_16x16x32_bf16 v[122:125], v[18:21], v[102:105], v[122:125]
	v_mfma_f32_16x16x32_bf16 v[102:105], v[50:53], v[102:105], v[126:129]
	s_waitcnt lgkmcnt(6)
	v_mfma_f32_16x16x32_bf16 v[122:125], v[14:17], v[106:109], v[122:125]
	v_mfma_f32_16x16x32_bf16 v[102:105], v[46:49], v[106:109], v[102:105]
	s_waitcnt lgkmcnt(5)
	v_mfma_f32_16x16x32_bf16 v[106:109], v[10:13], v[114:117], v[122:125]
	v_mfma_f32_16x16x32_bf16 v[102:105], v[42:45], v[114:117], v[102:105]
	s_waitcnt lgkmcnt(4)
	v_mfma_f32_16x16x32_bf16 v[126:129], v[6:9], v[118:121], v[106:109]
	v_mfma_f32_16x16x32_bf16 v[122:125], v[38:41], v[118:121], v[102:105]
	s_setprio 0
	s_nop 3
	v_add_u32_e32 v102, v208, v186
	v_add_u32_e32 v106, v208, v188
	v_add_u32_e32 v114, v208, v190
	ds_read_b128 v[102:105], v102
	ds_read_b128 v[106:109], v106
	v_add_u32_e32 v118, v208, v191
	ds_read_b128 v[114:117], v114
	ds_read_b128 v[208:211], v118
	s_setprio 1
	s_waitcnt lgkmcnt(7)
	v_mfma_f32_16x16x32_bf16 v[118:121], v[34:37], v[192:195], 0
	v_mfma_f32_16x16x32_bf16 v[192:195], v[66:69], v[192:195], 0
	s_waitcnt lgkmcnt(6)
	v_mfma_f32_16x16x32_bf16 v[118:121], v[30:33], v[196:199], v[118:121]
	v_mfma_f32_16x16x32_bf16 v[192:195], v[62:65], v[196:199], v[192:195]
	s_waitcnt lgkmcnt(5)
	v_mfma_f32_16x16x32_bf16 v[118:121], v[26:29], v[200:203], v[118:121]
	v_mfma_f32_16x16x32_bf16 v[192:195], v[58:61], v[200:203], v[192:195]
	s_waitcnt lgkmcnt(4)
	v_mfma_f32_16x16x32_bf16 v[118:121], v[22:25], v[204:207], v[118:121]
	v_mfma_f32_16x16x32_bf16 v[192:195], v[54:57], v[204:207], v[192:195]
	s_setprio 0
	v_add_u32_e32 v216, 0x1c000, v183
	v_add_u32_e32 v196, v216, v184
	v_add_u32_e32 v200, v216, v185
	v_add_u32_e32 v204, v216, v187
	v_add_u32_e32 v212, v216, v189
	ds_read_b128 v[196:199], v196
	ds_read_b128 v[200:203], v200
	ds_read_b128 v[204:207], v204
	ds_read_b128 v[212:215], v212
	s_setprio 1
	s_waitcnt lgkmcnt(7)
	v_mfma_f32_16x16x32_bf16 v[118:121], v[18:21], v[102:105], v[118:121]
	v_mfma_f32_16x16x32_bf16 v[102:105], v[50:53], v[102:105], v[192:195]
	s_waitcnt lgkmcnt(6)
	v_mfma_f32_16x16x32_bf16 v[118:121], v[14:17], v[106:109], v[118:121]
	v_mfma_f32_16x16x32_bf16 v[102:105], v[46:49], v[106:109], v[102:105]
	s_waitcnt lgkmcnt(5)
	v_mfma_f32_16x16x32_bf16 v[106:109], v[10:13], v[114:117], v[118:121]
	v_mfma_f32_16x16x32_bf16 v[102:105], v[42:45], v[114:117], v[102:105]
	s_waitcnt lgkmcnt(4)
	v_mfma_f32_16x16x32_bf16 v[118:121], v[6:9], v[208:211], v[106:109]
	v_mfma_f32_16x16x32_bf16 v[114:117], v[38:41], v[208:211], v[102:105]
	s_setprio 0
	s_nop 3
	v_add_u32_e32 v102, v216, v186
	v_add_u32_e32 v106, v216, v188
	v_add_u32_e32 v192, v216, v190
	v_add_u32_e32 v208, v216, v191
	ds_read_b128 v[102:105], v102
	ds_read_b128 v[106:109], v106
	ds_read_b128 v[192:195], v192
	ds_read_b128 v[208:211], v208
	s_setprio 1
	s_waitcnt lgkmcnt(7)
	v_mfma_f32_16x16x32_bf16 v[216:219], v[34:37], v[196:199], 0
	v_mfma_f32_16x16x32_bf16 v[196:199], v[66:69], v[196:199], 0
	s_waitcnt lgkmcnt(6)
	v_mfma_f32_16x16x32_bf16 v[216:219], v[30:33], v[200:203], v[216:219]
	v_mfma_f32_16x16x32_bf16 v[196:199], v[62:65], v[200:203], v[196:199]
	s_waitcnt lgkmcnt(5)
	v_mfma_f32_16x16x32_bf16 v[200:203], v[26:29], v[204:207], v[216:219]
	v_mfma_f32_16x16x32_bf16 v[196:199], v[58:61], v[204:207], v[196:199]
	s_waitcnt lgkmcnt(4)
	v_mfma_f32_16x16x32_bf16 v[200:203], v[22:25], v[212:215], v[200:203]
	v_mfma_f32_16x16x32_bf16 v[196:199], v[54:57], v[212:215], v[196:199]
	s_setprio 0
	v_add_u32_e32 v183, 0x1e000, v183
	v_add_u32_e32 v184, v183, v184
	v_add_u32_e32 v185, v183, v185
	ds_read_b128 v[204:207], v184
	ds_read_b128 v[212:215], v185
	v_add_u32_e32 v184, v183, v187
	v_add_u32_e32 v185, v183, v189
	ds_read_b128 v[216:219], v184
	ds_read_b128 v[220:223], v185
	s_setprio 1
	s_waitcnt lgkmcnt(7)
	v_mfma_f32_16x16x32_bf16 v[200:203], v[18:21], v[102:105], v[200:203]
	v_mfma_f32_16x16x32_bf16 v[102:105], v[50:53], v[102:105], v[196:199]
	s_waitcnt lgkmcnt(6)
	v_mfma_f32_16x16x32_bf16 v[196:199], v[14:17], v[106:109], v[200:203]
	v_mfma_f32_16x16x32_bf16 v[102:105], v[46:49], v[106:109], v[102:105]
	s_waitcnt lgkmcnt(5)
	v_mfma_f32_16x16x32_bf16 v[106:109], v[10:13], v[192:195], v[196:199]
	v_mfma_f32_16x16x32_bf16 v[102:105], v[42:45], v[192:195], v[102:105]
	s_waitcnt lgkmcnt(4)
	v_mfma_f32_16x16x32_bf16 v[106:109], v[6:9], v[208:211], v[106:109]
	v_mfma_f32_16x16x32_bf16 v[102:105], v[38:41], v[208:211], v[102:105]
	s_setprio 0
	v_add_u32_e32 v184, v183, v186
	v_add_u32_e32 v188, v183, v188
	ds_read_b128 v[184:187], v184
	ds_read_b128 v[192:195], v188
	v_add_u32_e32 v188, v183, v190
	v_add_u32_e32 v183, v183, v191
	ds_read_b128 v[188:191], v188
	ds_read_b128 v[196:199], v183
	s_setprio 1
	s_waitcnt lgkmcnt(7)
	v_mfma_f32_16x16x32_bf16 v[34:37], v[34:37], v[204:207], 0
	v_mfma_f32_16x16x32_bf16 v[66:69], v[66:69], v[204:207], 0
	s_waitcnt lgkmcnt(6)
	v_mfma_f32_16x16x32_bf16 v[30:33], v[30:33], v[212:215], v[34:37]
	v_mfma_f32_16x16x32_bf16 v[34:37], v[62:65], v[212:215], v[66:69]
	s_waitcnt lgkmcnt(5)
	v_mfma_f32_16x16x32_bf16 v[26:29], v[26:29], v[216:219], v[30:33]
	v_mfma_f32_16x16x32_bf16 v[30:33], v[58:61], v[216:219], v[34:37]
	s_waitcnt lgkmcnt(4)
	v_mfma_f32_16x16x32_bf16 v[22:25], v[22:25], v[220:223], v[26:29]
	v_mfma_f32_16x16x32_bf16 v[26:29], v[54:57], v[220:223], v[30:33]
	s_setprio 0
	s_setprio 1
	s_waitcnt lgkmcnt(3)
	v_mfma_f32_16x16x32_bf16 v[18:21], v[18:21], v[184:187], v[22:25]
	v_mfma_f32_16x16x32_bf16 v[22:25], v[50:53], v[184:187], v[26:29]
	s_waitcnt lgkmcnt(2)
	v_mfma_f32_16x16x32_bf16 v[14:17], v[14:17], v[192:195], v[18:21]
	v_mfma_f32_16x16x32_bf16 v[18:21], v[46:49], v[192:195], v[22:25]
	s_waitcnt lgkmcnt(1)
	v_mfma_f32_16x16x32_bf16 v[10:13], v[10:13], v[188:191], v[14:17]
	v_mfma_f32_16x16x32_bf16 v[14:17], v[42:45], v[188:191], v[18:21]
	s_waitcnt lgkmcnt(0)
	v_mfma_f32_16x16x32_bf16 v[10:13], v[6:9], v[196:199], v[10:13]
	v_mfma_f32_16x16x32_bf16 v[6:9], v[38:41], v[196:199], v[14:17]
	s_setprio 0
	s_waitcnt vmcnt(7)
	s_nop 2
	v_lshlrev_b32_e32 v14, 16, v134
	v_and_b32_e32 v15, 0xffff0000, v134
	v_lshlrev_b32_e32 v16, 16, v135
	v_and_b32_e32 v17, 0xffff0000, v135
	v_pk_fma_f32 v[16:17], v[76:77], v[164:165], v[16:17]
	v_pk_fma_f32 v[14:15], v[74:75], v[162:163], v[14:15]
	v_lshlrev_b32_e32 v18, 16, v136
	v_and_b32_e32 v19, 0xffff0000, v136
	v_lshlrev_b32_e32 v20, 16, v137
	v_and_b32_e32 v21, 0xffff0000, v137
	v_mul_f32_e32 v22, v15, v15
	v_mul_f32_e32 v23, v17, v17
	v_pk_fma_f32 v[20:21], v[72:73], v[160:161], v[20:21]
	v_pk_fma_f32 v[18:19], v[70:71], v[158:159], v[18:19]
	v_fmac_f32_e32 v22, v14, v14
	v_fmac_f32_e32 v23, v16, v16
	v_add_f32_e32 v22, v22, v23
	v_mul_f32_e32 v23, v19, v19
	v_mul_f32_e32 v24, v21, v21
	v_fmac_f32_e32 v23, v18, v18
	v_fmac_f32_e32 v24, v20, v20
	v_add_f32_e32 v23, v23, v24
	v_add_f32_e32 v24, v22, v23
	v_or_b32_e32 v22, s4, v5
	v_ashrrev_i32_e32 v23, 31, v22
	v_mov_b32_e32 v5, v24
	v_lshlrev_b64 v[22:23], 11, v[22:23]
	s_nop 0
	v_permlane16_swap_b32_e32 v24, v5
	v_lshl_add_u64 v[22:23], v[166:167], 0, v[22:23]
	v_cvt_pk_bf16_f32 v14, v14, v15
	v_add_f32_e32 v5, v24, v5
	v_cvt_pk_bf16_f32 v15, v16, v17
	v_cvt_pk_bf16_f32 v16, v18, v19
	v_cvt_pk_bf16_f32 v17, v20, v21
	global_store_dwordx4 v[22:23], v[14:17], off
	s_nop 1
	v_mov_b32_e32 v14, v5
	s_nop 1
	v_permlane32_swap_b32_e32 v5, v14
	s_and_saveexec_b64 s[2:3], vcc
	v_add_f32_e32 v5, v5, v14
	ds_write_b32 v182, v5 offset:512
	s_or_b64 exec, exec, s[2:3]
	s_waitcnt vmcnt(7)
	v_lshlrev_b32_e32 v14, 16, v110
	v_and_b32_e32 v15, 0xffff0000, v110
	v_lshlrev_b32_e32 v16, 16, v111
	v_and_b32_e32 v17, 0xffff0000, v111
	v_pk_fma_f32 v[16:17], v[76:77], v[156:157], v[16:17]
	v_pk_fma_f32 v[14:15], v[74:75], v[154:155], v[14:15]
	v_lshlrev_b32_e32 v18, 16, v112
	v_and_b32_e32 v19, 0xffff0000, v112
	v_lshlrev_b32_e32 v20, 16, v113
	v_and_b32_e32 v21, 0xffff0000, v113
	v_mul_f32_e32 v5, v15, v15
	v_mul_f32_e32 v22, v17, v17
	v_pk_fma_f32 v[20:21], v[72:73], v[152:153], v[20:21]
	v_pk_fma_f32 v[18:19], v[70:71], v[150:151], v[18:19]
	v_fmac_f32_e32 v5, v14, v14
	v_fmac_f32_e32 v22, v16, v16
	v_add_f32_e32 v5, v5, v22
	v_mul_f32_e32 v22, v19, v19
	v_mul_f32_e32 v23, v21, v21
	v_fmac_f32_e32 v22, v18, v18
	v_fmac_f32_e32 v23, v20, v20
	v_add_f32_e32 v22, v22, v23
	v_add_f32_e32 v5, v5, v22
	v_cvt_pk_bf16_f32 v14, v14, v15
	v_cvt_pk_bf16_f32 v15, v16, v17
	v_cvt_pk_bf16_f32 v16, v18, v19
	v_cvt_pk_bf16_f32 v17, v20, v21
	global_store_dwordx4 v[180:181], v[14:17], off
	s_nop 1
	v_mov_b32_e32 v14, v5
	s_nop 1
	v_permlane16_swap_b32_e32 v5, v14
	v_add_f32_e32 v5, v5, v14
	v_mov_b32_e32 v14, v5
	s_nop 1
	v_permlane32_swap_b32_e32 v5, v14
	s_and_saveexec_b64 s[2:3], vcc
	v_add_f32_e32 v5, v5, v14
	ds_write_b32 v182, v5 offset:576
	s_or_b64 exec, exec, s[2:3]
	s_waitcnt vmcnt(7)
	v_lshlrev_b32_e32 v14, 16, v98
	v_and_b32_e32 v15, 0xffff0000, v98
	v_lshlrev_b32_e32 v16, 16, v99
	v_and_b32_e32 v17, 0xffff0000, v99
	v_pk_fma_f32 v[16:17], v[76:77], v[148:149], v[16:17]
	v_pk_fma_f32 v[14:15], v[74:75], v[146:147], v[14:15]
	v_lshlrev_b32_e32 v18, 16, v100
	v_and_b32_e32 v19, 0xffff0000, v100
	v_lshlrev_b32_e32 v20, 16, v101
	v_and_b32_e32 v21, 0xffff0000, v101
	v_mul_f32_e32 v5, v15, v15
	v_mul_f32_e32 v22, v17, v17
	v_pk_fma_f32 v[20:21], v[72:73], v[144:145], v[20:21]
	v_pk_fma_f32 v[18:19], v[70:71], v[142:143], v[18:19]
	v_fmac_f32_e32 v5, v14, v14
	v_fmac_f32_e32 v22, v16, v16
	v_add_f32_e32 v5, v5, v22
	v_mul_f32_e32 v22, v19, v19
	v_mul_f32_e32 v23, v21, v21
	v_fmac_f32_e32 v22, v18, v18
	v_fmac_f32_e32 v23, v20, v20
	v_add_f32_e32 v22, v22, v23
	v_add_f32_e32 v5, v5, v22
	v_lshlrev_b64 v[22:23], 11, v[178:179]
	v_lshl_add_u64 v[22:23], v[166:167], 0, v[22:23]
	v_cvt_pk_bf16_f32 v14, v14, v15
	v_cvt_pk_bf16_f32 v15, v16, v17
	v_cvt_pk_bf16_f32 v16, v18, v19
	v_cvt_pk_bf16_f32 v17, v20, v21
	global_store_dwordx4 v[22:23], v[14:17], off
	s_nop 1
	v_mov_b32_e32 v14, v5
	s_nop 1
	v_permlane16_swap_b32_e32 v5, v14
	v_add_f32_e32 v5, v5, v14
	v_mov_b32_e32 v14, v5
	s_nop 1
	v_permlane32_swap_b32_e32 v5, v14
	s_and_saveexec_b64 s[2:3], vcc
	v_add_f32_e32 v5, v5, v14
	ds_write_b32 v182, v5 offset:640
	s_or_b64 exec, exec, s[2:3]
	s_waitcnt vmcnt(7)
	v_lshlrev_b32_e32 v14, 16, v94
	v_and_b32_e32 v15, 0xffff0000, v94
	v_lshlrev_b32_e32 v16, 16, v95
	v_and_b32_e32 v17, 0xffff0000, v95
	v_pk_fma_f32 v[16:17], v[76:77], v[140:141], v[16:17]
	v_pk_fma_f32 v[14:15], v[74:75], v[138:139], v[14:15]
	v_lshlrev_b32_e32 v18, 16, v96
	v_and_b32_e32 v19, 0xffff0000, v96
	v_lshlrev_b32_e32 v20, 16, v97
	v_and_b32_e32 v21, 0xffff0000, v97
	v_mul_f32_e32 v5, v15, v15
	v_mul_f32_e32 v22, v17, v17
	v_pk_fma_f32 v[20:21], v[72:73], v[132:133], v[20:21]
	v_pk_fma_f32 v[18:19], v[70:71], v[130:131], v[18:19]
	v_fmac_f32_e32 v5, v14, v14
	v_fmac_f32_e32 v22, v16, v16
	v_add_f32_e32 v5, v5, v22
	v_mul_f32_e32 v22, v19, v19
	v_mul_f32_e32 v23, v21, v21
	v_fmac_f32_e32 v22, v18, v18
	v_fmac_f32_e32 v23, v20, v20
	v_add_f32_e32 v22, v22, v23
	v_add_f32_e32 v5, v5, v22
	v_lshlrev_b64 v[22:23], 11, v[176:177]
	v_lshl_add_u64 v[22:23], v[166:167], 0, v[22:23]
	v_cvt_pk_bf16_f32 v14, v14, v15
	v_cvt_pk_bf16_f32 v15, v16, v17
	v_cvt_pk_bf16_f32 v16, v18, v19
	v_cvt_pk_bf16_f32 v17, v20, v21
	global_store_dwordx4 v[22:23], v[14:17], off
	s_nop 1
	v_mov_b32_e32 v14, v5
	s_nop 1
	v_permlane16_swap_b32_e32 v5, v14
	v_add_f32_e32 v5, v5, v14
	v_mov_b32_e32 v14, v5
	s_nop 1
	v_permlane32_swap_b32_e32 v5, v14
	s_and_saveexec_b64 s[2:3], vcc
	v_add_f32_e32 v5, v5, v14
	ds_write_b32 v182, v5 offset:704
	s_or_b64 exec, exec, s[2:3]
	s_waitcnt vmcnt(7)
	v_lshlrev_b32_e32 v14, 16, v90
	v_and_b32_e32 v15, 0xffff0000, v90
	v_lshlrev_b32_e32 v16, 16, v91
	v_and_b32_e32 v17, 0xffff0000, v91
	v_pk_fma_f32 v[16:17], v[76:77], v[128:129], v[16:17]
	v_pk_fma_f32 v[14:15], v[74:75], v[126:127], v[14:15]
	v_lshlrev_b32_e32 v18, 16, v92
	v_and_b32_e32 v19, 0xffff0000, v92
	v_lshlrev_b32_e32 v20, 16, v93
	v_and_b32_e32 v21, 0xffff0000, v93
	v_mul_f32_e32 v5, v15, v15
	v_mul_f32_e32 v22, v17, v17
	v_pk_fma_f32 v[20:21], v[72:73], v[124:125], v[20:21]
	v_pk_fma_f32 v[18:19], v[70:71], v[122:123], v[18:19]
	v_fmac_f32_e32 v5, v14, v14
	v_fmac_f32_e32 v22, v16, v16
	v_add_f32_e32 v5, v5, v22
	v_mul_f32_e32 v22, v19, v19
	v_mul_f32_e32 v23, v21, v21
	v_fmac_f32_e32 v22, v18, v18
	v_fmac_f32_e32 v23, v20, v20
	v_add_f32_e32 v22, v22, v23
	v_add_f32_e32 v5, v5, v22
	v_lshlrev_b64 v[22:23], 11, v[174:175]
	v_lshl_add_u64 v[22:23], v[166:167], 0, v[22:23]
	v_cvt_pk_bf16_f32 v14, v14, v15
	v_cvt_pk_bf16_f32 v15, v16, v17
	v_cvt_pk_bf16_f32 v16, v18, v19
	v_cvt_pk_bf16_f32 v17, v20, v21
	global_store_dwordx4 v[22:23], v[14:17], off
	s_nop 1
	v_mov_b32_e32 v14, v5
	s_nop 1
	v_permlane16_swap_b32_e32 v5, v14
	v_add_f32_e32 v5, v5, v14
	v_mov_b32_e32 v14, v5
	s_nop 1
	v_permlane32_swap_b32_e32 v5, v14
	s_and_saveexec_b64 s[2:3], vcc
	v_add_f32_e32 v5, v5, v14
	ds_write_b32 v182, v5 offset:768
	s_or_b64 exec, exec, s[2:3]
	s_waitcnt vmcnt(7)
	v_lshlrev_b32_e32 v14, 16, v86
	v_and_b32_e32 v15, 0xffff0000, v86
	v_lshlrev_b32_e32 v16, 16, v87
	v_and_b32_e32 v17, 0xffff0000, v87
	v_pk_fma_f32 v[16:17], v[76:77], v[120:121], v[16:17]
	v_pk_fma_f32 v[14:15], v[74:75], v[118:119], v[14:15]
	v_lshlrev_b32_e32 v18, 16, v88
	v_and_b32_e32 v19, 0xffff0000, v88
	v_lshlrev_b32_e32 v20, 16, v89
	v_and_b32_e32 v21, 0xffff0000, v89
	v_mul_f32_e32 v5, v15, v15
	v_mul_f32_e32 v22, v17, v17
	v_pk_fma_f32 v[20:21], v[72:73], v[116:117], v[20:21]
	v_pk_fma_f32 v[18:19], v[70:71], v[114:115], v[18:19]
	v_fmac_f32_e32 v5, v14, v14
	v_fmac_f32_e32 v22, v16, v16
	v_add_f32_e32 v5, v5, v22
	v_mul_f32_e32 v22, v19, v19
	v_mul_f32_e32 v23, v21, v21
	v_fmac_f32_e32 v22, v18, v18
	v_fmac_f32_e32 v23, v20, v20
	v_add_f32_e32 v22, v22, v23
	v_add_f32_e32 v5, v5, v22
	v_lshlrev_b64 v[22:23], 11, v[172:173]
	v_lshl_add_u64 v[22:23], v[166:167], 0, v[22:23]
	v_cvt_pk_bf16_f32 v14, v14, v15
	v_cvt_pk_bf16_f32 v15, v16, v17
	v_cvt_pk_bf16_f32 v16, v18, v19
	v_cvt_pk_bf16_f32 v17, v20, v21
	global_store_dwordx4 v[22:23], v[14:17], off
	s_nop 1
	v_mov_b32_e32 v14, v5
	s_nop 1
	v_permlane16_swap_b32_e32 v5, v14
	v_add_f32_e32 v5, v5, v14
	v_mov_b32_e32 v14, v5
	s_nop 1
	v_permlane32_swap_b32_e32 v5, v14
	s_and_saveexec_b64 s[2:3], vcc
	v_add_f32_e32 v5, v5, v14
	ds_write_b32 v182, v5 offset:832
	s_or_b64 exec, exec, s[2:3]
	s_waitcnt vmcnt(7)
	v_lshlrev_b32_e32 v14, 16, v82
	v_and_b32_e32 v15, 0xffff0000, v82
	v_lshlrev_b32_e32 v16, 16, v83
	v_and_b32_e32 v17, 0xffff0000, v83
	v_pk_fma_f32 v[16:17], v[76:77], v[108:109], v[16:17]
	v_pk_fma_f32 v[14:15], v[74:75], v[106:107], v[14:15]
	v_lshlrev_b32_e32 v18, 16, v84
	v_and_b32_e32 v19, 0xffff0000, v84
	v_lshlrev_b32_e32 v20, 16, v85
	v_and_b32_e32 v21, 0xffff0000, v85
	v_mul_f32_e32 v5, v15, v15
	v_mul_f32_e32 v22, v17, v17
	v_pk_fma_f32 v[20:21], v[72:73], v[104:105], v[20:21]
	v_pk_fma_f32 v[18:19], v[70:71], v[102:103], v[18:19]
	v_fmac_f32_e32 v5, v14, v14
	v_fmac_f32_e32 v22, v16, v16
	v_add_f32_e32 v5, v5, v22
	v_mul_f32_e32 v22, v19, v19
	v_mul_f32_e32 v23, v21, v21
	v_fmac_f32_e32 v22, v18, v18
	v_fmac_f32_e32 v23, v20, v20
	v_add_f32_e32 v22, v22, v23
	v_add_f32_e32 v5, v5, v22
	v_lshlrev_b64 v[22:23], 11, v[170:171]
	v_lshl_add_u64 v[22:23], v[166:167], 0, v[22:23]
	v_cvt_pk_bf16_f32 v14, v14, v15
	v_cvt_pk_bf16_f32 v15, v16, v17
	v_cvt_pk_bf16_f32 v16, v18, v19
	v_cvt_pk_bf16_f32 v17, v20, v21
	global_store_dwordx4 v[22:23], v[14:17], off
	s_nop 1
	v_mov_b32_e32 v14, v5
	s_nop 1
	v_permlane16_swap_b32_e32 v5, v14
	v_add_f32_e32 v5, v5, v14
	v_mov_b32_e32 v14, v5
	s_nop 1
	v_permlane32_swap_b32_e32 v5, v14
	s_and_saveexec_b64 s[2:3], vcc
	v_add_f32_e32 v5, v5, v14
	ds_write_b32 v182, v5 offset:896
	s_or_b64 exec, exec, s[2:3]
	s_waitcnt vmcnt(7)
	v_lshlrev_b32_e32 v14, 16, v78
	v_and_b32_e32 v15, 0xffff0000, v78
	v_lshlrev_b32_e32 v16, 16, v79
	v_and_b32_e32 v17, 0xffff0000, v79
	v_pk_fma_f32 v[12:13], v[76:77], v[12:13], v[16:17]
	v_pk_fma_f32 v[10:11], v[74:75], v[10:11], v[14:15]
	v_lshlrev_b32_e32 v14, 16, v80
	v_and_b32_e32 v15, 0xffff0000, v80
	v_lshlrev_b32_e32 v16, 16, v81
	v_and_b32_e32 v17, 0xffff0000, v81
	v_pk_fma_f32 v[16:17], v[72:73], v[8:9], v[16:17]
	v_pk_fma_f32 v[8:9], v[70:71], v[6:7], v[14:15]
	v_mul_f32_e32 v5, v11, v11
	v_mul_f32_e32 v6, v13, v13
	v_fmac_f32_e32 v5, v10, v10
	v_fmac_f32_e32 v6, v12, v12
	v_add_f32_e32 v5, v5, v6
	v_mul_f32_e32 v6, v9, v9
	v_mul_f32_e32 v7, v17, v17
	v_fmac_f32_e32 v6, v8, v8
	v_fmac_f32_e32 v7, v16, v16
	v_add_f32_e32 v6, v6, v7
	v_add_f32_e32 v5, v5, v6
	v_lshlrev_b64 v[6:7], 11, v[168:169]
	v_lshl_add_u64 v[14:15], v[166:167], 0, v[6:7]
	v_cvt_pk_bf16_f32 v6, v10, v11
	v_cvt_pk_bf16_f32 v7, v12, v13
	v_cvt_pk_bf16_f32 v8, v8, v9
	v_cvt_pk_bf16_f32 v9, v16, v17
	global_store_dwordx4 v[14:15], v[6:9], off
	s_nop 1
	v_mov_b32_e32 v6, v5
	s_nop 1
	v_permlane16_swap_b32_e32 v5, v6
	v_add_f32_e32 v5, v5, v6
	v_mov_b32_e32 v6, v5
	s_nop 1
	v_permlane32_swap_b32_e32 v5, v6
	s_and_saveexec_b64 s[2:3], vcc
	v_add_f32_e32 v5, v5, v6
	ds_write_b32 v182, v5 offset:960
	s_or_b64 exec, exec, s[2:3]
	s_movk_i32 s2, 0x400
	v_cmp_gt_i32_e32 vcc, s2, v2
	s_waitcnt lgkmcnt(0)
	s_barrier
	s_and_saveexec_b64 s[2:3], vcc
	s_cbranch_execz .LBB0_443
	v_readlane_b32 s5, v253, 6
	s_lshl_b32 s5, s5, 2
	v_readlane_b32 s6, v254, 33
	v_readlane_b32 s7, v254, 34
	s_add_u32 s6, s6, s5
	s_addc_u32 s7, s7, 0
	s_add_i32 s5, 0, 0x21000
	v_lshl_or_b32 v6, s78, 2, v3
	v_lshl_add_u32 v5, v3, 11, s5
	v_ashrrev_i32_e32 v7, 31, v6
	v_max_i32_e32 v3, 0x200, v2
	v_lshlrev_b64 v[6:7], 14, v[6:7]
	v_sub_u32_e32 v3, v3, v2
	v_lshl_add_u64 v[6:7], s[6:7], 0, v[6:7]
	s_mov_b64 s[6:7], 0x300000
	v_add_u32_e32 v3, 0x1ff, v3
	v_lshl_add_u64 v[6:7], v[6:7], 0, s[6:7]
	v_cmp_lt_u32_e32 vcc, s12, v3
	s_mov_b64 s[8:9], -1
	s_and_saveexec_b64 s[6:7], vcc
	s_cbranch_execz .LBB0_440
	v_lshrrev_b32_e32 v10, 9, v3
	v_add_u32_e32 v8, -1, v10
	v_add_u32_e32 v3, 0x200, v2
	v_lshrrev_b32_e32 v9, 1, v8
	v_add_u32_e32 v11, 1, v9
	v_cmp_lt_u32_e32 vcc, 5, v8
	v_mov_b64_e32 v[8:9], v[2:3]
	s_and_saveexec_b64 s[8:9], vcc
	s_cbranch_execz .LBB0_436
	v_and_b32_e32 v12, -4, v11
	s_mov_b64 s[10:11], 0
	v_mov_b64_e32 v[8:9], v[2:3]

.LBB0_447:
	s_or_b64 exec, exec, s[6:7]
	s_waitcnt lgkmcnt(1)
	v_cvt_f32_u32_e32 v7, v5
	s_waitcnt vmcnt(0)
	v_readfirstlane_b32 s4, v6
	v_sub_u32_e32 v6, 0, v5
	v_rcp_iflag_f32_e32 v7, v7
	v_add_u32_e32 v8, s4, v3
	v_mul_f32_e32 v7, 0x4f7ffffe, v7
	v_cvt_u32_f32_e32 v7, v7
	v_mul_lo_u32 v3, v6, v7
	v_mul_hi_u32 v3, v7, v3
	v_add_u32_e32 v3, v7, v3
	v_mul_hi_u32 v3, v8, v3
	v_mul_lo_u32 v6, v3, v5
	v_sub_u32_e32 v6, v8, v6
	v_add_u32_e32 v7, 1, v3
	v_cmp_ge_u32_e32 vcc, v6, v5
	s_nop 1
	v_cndmask_b32_e32 v3, v3, v7, vcc
	v_sub_u32_e32 v7, v6, v5
	v_cndmask_b32_e32 v6, v6, v7, vcc
	v_add_u32_e32 v7, 1, v3
	v_cmp_ge_u32_e32 vcc, v6, v5
	v_add_u32_e32 v6, 1, v8
	s_nop 0
	v_cndmask_b32_e32 v3, v3, v7, vcc
	v_mul_lo_u32 v7, v5, v3
	v_add_u32_e32 v5, v7, v5
	v_cmp_ne_u32_e32 vcc, v6, v5
	s_and_saveexec_b64 s[4:5], vcc
	s_xor_b64 s[4:5], exec, s[4:5]
	s_cbranch_execz .LBB0_461
	s_waitcnt lgkmcnt(0)
	buffer_inv sc1
	global_load_dword v2, v4, s[82:83] sc1
	s_waitcnt vmcnt(0)
	v_cmp_eq_u32_e32 vcc, v2, v3
	s_and_saveexec_b64 s[6:7], vcc
	s_cbranch_execz .LBB0_460
	s_mov_b32 s18, 1
	s_mov_b64 s[8:9], 0
	s_branch .LBB0_451

.LBB0_460:
	s_or_b64 exec, exec, s[6:7]
	s_waitcnt vmcnt(0)
	s_waitcnt vmcnt(0)
.LBB0_461:
	s_andn2_saveexec_b64 s[4:5], s[4:5]
	s_cbranch_execz .LBB0_481
	s_mov_b64 s[4:5], exec
	buffer_wbl2 sc1
	s_waitcnt lgkmcnt(0)
	s_waitcnt vmcnt(0)
	buffer_inv sc1
	v_mbcnt_lo_u32_b32 v3, s4, 0
	v_mbcnt_hi_u32_b32 v3, s5, v3
	v_cmp_eq_u32_e32 vcc, 0, v3
	s_and_saveexec_b64 s[6:7], vcc
	s_cbranch_execz .LBB0_464
	s_bcnt1_i32_b64 s4, s[4:5]
	v_mov_b32_e32 v5, s4
	v_readlane_b32 s4, v253, 9
	v_readlane_b32 s5, v253, 10
	s_nop 4
	global_atomic_add v5, v4, v5, s[4:5] sc0

.LBB0_510:
	v_lshl_or_b32 v40, s58, 8, v228
	v_ashrrev_i32_e32 v41, 31, v40
	v_mov_b64_e32 v[38:39], s[4:5]
	v_mad_i64_i32 v[160:161], s[22:23], v148, s77, v[38:39]
	v_lshlrev_b64 v[40:41], 1, v[40:41]
	v_lshl_add_u64 v[160:161], v[160:161], 0, v[40:41]
	v_pk_mul_f32 v[136:137], v[136:137], v[150:151] op_sel_hi:[1,0]
	v_pk_mul_f32 v[134:135], v[134:135], v[150:151] op_sel_hi:[1,0]
	v_pk_mul_f32 v[164:165], v[132:133], v[150:151] op_sel_hi:[1,0]
	v_pk_mul_f32 v[132:133], v[130:131], v[150:151] op_sel_hi:[1,0]
	v_cvt_pk_bf16_f32 v130, v134, v135
	v_cvt_pk_bf16_f32 v131, v136, v137
	v_pk_mul_f32 v[126:127], v[126:127], v[150:151] op_sel_hi:[1,0]
	v_cvt_pk_bf16_f32 v132, v132, v133
	v_cvt_pk_bf16_f32 v133, v164, v165
	global_store_dwordx4 v[160:161], v[130:133], off
	v_pk_mul_f32 v[128:129], v[128:129], v[150:151] op_sel_hi:[1,0]
	v_pk_mul_f32 v[120:121], v[120:121], v[152:153] op_sel_hi:[1,0]
	v_pk_mul_f32 v[130:131], v[124:125], v[150:151] op_sel_hi:[1,0]
	v_pk_mul_f32 v[124:125], v[122:123], v[150:151] op_sel_hi:[1,0]
	v_cvt_pk_bf16_f32 v122, v126, v127
	v_cvt_pk_bf16_f32 v123, v128, v129
	v_pk_mul_f32 v[118:119], v[118:119], v[152:153] op_sel_hi:[1,0]
	v_cvt_pk_bf16_f32 v124, v124, v125
	v_cvt_pk_bf16_f32 v125, v130, v131
	global_store_dwordx4 v[160:161], v[122:125], off offset:64
	v_pk_mul_f32 v[110:111], v[110:111], v[152:153] op_sel_hi:[1,0]
	v_pk_mul_f32 v[112:113], v[112:113], v[152:153] op_sel_hi:[1,0]
	v_or_b32_e32 v122, 16, v148
	v_mad_i64_i32 v[122:123], s[22:23], v122, s77, v[38:39]
	v_lshl_add_u64 v[122:123], v[122:123], 0, v[40:41]
	v_pk_mul_f32 v[124:125], v[116:117], v[152:153] op_sel_hi:[1,0]
	v_pk_mul_f32 v[116:117], v[114:115], v[152:153] op_sel_hi:[1,0]
	v_cvt_pk_bf16_f32 v114, v118, v119
	v_cvt_pk_bf16_f32 v115, v120, v121
	v_pk_mul_f32 v[104:105], v[104:105], v[154:155] op_sel_hi:[1,0]
	v_cvt_pk_bf16_f32 v116, v116, v117
	v_cvt_pk_bf16_f32 v117, v124, v125
	global_store_dwordx4 v[122:123], v[114:117], off
	v_pk_mul_f32 v[102:103], v[102:103], v[154:155] op_sel_hi:[1,0]
	v_pk_mul_f32 v[94:95], v[94:95], v[154:155] op_sel_hi:[1,0]
	v_pk_mul_f32 v[114:115], v[108:109], v[152:153] op_sel_hi:[1,0]
	v_pk_mul_f32 v[108:109], v[106:107], v[152:153] op_sel_hi:[1,0]
	v_cvt_pk_bf16_f32 v106, v110, v111
	v_cvt_pk_bf16_f32 v107, v112, v113
	v_pk_mul_f32 v[96:97], v[96:97], v[154:155] op_sel_hi:[1,0]
	v_cvt_pk_bf16_f32 v108, v108, v109
	v_cvt_pk_bf16_f32 v109, v114, v115
	global_store_dwordx4 v[122:123], v[106:109], off offset:64
	v_pk_mul_f32 v[88:89], v[88:89], v[156:157] op_sel_hi:[1,0]
	v_pk_mul_f32 v[86:87], v[86:87], v[156:157] op_sel_hi:[1,0]
	v_or_b32_e32 v106, 32, v148
	v_mad_i64_i32 v[106:107], s[22:23], v106, s77, v[38:39]
	v_lshl_add_u64 v[106:107], v[106:107], 0, v[40:41]
	v_pk_mul_f32 v[108:109], v[100:101], v[154:155] op_sel_hi:[1,0]
	v_pk_mul_f32 v[100:101], v[98:99], v[154:155] op_sel_hi:[1,0]
	v_cvt_pk_bf16_f32 v98, v102, v103
	v_cvt_pk_bf16_f32 v99, v104, v105
	v_pk_mul_f32 v[80:81], v[80:81], v[156:157] op_sel_hi:[1,0]
	v_cvt_pk_bf16_f32 v100, v100, v101
	v_cvt_pk_bf16_f32 v101, v108, v109
	global_store_dwordx4 v[106:107], v[98:101], off
	v_pk_mul_f32 v[78:79], v[78:79], v[156:157] op_sel_hi:[1,0]
	v_pk_mul_f32 v[72:73], v[72:73], v[142:143] op_sel_hi:[1,0]
	v_pk_mul_f32 v[98:99], v[92:93], v[154:155] op_sel_hi:[1,0]
	v_pk_mul_f32 v[92:93], v[90:91], v[154:155] op_sel_hi:[1,0]
	v_cvt_pk_bf16_f32 v90, v94, v95
	v_cvt_pk_bf16_f32 v91, v96, v97
	v_pk_mul_f32 v[70:71], v[70:71], v[142:143] op_sel_hi:[1,0]
	v_cvt_pk_bf16_f32 v92, v92, v93
	v_cvt_pk_bf16_f32 v93, v98, v99
	global_store_dwordx4 v[106:107], v[90:93], off offset:64
	v_pk_mul_f32 v[62:63], v[62:63], v[142:143] op_sel_hi:[1,0]
	v_pk_mul_f32 v[64:65], v[64:65], v[142:143] op_sel_hi:[1,0]
	v_or_b32_e32 v90, 48, v148
	v_mad_i64_i32 v[90:91], s[22:23], v90, s77, v[38:39]
	v_lshl_add_u64 v[90:91], v[90:91], 0, v[40:41]
	v_pk_mul_f32 v[92:93], v[84:85], v[156:157] op_sel_hi:[1,0]
	v_pk_mul_f32 v[84:85], v[82:83], v[156:157] op_sel_hi:[1,0]
	v_cvt_pk_bf16_f32 v82, v86, v87
	v_cvt_pk_bf16_f32 v83, v88, v89
	v_pk_mul_f32 v[56:57], v[56:57], v[142:143] op_sel:[0,1]
	v_cvt_pk_bf16_f32 v84, v84, v85
	v_cvt_pk_bf16_f32 v85, v92, v93
	global_store_dwordx4 v[90:91], v[82:85], off
	v_pk_mul_f32 v[54:55], v[54:55], v[142:143] op_sel:[0,1]
	v_pk_mul_f32 v[46:47], v[46:47], v[142:143] op_sel:[0,1]
	v_pk_mul_f32 v[82:83], v[76:77], v[156:157] op_sel_hi:[1,0]
	v_pk_mul_f32 v[76:77], v[74:75], v[156:157] op_sel_hi:[1,0]
	v_cvt_pk_bf16_f32 v74, v78, v79
	v_cvt_pk_bf16_f32 v75, v80, v81
	v_pk_mul_f32 v[48:49], v[48:49], v[142:143] op_sel:[0,1]
	v_cvt_pk_bf16_f32 v76, v76, v77
	v_cvt_pk_bf16_f32 v77, v82, v83
	global_store_dwordx4 v[90:91], v[74:77], off offset:64
	v_pk_mul_f32 v[36:37], v[36:37], v[144:145] op_sel_hi:[1,0]
	v_pk_mul_f32 v[34:35], v[34:35], v[144:145] op_sel_hi:[1,0]
	v_mad_u64_u32 v[74:75], s[22:23], v162, s77, v[38:39]
	v_mov_b32_e32 v76, v75
	v_mad_u64_u32 v[76:77], s[22:23], v163, s77, v[76:77]
	v_mov_b32_e32 v75, v76
	v_lshl_add_u64 v[74:75], v[74:75], 0, v[40:41]
	v_pk_mul_f32 v[76:77], v[68:69], v[142:143] op_sel_hi:[1,0]
	v_pk_mul_f32 v[68:69], v[66:67], v[142:143] op_sel_hi:[1,0]
	v_cvt_pk_bf16_f32 v66, v70, v71
	v_cvt_pk_bf16_f32 v67, v72, v73
	v_pk_mul_f32 v[26:27], v[26:27], v[144:145] op_sel_hi:[1,0]
	v_cvt_pk_bf16_f32 v68, v68, v69
	v_cvt_pk_bf16_f32 v69, v76, v77
	global_store_dwordx4 v[74:75], v[66:69], off
	v_pk_mul_f32 v[28:29], v[28:29], v[144:145] op_sel_hi:[1,0]
	v_pk_mul_f32 v[20:21], v[20:21], v[158:159] op_sel_hi:[1,0]
	v_pk_mul_f32 v[66:67], v[60:61], v[142:143] op_sel_hi:[1,0]
	v_pk_mul_f32 v[60:61], v[58:59], v[142:143] op_sel_hi:[1,0]
	v_cvt_pk_bf16_f32 v58, v62, v63
	v_cvt_pk_bf16_f32 v59, v64, v65
	v_pk_mul_f32 v[18:19], v[18:19], v[158:159] op_sel_hi:[1,0]
	v_cvt_pk_bf16_f32 v60, v60, v61
	v_cvt_pk_bf16_f32 v61, v66, v67
	global_store_dwordx4 v[74:75], v[58:61], off offset:64
	s_andn2_b64 vcc, exec, s[20:21]
	s_mov_b64 s[20:21], -1
	v_add_u32_e32 v58, 16, v146
	v_mad_i64_i32 v[58:59], s[22:23], v58, s77, v[38:39]
	v_lshl_add_u64 v[58:59], v[58:59], 0, v[40:41]
	v_pk_mul_f32 v[60:61], v[52:53], v[142:143] op_sel:[0,1]
	v_pk_mul_f32 v[52:53], v[50:51], v[142:143] op_sel:[0,1]
	v_cvt_pk_bf16_f32 v50, v54, v55
	v_cvt_pk_bf16_f32 v51, v56, v57
	v_pk_mul_f32 v[12:13], v[12:13], v[158:159] op_sel_hi:[1,0]
	v_cvt_pk_bf16_f32 v52, v52, v53
	v_cvt_pk_bf16_f32 v53, v60, v61
	global_store_dwordx4 v[58:59], v[50:53], off
	v_pk_mul_f32 v[10:11], v[10:11], v[158:159] op_sel_hi:[1,0]
	s_nop 0
	v_pk_mul_f32 v[50:51], v[44:45], v[142:143] op_sel:[0,1]
	v_pk_mul_f32 v[44:45], v[42:43], v[142:143] op_sel:[0,1]
	v_cvt_pk_bf16_f32 v42, v46, v47
	v_cvt_pk_bf16_f32 v43, v48, v49
	s_nop 0
	v_cvt_pk_bf16_f32 v44, v44, v45
	v_cvt_pk_bf16_f32 v45, v50, v51
	global_store_dwordx4 v[58:59], v[42:45], off offset:64
	s_nop 1
	v_add_u32_e32 v42, 32, v146
	v_mad_i64_i32 v[42:43], s[22:23], v42, s77, v[38:39]
	v_lshl_add_u64 v[42:43], v[42:43], 0, v[40:41]
	v_pk_mul_f32 v[44:45], v[32:33], v[144:145] op_sel_hi:[1,0]
	v_pk_mul_f32 v[32:33], v[30:31], v[144:145] op_sel_hi:[1,0]
	v_cvt_pk_bf16_f32 v30, v34, v35
	v_cvt_pk_bf16_f32 v31, v36, v37
	s_nop 0
	v_cvt_pk_bf16_f32 v32, v32, v33
	v_cvt_pk_bf16_f32 v33, v44, v45
	global_store_dwordx4 v[42:43], v[30:33], off
	s_nop 1
	v_pk_mul_f32 v[30:31], v[24:25], v[144:145] op_sel_hi:[1,0]
	v_pk_mul_f32 v[24:25], v[22:23], v[144:145] op_sel_hi:[1,0]
	v_cvt_pk_bf16_f32 v22, v26, v27
	v_cvt_pk_bf16_f32 v23, v28, v29
	s_nop 0
	v_cvt_pk_bf16_f32 v24, v24, v25
	v_cvt_pk_bf16_f32 v25, v30, v31
	global_store_dwordx4 v[42:43], v[22:25], off offset:64
	s_nop 1
	v_add_u32_e32 v22, 48, v146
	v_mad_i64_i32 v[22:23], s[22:23], v22, s77, v[38:39]
	v_lshl_add_u64 v[22:23], v[22:23], 0, v[40:41]
	v_pk_mul_f32 v[24:25], v[16:17], v[158:159] op_sel_hi:[1,0]
	v_pk_mul_f32 v[16:17], v[14:15], v[158:159] op_sel_hi:[1,0]
	v_cvt_pk_bf16_f32 v14, v18, v19
	v_cvt_pk_bf16_f32 v15, v20, v21
	s_nop 0
	v_cvt_pk_bf16_f32 v16, v16, v17
	v_cvt_pk_bf16_f32 v17, v24, v25
	global_store_dwordx4 v[22:23], v[14:17], off
	s_nop 1
	v_pk_mul_f32 v[14:15], v[8:9], v[158:159] op_sel_hi:[1,0]
	v_pk_mul_f32 v[8:9], v[6:7], v[158:159] op_sel_hi:[1,0]
	v_cvt_pk_bf16_f32 v6, v10, v11
	v_cvt_pk_bf16_f32 v7, v12, v13
	s_nop 0
	v_cvt_pk_bf16_f32 v8, v8, v9
	v_cvt_pk_bf16_f32 v9, v14, v15
	global_store_dwordx4 v[22:23], v[6:9], off offset:64
	s_cbranch_vccnz .LBB0_488
	s_andn2_b64 vcc, exec, s[2:3]
	s_cbranch_vccnz .LBB0_487
	s_barrier
	s_branch .LBB0_487

.LBB0_533:
	s_lshl_b32 s6, s21, 6
	s_add_u32 s4, s4, s80
	s_addc_u32 s5, s5, 0
	v_readlane_b32 s7, v253, 37
	s_add_u32 s4, s4, 0x800000
	s_addc_u32 s5, s5, 0
	v_add_u32_e32 v134, s7, v216
	v_readlane_b32 s7, v253, 38
	s_or_b32 s6, s6, s7
	v_ashrrev_i32_e32 v135, 31, v134
	v_cvt_pk_bf16_f32 v122, v122, v123
	v_cvt_pk_bf16_f32 v123, v124, v125
	v_cvt_pk_bf16_f32 v124, v118, v119
	v_or_b32_e32 v118, 16, v134
	v_cvt_pk_bf16_f32 v106, v106, v107
	v_cvt_pk_bf16_f32 v107, v108, v109
	v_cvt_pk_bf16_f32 v108, v102, v103
	v_or_b32_e32 v102, 32, v134
	v_cvt_pk_bf16_f32 v90, v90, v91
	v_cvt_pk_bf16_f32 v91, v92, v93
	v_cvt_pk_bf16_f32 v92, v86, v87
	v_or_b32_e32 v86, 48, v134
	v_or_b32_e32 v5, s6, v5
	v_lshlrev_b64 v[2:3], 12, v[134:135]
	v_ashrrev_i32_e32 v119, 31, v118
	v_ashrrev_i32_e32 v103, 31, v102
	v_ashrrev_i32_e32 v87, 31, v86
	v_lshl_add_u64 v[2:3], s[4:5], 0, v[2:3]
	v_lshlrev_b32_e32 v136, 1, v5
	v_mov_b32_e32 v137, v4
	v_lshlrev_b64 v[118:119], 12, v[118:119]
	v_lshlrev_b64 v[102:103], 12, v[102:103]
	v_lshlrev_b64 v[86:87], 12, v[86:87]
	v_lshl_add_u64 v[2:3], v[2:3], 0, v[136:137]
	v_lshl_add_u64 v[118:119], s[4:5], 0, v[118:119]
	v_lshl_add_u64 v[102:103], s[4:5], 0, v[102:103]
	v_lshl_add_u64 v[86:87], s[4:5], 0, v[86:87]
	s_mov_b64 s[4:5], 0x80000
	v_cvt_pk_bf16_f32 v74, v74, v75
	v_cvt_pk_bf16_f32 v75, v76, v77
	v_cvt_pk_bf16_f32 v76, v70, v71
	v_lshl_add_u64 v[70:71], v[2:3], 0, s[4:5]
	s_mov_b32 s4, 0x80000
	v_cvt_pk_bf16_f32 v66, v66, v67
	v_cvt_pk_bf16_f32 v67, v68, v69
	v_cvt_pk_bf16_f32 v68, v62, v63
	v_add_co_u32_e32 v62, vcc, s4, v2
	s_mov_b64 s[4:5], 0x90000
	s_nop 0
	v_addc_co_u32_e32 v63, vcc, 0, v3, vcc
	v_cvt_pk_bf16_f32 v58, v58, v59
	v_cvt_pk_bf16_f32 v59, v60, v61
	v_cvt_pk_bf16_f32 v60, v54, v55
	v_lshl_add_u64 v[54:55], v[2:3], 0, s[4:5]
	s_mov_b32 s4, 0x90000
	v_cvt_pk_bf16_f32 v50, v50, v51
	v_cvt_pk_bf16_f32 v51, v52, v53
	v_cvt_pk_bf16_f32 v52, v46, v47
	v_add_co_u32_e32 v46, vcc, s4, v2
	s_mov_b64 s[4:5], 0xa0000
	s_nop 0
	v_addc_co_u32_e32 v47, vcc, 0, v3, vcc
	v_cvt_pk_bf16_f32 v42, v42, v43
	v_cvt_pk_bf16_f32 v43, v44, v45
	v_cvt_pk_bf16_f32 v44, v38, v39
	v_lshl_add_u64 v[38:39], v[2:3], 0, s[4:5]
	s_mov_b32 s4, 0xa0000
	v_cvt_pk_bf16_f32 v34, v34, v35
	v_cvt_pk_bf16_f32 v35, v36, v37
	v_cvt_pk_bf16_f32 v36, v30, v31
	v_add_co_u32_e32 v30, vcc, s4, v2
	s_mov_b64 s[4:5], 0xb0000
	s_nop 0
	v_addc_co_u32_e32 v31, vcc, 0, v3, vcc
	v_cvt_pk_bf16_f32 v26, v26, v27
	v_cvt_pk_bf16_f32 v27, v28, v29
	v_cvt_pk_bf16_f32 v28, v22, v23
	v_lshl_add_u64 v[22:23], v[2:3], 0, s[4:5]
	s_mov_b32 s4, 0xb0000
	v_cvt_pk_bf16_f32 v130, v130, v131
	v_cvt_pk_bf16_f32 v131, v132, v133
	v_cvt_pk_bf16_f32 v132, v126, v127
	v_cvt_pk_bf16_f32 v133, v128, v129
	global_store_dwordx4 v[2:3], v[130:133], off
	v_cvt_pk_bf16_f32 v125, v120, v121
	global_store_dwordx4 v[2:3], v[122:125], off offset:64
	v_add_co_u32_e32 v2, vcc, s4, v2
	v_lshl_add_u64 v[118:119], v[118:119], 0, v[136:137]
	v_lshl_add_u64 v[102:103], v[102:103], 0, v[136:137]
	v_lshl_add_u64 v[86:87], v[86:87], 0, v[136:137]
	v_addc_co_u32_e32 v3, vcc, 0, v3, vcc
	v_cvt_pk_bf16_f32 v114, v114, v115
	v_cvt_pk_bf16_f32 v115, v116, v117
	v_cvt_pk_bf16_f32 v116, v110, v111
	v_cvt_pk_bf16_f32 v117, v112, v113
	global_store_dwordx4 v[118:119], v[114:117], off
	v_cvt_pk_bf16_f32 v109, v104, v105
	global_store_dwordx4 v[118:119], v[106:109], off offset:64
	v_cvt_pk_bf16_f32 v98, v98, v99
	v_cvt_pk_bf16_f32 v99, v100, v101
	v_cvt_pk_bf16_f32 v100, v94, v95
	v_cvt_pk_bf16_f32 v101, v96, v97
	global_store_dwordx4 v[102:103], v[98:101], off
	v_cvt_pk_bf16_f32 v93, v88, v89
	global_store_dwordx4 v[102:103], v[90:93], off offset:64
	v_cvt_pk_bf16_f32 v82, v82, v83
	v_cvt_pk_bf16_f32 v83, v84, v85
	v_cvt_pk_bf16_f32 v84, v78, v79
	v_cvt_pk_bf16_f32 v85, v80, v81
	global_store_dwordx4 v[86:87], v[82:85], off
	v_cvt_pk_bf16_f32 v77, v72, v73
	global_store_dwordx4 v[86:87], v[74:77], off offset:64
	v_cvt_pk_bf16_f32 v69, v64, v65
	global_store_dwordx4 v[62:63], v[66:69], off
	v_cvt_pk_bf16_f32 v61, v56, v57
	global_store_dwordx4 v[70:71], v[58:61], off offset:64
	v_cvt_pk_bf16_f32 v53, v48, v49
	global_store_dwordx4 v[46:47], v[50:53], off
	v_cvt_pk_bf16_f32 v45, v40, v41
	global_store_dwordx4 v[54:55], v[42:45], off offset:64
	v_cvt_pk_bf16_f32 v37, v32, v33
	global_store_dwordx4 v[30:31], v[34:37], off
	v_cvt_pk_bf16_f32 v29, v24, v25
	global_store_dwordx4 v[38:39], v[26:29], off offset:64
	v_cvt_pk_bf16_f32 v18, v18, v19
	v_cvt_pk_bf16_f32 v19, v20, v21
	v_cvt_pk_bf16_f32 v20, v14, v15
	v_cvt_pk_bf16_f32 v21, v16, v17
	global_store_dwordx4 v[2:3], v[18:21], off
	v_cvt_pk_bf16_f32 v10, v10, v11
	v_cvt_pk_bf16_f32 v11, v12, v13
	v_cvt_pk_bf16_f32 v12, v6, v7
	v_cvt_pk_bf16_f32 v13, v8, v9
	global_store_dwordx4 v[22:23], v[10:13], off offset:64
	s_waitcnt vmcnt(0)
	s_barrier

.LBB0_537:
	s_or_b64 exec, exec, s[8:9]
	s_waitcnt lgkmcnt(1)
	v_cvt_f32_u32_e32 v7, v5
	s_waitcnt vmcnt(0)
	v_readfirstlane_b32 s6, v6
	v_sub_u32_e32 v6, 0, v5
	v_rcp_iflag_f32_e32 v7, v7
	v_add_u32_e32 v8, s6, v3
	v_mul_f32_e32 v7, 0x4f7ffffe, v7
	v_cvt_u32_f32_e32 v7, v7
	v_mul_lo_u32 v3, v6, v7
	v_mul_hi_u32 v3, v7, v3
	v_add_u32_e32 v3, v7, v3
	v_mul_hi_u32 v3, v8, v3
	v_mul_lo_u32 v6, v3, v5
	v_sub_u32_e32 v6, v8, v6
	v_add_u32_e32 v7, 1, v3
	v_cmp_ge_u32_e32 vcc, v6, v5
	s_nop 1
	v_cndmask_b32_e32 v3, v3, v7, vcc
	v_sub_u32_e32 v7, v6, v5
	v_cndmask_b32_e32 v6, v6, v7, vcc
	v_add_u32_e32 v7, 1, v3
	v_cmp_ge_u32_e32 vcc, v6, v5
	v_add_u32_e32 v6, 1, v8
	s_nop 0
	v_cndmask_b32_e32 v3, v3, v7, vcc
	v_mul_lo_u32 v7, v5, v3
	v_add_u32_e32 v5, v7, v5
	v_cmp_ne_u32_e32 vcc, v6, v5
	s_and_saveexec_b64 s[6:7], vcc
	s_xor_b64 s[6:7], exec, s[6:7]
	s_cbranch_execz .LBB0_551
	s_waitcnt lgkmcnt(0)
	buffer_inv sc1
	global_load_dword v2, v4, s[82:83] sc1
	s_waitcnt vmcnt(0)
	v_cmp_eq_u32_e32 vcc, v2, v3
	s_and_saveexec_b64 s[8:9], vcc
	s_cbranch_execz .LBB0_550
	s_mov_b32 s20, 1
	s_mov_b64 s[10:11], 0
	s_branch .LBB0_541

.LBB0_550:
	s_or_b64 exec, exec, s[8:9]
	s_waitcnt vmcnt(0)
	s_waitcnt vmcnt(0)
.LBB0_551:
	s_andn2_saveexec_b64 s[6:7], s[6:7]
	s_cbranch_execz .LBB0_571
	s_mov_b64 s[6:7], exec
	buffer_wbl2 sc1
	s_waitcnt lgkmcnt(0)
	s_waitcnt vmcnt(0)
	buffer_inv sc1
	v_mbcnt_lo_u32_b32 v3, s6, 0
	v_mbcnt_hi_u32_b32 v3, s7, v3
	v_cmp_eq_u32_e32 vcc, 0, v3
	s_and_saveexec_b64 s[8:9], vcc
	s_cbranch_execz .LBB0_554
	s_bcnt1_i32_b64 s6, s[6:7]
	v_mov_b32_e32 v5, s6
	v_readlane_b32 s6, v253, 9
	v_readlane_b32 s7, v253, 10
	s_nop 4
	global_atomic_add v5, v4, v5, s[6:7] sc0

.LBB0_593:
	s_or_b64 exec, exec, s[2:3]
	s_add_u32 s2, s18, s80
	s_addc_u32 s3, s19, 0
	s_or_b32 s12, s12, s38
	s_add_u32 s6, s16, s80
	s_addc_u32 s7, s17, 0
	v_lshlrev_b32_e32 v6, 1, v2
	v_mov_b32_e32 v7, v4
	v_or_b32_e32 v2, v3, v5
	v_lshl_add_u64 v[10:11], s[6:7], 0, v[6:7]
	v_lshl_add_u64 v[6:7], s[2:3], 0, v[6:7]
	v_add_u32_e32 v5, s54, v2
	s_waitcnt lgkmcnt(0)
	s_barrier
	v_lshl_add_u64 v[12:13], v[6:7], 0, s[48:49]
	ds_read_b128 v[6:9], v5
	v_ashrrev_i32_e32 v71, 31, v70
	v_lshl_add_u64 v[14:15], s[12:13], 0, v[70:71]
	v_lshlrev_b64 v[14:15], 10, v[14:15]
	s_add_i32 s2, 0, 0x18000
	v_lshl_add_u64 v[16:17], v[10:11], 0, v[14:15]
	v_add_u32_e32 v2, s2, v2
	s_waitcnt lgkmcnt(0)
	global_store_dwordx4 v[16:17], v[6:9], off
	ds_read_b128 v[6:9], v2
	v_or_b32_e32 v2, v3, v73
	v_lshl_add_u64 v[14:15], v[12:13], 0, v[14:15]
	v_add_u32_e32 v5, s54, v2
	v_ashrrev_i32_e32 v73, 31, v72
	s_waitcnt lgkmcnt(0)
	global_store_dwordx4 v[14:15], v[6:9], off
	ds_read_b128 v[6:9], v5
	v_lshl_add_u64 v[14:15], s[12:13], 0, v[72:73]
	v_lshlrev_b64 v[14:15], 10, v[14:15]
	v_lshl_add_u64 v[16:17], v[10:11], 0, v[14:15]
	v_add_u32_e32 v2, s2, v2
	s_waitcnt lgkmcnt(0)
	global_store_dwordx4 v[16:17], v[6:9], off
	ds_read_b128 v[6:9], v2
	v_or_b32_e32 v2, v3, v75
	v_lshl_add_u64 v[14:15], v[12:13], 0, v[14:15]
	v_add_u32_e32 v5, s54, v2
	v_ashrrev_i32_e32 v75, 31, v74
	s_waitcnt lgkmcnt(0)
	global_store_dwordx4 v[14:15], v[6:9], off
	ds_read_b128 v[6:9], v5
	v_lshl_add_u64 v[14:15], s[12:13], 0, v[74:75]
	v_lshlrev_b64 v[14:15], 10, v[14:15]
	v_lshl_add_u64 v[16:17], v[10:11], 0, v[14:15]
	v_add_u32_e32 v2, s2, v2
	s_waitcnt lgkmcnt(0)
	global_store_dwordx4 v[16:17], v[6:9], off
	ds_read_b128 v[6:9], v2
	v_lshl_add_u64 v[14:15], v[12:13], 0, v[14:15]
	v_or_b32_e32 v5, v3, v77
	v_ashrrev_i32_e32 v77, 31, v76
	v_lshl_add_u64 v[2:3], s[12:13], 0, v[76:77]
	s_waitcnt lgkmcnt(0)
	global_store_dwordx4 v[14:15], v[6:9], off
	v_lshlrev_b64 v[2:3], 10, v[2:3]
	v_lshl_add_u64 v[10:11], v[10:11], 0, v[2:3]
	v_add_u32_e32 v6, s54, v5
	ds_read_b128 v[6:9], v6
	v_add_u32_e32 v5, s2, v5
	s_add_i32 s2, s37, 64
	v_lshl_add_u64 v[2:3], v[12:13], 0, v[2:3]
	s_cmp_gt_i32 s37, 63
	s_waitcnt lgkmcnt(0)
	global_store_dwordx4 v[10:11], v[6:9], off
	ds_read_b128 v[6:9], v5
	s_mov_b32 s37, s2
	s_waitcnt lgkmcnt(0)
	global_store_dwordx4 v[2:3], v[6:9], off
	s_barrier
	s_cbranch_scc1 .LBB0_600

.LBB0_642:
	v_lshlrev_b32_e32 v112, 3, v5
	v_lshl_add_u32 v78, v78, 2, 0
	v_lshl_add_u32 v5, v5, 5, 0
	s_waitcnt vmcnt(4)
	v_add_f32_e32 v79, v124, v122
	ds_write_b32 v78, v126
	s_waitcnt lgkmcnt(0)
	s_barrier
	ds_read_b128 v[82:85], v5
	s_waitcnt vmcnt(0)
	v_add_f32_e32 v113, v79, v125
	v_add_f32_e32 v79, v119, v120
	v_add_f32_e32 v119, v79, v123
	v_add_f32_e32 v79, v117, v118
	v_add_f32_e32 v117, v79, v121
	v_add_f32_e32 v79, v114, v116
	v_add_f32_e32 v114, v79, v115
	ds_read_b128 v[78:81], v5 offset:16
	v_lshlrev_b32_e32 v5, 16, v86
	v_lshlrev_b32_e32 v115, 16, v90
	v_and_b32_e32 v86, 0xffff0000, v86
	v_and_b32_e32 v90, 0xffff0000, v90
	s_waitcnt lgkmcnt(1)
	v_fmac_f32_e32 v5, v82, v115
	v_fmac_f32_e32 v86, v83, v90
	v_cvt_pk_bf16_f32 v90, v5, v86
	v_lshlrev_b32_e32 v5, 16, v87
	v_lshlrev_b32_e32 v86, 16, v91
	v_fmac_f32_e32 v5, v84, v86
	v_and_b32_e32 v86, 0xffff0000, v87
	v_and_b32_e32 v87, 0xffff0000, v91
	v_fmac_f32_e32 v86, v85, v87
	v_cvt_pk_bf16_f32 v91, v5, v86
	v_lshlrev_b32_e32 v5, 16, v88
	v_lshlrev_b32_e32 v86, 16, v92
	s_waitcnt lgkmcnt(0)
	v_fmac_f32_e32 v5, v78, v86
	v_and_b32_e32 v86, 0xffff0000, v88
	v_and_b32_e32 v87, 0xffff0000, v92
	v_fmac_f32_e32 v86, v79, v87
	v_cvt_pk_bf16_f32 v92, v5, v86
	v_lshlrev_b32_e32 v5, 16, v89
	v_lshlrev_b32_e32 v86, 16, v93
	s_add_u32 s4, s4, s81
	v_fmac_f32_e32 v5, v80, v86
	v_and_b32_e32 v86, 0xffff0000, v89
	v_and_b32_e32 v87, 0xffff0000, v93
	s_addc_u32 s5, s5, 0
	v_fmac_f32_e32 v86, v81, v87
	v_cvt_pk_bf16_f32 v93, v5, v86
	v_div_scale_f32 v5, s[6:7], v114, v114, 1.0
	s_add_u32 s4, s4, 0x9600000
	v_lshlrev_b64 v[86:87], 11, v[104:105]
	v_rcp_f32_e32 v105, v5
	s_addc_u32 s5, s5, 0
	v_lshl_add_u64 v[88:89], s[4:5], 0, v[86:87]
	v_lshlrev_b32_e32 v86, 1, v112
	v_mov_b32_e32 v87, v4
	v_lshl_add_u64 v[88:89], v[88:89], 0, v[86:87]
	global_store_dwordx4 v[88:89], v[90:93], off offset:1024
	s_nop 1
	v_fma_f32 v90, -v5, v105, 1.0
	v_fmac_f32_e32 v105, v90, v105
	v_div_scale_f32 v90, vcc, 1.0, v114, 1.0
	v_mul_f32_e32 v91, v90, v105
	v_fma_f32 v92, -v5, v91, v90
	v_fmac_f32_e32 v91, v92, v105
	v_fma_f32 v5, -v5, v91, v90
	v_div_fmas_f32 v5, v5, v105, v91
	v_lshlrev_b32_e32 v90, 16, v66
	v_lshlrev_b32_e32 v91, 16, v70
	v_and_b32_e32 v70, 0xffff0000, v70
	v_and_b32_e32 v66, 0xffff0000, v66
	v_add_f32_e32 v66, v70, v66
	v_and_b32_e32 v70, 0xffff0000, v74
	v_add_f32_e32 v90, v91, v90
	v_lshlrev_b32_e32 v91, 16, v74
	v_add_f32_e32 v66, v66, v70
	v_lshlrev_b32_e32 v70, 16, v67
	v_lshlrev_b32_e32 v74, 16, v71
	v_and_b32_e32 v71, 0xffff0000, v71
	v_and_b32_e32 v67, 0xffff0000, v67
	v_add_f32_e32 v70, v74, v70
	v_lshlrev_b32_e32 v74, 16, v75
	v_add_f32_e32 v67, v71, v67
	v_and_b32_e32 v71, 0xffff0000, v75
	v_div_fixup_f32 v5, v5, v114, 1.0
	v_add_f32_e32 v70, v70, v74
	v_add_f32_e32 v67, v67, v71
	v_mul_f32_e32 v70, v70, v5
	v_mul_f32_e32 v67, v67, v5
	v_cvt_pk_bf16_f32 v67, v70, v67
	v_lshlrev_b32_e32 v70, 16, v68
	v_lshlrev_b32_e32 v71, 16, v72
	v_add_f32_e32 v70, v71, v70
	v_lshlrev_b32_e32 v71, 16, v76
	v_add_f32_e32 v70, v70, v71
	v_and_b32_e32 v71, 0xffff0000, v72
	v_and_b32_e32 v68, 0xffff0000, v68
	v_add_f32_e32 v68, v71, v68
	v_and_b32_e32 v71, 0xffff0000, v76
	v_add_f32_e32 v68, v68, v71
	v_mul_f32_e32 v70, v70, v5
	v_mul_f32_e32 v68, v68, v5
	v_cvt_pk_bf16_f32 v68, v70, v68
	v_lshlrev_b32_e32 v70, 16, v69
	v_lshlrev_b32_e32 v71, 16, v73
	v_add_f32_e32 v70, v71, v70
	v_lshlrev_b32_e32 v71, 16, v77
	v_add_f32_e32 v70, v70, v71
	v_and_b32_e32 v71, 0xffff0000, v73
	v_and_b32_e32 v69, 0xffff0000, v69
	v_add_f32_e32 v69, v71, v69
	v_and_b32_e32 v71, 0xffff0000, v77
	v_add_f32_e32 v90, v90, v91
	v_mul_f32_e32 v66, v66, v5
	v_add_f32_e32 v69, v69, v71
	v_mul_f32_e32 v90, v90, v5
	v_cvt_pk_bf16_f32 v66, v90, v66
	v_mul_f32_e32 v70, v70, v5
	v_mul_f32_e32 v5, v69, v5
	v_cvt_pk_bf16_f32 v69, v70, v5
	global_store_dwordx4 v[88:89], v[66:69], off
	v_lshlrev_b32_e32 v5, 16, v58
	v_and_b32_e32 v58, 0xffff0000, v58
	v_lshlrev_b32_e32 v66, 16, v62
	v_and_b32_e32 v62, 0xffff0000, v62
	v_fmac_f32_e32 v5, v82, v66
	v_fmac_f32_e32 v58, v83, v62
	v_cvt_pk_bf16_f32 v58, v5, v58
	v_lshlrev_b32_e32 v5, 16, v59
	v_lshlrev_b32_e32 v62, 16, v63
	v_fmac_f32_e32 v5, v84, v62
	v_and_b32_e32 v59, 0xffff0000, v59
	v_and_b32_e32 v62, 0xffff0000, v63
	v_fmac_f32_e32 v59, v85, v62
	v_cvt_pk_bf16_f32 v59, v5, v59
	v_lshlrev_b32_e32 v5, 16, v60
	v_lshlrev_b32_e32 v62, 16, v64
	v_fmac_f32_e32 v5, v78, v62
	v_and_b32_e32 v60, 0xffff0000, v60
	v_and_b32_e32 v62, 0xffff0000, v64
	v_fmac_f32_e32 v60, v79, v62
	v_cvt_pk_bf16_f32 v60, v5, v60
	v_lshlrev_b32_e32 v5, 16, v61
	v_lshlrev_b32_e32 v62, 16, v65
	v_fmac_f32_e32 v5, v80, v62
	v_and_b32_e32 v61, 0xffff0000, v61
	v_and_b32_e32 v62, 0xffff0000, v65
	v_fmac_f32_e32 v61, v81, v62
	v_cvt_pk_bf16_f32 v61, v5, v61
	v_div_scale_f32 v5, s[6:7], v117, v117, 1.0
	v_rcp_f32_e32 v64, v5
	v_lshlrev_b64 v[62:63], 11, v[110:111]
	v_lshl_add_u64 v[62:63], s[4:5], 0, v[62:63]
	v_lshl_add_u64 v[62:63], v[62:63], 0, v[86:87]
	global_store_dwordx4 v[62:63], v[58:61], off offset:1024
	s_nop 1
	v_fma_f32 v58, -v5, v64, 1.0
	v_fmac_f32_e32 v64, v58, v64
	v_div_scale_f32 v58, vcc, 1.0, v117, 1.0
	v_mul_f32_e32 v59, v58, v64
	v_fma_f32 v60, -v5, v59, v58
	v_fmac_f32_e32 v59, v60, v64
	v_fma_f32 v5, -v5, v59, v58
	v_div_fmas_f32 v5, v5, v64, v59
	v_lshlrev_b32_e32 v58, 16, v46
	v_lshlrev_b32_e32 v59, 16, v50
	v_and_b32_e32 v50, 0xffff0000, v50
	v_and_b32_e32 v46, 0xffff0000, v46
	v_add_f32_e32 v46, v50, v46
	v_and_b32_e32 v50, 0xffff0000, v54
	v_add_f32_e32 v58, v59, v58
	v_lshlrev_b32_e32 v59, 16, v54
	v_add_f32_e32 v46, v46, v50
	v_lshlrev_b32_e32 v50, 16, v47
	v_lshlrev_b32_e32 v54, 16, v51
	v_and_b32_e32 v51, 0xffff0000, v51
	v_and_b32_e32 v47, 0xffff0000, v47
	v_add_f32_e32 v50, v54, v50
	v_lshlrev_b32_e32 v54, 16, v55
	v_add_f32_e32 v47, v51, v47
	v_and_b32_e32 v51, 0xffff0000, v55
	v_div_fixup_f32 v5, v5, v117, 1.0
	v_add_f32_e32 v50, v50, v54
	v_add_f32_e32 v47, v47, v51
	v_mul_f32_e32 v50, v50, v5
	v_mul_f32_e32 v47, v47, v5
	v_cvt_pk_bf16_f32 v47, v50, v47
	v_lshlrev_b32_e32 v50, 16, v48
	v_lshlrev_b32_e32 v51, 16, v52
	v_add_f32_e32 v50, v51, v50
	v_lshlrev_b32_e32 v51, 16, v56
	v_add_f32_e32 v50, v50, v51
	v_and_b32_e32 v51, 0xffff0000, v52
	v_and_b32_e32 v48, 0xffff0000, v48
	v_add_f32_e32 v48, v51, v48
	v_and_b32_e32 v51, 0xffff0000, v56
	v_add_f32_e32 v48, v48, v51
	v_mul_f32_e32 v50, v50, v5
	v_mul_f32_e32 v48, v48, v5
	v_cvt_pk_bf16_f32 v48, v50, v48
	v_lshlrev_b32_e32 v50, 16, v49
	v_lshlrev_b32_e32 v51, 16, v53
	v_add_f32_e32 v50, v51, v50
	v_lshlrev_b32_e32 v51, 16, v57
	v_add_f32_e32 v50, v50, v51
	v_and_b32_e32 v51, 0xffff0000, v53
	v_and_b32_e32 v49, 0xffff0000, v49
	v_add_f32_e32 v49, v51, v49
	v_and_b32_e32 v51, 0xffff0000, v57
	v_add_f32_e32 v58, v58, v59
	v_mul_f32_e32 v46, v46, v5
	v_add_f32_e32 v49, v49, v51
	v_mul_f32_e32 v58, v58, v5
	v_cvt_pk_bf16_f32 v46, v58, v46
	v_mul_f32_e32 v50, v50, v5
	v_mul_f32_e32 v5, v49, v5
	v_cvt_pk_bf16_f32 v49, v50, v5
	global_store_dwordx4 v[62:63], v[46:49], off
	v_lshlrev_b32_e32 v5, 16, v38
	v_and_b32_e32 v38, 0xffff0000, v38
	v_lshlrev_b32_e32 v46, 16, v42
	v_and_b32_e32 v42, 0xffff0000, v42
	v_fmac_f32_e32 v5, v82, v46
	v_fmac_f32_e32 v38, v83, v42
	v_cvt_pk_bf16_f32 v38, v5, v38
	v_lshlrev_b32_e32 v5, 16, v39
	v_lshlrev_b32_e32 v42, 16, v43
	v_fmac_f32_e32 v5, v84, v42
	v_and_b32_e32 v39, 0xffff0000, v39
	v_and_b32_e32 v42, 0xffff0000, v43
	v_fmac_f32_e32 v39, v85, v42
	v_cvt_pk_bf16_f32 v39, v5, v39
	v_lshlrev_b32_e32 v5, 16, v40
	v_lshlrev_b32_e32 v42, 16, v44
	v_fmac_f32_e32 v5, v78, v42
	v_and_b32_e32 v40, 0xffff0000, v40
	v_and_b32_e32 v42, 0xffff0000, v44
	v_fmac_f32_e32 v40, v79, v42
	v_cvt_pk_bf16_f32 v40, v5, v40
	v_lshlrev_b32_e32 v5, 16, v41
	v_lshlrev_b32_e32 v42, 16, v45
	v_fmac_f32_e32 v5, v80, v42
	v_and_b32_e32 v41, 0xffff0000, v41
	v_and_b32_e32 v42, 0xffff0000, v45
	v_fmac_f32_e32 v41, v81, v42
	v_cvt_pk_bf16_f32 v41, v5, v41
	v_div_scale_f32 v5, s[6:7], v119, v119, 1.0
	v_rcp_f32_e32 v44, v5
	v_lshlrev_b64 v[42:43], 11, v[108:109]
	v_lshl_add_u64 v[42:43], s[4:5], 0, v[42:43]
	v_lshl_add_u64 v[42:43], v[42:43], 0, v[86:87]
	global_store_dwordx4 v[42:43], v[38:41], off offset:1024
	v_add_u32_e32 v64, 32, v104
	v_ashrrev_i32_e32 v65, 31, v64
	v_fma_f32 v38, -v5, v44, 1.0
	v_fmac_f32_e32 v44, v38, v44
	v_div_scale_f32 v38, vcc, 1.0, v119, 1.0
	v_mul_f32_e32 v39, v38, v44
	v_fma_f32 v40, -v5, v39, v38
	v_fmac_f32_e32 v39, v40, v44
	v_fma_f32 v5, -v5, v39, v38
	v_div_fmas_f32 v5, v5, v44, v39
	v_lshlrev_b32_e32 v38, 16, v26
	v_lshlrev_b32_e32 v39, 16, v30
	v_and_b32_e32 v30, 0xffff0000, v30
	v_and_b32_e32 v26, 0xffff0000, v26
	v_add_f32_e32 v26, v30, v26
	v_and_b32_e32 v30, 0xffff0000, v34
	v_add_f32_e32 v38, v39, v38
	v_lshlrev_b32_e32 v39, 16, v34
	v_add_f32_e32 v26, v26, v30
	v_lshlrev_b32_e32 v30, 16, v27
	v_lshlrev_b32_e32 v34, 16, v31
	v_and_b32_e32 v31, 0xffff0000, v31
	v_and_b32_e32 v27, 0xffff0000, v27
	v_add_f32_e32 v30, v34, v30
	v_lshlrev_b32_e32 v34, 16, v35
	v_add_f32_e32 v27, v31, v27
	v_and_b32_e32 v31, 0xffff0000, v35
	v_div_fixup_f32 v5, v5, v119, 1.0
	v_add_f32_e32 v30, v30, v34
	v_add_f32_e32 v27, v27, v31
	v_mul_f32_e32 v30, v30, v5
	v_mul_f32_e32 v27, v27, v5
	v_cvt_pk_bf16_f32 v27, v30, v27
	v_lshlrev_b32_e32 v30, 16, v28
	v_lshlrev_b32_e32 v31, 16, v32
	v_add_f32_e32 v30, v31, v30
	v_lshlrev_b32_e32 v31, 16, v36
	v_add_f32_e32 v30, v30, v31
	v_and_b32_e32 v31, 0xffff0000, v32
	v_and_b32_e32 v28, 0xffff0000, v28
	v_add_f32_e32 v28, v31, v28
	v_and_b32_e32 v31, 0xffff0000, v36
	v_add_f32_e32 v28, v28, v31
	v_mul_f32_e32 v30, v30, v5
	v_mul_f32_e32 v28, v28, v5
	v_cvt_pk_bf16_f32 v28, v30, v28
	v_lshlrev_b32_e32 v30, 16, v29
	v_lshlrev_b32_e32 v31, 16, v33
	v_add_f32_e32 v30, v31, v30
	v_lshlrev_b32_e32 v31, 16, v37
	v_add_f32_e32 v30, v30, v31
	v_and_b32_e32 v31, 0xffff0000, v33
	v_and_b32_e32 v29, 0xffff0000, v29
	v_add_f32_e32 v29, v31, v29
	v_and_b32_e32 v31, 0xffff0000, v37
	v_add_f32_e32 v38, v38, v39
	v_mul_f32_e32 v26, v26, v5
	v_add_f32_e32 v29, v29, v31
	v_mul_f32_e32 v38, v38, v5
	v_cvt_pk_bf16_f32 v26, v38, v26
	v_mul_f32_e32 v30, v30, v5
	v_mul_f32_e32 v5, v29, v5
	v_cvt_pk_bf16_f32 v29, v30, v5
	global_store_dwordx4 v[42:43], v[26:29], off
	v_lshlrev_b32_e32 v5, 16, v18
	v_and_b32_e32 v18, 0xffff0000, v18
	v_lshlrev_b32_e32 v26, 16, v22
	v_and_b32_e32 v22, 0xffff0000, v22
	v_fmac_f32_e32 v5, v82, v26
	v_fmac_f32_e32 v18, v83, v22
	v_cvt_pk_bf16_f32 v18, v5, v18
	v_lshlrev_b32_e32 v5, 16, v19
	v_lshlrev_b32_e32 v22, 16, v23
	v_fmac_f32_e32 v5, v84, v22
	v_and_b32_e32 v19, 0xffff0000, v19
	v_and_b32_e32 v22, 0xffff0000, v23
	v_fmac_f32_e32 v19, v85, v22
	v_cvt_pk_bf16_f32 v19, v5, v19
	v_lshlrev_b32_e32 v5, 16, v20
	v_lshlrev_b32_e32 v22, 16, v24
	v_fmac_f32_e32 v5, v78, v22
	v_and_b32_e32 v20, 0xffff0000, v20
	v_and_b32_e32 v22, 0xffff0000, v24
	v_fmac_f32_e32 v20, v79, v22
	v_cvt_pk_bf16_f32 v20, v5, v20
	v_lshlrev_b32_e32 v5, 16, v21
	v_lshlrev_b32_e32 v22, 16, v25
	v_fmac_f32_e32 v5, v80, v22
	v_and_b32_e32 v21, 0xffff0000, v21
	v_and_b32_e32 v22, 0xffff0000, v25
	v_fmac_f32_e32 v21, v81, v22
	v_cvt_pk_bf16_f32 v21, v5, v21
	v_div_scale_f32 v5, s[6:7], v113, v113, 1.0
	v_rcp_f32_e32 v24, v5
	v_lshlrev_b64 v[22:23], 11, v[106:107]
	v_lshl_add_u64 v[22:23], s[4:5], 0, v[22:23]
	v_lshl_add_u64 v[22:23], v[22:23], 0, v[86:87]
	global_store_dwordx4 v[22:23], v[18:21], off offset:1024
	v_add_u32_e32 v62, 40, v104
	v_ashrrev_i32_e32 v63, 31, v62
	v_fma_f32 v18, -v5, v24, 1.0
	v_fmac_f32_e32 v24, v18, v24
	v_div_scale_f32 v18, vcc, 1.0, v113, 1.0
	v_mul_f32_e32 v19, v18, v24
	v_fma_f32 v20, -v5, v19, v18
	v_fmac_f32_e32 v19, v20, v24
	v_fma_f32 v5, -v5, v19, v18
	v_div_fmas_f32 v5, v5, v24, v19
	v_lshlrev_b32_e32 v18, 16, v6
	v_lshlrev_b32_e32 v19, 16, v10
	v_and_b32_e32 v10, 0xffff0000, v10
	v_and_b32_e32 v6, 0xffff0000, v6
	v_add_f32_e32 v6, v10, v6
	v_and_b32_e32 v10, 0xffff0000, v14
	v_add_f32_e32 v18, v19, v18
	v_lshlrev_b32_e32 v19, 16, v14
	v_add_f32_e32 v6, v6, v10
	v_lshlrev_b32_e32 v10, 16, v7
	v_lshlrev_b32_e32 v14, 16, v11
	v_add_f32_e32 v10, v14, v10
	v_lshlrev_b32_e32 v14, 16, v15
	v_div_fixup_f32 v5, v5, v113, 1.0
	v_add_f32_e32 v18, v18, v19
	v_add_f32_e32 v10, v10, v14
	v_mul_f32_e32 v18, v18, v5
	v_mul_f32_e32 v6, v6, v5
	v_mul_f32_e32 v14, v10, v5
	v_and_b32_e32 v24, 0xffff0000, v11
	v_lshlrev_b64 v[10:11], 2, v[64:65]
	v_cvt_pk_bf16_f32 v6, v18, v6
	v_lshl_add_u64 v[18:19], v[100:101], 0, v[10:11]
	v_lshl_add_u64 v[20:21], v[102:103], 0, v[10:11]
	v_lshl_add_u64 v[10:11], v[98:99], 0, v[10:11]
	global_load_dword v25, v[18:19], off
	s_nop 0
	global_load_dword v20, v[20:21], off
	s_nop 0
	global_load_dword v21, v[10:11], off
	v_and_b32_e32 v7, 0xffff0000, v7
	v_add_f32_e32 v7, v24, v7
	v_and_b32_e32 v10, 0xffff0000, v15
	v_add_f32_e32 v7, v7, v10
	v_lshlrev_b32_e32 v10, 16, v8
	v_lshlrev_b32_e32 v11, 16, v12
	v_add_f32_e32 v10, v11, v10
	v_lshlrev_b32_e32 v11, 16, v16
	v_add_f32_e32 v10, v10, v11
	v_mul_f32_e32 v7, v7, v5
	v_mul_f32_e32 v24, v10, v5
	v_lshlrev_b64 v[10:11], 2, v[62:63]
	v_cvt_pk_bf16_f32 v7, v14, v7
	v_lshl_add_u64 v[14:15], v[100:101], 0, v[10:11]
	v_lshl_add_u64 v[18:19], v[102:103], 0, v[10:11]
	v_lshl_add_u64 v[10:11], v[98:99], 0, v[10:11]
	global_load_dword v26, v[14:15], off
	global_load_dword v27, v[18:19], off
	global_load_dword v28, v[10:11], off
	v_and_b32_e32 v12, 0xffff0000, v12
	v_and_b32_e32 v8, 0xffff0000, v8
	v_add_f32_e32 v8, v12, v8
	v_and_b32_e32 v10, 0xffff0000, v16
	v_add_f32_e32 v8, v8, v10
	v_lshlrev_b32_e32 v10, 16, v9
	v_lshlrev_b32_e32 v11, 16, v13
	v_add_f32_e32 v10, v11, v10
	v_lshlrev_b32_e32 v11, 16, v17
	v_add_u32_e32 v60, 48, v104
	v_add_f32_e32 v10, v10, v11
	v_ashrrev_i32_e32 v61, 31, v60
	v_mul_f32_e32 v12, v10, v5
	v_lshlrev_b64 v[10:11], 2, v[60:61]
	v_lshl_add_u64 v[14:15], v[100:101], 0, v[10:11]
	v_lshl_add_u64 v[18:19], v[102:103], 0, v[10:11]
	v_lshl_add_u64 v[10:11], v[98:99], 0, v[10:11]
	global_load_dword v16, v[14:15], off
	s_nop 0
	global_load_dword v18, v[18:19], off
	s_nop 0
	global_load_dword v19, v[10:11], off
	v_and_b32_e32 v10, 0xffff0000, v13
	v_and_b32_e32 v9, 0xffff0000, v9
	v_add_f32_e32 v9, v10, v9
	v_and_b32_e32 v10, 0xffff0000, v17
	v_add_u32_e32 v58, 56, v104
	v_mul_f32_e32 v8, v8, v5
	v_add_f32_e32 v9, v9, v10
	v_ashrrev_i32_e32 v59, 31, v58
	v_cvt_pk_bf16_f32 v8, v24, v8
	v_mul_f32_e32 v5, v9, v5
	v_cvt_pk_bf16_f32 v9, v12, v5
	global_store_dwordx4 v[22:23], v[6:9], off
	v_lshlrev_b64 v[10:11], 2, v[58:59]
	v_lshl_add_u64 v[12:13], v[100:101], 0, v[10:11]
	v_lshlrev_b64 v[6:7], 10, v[64:65]
	v_lshl_add_u64 v[8:9], v[94:95], 0, v[6:7]
	global_load_dwordx4 v[66:69], v[8:9], off nt
	v_lshl_add_u64 v[8:9], v[96:97], 0, v[6:7]
	v_lshl_add_u64 v[14:15], v[102:103], 0, v[10:11]
	v_lshl_add_u64 v[10:11], v[98:99], 0, v[10:11]
	global_load_dword v5, v[12:13], off
	global_load_dword v92, v[14:15], off
	global_load_dword v93, v[10:11], off
	global_load_dwordx4 v[70:73], v[8:9], off nt
	v_lshl_add_u64 v[8:9], v[2:3], 0, v[6:7]
	v_lshl_add_u64 v[6:7], s[2:3], 0, v[6:7]
	v_lshl_add_u64 v[6:7], v[6:7], 0, v[86:87]
	s_mov_b32 s6, 0x400000
	v_add_co_u32_e32 v10, vcc, s6, v6
	s_nop 1
	v_addc_co_u32_e32 v11, vcc, 0, v7, vcc
	v_add_co_u32_e32 v6, vcc, s45, v6
	global_load_dwordx4 v[74:77], v[8:9], off nt
	global_load_dwordx4 v[88:91], v[10:11], off nt
	v_addc_co_u32_e32 v7, vcc, 0, v7, vcc
	global_load_dwordx4 v[98:101], v[6:7], off nt
	s_waitcnt vmcnt(16)
	v_add_f32_e32 v6, v25, v20
	s_waitcnt vmcnt(15)
	v_add_f32_e32 v110, v6, v21
	v_lshlrev_b64 v[6:7], 10, v[62:63]
	v_lshl_add_u64 v[8:9], v[94:95], 0, v[6:7]
	global_load_dwordx4 v[102:105], v[8:9], off nt
	v_lshl_add_u64 v[8:9], v[96:97], 0, v[6:7]
	global_load_dwordx4 v[106:109], v[8:9], off nt
	v_lshl_add_u64 v[8:9], v[2:3], 0, v[6:7]
	v_lshl_add_u64 v[6:7], s[2:3], 0, v[6:7]
	v_lshl_add_u64 v[6:7], v[6:7], 0, v[86:87]
	v_add_co_u32_e32 v10, vcc, s6, v6
	s_nop 1
	v_addc_co_u32_e32 v11, vcc, 0, v7, vcc
	v_add_co_u32_e32 v6, vcc, s45, v6
	global_load_dwordx4 v[46:49], v[8:9], off nt
	global_load_dwordx4 v[50:53], v[10:11], off nt
	v_addc_co_u32_e32 v7, vcc, 0, v7, vcc
	global_load_dwordx4 v[54:57], v[6:7], off nt
	s_waitcnt vmcnt(18)
	v_add_f32_e32 v6, v26, v27
	s_waitcnt vmcnt(17)
	v_add_f32_e32 v111, v6, v28
	v_lshlrev_b64 v[6:7], 10, v[60:61]
	v_lshl_add_u64 v[8:9], v[94:95], 0, v[6:7]
	global_load_dwordx4 v[38:41], v[8:9], off nt
	v_lshl_add_u64 v[8:9], v[96:97], 0, v[6:7]
	global_load_dwordx4 v[42:45], v[8:9], off nt
	v_lshl_add_u64 v[8:9], v[2:3], 0, v[6:7]
	v_lshl_add_u64 v[6:7], s[2:3], 0, v[6:7]
	v_lshl_add_u64 v[6:7], v[6:7], 0, v[86:87]
	v_add_co_u32_e32 v10, vcc, s6, v6
	s_nop 1
	v_addc_co_u32_e32 v11, vcc, 0, v7, vcc
	v_add_co_u32_e32 v6, vcc, s45, v6
	global_load_dwordx4 v[26:29], v[8:9], off nt
	global_load_dwordx4 v[30:33], v[10:11], off nt
	v_addc_co_u32_e32 v7, vcc, 0, v7, vcc
	global_load_dwordx4 v[34:37], v[6:7], off nt
	s_waitcnt vmcnt(20)
	v_add_f32_e32 v6, v16, v18
	s_waitcnt vmcnt(19)
	v_add_f32_e32 v112, v6, v19
	v_lshlrev_b64 v[6:7], 10, v[58:59]
	v_lshl_add_u64 v[8:9], v[94:95], 0, v[6:7]
	global_load_dwordx4 v[18:21], v[8:9], off nt
	v_lshl_add_u64 v[8:9], v[96:97], 0, v[6:7]
	v_lshl_add_u64 v[2:3], v[2:3], 0, v[6:7]
	v_lshl_add_u64 v[6:7], s[2:3], 0, v[6:7]
	v_lshl_add_u64 v[14:15], v[6:7], 0, v[86:87]
	v_add_co_u32_e32 v10, vcc, s6, v14
	global_load_dwordx4 v[22:25], v[8:9], off nt
	s_nop 0
	v_addc_co_u32_e32 v11, vcc, 0, v15, vcc
	global_load_dwordx4 v[6:9], v[2:3], off nt
	s_nop 0
	global_load_dwordx4 v[10:13], v[10:11], off nt
	v_add_co_u32_e32 v2, vcc, s45, v14
	s_nop 1
	v_addc_co_u32_e32 v3, vcc, 0, v15, vcc
	global_load_dwordx4 v[14:17], v[2:3], off nt
	s_waitcnt vmcnt(20)
	v_add_f32_e32 v2, v5, v92
	s_waitcnt vmcnt(19)
	v_add_f32_e32 v5, v2, v93
	v_lshlrev_b32_e32 v2, 16, v66
	s_waitcnt vmcnt(18)
	v_lshlrev_b32_e32 v3, 16, v70
	v_fmac_f32_e32 v2, v82, v3
	v_and_b32_e32 v3, 0xffff0000, v66
	v_and_b32_e32 v66, 0xffff0000, v70
	v_fmac_f32_e32 v3, v83, v66
	v_cvt_pk_bf16_f32 v66, v2, v3
	v_lshlrev_b32_e32 v2, 16, v67
	v_lshlrev_b32_e32 v3, 16, v71
	v_fmac_f32_e32 v2, v84, v3
	v_and_b32_e32 v3, 0xffff0000, v67
	v_and_b32_e32 v67, 0xffff0000, v71
	v_fmac_f32_e32 v3, v85, v67
	v_cvt_pk_bf16_f32 v67, v2, v3
	v_lshlrev_b32_e32 v2, 16, v68
	v_lshlrev_b32_e32 v3, 16, v72
	v_fmac_f32_e32 v2, v78, v3
	v_and_b32_e32 v3, 0xffff0000, v68
	v_and_b32_e32 v68, 0xffff0000, v72
	v_fmac_f32_e32 v3, v79, v68
	v_cvt_pk_bf16_f32 v68, v2, v3
	v_lshlrev_b32_e32 v2, 16, v69
	v_lshlrev_b32_e32 v3, 16, v73
	v_fmac_f32_e32 v2, v80, v3
	v_and_b32_e32 v3, 0xffff0000, v69
	v_and_b32_e32 v69, 0xffff0000, v73
	v_fmac_f32_e32 v3, v81, v69
	v_cvt_pk_bf16_f32 v69, v2, v3
	v_lshlrev_b64 v[2:3], 11, v[64:65]
	v_div_scale_f32 v64, s[2:3], v110, v110, 1.0
	v_rcp_f32_e32 v65, v64
	v_lshl_add_u64 v[2:3], s[4:5], 0, v[2:3]
	v_lshl_add_u64 v[2:3], v[2:3], 0, v[86:87]
	global_store_dwordx4 v[2:3], v[66:69], off offset:1024
	s_waitcnt vmcnt(18)
	v_and_b32_e32 v70, 0xffff0000, v77
	v_fma_f32 v66, -v64, v65, 1.0
	v_fmac_f32_e32 v65, v66, v65
	v_div_scale_f32 v66, vcc, 1.0, v110, 1.0
	v_mul_f32_e32 v67, v66, v65
	v_fma_f32 v68, -v64, v67, v66
	v_fmac_f32_e32 v67, v68, v65
	v_fma_f32 v64, -v64, v67, v66
	v_div_fmas_f32 v64, v64, v65, v67
	v_div_fixup_f32 v67, v64, v110, 1.0
	s_waitcnt vmcnt(17)
	v_lshlrev_b32_e32 v64, 16, v88
	v_lshlrev_b32_e32 v65, 16, v74
	v_add_f32_e32 v64, v64, v65
	s_waitcnt vmcnt(16)
	v_lshlrev_b32_e32 v65, 16, v98
	v_add_f32_e32 v64, v64, v65
	v_and_b32_e32 v65, 0xffff0000, v88
	v_and_b32_e32 v66, 0xffff0000, v74
	v_add_f32_e32 v65, v65, v66
	v_and_b32_e32 v66, 0xffff0000, v98
	v_add_f32_e32 v65, v65, v66
	v_mul_f32_e32 v64, v64, v67
	v_mul_f32_e32 v65, v65, v67
	v_cvt_pk_bf16_f32 v64, v64, v65
	v_lshlrev_b32_e32 v65, 16, v89
	v_lshlrev_b32_e32 v66, 16, v75
	v_add_f32_e32 v65, v65, v66
	v_lshlrev_b32_e32 v66, 16, v99
	v_add_f32_e32 v65, v65, v66
	v_and_b32_e32 v66, 0xffff0000, v89
	v_and_b32_e32 v68, 0xffff0000, v75
	v_add_f32_e32 v66, v66, v68
	v_and_b32_e32 v68, 0xffff0000, v99
	v_add_f32_e32 v66, v66, v68
	v_mul_f32_e32 v65, v65, v67
	v_mul_f32_e32 v66, v66, v67
	v_cvt_pk_bf16_f32 v65, v65, v66
	v_lshlrev_b32_e32 v66, 16, v90
	v_lshlrev_b32_e32 v68, 16, v76
	v_add_f32_e32 v66, v66, v68
	v_lshlrev_b32_e32 v68, 16, v100
	v_add_f32_e32 v66, v66, v68
	v_and_b32_e32 v68, 0xffff0000, v90
	v_and_b32_e32 v69, 0xffff0000, v76
	v_add_f32_e32 v68, v68, v69
	v_and_b32_e32 v69, 0xffff0000, v100
	v_add_f32_e32 v68, v68, v69
	v_mul_f32_e32 v66, v66, v67
	v_mul_f32_e32 v68, v68, v67
	v_cvt_pk_bf16_f32 v66, v66, v68
	v_lshlrev_b32_e32 v68, 16, v91
	v_lshlrev_b32_e32 v69, 16, v77
	v_add_f32_e32 v68, v68, v69
	v_lshlrev_b32_e32 v69, 16, v101
	v_add_f32_e32 v68, v68, v69
	v_and_b32_e32 v69, 0xffff0000, v91
	v_add_f32_e32 v69, v69, v70
	v_and_b32_e32 v70, 0xffff0000, v101
	v_add_f32_e32 v69, v69, v70
	v_mul_f32_e32 v68, v68, v67
	v_mul_f32_e32 v67, v69, v67
	v_cvt_pk_bf16_f32 v67, v68, v67
	global_store_dwordx4 v[2:3], v[64:67], off
	s_waitcnt vmcnt(16)
	v_lshlrev_b32_e32 v2, 16, v102
	s_waitcnt vmcnt(15)
	v_lshlrev_b32_e32 v3, 16, v106
	v_fmac_f32_e32 v2, v82, v3
	v_and_b32_e32 v3, 0xffff0000, v102
	v_and_b32_e32 v64, 0xffff0000, v106
	v_fmac_f32_e32 v3, v83, v64
	v_cvt_pk_bf16_f32 v64, v2, v3
	v_lshlrev_b32_e32 v2, 16, v103
	v_lshlrev_b32_e32 v3, 16, v107
	v_fmac_f32_e32 v2, v84, v3
	v_and_b32_e32 v3, 0xffff0000, v103
	v_and_b32_e32 v65, 0xffff0000, v107
	v_fmac_f32_e32 v3, v85, v65
	v_cvt_pk_bf16_f32 v65, v2, v3
	v_lshlrev_b32_e32 v2, 16, v104
	v_lshlrev_b32_e32 v3, 16, v108
	v_fmac_f32_e32 v2, v78, v3
	v_and_b32_e32 v3, 0xffff0000, v104
	v_and_b32_e32 v66, 0xffff0000, v108
	v_fmac_f32_e32 v3, v79, v66
	v_cvt_pk_bf16_f32 v66, v2, v3
	v_lshlrev_b32_e32 v2, 16, v105
	v_lshlrev_b32_e32 v3, 16, v109
	v_fmac_f32_e32 v2, v80, v3
	v_and_b32_e32 v3, 0xffff0000, v105
	v_and_b32_e32 v67, 0xffff0000, v109
	v_fmac_f32_e32 v3, v81, v67
	v_cvt_pk_bf16_f32 v67, v2, v3
	v_lshlrev_b64 v[2:3], 11, v[62:63]
	v_div_scale_f32 v62, s[2:3], v111, v111, 1.0
	v_rcp_f32_e32 v63, v62
	v_lshl_add_u64 v[2:3], s[4:5], 0, v[2:3]
	v_lshl_add_u64 v[2:3], v[2:3], 0, v[86:87]
	global_store_dwordx4 v[2:3], v[64:67], off offset:1024
	s_nop 1
	v_fma_f32 v64, -v62, v63, 1.0
	v_fmac_f32_e32 v63, v64, v63
	v_div_scale_f32 v64, vcc, 1.0, v111, 1.0
	v_mul_f32_e32 v65, v64, v63
	v_fma_f32 v66, -v62, v65, v64
	v_fmac_f32_e32 v65, v66, v63
	v_fma_f32 v62, -v62, v65, v64
	v_div_fmas_f32 v62, v62, v63, v65
	s_waitcnt vmcnt(14)
	v_lshlrev_b32_e32 v63, 16, v50
	v_lshlrev_b32_e32 v64, 16, v46
	v_and_b32_e32 v50, 0xffff0000, v50
	v_and_b32_e32 v46, 0xffff0000, v46
	v_add_f32_e32 v46, v50, v46
	s_waitcnt vmcnt(13)
	v_and_b32_e32 v50, 0xffff0000, v54
	v_add_f32_e32 v63, v63, v64
	v_lshlrev_b32_e32 v64, 16, v54
	v_add_f32_e32 v46, v46, v50
	v_lshlrev_b32_e32 v50, 16, v51
	v_lshlrev_b32_e32 v54, 16, v47
	v_and_b32_e32 v51, 0xffff0000, v51
	v_and_b32_e32 v47, 0xffff0000, v47
	v_add_f32_e32 v50, v50, v54
	v_lshlrev_b32_e32 v54, 16, v55
	v_add_f32_e32 v47, v51, v47
	v_and_b32_e32 v51, 0xffff0000, v55
	v_div_fixup_f32 v62, v62, v111, 1.0
	v_add_f32_e32 v50, v50, v54
	v_add_f32_e32 v47, v47, v51
	v_mul_f32_e32 v50, v50, v62
	v_mul_f32_e32 v47, v47, v62
	v_cvt_pk_bf16_f32 v47, v50, v47
	v_lshlrev_b32_e32 v50, 16, v52
	v_lshlrev_b32_e32 v51, 16, v48
	v_add_f32_e32 v50, v50, v51
	v_lshlrev_b32_e32 v51, 16, v56
	v_add_f32_e32 v50, v50, v51
	v_and_b32_e32 v51, 0xffff0000, v52
	v_and_b32_e32 v48, 0xffff0000, v48
	v_add_f32_e32 v48, v51, v48
	v_and_b32_e32 v51, 0xffff0000, v56
	v_add_f32_e32 v48, v48, v51
	v_mul_f32_e32 v50, v50, v62
	v_mul_f32_e32 v48, v48, v62
	v_cvt_pk_bf16_f32 v48, v50, v48
	v_lshlrev_b32_e32 v50, 16, v53
	v_lshlrev_b32_e32 v51, 16, v49
	v_add_f32_e32 v50, v50, v51
	v_lshlrev_b32_e32 v51, 16, v57
	v_add_f32_e32 v50, v50, v51
	v_and_b32_e32 v51, 0xffff0000, v53
	v_and_b32_e32 v49, 0xffff0000, v49
	v_add_f32_e32 v49, v51, v49
	v_and_b32_e32 v51, 0xffff0000, v57
	v_add_f32_e32 v49, v49, v51
	v_add_f32_e32 v63, v63, v64
	v_mul_f32_e32 v46, v46, v62
	v_mul_f32_e32 v49, v49, v62
	v_mul_f32_e32 v63, v63, v62
	v_cvt_pk_bf16_f32 v46, v63, v46
	v_mul_f32_e32 v50, v50, v62
	v_cvt_pk_bf16_f32 v49, v50, v49
	global_store_dwordx4 v[2:3], v[46:49], off
	s_waitcnt vmcnt(13)
	v_lshlrev_b32_e32 v2, 16, v38
	s_waitcnt vmcnt(12)
	v_lshlrev_b32_e32 v3, 16, v42
	v_fmac_f32_e32 v2, v82, v3
	v_and_b32_e32 v3, 0xffff0000, v38
	v_and_b32_e32 v38, 0xffff0000, v42
	v_fmac_f32_e32 v3, v83, v38
	v_cvt_pk_bf16_f32 v38, v2, v3
	v_lshlrev_b32_e32 v2, 16, v39
	v_lshlrev_b32_e32 v3, 16, v43
	v_fmac_f32_e32 v2, v84, v3
	v_and_b32_e32 v3, 0xffff0000, v39
	v_and_b32_e32 v39, 0xffff0000, v43
	v_fmac_f32_e32 v3, v85, v39
	v_cvt_pk_bf16_f32 v39, v2, v3
	v_lshlrev_b32_e32 v2, 16, v40
	v_lshlrev_b32_e32 v3, 16, v44
	v_fmac_f32_e32 v2, v78, v3
	v_and_b32_e32 v3, 0xffff0000, v40
	v_and_b32_e32 v40, 0xffff0000, v44
	v_fmac_f32_e32 v3, v79, v40
	v_cvt_pk_bf16_f32 v40, v2, v3
	v_lshlrev_b32_e32 v2, 16, v41
	v_lshlrev_b32_e32 v3, 16, v45
	v_fmac_f32_e32 v2, v80, v3
	v_and_b32_e32 v3, 0xffff0000, v41
	v_and_b32_e32 v41, 0xffff0000, v45
	v_div_scale_f32 v42, s[2:3], v112, v112, 1.0
	v_fmac_f32_e32 v3, v81, v41
	v_rcp_f32_e32 v43, v42
	v_cvt_pk_bf16_f32 v41, v2, v3
	v_lshlrev_b64 v[2:3], 11, v[60:61]
	v_lshl_add_u64 v[2:3], s[4:5], 0, v[2:3]
	v_lshl_add_u64 v[2:3], v[2:3], 0, v[86:87]
	global_store_dwordx4 v[2:3], v[38:41], off offset:1024
	s_nop 1
	v_fma_f32 v38, -v42, v43, 1.0
	v_fmac_f32_e32 v43, v38, v43
	v_div_scale_f32 v38, vcc, 1.0, v112, 1.0
	v_mul_f32_e32 v39, v38, v43
	v_fma_f32 v40, -v42, v39, v38
	v_fmac_f32_e32 v39, v40, v43
	v_fma_f32 v38, -v42, v39, v38
	v_div_fmas_f32 v38, v38, v43, v39
	s_waitcnt vmcnt(11)
	v_lshlrev_b32_e32 v39, 16, v30
	v_lshlrev_b32_e32 v40, 16, v26
	v_and_b32_e32 v30, 0xffff0000, v30
	v_and_b32_e32 v26, 0xffff0000, v26
	v_add_f32_e32 v26, v30, v26
	s_waitcnt vmcnt(10)
	v_and_b32_e32 v30, 0xffff0000, v34
	v_add_f32_e32 v39, v39, v40
	v_lshlrev_b32_e32 v40, 16, v34
	v_add_f32_e32 v26, v26, v30
	v_lshlrev_b32_e32 v30, 16, v31
	v_lshlrev_b32_e32 v34, 16, v27
	v_and_b32_e32 v31, 0xffff0000, v31
	v_and_b32_e32 v27, 0xffff0000, v27
	v_add_f32_e32 v30, v30, v34
	v_lshlrev_b32_e32 v34, 16, v35
	v_add_f32_e32 v27, v31, v27
	v_and_b32_e32 v31, 0xffff0000, v35
	v_div_fixup_f32 v38, v38, v112, 1.0
	v_add_f32_e32 v30, v30, v34
	v_add_f32_e32 v27, v27, v31
	v_mul_f32_e32 v30, v30, v38
	v_mul_f32_e32 v27, v27, v38
	v_cvt_pk_bf16_f32 v27, v30, v27
	v_lshlrev_b32_e32 v30, 16, v32
	v_lshlrev_b32_e32 v31, 16, v28
	v_add_f32_e32 v30, v30, v31
	v_lshlrev_b32_e32 v31, 16, v36
	v_add_f32_e32 v30, v30, v31
	v_and_b32_e32 v31, 0xffff0000, v32
	v_and_b32_e32 v28, 0xffff0000, v28
	v_add_f32_e32 v28, v31, v28
	v_and_b32_e32 v31, 0xffff0000, v36
	v_add_f32_e32 v28, v28, v31
	v_mul_f32_e32 v30, v30, v38
	v_mul_f32_e32 v28, v28, v38
	v_cvt_pk_bf16_f32 v28, v30, v28
	v_lshlrev_b32_e32 v30, 16, v33
	v_lshlrev_b32_e32 v31, 16, v29
	v_add_f32_e32 v30, v30, v31
	v_lshlrev_b32_e32 v31, 16, v37
	v_add_f32_e32 v30, v30, v31
	v_and_b32_e32 v31, 0xffff0000, v33
	v_and_b32_e32 v29, 0xffff0000, v29
	v_add_f32_e32 v29, v31, v29
	v_and_b32_e32 v31, 0xffff0000, v37
	v_add_f32_e32 v29, v29, v31
	v_add_f32_e32 v39, v39, v40
	v_mul_f32_e32 v26, v26, v38
	v_mul_f32_e32 v29, v29, v38
	v_mul_f32_e32 v39, v39, v38
	v_cvt_pk_bf16_f32 v26, v39, v26
	v_mul_f32_e32 v30, v30, v38
	v_cvt_pk_bf16_f32 v29, v30, v29
	global_store_dwordx4 v[2:3], v[26:29], off
	s_waitcnt vmcnt(10)
	v_lshlrev_b32_e32 v2, 16, v18
	s_waitcnt vmcnt(9)
	v_lshlrev_b32_e32 v3, 16, v22
	v_fmac_f32_e32 v2, v82, v3
	v_and_b32_e32 v3, 0xffff0000, v18
	v_and_b32_e32 v18, 0xffff0000, v22
	v_fmac_f32_e32 v3, v83, v18
	v_cvt_pk_bf16_f32 v18, v2, v3
	v_lshlrev_b32_e32 v2, 16, v19
	v_lshlrev_b32_e32 v3, 16, v23
	v_fmac_f32_e32 v2, v84, v3
	v_and_b32_e32 v3, 0xffff0000, v19
	v_and_b32_e32 v19, 0xffff0000, v23
	v_fmac_f32_e32 v3, v85, v19
	v_cvt_pk_bf16_f32 v19, v2, v3
	v_lshlrev_b32_e32 v2, 16, v20
	v_lshlrev_b32_e32 v3, 16, v24
	v_fmac_f32_e32 v2, v78, v3
	v_and_b32_e32 v3, 0xffff0000, v20
	v_and_b32_e32 v20, 0xffff0000, v24
	v_fmac_f32_e32 v3, v79, v20
	v_cvt_pk_bf16_f32 v20, v2, v3
	v_lshlrev_b32_e32 v2, 16, v21
	v_lshlrev_b32_e32 v3, 16, v25
	v_fmac_f32_e32 v2, v80, v3
	v_and_b32_e32 v3, 0xffff0000, v21
	v_and_b32_e32 v21, 0xffff0000, v25
	v_div_scale_f32 v22, s[2:3], v5, v5, 1.0
	v_fmac_f32_e32 v3, v81, v21
	v_rcp_f32_e32 v23, v22
	v_cvt_pk_bf16_f32 v21, v2, v3
	v_lshlrev_b64 v[2:3], 11, v[58:59]
	v_lshl_add_u64 v[2:3], s[4:5], 0, v[2:3]
	v_lshl_add_u64 v[2:3], v[2:3], 0, v[86:87]
	global_store_dwordx4 v[2:3], v[18:21], off offset:1024
	s_nop 1
	v_fma_f32 v18, -v22, v23, 1.0
	v_fmac_f32_e32 v23, v18, v23
	v_div_scale_f32 v18, vcc, 1.0, v5, 1.0
	v_mul_f32_e32 v19, v18, v23
	v_fma_f32 v20, -v22, v19, v18
	v_fmac_f32_e32 v19, v20, v23
	v_fma_f32 v18, -v22, v19, v18
	v_div_fmas_f32 v18, v18, v23, v19
	v_div_fixup_f32 v5, v18, v5, 1.0
	s_waitcnt vmcnt(8)
	v_lshlrev_b32_e32 v18, 16, v10
	v_lshlrev_b32_e32 v19, 16, v6
	v_and_b32_e32 v10, 0xffff0000, v10
	v_and_b32_e32 v6, 0xffff0000, v6
	v_add_f32_e32 v6, v10, v6
	s_waitcnt vmcnt(7)
	v_and_b32_e32 v10, 0xffff0000, v14
	v_add_f32_e32 v18, v18, v19
	v_lshlrev_b32_e32 v19, 16, v14
	v_add_f32_e32 v6, v6, v10
	v_lshlrev_b32_e32 v10, 16, v11
	v_lshlrev_b32_e32 v14, 16, v7
	v_and_b32_e32 v11, 0xffff0000, v11
	v_and_b32_e32 v7, 0xffff0000, v7
	v_add_f32_e32 v10, v10, v14
	v_lshlrev_b32_e32 v14, 16, v15
	v_add_f32_e32 v7, v11, v7
	v_and_b32_e32 v11, 0xffff0000, v15
	v_add_f32_e32 v10, v10, v14
	v_add_f32_e32 v7, v7, v11
	v_mul_f32_e32 v10, v10, v5
	v_mul_f32_e32 v7, v7, v5
	v_cvt_pk_bf16_f32 v7, v10, v7
	v_lshlrev_b32_e32 v10, 16, v12
	v_lshlrev_b32_e32 v11, 16, v8
	v_add_f32_e32 v10, v10, v11
	v_lshlrev_b32_e32 v11, 16, v16
	v_add_f32_e32 v10, v10, v11
	v_and_b32_e32 v11, 0xffff0000, v12
	v_and_b32_e32 v8, 0xffff0000, v8
	v_add_f32_e32 v8, v11, v8
	v_and_b32_e32 v11, 0xffff0000, v16
	v_add_f32_e32 v8, v8, v11
	v_mul_f32_e32 v10, v10, v5
	v_mul_f32_e32 v8, v8, v5
	v_cvt_pk_bf16_f32 v8, v10, v8
	v_lshlrev_b32_e32 v10, 16, v13
	v_lshlrev_b32_e32 v11, 16, v9
	v_add_f32_e32 v10, v10, v11
	v_lshlrev_b32_e32 v11, 16, v17
	v_add_f32_e32 v10, v10, v11
	v_and_b32_e32 v11, 0xffff0000, v13
	v_and_b32_e32 v9, 0xffff0000, v9
	v_add_f32_e32 v9, v11, v9
	v_and_b32_e32 v11, 0xffff0000, v17
	v_add_f32_e32 v18, v18, v19
	v_mul_f32_e32 v6, v6, v5
	v_add_f32_e32 v9, v9, v11
	v_mul_f32_e32 v18, v18, v5
	v_cvt_pk_bf16_f32 v6, v18, v6
	v_mul_f32_e32 v10, v10, v5
	v_mul_f32_e32 v5, v9, v5
	v_cvt_pk_bf16_f32 v9, v10, v5
	global_store_dwordx4 v[2:3], v[6:9], off
	s_barrier
	s_waitcnt vmcnt(0)
	s_barrier
	s_and_saveexec_b64 s[2:3], s[90:91]
	s_cbranch_execz .LBB0_679
	v_readlane_b32 s6, v253, 48
	s_waitcnt vmcnt(0) expcnt(0) lgkmcnt(0)
	s_mov_b64 s[4:5], exec
	v_mov_b32_e32 v2, s6
	v_readlane_b32 s6, v253, 49
	ds_read_b32 v5, v2
	v_mbcnt_lo_u32_b32 v3, s4, 0
	v_mov_b32_e32 v2, s6
	ds_read_b32 v2, v2
	v_mbcnt_hi_u32_b32 v3, s5, v3
	v_cmp_eq_u32_e32 vcc, 0, v3
	s_and_saveexec_b64 s[6:7], vcc
	s_cbranch_execz .LBB0_645
	s_bcnt1_i32_b64 s4, s[4:5]
	v_mov_b32_e32 v6, s4
	v_readlane_b32 s4, v253, 7
	v_readlane_b32 s5, v253, 8
	s_nop 4
	global_atomic_add v6, v4, v6, s[4:5] sc0

.LBB0_702:
	v_lshl_or_b32 v196, s60, 8, v226
	v_lshl_add_u32 v194, s61, 8, v5
	v_ashrrev_i32_e32 v197, 31, v196
	v_lshlrev_b64 v[222:223], 1, v[196:197]
	v_ashrrev_i32_e32 v195, 31, v194
	v_lshl_add_u64 v[126:127], s[4:5], 0, v[222:223]
	v_lshlrev_b64 v[224:225], 11, v[194:195]
	v_lshl_add_u64 v[128:129], v[126:127], 0, v[224:225]
	global_load_dwordx4 v[230:233], v[128:129], off
	global_load_dwordx4 v[190:193], v[128:129], off offset:64
	v_or_b32_e32 v128, 16, v194
	v_ashrrev_i32_e32 v129, 31, v128
	v_lshlrev_b64 v[220:221], 11, v[128:129]
	v_lshl_add_u64 v[128:129], v[126:127], 0, v[220:221]
	global_load_dwordx4 v[186:189], v[128:129], off
	global_load_dwordx4 v[182:185], v[128:129], off offset:64
	v_or_b32_e32 v128, 32, v194
	v_ashrrev_i32_e32 v129, 31, v128
	v_lshlrev_b64 v[218:219], 11, v[128:129]
	v_lshl_add_u64 v[128:129], v[126:127], 0, v[218:219]
	global_load_dwordx4 v[178:181], v[128:129], off
	global_load_dwordx4 v[174:177], v[128:129], off offset:64
	v_or_b32_e32 v128, 48, v194
	v_ashrrev_i32_e32 v129, 31, v128
	s_mov_b64 s[22:23], 0x40000
	v_lshlrev_b64 v[216:217], 11, v[128:129]
	v_lshl_add_u64 v[214:215], v[224:225], 0, s[22:23]
	s_mov_b64 s[22:23], 0x48000
	v_lshl_add_u64 v[128:129], v[126:127], 0, v[216:217]
	v_lshl_add_u64 v[212:213], v[224:225], 0, s[22:23]
	s_mov_b64 s[22:23], 0x50000
	global_load_dwordx4 v[170:173], v[128:129], off
	global_load_dwordx4 v[166:169], v[128:129], off offset:64
	v_lshl_add_u64 v[128:129], v[126:127], 0, v[214:215]
	v_lshl_add_u64 v[200:201], v[224:225], 0, s[22:23]
	s_mov_b64 s[22:23], 0x58000
	global_load_dwordx4 v[162:165], v[128:129], off
	global_load_dwordx4 v[158:161], v[128:129], off offset:64
	v_lshl_add_u64 v[128:129], v[126:127], 0, v[212:213]
	v_lshl_add_u64 v[198:199], v[224:225], 0, s[22:23]
	global_load_dwordx4 v[154:157], v[128:129], off
	global_load_dwordx4 v[150:153], v[128:129], off offset:64
	v_lshl_add_u64 v[128:129], v[126:127], 0, v[200:201]
	v_lshl_add_u64 v[126:127], v[126:127], 0, v[198:199]
	global_load_dwordx4 v[146:149], v[128:129], off
	global_load_dwordx4 v[138:141], v[128:129], off offset:64
	global_load_dwordx4 v[142:145], v[126:127], off
	s_nop 0
	global_load_dwordx4 v[126:129], v[126:127], off offset:64
	s_lshl_b32 s13, s60, 2
	s_or_b32 s22, s13, s56
	s_ashr_i32 s23, s22, 31
	s_lshl_b64 s[22:23], s[22:23], 14
	s_waitcnt vmcnt(0)
	v_lshlrev_b32_e32 v242, 16, v230
	v_and_b32_e32 v243, 0xffff0000, v230
	v_lshlrev_b32_e32 v230, 16, v231
	v_and_b32_e32 v231, 0xffff0000, v231
	v_pk_add_f32 v[132:133], v[132:133], v[230:231]
	v_pk_add_f32 v[130:131], v[130:131], v[242:243]
	v_lshlrev_b32_e32 v244, 16, v232
	v_and_b32_e32 v245, 0xffff0000, v232
	v_mul_f32_e32 v229, v131, v131
	v_mul_f32_e32 v230, v133, v133
	v_pk_add_f32 v[134:135], v[134:135], v[244:245]
	v_fmac_f32_e32 v229, v130, v130
	v_fmac_f32_e32 v230, v132, v132
	v_add_f32_e32 v229, v229, v230
	v_mul_f32_e32 v230, v135, v135
	v_lshlrev_b32_e32 v232, 16, v233
	v_and_b32_e32 v233, 0xffff0000, v233
	v_fmac_f32_e32 v230, v134, v134
	v_cvt_pk_bf16_f32 v130, v130, v131
	v_cvt_pk_bf16_f32 v131, v132, v133
	v_cvt_pk_bf16_f32 v132, v134, v135
	v_lshl_add_u64 v[134:135], s[4:5], 0, v[224:225]
	v_pk_add_f32 v[136:137], v[136:137], v[232:233]
	v_lshl_add_u64 v[134:135], v[134:135], 0, v[222:223]
	v_cvt_pk_bf16_f32 v133, v136, v137
	v_mul_f32_e32 v231, v137, v137
	global_store_dwordx4 v[134:135], v[130:133], off
	v_fmac_f32_e32 v231, v136, v136
	v_lshlrev_b32_e32 v136, 16, v192
	v_lshlrev_b32_e32 v130, 16, v190
	v_and_b32_e32 v131, 0xffff0000, v190
	v_lshlrev_b32_e32 v132, 16, v191
	v_and_b32_e32 v133, 0xffff0000, v191
	v_and_b32_e32 v137, 0xffff0000, v192
	v_lshlrev_b32_e32 v190, 16, v193
	v_and_b32_e32 v191, 0xffff0000, v193
	v_pk_add_f32 v[124:125], v[124:125], v[132:133]
	v_pk_add_f32 v[122:123], v[122:123], v[130:131]
	v_pk_add_f32 v[130:131], v[120:121], v[190:191]
	v_pk_add_f32 v[120:121], v[118:119], v[136:137]
	v_mul_f32_e32 v118, v123, v123
	v_mul_f32_e32 v119, v125, v125
	v_fmac_f32_e32 v118, v122, v122
	v_fmac_f32_e32 v119, v124, v124
	v_add_f32_e32 v118, v118, v119
	v_mul_f32_e32 v119, v121, v121
	v_mul_f32_e32 v132, v131, v131
	v_fmac_f32_e32 v119, v120, v120
	v_fmac_f32_e32 v132, v130, v130
	v_add_f32_e32 v230, v230, v231
	v_add_f32_e32 v119, v119, v132
	v_add_f32_e32 v229, v229, v230
	v_add_f32_e32 v118, v118, v119
	v_add_f32_e32 v132, v229, v118
	v_cvt_pk_bf16_f32 v118, v122, v123
	v_cvt_pk_bf16_f32 v119, v124, v125
	v_cvt_pk_bf16_f32 v120, v120, v121
	v_cvt_pk_bf16_f32 v121, v130, v131
	global_store_dwordx4 v[134:135], v[118:121], off offset:64
	s_nop 1
	v_mov_b32_e32 v118, v132
	s_nop 1
	v_permlane16_swap_b32_e32 v132, v118
	v_add_f32_e32 v118, v132, v118
	v_mov_b32_e32 v119, v118
	s_nop 1
	v_permlane32_swap_b32_e32 v118, v119
	s_and_saveexec_b64 s[24:25], s[6:7]
	s_cbranch_execz .LBB0_704
	s_add_u32 s26, s54, s22
	s_addc_u32 s27, s55, s23
	v_lshl_add_u64 v[120:121], v[194:195], 2, s[26:27]
	v_add_f32_e32 v118, v118, v119
	global_store_dword v[120:121], v118, off
.LBB0_704:
	s_or_b64 exec, exec, s[24:25]
	v_lshlrev_b32_e32 v118, 16, v186
	v_and_b32_e32 v119, 0xffff0000, v186
	v_lshlrev_b32_e32 v120, 16, v187
	v_and_b32_e32 v121, 0xffff0000, v187
	v_lshlrev_b32_e32 v122, 16, v188
	v_and_b32_e32 v123, 0xffff0000, v188
	v_lshlrev_b32_e32 v124, 16, v189
	v_and_b32_e32 v125, 0xffff0000, v189
	v_pk_add_f32 v[116:117], v[116:117], v[120:121]
	v_pk_add_f32 v[114:115], v[114:115], v[118:119]
	v_pk_add_f32 v[118:119], v[112:113], v[124:125]
	v_pk_add_f32 v[112:113], v[110:111], v[122:123]
	v_mul_f32_e32 v110, v115, v115
	v_mul_f32_e32 v111, v117, v117
	v_fmac_f32_e32 v110, v114, v114
	v_fmac_f32_e32 v111, v116, v116
	v_add_f32_e32 v110, v110, v111
	v_mul_f32_e32 v111, v113, v113
	v_mul_f32_e32 v120, v119, v119
	v_fmac_f32_e32 v111, v112, v112
	v_fmac_f32_e32 v120, v118, v118
	v_add_f32_e32 v111, v111, v120
	v_add_f32_e32 v120, v110, v111
	v_cvt_pk_bf16_f32 v110, v114, v115
	v_lshl_add_u64 v[114:115], s[4:5], 0, v[220:221]
	v_cvt_pk_bf16_f32 v111, v116, v117
	v_cvt_pk_bf16_f32 v112, v112, v113
	v_cvt_pk_bf16_f32 v113, v118, v119
	v_lshl_add_u64 v[114:115], v[196:197], 1, v[114:115]
	global_store_dwordx4 v[114:115], v[110:113], off
	v_lshlrev_b32_e32 v116, 16, v184
	v_and_b32_e32 v117, 0xffff0000, v184
	v_lshlrev_b32_e32 v110, 16, v182
	v_and_b32_e32 v111, 0xffff0000, v182
	v_lshlrev_b32_e32 v112, 16, v183
	v_and_b32_e32 v113, 0xffff0000, v183
	v_lshlrev_b32_e32 v118, 16, v185
	v_and_b32_e32 v119, 0xffff0000, v185
	v_pk_add_f32 v[108:109], v[108:109], v[112:113]
	v_pk_add_f32 v[106:107], v[106:107], v[110:111]
	v_pk_add_f32 v[110:111], v[104:105], v[118:119]
	v_pk_add_f32 v[104:105], v[102:103], v[116:117]
	v_mul_f32_e32 v102, v107, v107
	v_mul_f32_e32 v103, v109, v109
	v_fmac_f32_e32 v102, v106, v106
	v_fmac_f32_e32 v103, v108, v108
	v_add_f32_e32 v102, v102, v103
	v_mul_f32_e32 v103, v105, v105
	v_mul_f32_e32 v112, v111, v111
	v_fmac_f32_e32 v103, v104, v104
	v_fmac_f32_e32 v112, v110, v110
	v_add_f32_e32 v103, v103, v112
	v_add_f32_e32 v102, v102, v103
	v_add_f32_e32 v112, v120, v102
	v_cvt_pk_bf16_f32 v102, v106, v107
	v_cvt_pk_bf16_f32 v103, v108, v109
	v_cvt_pk_bf16_f32 v104, v104, v105
	v_cvt_pk_bf16_f32 v105, v110, v111
	global_store_dwordx4 v[114:115], v[102:105], off offset:64
	s_nop 1
	v_mov_b32_e32 v102, v112
	s_nop 1
	v_permlane16_swap_b32_e32 v112, v102
	v_add_f32_e32 v102, v112, v102
	v_mov_b32_e32 v103, v102
	s_nop 1
	v_permlane32_swap_b32_e32 v102, v103
	s_and_saveexec_b64 s[24:25], s[6:7]
	s_cbranch_execz .LBB0_706
	s_add_u32 s26, s54, s22
	s_addc_u32 s27, s55, s23
	v_lshl_add_u64 v[104:105], v[194:195], 2, s[26:27]
	v_add_f32_e32 v102, v102, v103
	global_store_dword v[104:105], v102, off offset:64
.LBB0_706:
	s_or_b64 exec, exec, s[24:25]
	v_lshlrev_b32_e32 v102, 16, v178
	v_and_b32_e32 v103, 0xffff0000, v178
	v_lshlrev_b32_e32 v104, 16, v179
	v_and_b32_e32 v105, 0xffff0000, v179
	v_lshlrev_b32_e32 v106, 16, v180
	v_and_b32_e32 v107, 0xffff0000, v180
	v_lshlrev_b32_e32 v108, 16, v181
	v_and_b32_e32 v109, 0xffff0000, v181
	v_pk_add_f32 v[100:101], v[100:101], v[104:105]
	v_pk_add_f32 v[98:99], v[98:99], v[102:103]
	v_pk_add_f32 v[102:103], v[96:97], v[108:109]
	v_pk_add_f32 v[96:97], v[94:95], v[106:107]
	v_mul_f32_e32 v94, v99, v99
	v_mul_f32_e32 v95, v101, v101
	v_fmac_f32_e32 v94, v98, v98
	v_fmac_f32_e32 v95, v100, v100
	v_add_f32_e32 v94, v94, v95
	v_mul_f32_e32 v95, v97, v97
	v_mul_f32_e32 v104, v103, v103
	v_fmac_f32_e32 v95, v96, v96
	v_fmac_f32_e32 v104, v102, v102
	v_add_f32_e32 v95, v95, v104
	v_add_f32_e32 v104, v94, v95
	v_cvt_pk_bf16_f32 v94, v98, v99
	v_lshl_add_u64 v[98:99], s[4:5], 0, v[218:219]
	v_cvt_pk_bf16_f32 v95, v100, v101
	v_cvt_pk_bf16_f32 v96, v96, v97
	v_cvt_pk_bf16_f32 v97, v102, v103
	v_lshl_add_u64 v[98:99], v[196:197], 1, v[98:99]
	global_store_dwordx4 v[98:99], v[94:97], off
	v_lshlrev_b32_e32 v100, 16, v176
	v_and_b32_e32 v101, 0xffff0000, v176
	v_lshlrev_b32_e32 v94, 16, v174
	v_and_b32_e32 v95, 0xffff0000, v174
	v_lshlrev_b32_e32 v96, 16, v175
	v_and_b32_e32 v97, 0xffff0000, v175
	v_lshlrev_b32_e32 v102, 16, v177
	v_and_b32_e32 v103, 0xffff0000, v177
	v_pk_add_f32 v[92:93], v[92:93], v[96:97]
	v_pk_add_f32 v[90:91], v[90:91], v[94:95]
	v_pk_add_f32 v[94:95], v[88:89], v[102:103]
	v_pk_add_f32 v[88:89], v[86:87], v[100:101]
	v_mul_f32_e32 v86, v91, v91
	v_mul_f32_e32 v87, v93, v93
	v_fmac_f32_e32 v86, v90, v90
	v_fmac_f32_e32 v87, v92, v92
	v_add_f32_e32 v86, v86, v87
	v_mul_f32_e32 v87, v89, v89
	v_mul_f32_e32 v96, v95, v95
	v_fmac_f32_e32 v87, v88, v88
	v_fmac_f32_e32 v96, v94, v94
	v_add_f32_e32 v87, v87, v96
	v_add_f32_e32 v86, v86, v87
	v_add_f32_e32 v96, v104, v86
	v_cvt_pk_bf16_f32 v86, v90, v91
	v_cvt_pk_bf16_f32 v87, v92, v93
	v_cvt_pk_bf16_f32 v88, v88, v89
	v_cvt_pk_bf16_f32 v89, v94, v95
	global_store_dwordx4 v[98:99], v[86:89], off offset:64
	s_nop 1
	v_mov_b32_e32 v86, v96
	s_nop 1
	v_permlane16_swap_b32_e32 v96, v86
	v_add_f32_e32 v86, v96, v86
	v_mov_b32_e32 v87, v86
	s_nop 1
	v_permlane32_swap_b32_e32 v86, v87
	s_and_saveexec_b64 s[24:25], s[6:7]
	s_cbranch_execz .LBB0_708
	s_add_u32 s26, s54, s22
	s_addc_u32 s27, s55, s23
	v_lshl_add_u64 v[88:89], v[194:195], 2, s[26:27]
	v_add_f32_e32 v86, v86, v87
	global_store_dword v[88:89], v86, off offset:128
.LBB0_708:
	s_or_b64 exec, exec, s[24:25]
	v_lshlrev_b32_e32 v86, 16, v170
	v_and_b32_e32 v87, 0xffff0000, v170
	v_lshlrev_b32_e32 v88, 16, v171
	v_and_b32_e32 v89, 0xffff0000, v171
	v_lshlrev_b32_e32 v90, 16, v172
	v_and_b32_e32 v91, 0xffff0000, v172
	v_lshlrev_b32_e32 v92, 16, v173
	v_and_b32_e32 v93, 0xffff0000, v173
	v_pk_add_f32 v[84:85], v[84:85], v[88:89]
	v_pk_add_f32 v[82:83], v[82:83], v[86:87]
	v_pk_add_f32 v[86:87], v[80:81], v[92:93]
	v_pk_add_f32 v[80:81], v[78:79], v[90:91]
	v_mul_f32_e32 v78, v83, v83
	v_mul_f32_e32 v79, v85, v85
	v_fmac_f32_e32 v78, v82, v82
	v_fmac_f32_e32 v79, v84, v84
	v_add_f32_e32 v78, v78, v79
	v_mul_f32_e32 v79, v81, v81
	v_mul_f32_e32 v88, v87, v87
	v_fmac_f32_e32 v79, v80, v80
	v_fmac_f32_e32 v88, v86, v86
	v_add_f32_e32 v79, v79, v88
	v_add_f32_e32 v88, v78, v79
	v_cvt_pk_bf16_f32 v78, v82, v83
	v_lshl_add_u64 v[82:83], s[4:5], 0, v[216:217]
	v_cvt_pk_bf16_f32 v79, v84, v85
	v_cvt_pk_bf16_f32 v80, v80, v81
	v_cvt_pk_bf16_f32 v81, v86, v87
	v_lshl_add_u64 v[82:83], v[196:197], 1, v[82:83]
	global_store_dwordx4 v[82:83], v[78:81], off
	v_lshlrev_b32_e32 v84, 16, v168
	v_and_b32_e32 v85, 0xffff0000, v168
	v_lshlrev_b32_e32 v78, 16, v166
	v_and_b32_e32 v79, 0xffff0000, v166
	v_lshlrev_b32_e32 v80, 16, v167
	v_and_b32_e32 v81, 0xffff0000, v167
	v_lshlrev_b32_e32 v86, 16, v169
	v_and_b32_e32 v87, 0xffff0000, v169
	v_pk_add_f32 v[76:77], v[76:77], v[80:81]
	v_pk_add_f32 v[74:75], v[74:75], v[78:79]
	v_pk_add_f32 v[78:79], v[72:73], v[86:87]
	v_pk_add_f32 v[72:73], v[70:71], v[84:85]
	v_mul_f32_e32 v70, v75, v75
	v_mul_f32_e32 v71, v77, v77
	v_fmac_f32_e32 v70, v74, v74
	v_fmac_f32_e32 v71, v76, v76
	v_add_f32_e32 v70, v70, v71
	v_mul_f32_e32 v71, v73, v73
	v_mul_f32_e32 v80, v79, v79
	v_fmac_f32_e32 v71, v72, v72
	v_fmac_f32_e32 v80, v78, v78
	v_add_f32_e32 v71, v71, v80
	v_add_f32_e32 v70, v70, v71
	v_add_f32_e32 v80, v88, v70
	v_cvt_pk_bf16_f32 v70, v74, v75
	v_cvt_pk_bf16_f32 v71, v76, v77
	v_cvt_pk_bf16_f32 v72, v72, v73
	v_cvt_pk_bf16_f32 v73, v78, v79
	global_store_dwordx4 v[82:83], v[70:73], off offset:64
	s_nop 1
	v_mov_b32_e32 v70, v80
	s_nop 1
	v_permlane16_swap_b32_e32 v80, v70
	v_add_f32_e32 v70, v80, v70
	v_mov_b32_e32 v71, v70
	s_nop 1
	v_permlane32_swap_b32_e32 v70, v71
	s_and_saveexec_b64 s[24:25], s[6:7]
	s_cbranch_execz .LBB0_710
	s_add_u32 s26, s54, s22
	s_addc_u32 s27, s55, s23
	v_lshl_add_u64 v[72:73], v[194:195], 2, s[26:27]
	v_add_f32_e32 v70, v70, v71
	global_store_dword v[72:73], v70, off offset:192
.LBB0_710:
	s_or_b64 exec, exec, s[24:25]
	v_lshlrev_b32_e32 v70, 16, v162
	v_and_b32_e32 v71, 0xffff0000, v162
	v_lshlrev_b32_e32 v72, 16, v163
	v_and_b32_e32 v73, 0xffff0000, v163
	v_lshlrev_b32_e32 v74, 16, v164
	v_and_b32_e32 v75, 0xffff0000, v164
	v_lshlrev_b32_e32 v76, 16, v165
	v_and_b32_e32 v77, 0xffff0000, v165
	v_pk_add_f32 v[68:69], v[68:69], v[72:73]
	v_pk_add_f32 v[66:67], v[66:67], v[70:71]
	v_pk_add_f32 v[70:71], v[64:65], v[76:77]
	v_pk_add_f32 v[64:65], v[62:63], v[74:75]
	v_mul_f32_e32 v62, v67, v67
	v_mul_f32_e32 v63, v69, v69
	v_fmac_f32_e32 v62, v66, v66
	v_fmac_f32_e32 v63, v68, v68
	v_add_f32_e32 v62, v62, v63
	v_mul_f32_e32 v63, v65, v65
	v_mul_f32_e32 v72, v71, v71
	v_fmac_f32_e32 v63, v64, v64
	v_fmac_f32_e32 v72, v70, v70
	v_add_f32_e32 v63, v63, v72
	v_add_f32_e32 v72, v62, v63
	v_cvt_pk_bf16_f32 v62, v66, v67
	v_lshl_add_u64 v[66:67], s[4:5], 0, v[214:215]
	v_cvt_pk_bf16_f32 v63, v68, v69
	v_cvt_pk_bf16_f32 v64, v64, v65
	v_cvt_pk_bf16_f32 v65, v70, v71
	v_lshl_add_u64 v[66:67], v[196:197], 1, v[66:67]
	global_store_dwordx4 v[66:67], v[62:65], off
	v_lshlrev_b32_e32 v68, 16, v160
	v_and_b32_e32 v69, 0xffff0000, v160
	v_lshlrev_b32_e32 v62, 16, v158
	v_and_b32_e32 v63, 0xffff0000, v158
	v_lshlrev_b32_e32 v64, 16, v159
	v_and_b32_e32 v65, 0xffff0000, v159
	v_lshlrev_b32_e32 v70, 16, v161
	v_and_b32_e32 v71, 0xffff0000, v161
	v_pk_add_f32 v[60:61], v[60:61], v[64:65]
	v_pk_add_f32 v[58:59], v[58:59], v[62:63]
	v_pk_add_f32 v[62:63], v[56:57], v[70:71]
	v_pk_add_f32 v[56:57], v[54:55], v[68:69]
	v_mul_f32_e32 v54, v59, v59
	v_mul_f32_e32 v55, v61, v61
	v_fmac_f32_e32 v54, v58, v58
	v_fmac_f32_e32 v55, v60, v60
	v_add_f32_e32 v54, v54, v55
	v_mul_f32_e32 v55, v57, v57
	v_mul_f32_e32 v64, v63, v63
	v_fmac_f32_e32 v55, v56, v56
	v_fmac_f32_e32 v64, v62, v62
	v_add_f32_e32 v55, v55, v64
	v_add_f32_e32 v54, v54, v55
	v_add_f32_e32 v64, v72, v54
	v_cvt_pk_bf16_f32 v54, v58, v59
	v_cvt_pk_bf16_f32 v55, v60, v61
	v_cvt_pk_bf16_f32 v56, v56, v57
	v_cvt_pk_bf16_f32 v57, v62, v63
	global_store_dwordx4 v[66:67], v[54:57], off offset:64
	s_nop 1
	v_mov_b32_e32 v54, v64
	s_nop 1
	v_permlane16_swap_b32_e32 v64, v54
	v_add_f32_e32 v54, v64, v54
	v_mov_b32_e32 v55, v54
	s_nop 1
	v_permlane32_swap_b32_e32 v54, v55
	s_and_saveexec_b64 s[24:25], s[6:7]
	s_cbranch_execz .LBB0_712
	s_add_u32 s26, s54, s22
	s_addc_u32 s27, s55, s23
	v_lshl_add_u64 v[56:57], v[194:195], 2, s[26:27]
	v_add_f32_e32 v54, v54, v55
	global_store_dword v[56:57], v54, off offset:512
.LBB0_712:
	s_or_b64 exec, exec, s[24:25]
	v_lshlrev_b32_e32 v54, 16, v154
	v_and_b32_e32 v55, 0xffff0000, v154
	v_lshlrev_b32_e32 v56, 16, v155
	v_and_b32_e32 v57, 0xffff0000, v155
	v_lshlrev_b32_e32 v58, 16, v156
	v_and_b32_e32 v59, 0xffff0000, v156
	v_lshlrev_b32_e32 v60, 16, v157
	v_and_b32_e32 v61, 0xffff0000, v157
	v_pk_add_f32 v[52:53], v[52:53], v[56:57]
	v_pk_add_f32 v[50:51], v[50:51], v[54:55]
	v_pk_add_f32 v[54:55], v[48:49], v[60:61]
	v_pk_add_f32 v[48:49], v[46:47], v[58:59]
	v_mul_f32_e32 v46, v51, v51
	v_mul_f32_e32 v47, v53, v53
	v_fmac_f32_e32 v46, v50, v50
	v_fmac_f32_e32 v47, v52, v52
	v_add_f32_e32 v46, v46, v47
	v_mul_f32_e32 v47, v49, v49
	v_mul_f32_e32 v56, v55, v55
	v_fmac_f32_e32 v47, v48, v48
	v_fmac_f32_e32 v56, v54, v54
	v_add_f32_e32 v47, v47, v56
	v_add_f32_e32 v56, v46, v47
	v_cvt_pk_bf16_f32 v46, v50, v51
	v_lshl_add_u64 v[50:51], s[4:5], 0, v[212:213]
	v_cvt_pk_bf16_f32 v47, v52, v53
	v_cvt_pk_bf16_f32 v48, v48, v49
	v_cvt_pk_bf16_f32 v49, v54, v55
	v_lshl_add_u64 v[50:51], v[196:197], 1, v[50:51]
	global_store_dwordx4 v[50:51], v[46:49], off
	v_lshlrev_b32_e32 v52, 16, v152
	v_and_b32_e32 v53, 0xffff0000, v152
	v_lshlrev_b32_e32 v46, 16, v150
	v_and_b32_e32 v47, 0xffff0000, v150
	v_lshlrev_b32_e32 v48, 16, v151
	v_and_b32_e32 v49, 0xffff0000, v151
	v_lshlrev_b32_e32 v54, 16, v153
	v_and_b32_e32 v55, 0xffff0000, v153
	v_pk_add_f32 v[44:45], v[44:45], v[48:49]
	v_pk_add_f32 v[42:43], v[42:43], v[46:47]
	v_pk_add_f32 v[46:47], v[40:41], v[54:55]
	v_pk_add_f32 v[40:41], v[38:39], v[52:53]
	v_mul_f32_e32 v38, v43, v43
	v_mul_f32_e32 v39, v45, v45
	v_fmac_f32_e32 v38, v42, v42
	v_fmac_f32_e32 v39, v44, v44
	v_add_f32_e32 v38, v38, v39
	v_mul_f32_e32 v39, v41, v41
	v_mul_f32_e32 v48, v47, v47
	v_fmac_f32_e32 v39, v40, v40
	v_fmac_f32_e32 v48, v46, v46
	v_add_f32_e32 v39, v39, v48
	v_add_f32_e32 v38, v38, v39
	v_add_f32_e32 v48, v56, v38
	v_cvt_pk_bf16_f32 v38, v42, v43
	v_cvt_pk_bf16_f32 v39, v44, v45
	v_cvt_pk_bf16_f32 v40, v40, v41
	v_cvt_pk_bf16_f32 v41, v46, v47
	global_store_dwordx4 v[50:51], v[38:41], off offset:64
	s_nop 1
	v_mov_b32_e32 v38, v48
	s_nop 1
	v_permlane16_swap_b32_e32 v48, v38
	v_add_f32_e32 v38, v48, v38
	v_mov_b32_e32 v39, v38
	s_nop 1
	v_permlane32_swap_b32_e32 v38, v39
	s_and_saveexec_b64 s[24:25], s[6:7]
	s_cbranch_execz .LBB0_714
	s_add_u32 s26, s54, s22
	s_addc_u32 s27, s55, s23
	v_lshl_add_u64 v[40:41], v[194:195], 2, s[26:27]
	v_add_f32_e32 v38, v38, v39
	global_store_dword v[40:41], v38, off offset:576
.LBB0_714:
	s_or_b64 exec, exec, s[24:25]
	v_lshlrev_b32_e32 v38, 16, v146
	v_and_b32_e32 v39, 0xffff0000, v146
	v_lshlrev_b32_e32 v40, 16, v147
	v_and_b32_e32 v41, 0xffff0000, v147
	v_lshlrev_b32_e32 v42, 16, v148
	v_and_b32_e32 v43, 0xffff0000, v148
	v_lshlrev_b32_e32 v44, 16, v149
	v_and_b32_e32 v45, 0xffff0000, v149
	v_pk_add_f32 v[36:37], v[36:37], v[40:41]
	v_pk_add_f32 v[34:35], v[34:35], v[38:39]
	v_pk_add_f32 v[38:39], v[32:33], v[44:45]
	v_pk_add_f32 v[32:33], v[30:31], v[42:43]
	v_mul_f32_e32 v30, v35, v35
	v_mul_f32_e32 v31, v37, v37
	v_fmac_f32_e32 v30, v34, v34
	v_fmac_f32_e32 v31, v36, v36
	v_add_f32_e32 v30, v30, v31
	v_mul_f32_e32 v31, v33, v33
	v_mul_f32_e32 v40, v39, v39
	v_fmac_f32_e32 v31, v32, v32
	v_fmac_f32_e32 v40, v38, v38
	v_add_f32_e32 v31, v31, v40
	v_add_f32_e32 v40, v30, v31
	v_cvt_pk_bf16_f32 v30, v34, v35
	v_lshl_add_u64 v[34:35], s[4:5], 0, v[200:201]
	v_cvt_pk_bf16_f32 v31, v36, v37
	v_cvt_pk_bf16_f32 v32, v32, v33
	v_cvt_pk_bf16_f32 v33, v38, v39
	v_lshl_add_u64 v[34:35], v[196:197], 1, v[34:35]
	global_store_dwordx4 v[34:35], v[30:33], off
	v_lshlrev_b32_e32 v36, 16, v140
	v_and_b32_e32 v37, 0xffff0000, v140
	v_lshlrev_b32_e32 v30, 16, v138
	v_and_b32_e32 v31, 0xffff0000, v138
	v_lshlrev_b32_e32 v32, 16, v139
	v_and_b32_e32 v33, 0xffff0000, v139
	v_lshlrev_b32_e32 v38, 16, v141
	v_and_b32_e32 v39, 0xffff0000, v141
	v_pk_add_f32 v[28:29], v[28:29], v[32:33]
	v_pk_add_f32 v[26:27], v[26:27], v[30:31]
	v_pk_add_f32 v[30:31], v[24:25], v[38:39]
	v_pk_add_f32 v[24:25], v[22:23], v[36:37]
	v_mul_f32_e32 v22, v27, v27
	v_mul_f32_e32 v23, v29, v29
	v_fmac_f32_e32 v22, v26, v26
	v_fmac_f32_e32 v23, v28, v28
	v_add_f32_e32 v22, v22, v23
	v_mul_f32_e32 v23, v25, v25
	v_mul_f32_e32 v32, v31, v31
	v_fmac_f32_e32 v23, v24, v24
	v_fmac_f32_e32 v32, v30, v30
	v_add_f32_e32 v23, v23, v32
	v_add_f32_e32 v22, v22, v23
	v_add_f32_e32 v32, v40, v22
	v_cvt_pk_bf16_f32 v22, v26, v27
	v_cvt_pk_bf16_f32 v23, v28, v29
	v_cvt_pk_bf16_f32 v24, v24, v25
	v_cvt_pk_bf16_f32 v25, v30, v31
	global_store_dwordx4 v[34:35], v[22:25], off offset:64
	s_nop 1
	v_mov_b32_e32 v22, v32
	s_nop 1
	v_permlane16_swap_b32_e32 v32, v22
	v_add_f32_e32 v22, v32, v22
	v_mov_b32_e32 v23, v22
	s_nop 1
	v_permlane32_swap_b32_e32 v22, v23
	s_and_saveexec_b64 s[24:25], s[6:7]
	s_cbranch_execz .LBB0_716
	s_add_u32 s26, s54, s22
	s_addc_u32 s27, s55, s23
	v_lshl_add_u64 v[24:25], v[194:195], 2, s[26:27]
	v_add_f32_e32 v22, v22, v23
	global_store_dword v[24:25], v22, off offset:640
.LBB0_716:
	s_or_b64 exec, exec, s[24:25]
	v_lshlrev_b32_e32 v22, 16, v142
	v_and_b32_e32 v23, 0xffff0000, v142
	v_lshlrev_b32_e32 v24, 16, v143
	v_and_b32_e32 v25, 0xffff0000, v143
	v_lshlrev_b32_e32 v26, 16, v144
	v_and_b32_e32 v27, 0xffff0000, v144
	v_lshlrev_b32_e32 v28, 16, v145
	v_and_b32_e32 v29, 0xffff0000, v145
	v_pk_add_f32 v[20:21], v[20:21], v[24:25]
	v_pk_add_f32 v[18:19], v[18:19], v[22:23]
	v_pk_add_f32 v[22:23], v[16:17], v[28:29]
	v_pk_add_f32 v[16:17], v[14:15], v[26:27]
	v_mul_f32_e32 v14, v19, v19
	v_mul_f32_e32 v15, v21, v21
	v_fmac_f32_e32 v14, v18, v18
	v_fmac_f32_e32 v15, v20, v20
	v_add_f32_e32 v14, v14, v15
	v_mul_f32_e32 v15, v17, v17
	v_mul_f32_e32 v24, v23, v23
	v_fmac_f32_e32 v15, v16, v16
	v_fmac_f32_e32 v24, v22, v22
	v_add_f32_e32 v15, v15, v24
	v_add_f32_e32 v24, v14, v15
	v_cvt_pk_bf16_f32 v14, v18, v19
	v_lshl_add_u64 v[18:19], s[4:5], 0, v[198:199]
	v_cvt_pk_bf16_f32 v15, v20, v21
	v_cvt_pk_bf16_f32 v16, v16, v17
	v_cvt_pk_bf16_f32 v17, v22, v23
	v_lshl_add_u64 v[18:19], v[196:197], 1, v[18:19]
	global_store_dwordx4 v[18:19], v[14:17], off
	v_lshlrev_b32_e32 v20, 16, v128
	v_and_b32_e32 v21, 0xffff0000, v128
	v_lshlrev_b32_e32 v14, 16, v126
	v_and_b32_e32 v15, 0xffff0000, v126
	v_lshlrev_b32_e32 v16, 16, v127
	v_and_b32_e32 v17, 0xffff0000, v127
	v_lshlrev_b32_e32 v22, 16, v129
	v_and_b32_e32 v23, 0xffff0000, v129
	v_pk_add_f32 v[12:13], v[12:13], v[16:17]
	v_pk_add_f32 v[10:11], v[10:11], v[14:15]
	v_pk_add_f32 v[14:15], v[8:9], v[22:23]
	v_pk_add_f32 v[8:9], v[6:7], v[20:21]
	v_mul_f32_e32 v6, v11, v11
	v_mul_f32_e32 v7, v13, v13
	v_fmac_f32_e32 v6, v10, v10
	v_fmac_f32_e32 v7, v12, v12
	v_add_f32_e32 v6, v6, v7
	v_mul_f32_e32 v7, v9, v9
	v_mul_f32_e32 v16, v15, v15
	v_fmac_f32_e32 v7, v8, v8
	v_fmac_f32_e32 v16, v14, v14
	v_add_f32_e32 v7, v7, v16
	v_add_f32_e32 v6, v6, v7
	v_add_f32_e32 v16, v24, v6
	v_cvt_pk_bf16_f32 v6, v10, v11
	v_cvt_pk_bf16_f32 v7, v12, v13
	v_cvt_pk_bf16_f32 v8, v8, v9
	v_cvt_pk_bf16_f32 v9, v14, v15
	global_store_dwordx4 v[18:19], v[6:9], off offset:64
	s_nop 1
	v_mov_b32_e32 v6, v16
	s_nop 1
	v_permlane16_swap_b32_e32 v16, v6
	v_add_f32_e32 v6, v16, v6
	v_mov_b32_e32 v7, v6
	s_nop 1
	v_permlane32_swap_b32_e32 v6, v7
	s_and_saveexec_b64 s[24:25], s[6:7]
	s_cbranch_execz .LBB0_718
	s_add_u32 s22, s54, s22
	s_addc_u32 s23, s55, s23
	v_lshl_add_u64 v[8:9], v[194:195], 2, s[22:23]
	v_add_f32_e32 v6, v6, v7
	global_store_dword v[8:9], v6, off offset:704

.LBB0_788:
	v_lshl_add_u32 v134, s64, 8, v5
	v_ashrrev_i32_e32 v135, 31, v134
	v_lshl_add_u64 v[136:137], v[134:135], 2, s[4:5]
	v_mov_b32_e32 v211, v4
	v_lshl_add_u64 v[140:141], v[136:137], 0, v[210:211]
	v_mov_b32_e32 v213, v4
	v_mov_b32_e32 v209, v4
	global_load_dword v145, v[140:141], off
	v_lshl_add_u64 v[140:141], v[136:137], 0, v[212:213]
	v_mov_b32_e32 v215, v4
	v_lshl_add_u64 v[138:139], v[136:137], 0, v[208:209]
	global_load_dword v146, v[140:141], off
	v_lshl_add_u64 v[140:141], v[136:137], 0, v[214:215]
	global_load_dword v144, v[138:139], off
	global_load_dword v148, v[138:139], off offset:64
	global_load_dword v155, v[138:139], off offset:128
	global_load_dword v159, v[138:139], off offset:192
	global_load_dword v163, v[138:139], off offset:512
	global_load_dword v167, v[138:139], off offset:576
	global_load_dword v171, v[138:139], off offset:640
	global_load_dword v147, v[140:141], off
	v_lshl_add_u64 v[140:141], v[136:137], 0, 64
	v_lshl_add_u64 v[142:143], v[140:141], 0, v[210:211]
	global_load_dword v149, v[142:143], off
	v_lshl_add_u64 v[142:143], v[140:141], 0, v[212:213]
	v_lshl_add_u64 v[140:141], v[140:141], 0, v[214:215]
	global_load_dword v150, v[142:143], off
	global_load_dword v151, v[140:141], off
	v_lshl_add_u64 v[140:141], v[136:137], 0, s[68:69]
	v_lshl_add_u64 v[142:143], v[140:141], 0, v[210:211]
	global_load_dword v156, v[142:143], off
	v_lshl_add_u64 v[142:143], v[140:141], 0, v[212:213]
	v_lshl_add_u64 v[140:141], v[140:141], 0, v[214:215]
	global_load_dword v157, v[142:143], off
	global_load_dword v158, v[140:141], off
	s_mov_b64 s[24:25], 0xc0
	v_lshl_add_u64 v[140:141], v[136:137], 0, s[24:25]
	v_lshl_add_u64 v[142:143], v[140:141], 0, v[210:211]
	global_load_dword v160, v[142:143], off
	v_lshl_add_u64 v[142:143], v[140:141], 0, v[212:213]
	v_lshl_add_u64 v[140:141], v[140:141], 0, v[214:215]
	global_load_dword v161, v[142:143], off
	global_load_dword v162, v[140:141], off
	s_mov_b64 s[24:25], 0x200
	v_lshl_add_u64 v[140:141], v[136:137], 0, s[24:25]
	v_lshl_add_u64 v[142:143], v[140:141], 0, v[210:211]
	global_load_dword v164, v[142:143], off
	v_lshl_add_u64 v[142:143], v[140:141], 0, v[212:213]
	v_lshl_add_u64 v[140:141], v[140:141], 0, v[214:215]
	global_load_dword v165, v[142:143], off
	global_load_dword v166, v[140:141], off
	s_mov_b64 s[24:25], 0x240
	v_lshl_add_u64 v[140:141], v[136:137], 0, s[24:25]
	v_lshl_add_u64 v[142:143], v[140:141], 0, v[210:211]
	global_load_dword v168, v[142:143], off
	v_lshl_add_u64 v[142:143], v[140:141], 0, v[212:213]
	v_lshl_add_u64 v[140:141], v[140:141], 0, v[214:215]
	global_load_dword v169, v[142:143], off
	global_load_dword v170, v[140:141], off
	s_mov_b64 s[24:25], 0x280
	v_lshl_add_u64 v[140:141], v[136:137], 0, s[24:25]
	v_lshl_add_u64 v[142:143], v[140:141], 0, v[210:211]
	global_load_dword v172, v[142:143], off
	v_lshl_add_u64 v[142:143], v[140:141], 0, v[212:213]
	v_lshl_add_u64 v[140:141], v[140:141], 0, v[214:215]
	global_load_dword v142, v[142:143], off
	s_mov_b64 s[24:25], 0x2c0
	global_load_dword v140, v[140:141], off
	v_lshl_add_u64 v[136:137], v[136:137], 0, s[24:25]
	global_load_dword v141, v[138:139], off offset:704
	v_lshl_add_u64 v[138:139], v[136:137], 0, v[210:211]
	global_load_dword v173, v[138:139], off
	v_lshl_add_u64 v[138:139], v[136:137], 0, v[212:213]
	v_lshl_add_u64 v[136:137], v[136:137], 0, v[214:215]
	global_load_dword v138, v[138:139], off
	s_lshl_b32 s15, s63, 2
	global_load_dword v136, v[136:137], off
	s_or_b32 s24, s15, s59
	s_ashr_i32 s25, s24, 31
	s_lshl_b64 s[24:25], s[24:25], 14
	s_waitcnt vmcnt(0)
	v_add_f32_e32 v137, v144, v145
	v_add_f32_e32 v139, v146, v147
	v_add_f32_e32 v137, v137, v139
	v_mov_b32_e32 v139, v137
	s_nop 1
	v_permlane16_swap_b32_e32 v137, v139
	v_add_f32_e32 v137, v137, v139
	v_mov_b32_e32 v139, v137
	s_nop 1
	v_permlane32_swap_b32_e32 v137, v139
	v_add_f32_e32 v137, v137, v139
	v_fmamk_f32 v137, v137, 0x3a800000, v236
	v_rsq_f32_e32 v154, v137
	v_add_f32_e32 v137, v148, v149
	v_add_f32_e32 v139, v150, v151
	v_add_f32_e32 v137, v137, v139
	v_mov_b32_e32 v139, v137
	s_nop 1
	v_permlane16_swap_b32_e32 v137, v139
	v_add_f32_e32 v152, v137, v139
	v_add_f32_e32 v137, v155, v156
	v_add_f32_e32 v139, v157, v158
	v_add_f32_e32 v137, v137, v139
	v_mov_b32_e32 v139, v137
	s_nop 1
	v_permlane16_swap_b32_e32 v137, v139
	v_add_f32_e32 v150, v137, v139
	v_add_f32_e32 v137, v159, v160
	v_add_f32_e32 v139, v161, v162
	v_add_f32_e32 v137, v137, v139
	v_mov_b32_e32 v139, v137
	s_nop 1
	v_permlane16_swap_b32_e32 v137, v139
	v_add_f32_e32 v148, v137, v139
	v_add_f32_e32 v137, v163, v164
	v_add_f32_e32 v139, v165, v166
	v_add_f32_e32 v137, v137, v139
	v_mov_b32_e32 v139, v137
	s_nop 1
	v_permlane16_swap_b32_e32 v137, v139
	v_add_f32_e32 v146, v137, v139
	v_add_f32_e32 v137, v167, v168
	v_add_f32_e32 v139, v169, v170
	v_add_f32_e32 v137, v137, v139
	v_mov_b32_e32 v139, v137
	s_nop 1
	v_permlane16_swap_b32_e32 v137, v139
	v_add_f32_e32 v144, v137, v139
	v_add_f32_e32 v137, v171, v172
	v_add_f32_e32 v139, v142, v140
	v_add_f32_e32 v137, v137, v139
	v_mov_b32_e32 v139, v137
	v_pk_mul_f32 v[132:133], v[132:133], v[154:155] op_sel_hi:[1,0]
	v_pk_mul_f32 v[130:131], v[130:131], v[154:155] op_sel_hi:[1,0]
	v_permlane16_swap_b32_e32 v137, v139
	v_pk_mul_f32 v[156:157], v[128:129], v[154:155] op_sel_hi:[1,0]
	v_pk_mul_f32 v[128:129], v[126:127], v[154:155] op_sel_hi:[1,0]
	v_mul_f32_e32 v126, v131, v131
	v_mul_f32_e32 v127, v133, v133
	v_add_f32_e32 v142, v137, v139
	v_add_f32_e32 v137, v141, v173
	v_add_f32_e32 v136, v138, v136
	v_fmac_f32_e32 v126, v130, v130
	v_fmac_f32_e32 v127, v132, v132
	v_add_f32_e32 v136, v137, v136
	v_add_f32_e32 v126, v126, v127
	v_mul_f32_e32 v127, v129, v129
	v_mov_b32_e32 v137, v136
	v_fmac_f32_e32 v127, v128, v128
	s_nop 0
	v_permlane16_swap_b32_e32 v136, v137
	v_add_f32_e32 v126, v127, v126
	v_mul_f32_e32 v127, v157, v157
	v_add_f32_e32 v140, v136, v137
	v_lshl_or_b32 v138, s63, 8, v224
	v_lshlrev_b64 v[136:137], 11, v[134:135]
	v_fmac_f32_e32 v127, v156, v156
	v_ashrrev_i32_e32 v139, 31, v138
	v_lshl_add_u64 v[136:137], s[8:9], 0, v[136:137]
	v_add_f32_e32 v155, v127, v126
	v_lshl_add_u64 v[136:137], v[138:139], 1, v[136:137]
	v_cvt_pk_bf16_f32 v126, v130, v131
	v_cvt_pk_bf16_f32 v127, v132, v133
	v_pk_mul_f32 v[124:125], v[124:125], v[154:155] op_sel_hi:[1,0]
	v_pk_mul_f32 v[122:123], v[122:123], v[154:155] op_sel_hi:[1,0]
	v_cvt_pk_bf16_f32 v128, v128, v129
	v_cvt_pk_bf16_f32 v129, v156, v157
	global_store_dwordx4 v[136:137], v[126:129], off
	v_mov_b32_e32 v153, v152
	v_mov_b32_e32 v151, v150
	v_pk_mul_f32 v[126:127], v[120:121], v[154:155] op_sel_hi:[1,0]
	v_pk_mul_f32 v[120:121], v[118:119], v[154:155] op_sel_hi:[1,0]
	v_mul_f32_e32 v118, v123, v123
	v_mul_f32_e32 v119, v125, v125
	v_fmac_f32_e32 v118, v122, v122
	v_fmac_f32_e32 v119, v124, v124
	v_add_f32_e32 v118, v118, v119
	v_mul_f32_e32 v119, v121, v121
	v_fmac_f32_e32 v119, v120, v120
	v_add_f32_e32 v118, v119, v118
	v_mul_f32_e32 v119, v127, v127
	v_fmac_f32_e32 v119, v126, v126
	v_add_f32_e32 v118, v119, v118
	v_add_f32_e32 v128, v155, v118
	v_cvt_pk_bf16_f32 v118, v122, v123
	v_cvt_pk_bf16_f32 v119, v124, v125
	v_cvt_pk_bf16_f32 v120, v120, v121
	v_cvt_pk_bf16_f32 v121, v126, v127
	global_store_dwordx4 v[136:137], v[118:121], off offset:64
	v_mov_b32_e32 v149, v148
	v_mov_b32_e32 v147, v146
	v_mov_b32_e32 v118, v128
	s_nop 1
	v_permlane16_swap_b32_e32 v128, v118
	v_add_f32_e32 v118, v128, v118
	v_mov_b32_e32 v145, v144
	v_mov_b32_e32 v143, v142
	v_mov_b32_e32 v141, v140
	v_mov_b32_e32 v119, v118
	v_permlane32_swap_b32_e32 v152, v153
	v_permlane32_swap_b32_e32 v150, v151
	v_permlane32_swap_b32_e32 v148, v149
	v_permlane32_swap_b32_e32 v146, v147
	v_permlane32_swap_b32_e32 v144, v145
	v_permlane32_swap_b32_e32 v142, v143
	v_permlane32_swap_b32_e32 v140, v141
	v_permlane32_swap_b32_e32 v118, v119
	s_and_saveexec_b64 s[26:27], s[6:7]
	s_cbranch_execz .LBB0_790
	s_add_u32 s28, s57, s24
	s_addc_u32 s29, s58, s25
	v_lshl_add_u64 v[120:121], v[134:135], 2, s[28:29]
	v_add_f32_e32 v118, v118, v119
	global_store_dword v[120:121], v118, off
.LBB0_790:
	s_or_b64 exec, exec, s[26:27]
	v_add_f32_e32 v118, v152, v153
	v_fmamk_f32 v118, v118, 0x3a800000, v236
	v_rsq_f32_e32 v118, v118
	v_or_b32_e32 v120, 16, v134
	v_ashrrev_i32_e32 v121, 31, v120
	v_lshlrev_b64 v[120:121], 11, v[120:121]
	v_pk_mul_f32 v[116:117], v[116:117], v[118:119] op_sel_hi:[1,0]
	v_pk_mul_f32 v[114:115], v[114:115], v[118:119] op_sel_hi:[1,0]
	v_pk_mul_f32 v[122:123], v[112:113], v[118:119] op_sel_hi:[1,0]
	v_pk_mul_f32 v[112:113], v[110:111], v[118:119] op_sel_hi:[1,0]
	v_mul_f32_e32 v110, v115, v115
	v_mul_f32_e32 v111, v117, v117
	v_fmac_f32_e32 v110, v114, v114
	v_fmac_f32_e32 v111, v116, v116
	v_add_f32_e32 v110, v110, v111
	v_mul_f32_e32 v111, v113, v113
	v_fmac_f32_e32 v111, v112, v112
	v_add_f32_e32 v110, v111, v110
	v_mul_f32_e32 v111, v123, v123
	v_fmac_f32_e32 v111, v122, v122
	v_lshl_add_u64 v[120:121], s[8:9], 0, v[120:121]
	v_add_f32_e32 v119, v111, v110
	v_lshl_add_u64 v[120:121], v[138:139], 1, v[120:121]
	v_cvt_pk_bf16_f32 v110, v114, v115
	v_cvt_pk_bf16_f32 v111, v116, v117
	v_pk_mul_f32 v[108:109], v[108:109], v[118:119] op_sel_hi:[1,0]
	v_pk_mul_f32 v[106:107], v[106:107], v[118:119] op_sel_hi:[1,0]
	v_cvt_pk_bf16_f32 v112, v112, v113
	v_cvt_pk_bf16_f32 v113, v122, v123
	global_store_dwordx4 v[120:121], v[110:113], off
	s_nop 1
	v_pk_mul_f32 v[110:111], v[104:105], v[118:119] op_sel_hi:[1,0]
	v_pk_mul_f32 v[104:105], v[102:103], v[118:119] op_sel_hi:[1,0]
	v_mul_f32_e32 v102, v107, v107
	v_mul_f32_e32 v103, v109, v109
	v_fmac_f32_e32 v102, v106, v106
	v_fmac_f32_e32 v103, v108, v108
	v_add_f32_e32 v102, v102, v103
	v_mul_f32_e32 v103, v105, v105
	v_fmac_f32_e32 v103, v104, v104
	v_add_f32_e32 v102, v103, v102
	v_mul_f32_e32 v103, v111, v111
	v_fmac_f32_e32 v103, v110, v110
	v_add_f32_e32 v102, v103, v102
	v_add_f32_e32 v112, v119, v102
	v_cvt_pk_bf16_f32 v102, v106, v107
	v_cvt_pk_bf16_f32 v103, v108, v109
	v_cvt_pk_bf16_f32 v104, v104, v105
	v_cvt_pk_bf16_f32 v105, v110, v111
	global_store_dwordx4 v[120:121], v[102:105], off offset:64
	s_nop 1
	v_mov_b32_e32 v102, v112
	s_nop 1
	v_permlane16_swap_b32_e32 v112, v102
	v_add_f32_e32 v102, v112, v102
	v_mov_b32_e32 v103, v102
	s_nop 1
	v_permlane32_swap_b32_e32 v102, v103
	s_and_saveexec_b64 s[26:27], s[6:7]
	s_cbranch_execz .LBB0_792
	s_add_u32 s28, s57, s24
	s_addc_u32 s29, s58, s25
	v_lshl_add_u64 v[104:105], v[134:135], 2, s[28:29]
	v_add_f32_e32 v102, v102, v103
	global_store_dword v[104:105], v102, off offset:64
.LBB0_792:
	s_or_b64 exec, exec, s[26:27]
	v_add_f32_e32 v102, v150, v151
	v_fmamk_f32 v102, v102, 0x3a800000, v236
	v_rsq_f32_e32 v102, v102
	v_or_b32_e32 v104, 32, v134
	v_ashrrev_i32_e32 v105, 31, v104
	v_lshlrev_b64 v[104:105], 11, v[104:105]
	v_pk_mul_f32 v[100:101], v[100:101], v[102:103] op_sel_hi:[1,0]
	v_pk_mul_f32 v[98:99], v[98:99], v[102:103] op_sel_hi:[1,0]
	v_pk_mul_f32 v[106:107], v[96:97], v[102:103] op_sel_hi:[1,0]
	v_pk_mul_f32 v[96:97], v[94:95], v[102:103] op_sel_hi:[1,0]
	v_mul_f32_e32 v94, v99, v99
	v_mul_f32_e32 v95, v101, v101
	v_fmac_f32_e32 v94, v98, v98
	v_fmac_f32_e32 v95, v100, v100
	v_add_f32_e32 v94, v94, v95
	v_mul_f32_e32 v95, v97, v97
	v_fmac_f32_e32 v95, v96, v96
	v_add_f32_e32 v94, v95, v94
	v_mul_f32_e32 v95, v107, v107
	v_fmac_f32_e32 v95, v106, v106
	v_lshl_add_u64 v[104:105], s[8:9], 0, v[104:105]
	v_add_f32_e32 v103, v95, v94
	v_lshl_add_u64 v[104:105], v[138:139], 1, v[104:105]
	v_cvt_pk_bf16_f32 v94, v98, v99
	v_cvt_pk_bf16_f32 v95, v100, v101
	v_pk_mul_f32 v[92:93], v[92:93], v[102:103] op_sel_hi:[1,0]
	v_pk_mul_f32 v[90:91], v[90:91], v[102:103] op_sel_hi:[1,0]
	v_cvt_pk_bf16_f32 v96, v96, v97
	v_cvt_pk_bf16_f32 v97, v106, v107
	global_store_dwordx4 v[104:105], v[94:97], off
	s_nop 1
	v_pk_mul_f32 v[94:95], v[88:89], v[102:103] op_sel_hi:[1,0]
	v_pk_mul_f32 v[88:89], v[86:87], v[102:103] op_sel_hi:[1,0]
	v_mul_f32_e32 v86, v91, v91
	v_mul_f32_e32 v87, v93, v93
	v_fmac_f32_e32 v86, v90, v90
	v_fmac_f32_e32 v87, v92, v92
	v_add_f32_e32 v86, v86, v87
	v_mul_f32_e32 v87, v89, v89
	v_fmac_f32_e32 v87, v88, v88
	v_add_f32_e32 v86, v87, v86
	v_mul_f32_e32 v87, v95, v95
	v_fmac_f32_e32 v87, v94, v94
	v_add_f32_e32 v86, v87, v86
	v_add_f32_e32 v96, v103, v86
	v_cvt_pk_bf16_f32 v86, v90, v91
	v_cvt_pk_bf16_f32 v87, v92, v93
	v_cvt_pk_bf16_f32 v88, v88, v89
	v_cvt_pk_bf16_f32 v89, v94, v95
	global_store_dwordx4 v[104:105], v[86:89], off offset:64
	s_nop 1
	v_mov_b32_e32 v86, v96
	s_nop 1
	v_permlane16_swap_b32_e32 v96, v86
	v_add_f32_e32 v86, v96, v86
	v_mov_b32_e32 v87, v86
	s_nop 1
	v_permlane32_swap_b32_e32 v86, v87
	s_and_saveexec_b64 s[26:27], s[6:7]
	s_cbranch_execz .LBB0_794
	s_add_u32 s28, s57, s24
	s_addc_u32 s29, s58, s25
	v_lshl_add_u64 v[88:89], v[134:135], 2, s[28:29]
	v_add_f32_e32 v86, v86, v87
	global_store_dword v[88:89], v86, off offset:128
.LBB0_794:
	s_or_b64 exec, exec, s[26:27]
	v_add_f32_e32 v86, v148, v149
	v_fmamk_f32 v86, v86, 0x3a800000, v236
	v_rsq_f32_e32 v86, v86
	v_or_b32_e32 v88, 48, v134
	v_ashrrev_i32_e32 v89, 31, v88
	v_lshlrev_b64 v[88:89], 11, v[88:89]
	v_pk_mul_f32 v[84:85], v[84:85], v[86:87] op_sel_hi:[1,0]
	v_pk_mul_f32 v[82:83], v[82:83], v[86:87] op_sel_hi:[1,0]
	v_pk_mul_f32 v[90:91], v[80:81], v[86:87] op_sel_hi:[1,0]
	v_pk_mul_f32 v[80:81], v[78:79], v[86:87] op_sel_hi:[1,0]
	v_mul_f32_e32 v78, v83, v83
	v_mul_f32_e32 v79, v85, v85
	v_fmac_f32_e32 v78, v82, v82
	v_fmac_f32_e32 v79, v84, v84
	v_add_f32_e32 v78, v78, v79
	v_mul_f32_e32 v79, v81, v81
	v_fmac_f32_e32 v79, v80, v80
	v_add_f32_e32 v78, v79, v78
	v_mul_f32_e32 v79, v91, v91
	v_fmac_f32_e32 v79, v90, v90
	v_lshl_add_u64 v[88:89], s[8:9], 0, v[88:89]
	v_add_f32_e32 v87, v79, v78
	v_lshl_add_u64 v[88:89], v[138:139], 1, v[88:89]
	v_cvt_pk_bf16_f32 v78, v82, v83
	v_cvt_pk_bf16_f32 v79, v84, v85
	v_pk_mul_f32 v[76:77], v[76:77], v[86:87] op_sel_hi:[1,0]
	v_pk_mul_f32 v[74:75], v[74:75], v[86:87] op_sel_hi:[1,0]
	v_cvt_pk_bf16_f32 v80, v80, v81
	v_cvt_pk_bf16_f32 v81, v90, v91
	global_store_dwordx4 v[88:89], v[78:81], off
	s_nop 1
	v_pk_mul_f32 v[78:79], v[72:73], v[86:87] op_sel_hi:[1,0]
	v_pk_mul_f32 v[72:73], v[70:71], v[86:87] op_sel_hi:[1,0]
	v_mul_f32_e32 v70, v75, v75
	v_mul_f32_e32 v71, v77, v77
	v_fmac_f32_e32 v70, v74, v74
	v_fmac_f32_e32 v71, v76, v76
	v_add_f32_e32 v70, v70, v71
	v_mul_f32_e32 v71, v73, v73
	v_fmac_f32_e32 v71, v72, v72
	v_add_f32_e32 v70, v71, v70
	v_mul_f32_e32 v71, v79, v79
	v_fmac_f32_e32 v71, v78, v78
	v_add_f32_e32 v70, v71, v70
	v_add_f32_e32 v80, v87, v70
	v_cvt_pk_bf16_f32 v70, v74, v75
	v_cvt_pk_bf16_f32 v71, v76, v77
	v_cvt_pk_bf16_f32 v72, v72, v73
	v_cvt_pk_bf16_f32 v73, v78, v79
	global_store_dwordx4 v[88:89], v[70:73], off offset:64
	s_nop 1
	v_mov_b32_e32 v70, v80
	s_nop 1
	v_permlane16_swap_b32_e32 v80, v70
	v_add_f32_e32 v70, v80, v70
	v_mov_b32_e32 v71, v70
	s_nop 1
	v_permlane32_swap_b32_e32 v70, v71
	s_and_saveexec_b64 s[26:27], s[6:7]
	s_cbranch_execz .LBB0_796
	s_add_u32 s28, s57, s24
	s_addc_u32 s29, s58, s25
	v_lshl_add_u64 v[72:73], v[134:135], 2, s[28:29]
	v_add_f32_e32 v70, v70, v71
	global_store_dword v[72:73], v70, off offset:192
.LBB0_796:
	s_or_b64 exec, exec, s[26:27]
	v_add_f32_e32 v72, v146, v147
	v_fmamk_f32 v72, v72, 0x3a800000, v236
	v_rsq_f32_e32 v72, v72
	v_lshlrev_b64 v[70:71], 11, v[134:135]
	v_lshl_add_u64 v[70:71], s[8:9], 0, v[70:71]
	v_lshl_add_u64 v[70:71], v[138:139], 1, v[70:71]
	v_pk_mul_f32 v[68:69], v[68:69], v[72:73] op_sel_hi:[1,0]
	v_pk_mul_f32 v[66:67], v[66:67], v[72:73] op_sel_hi:[1,0]
	v_pk_mul_f32 v[76:77], v[64:65], v[72:73] op_sel_hi:[1,0]
	v_pk_mul_f32 v[64:65], v[62:63], v[72:73] op_sel_hi:[1,0]
	v_mul_f32_e32 v62, v67, v67
	v_mul_f32_e32 v63, v69, v69
	v_fmac_f32_e32 v62, v66, v66
	v_fmac_f32_e32 v63, v68, v68
	v_add_f32_e32 v62, v62, v63
	v_mul_f32_e32 v63, v65, v65
	v_fmac_f32_e32 v63, v64, v64
	v_add_f32_e32 v62, v63, v62
	v_mul_f32_e32 v63, v77, v77
	v_fmac_f32_e32 v63, v76, v76
	v_add_f32_e32 v73, v63, v62
	v_cvt_pk_bf16_f32 v62, v66, v67
	v_add_co_u32_e32 v66, vcc, s72, v70
	v_cvt_pk_bf16_f32 v63, v68, v69
	v_pk_mul_f32 v[60:61], v[60:61], v[72:73] op_sel_hi:[1,0]
	s_nop 0
	v_addc_co_u32_e32 v67, vcc, 0, v71, vcc
	v_pk_mul_f32 v[58:59], v[58:59], v[72:73] op_sel_hi:[1,0]
	v_cvt_pk_bf16_f32 v64, v64, v65
	v_cvt_pk_bf16_f32 v65, v76, v77
	global_store_dwordx4 v[66:67], v[62:65], off
	s_mov_b64 s[26:27], 0x40000
	v_lshl_add_u64 v[74:75], v[70:71], 0, s[26:27]
	v_pk_mul_f32 v[62:63], v[56:57], v[72:73] op_sel_hi:[1,0]
	v_pk_mul_f32 v[56:57], v[54:55], v[72:73] op_sel_hi:[1,0]
	v_mul_f32_e32 v54, v59, v59
	v_mul_f32_e32 v55, v61, v61
	v_fmac_f32_e32 v54, v58, v58
	v_fmac_f32_e32 v55, v60, v60
	v_add_f32_e32 v54, v54, v55
	v_mul_f32_e32 v55, v57, v57
	v_fmac_f32_e32 v55, v56, v56
	v_add_f32_e32 v54, v55, v54
	v_mul_f32_e32 v55, v63, v63
	v_fmac_f32_e32 v55, v62, v62
	v_add_f32_e32 v54, v55, v54
	v_add_f32_e32 v64, v73, v54
	v_cvt_pk_bf16_f32 v54, v58, v59
	v_cvt_pk_bf16_f32 v55, v60, v61
	v_cvt_pk_bf16_f32 v56, v56, v57
	v_cvt_pk_bf16_f32 v57, v62, v63
	global_store_dwordx4 v[74:75], v[54:57], off offset:64
	s_nop 1
	v_mov_b32_e32 v54, v64
	s_nop 1
	v_permlane16_swap_b32_e32 v64, v54
	v_add_f32_e32 v54, v64, v54
	v_mov_b32_e32 v55, v54
	s_nop 1
	v_permlane32_swap_b32_e32 v54, v55
	s_and_saveexec_b64 s[26:27], s[6:7]
	s_cbranch_execz .LBB0_798
	s_add_u32 s28, s57, s24
	s_addc_u32 s29, s58, s25
	v_lshl_add_u64 v[56:57], v[134:135], 2, s[28:29]
	v_add_f32_e32 v54, v54, v55
	global_store_dword v[56:57], v54, off offset:512
.LBB0_798:
	s_or_b64 exec, exec, s[26:27]
	v_add_f32_e32 v54, v144, v145
	v_fmamk_f32 v54, v54, 0x3a800000, v236
	v_rsq_f32_e32 v54, v54
	s_mov_b32 s15, 0x48000
	s_mov_b64 s[26:27], 0x48000
	v_lshl_add_u64 v[56:57], v[136:137], 0, s[26:27]
	v_pk_mul_f32 v[52:53], v[52:53], v[54:55] op_sel_hi:[1,0]
	v_pk_mul_f32 v[50:51], v[50:51], v[54:55] op_sel_hi:[1,0]
	v_pk_mul_f32 v[58:59], v[48:49], v[54:55] op_sel_hi:[1,0]
	v_pk_mul_f32 v[48:49], v[46:47], v[54:55] op_sel_hi:[1,0]
	v_mul_f32_e32 v46, v51, v51
	v_mul_f32_e32 v47, v53, v53
	v_fmac_f32_e32 v46, v50, v50
	v_fmac_f32_e32 v47, v52, v52
	v_add_f32_e32 v46, v46, v47
	v_mul_f32_e32 v47, v49, v49
	v_fmac_f32_e32 v47, v48, v48
	v_add_f32_e32 v46, v47, v46
	v_mul_f32_e32 v47, v59, v59
	v_fmac_f32_e32 v47, v58, v58
	v_add_f32_e32 v55, v47, v46
	v_cvt_pk_bf16_f32 v46, v50, v51
	v_add_co_u32_e32 v50, vcc, s15, v136
	v_cvt_pk_bf16_f32 v47, v52, v53
	v_pk_mul_f32 v[44:45], v[44:45], v[54:55] op_sel_hi:[1,0]
	s_nop 0
	v_addc_co_u32_e32 v51, vcc, 0, v137, vcc
	v_pk_mul_f32 v[42:43], v[42:43], v[54:55] op_sel_hi:[1,0]
	v_cvt_pk_bf16_f32 v48, v48, v49
	v_cvt_pk_bf16_f32 v49, v58, v59
	global_store_dwordx4 v[50:51], v[46:49], off
	s_nop 1
	v_pk_mul_f32 v[46:47], v[40:41], v[54:55] op_sel_hi:[1,0]
	v_pk_mul_f32 v[40:41], v[38:39], v[54:55] op_sel_hi:[1,0]
	v_mul_f32_e32 v38, v43, v43
	v_mul_f32_e32 v39, v45, v45
	v_fmac_f32_e32 v38, v42, v42
	v_fmac_f32_e32 v39, v44, v44
	v_add_f32_e32 v38, v38, v39
	v_mul_f32_e32 v39, v41, v41
	v_fmac_f32_e32 v39, v40, v40
	v_add_f32_e32 v38, v39, v38
	v_mul_f32_e32 v39, v47, v47
	v_fmac_f32_e32 v39, v46, v46
	v_add_f32_e32 v38, v39, v38
	v_add_f32_e32 v48, v55, v38
	v_cvt_pk_bf16_f32 v38, v42, v43
	v_cvt_pk_bf16_f32 v39, v44, v45
	v_cvt_pk_bf16_f32 v40, v40, v41
	v_cvt_pk_bf16_f32 v41, v46, v47
	global_store_dwordx4 v[56:57], v[38:41], off offset:64
	s_nop 1
	v_mov_b32_e32 v38, v48
	s_nop 1
	v_permlane16_swap_b32_e32 v48, v38
	v_add_f32_e32 v38, v48, v38
	v_mov_b32_e32 v39, v38
	s_nop 1
	v_permlane32_swap_b32_e32 v38, v39
	s_and_saveexec_b64 s[26:27], s[6:7]
	s_cbranch_execz .LBB0_800
	s_add_u32 s28, s57, s24
	s_addc_u32 s29, s58, s25
	v_lshl_add_u64 v[40:41], v[134:135], 2, s[28:29]
	v_add_f32_e32 v38, v38, v39
	global_store_dword v[40:41], v38, off offset:576
.LBB0_800:
	s_or_b64 exec, exec, s[26:27]
	v_add_f32_e32 v38, v142, v143
	v_fmamk_f32 v38, v38, 0x3a800000, v236
	v_rsq_f32_e32 v38, v38
	s_mov_b32 s15, 0x50000
	s_mov_b64 s[26:27], 0x50000
	v_lshl_add_u64 v[40:41], v[136:137], 0, s[26:27]
	v_pk_mul_f32 v[36:37], v[36:37], v[38:39] op_sel_hi:[1,0]
	v_pk_mul_f32 v[34:35], v[34:35], v[38:39] op_sel_hi:[1,0]
	v_pk_mul_f32 v[42:43], v[32:33], v[38:39] op_sel_hi:[1,0]
	v_pk_mul_f32 v[32:33], v[30:31], v[38:39] op_sel_hi:[1,0]
	v_mul_f32_e32 v30, v35, v35
	v_mul_f32_e32 v31, v37, v37
	v_fmac_f32_e32 v30, v34, v34
	v_fmac_f32_e32 v31, v36, v36
	v_add_f32_e32 v30, v30, v31
	v_mul_f32_e32 v31, v33, v33
	v_fmac_f32_e32 v31, v32, v32
	v_add_f32_e32 v30, v31, v30
	v_mul_f32_e32 v31, v43, v43
	v_fmac_f32_e32 v31, v42, v42
	v_add_f32_e32 v39, v31, v30
	v_cvt_pk_bf16_f32 v30, v34, v35
	v_add_co_u32_e32 v34, vcc, s15, v136
	v_cvt_pk_bf16_f32 v31, v36, v37
	v_pk_mul_f32 v[28:29], v[28:29], v[38:39] op_sel_hi:[1,0]
	s_nop 0
	v_addc_co_u32_e32 v35, vcc, 0, v137, vcc
	v_pk_mul_f32 v[26:27], v[26:27], v[38:39] op_sel_hi:[1,0]
	v_cvt_pk_bf16_f32 v32, v32, v33
	v_cvt_pk_bf16_f32 v33, v42, v43
	global_store_dwordx4 v[34:35], v[30:33], off
	s_nop 1
	v_pk_mul_f32 v[30:31], v[24:25], v[38:39] op_sel_hi:[1,0]
	v_pk_mul_f32 v[24:25], v[22:23], v[38:39] op_sel_hi:[1,0]
	v_mul_f32_e32 v22, v27, v27
	v_mul_f32_e32 v23, v29, v29
	v_fmac_f32_e32 v22, v26, v26
	v_fmac_f32_e32 v23, v28, v28
	v_add_f32_e32 v22, v22, v23
	v_mul_f32_e32 v23, v25, v25
	v_fmac_f32_e32 v23, v24, v24
	v_add_f32_e32 v22, v23, v22
	v_mul_f32_e32 v23, v31, v31
	v_fmac_f32_e32 v23, v30, v30
	v_add_f32_e32 v22, v23, v22
	v_add_f32_e32 v32, v39, v22
	v_cvt_pk_bf16_f32 v22, v26, v27
	v_cvt_pk_bf16_f32 v23, v28, v29
	v_cvt_pk_bf16_f32 v24, v24, v25
	v_cvt_pk_bf16_f32 v25, v30, v31
	global_store_dwordx4 v[40:41], v[22:25], off offset:64
	s_nop 1
	v_mov_b32_e32 v22, v32
	s_nop 1
	v_permlane16_swap_b32_e32 v32, v22
	v_add_f32_e32 v22, v32, v22
	v_mov_b32_e32 v23, v22
	s_nop 1
	v_permlane32_swap_b32_e32 v22, v23
	s_and_saveexec_b64 s[26:27], s[6:7]
	s_cbranch_execz .LBB0_802
	s_add_u32 s28, s57, s24
	s_addc_u32 s29, s58, s25
	v_lshl_add_u64 v[24:25], v[134:135], 2, s[28:29]
	v_add_f32_e32 v22, v22, v23
	global_store_dword v[24:25], v22, off offset:640
.LBB0_802:
	s_or_b64 exec, exec, s[26:27]
	v_add_f32_e32 v22, v140, v141
	v_fmamk_f32 v22, v22, 0x3a800000, v236
	v_rsq_f32_e32 v22, v22
	s_mov_b32 s15, 0x58000
	s_mov_b64 s[26:27], 0x58000
	v_lshl_add_u64 v[24:25], v[136:137], 0, s[26:27]
	v_pk_mul_f32 v[20:21], v[20:21], v[22:23] op_sel_hi:[1,0]
	v_pk_mul_f32 v[18:19], v[18:19], v[22:23] op_sel_hi:[1,0]
	v_pk_mul_f32 v[26:27], v[16:17], v[22:23] op_sel_hi:[1,0]
	v_pk_mul_f32 v[16:17], v[14:15], v[22:23] op_sel_hi:[1,0]
	v_mul_f32_e32 v14, v19, v19
	v_mul_f32_e32 v15, v21, v21
	v_fmac_f32_e32 v14, v18, v18
	v_fmac_f32_e32 v15, v20, v20
	v_add_f32_e32 v14, v14, v15
	v_mul_f32_e32 v15, v17, v17
	v_fmac_f32_e32 v15, v16, v16
	v_add_f32_e32 v14, v15, v14
	v_mul_f32_e32 v15, v27, v27
	v_fmac_f32_e32 v15, v26, v26
	v_add_f32_e32 v23, v15, v14
	v_cvt_pk_bf16_f32 v14, v18, v19
	v_add_co_u32_e32 v18, vcc, s15, v136
	v_cvt_pk_bf16_f32 v15, v20, v21
	v_pk_mul_f32 v[12:13], v[12:13], v[22:23] op_sel_hi:[1,0]
	s_nop 0
	v_addc_co_u32_e32 v19, vcc, 0, v137, vcc
	v_pk_mul_f32 v[10:11], v[10:11], v[22:23] op_sel_hi:[1,0]
	v_cvt_pk_bf16_f32 v16, v16, v17
	v_cvt_pk_bf16_f32 v17, v26, v27
	global_store_dwordx4 v[18:19], v[14:17], off
	s_nop 1
	v_pk_mul_f32 v[14:15], v[8:9], v[22:23] op_sel_hi:[1,0]
	v_pk_mul_f32 v[8:9], v[6:7], v[22:23] op_sel_hi:[1,0]
	v_mul_f32_e32 v6, v11, v11
	v_mul_f32_e32 v7, v13, v13
	v_fmac_f32_e32 v6, v10, v10
	v_fmac_f32_e32 v7, v12, v12
	v_add_f32_e32 v6, v6, v7
	v_mul_f32_e32 v7, v9, v9
	v_fmac_f32_e32 v7, v8, v8
	v_add_f32_e32 v6, v7, v6
	v_mul_f32_e32 v7, v15, v15
	v_fmac_f32_e32 v7, v14, v14
	v_add_f32_e32 v6, v7, v6
	v_add_f32_e32 v16, v23, v6
	v_cvt_pk_bf16_f32 v6, v10, v11
	v_cvt_pk_bf16_f32 v7, v12, v13
	v_cvt_pk_bf16_f32 v8, v8, v9
	v_cvt_pk_bf16_f32 v9, v14, v15
	global_store_dwordx4 v[24:25], v[6:9], off offset:64
	s_nop 1
	v_mov_b32_e32 v6, v16
	s_nop 1
	v_permlane16_swap_b32_e32 v16, v6
	v_add_f32_e32 v6, v16, v6
	v_mov_b32_e32 v7, v6
	s_nop 1
	v_permlane32_swap_b32_e32 v6, v7
	s_and_saveexec_b64 s[26:27], s[6:7]
	s_cbranch_execz .LBB0_804
	s_add_u32 s24, s57, s24
	s_addc_u32 s25, s58, s25
	v_lshl_add_u64 v[8:9], v[134:135], 2, s[24:25]
	v_add_f32_e32 v6, v6, v7
	global_store_dword v[8:9], v6, off offset:704

.LBB0_812:
	s_or_b64 exec, exec, s[2:3]
	s_and_b64 vcc, exec, s[50:51]
	s_barrier
	s_cbranch_vccnz .LBB0_814
	s_mov_b32 s2, s87
	s_ashr_i32 s3, s2, 31
	s_lshl_b64 s[2:3], s[2:3], 3
	s_add_u32 s2, s0, s2
	s_addc_u32 s3, s1, s3
	s_load_dwordx2 s[2:3], s[2:3], 0xd8
	s_mov_b32 s4, s87
	s_mov_b32 s6, s87
	v_mov_b32_e32 v145, v0
	s_waitcnt lgkmcnt(0)
	s_add_u32 s8, s2, s81
	s_addc_u32 s16, s3, 0
	s_ashr_i32 s5, s4, 31
	s_lshl_b64 s[2:3], s[4:5], 3
	s_add_u32 s2, s0, s2
	s_addc_u32 s3, s1, s3
	s_load_dwordx2 s[2:3], s[2:3], 0xd8
	s_mov_b32 s5, s87
	s_mov_b32 s4, s87
	s_waitcnt lgkmcnt(0)
	s_add_u32 s2, s2, s84
	s_addc_u32 s3, s3, 0
	s_add_u32 s17, s2, 0x200000
	s_addc_u32 s18, s3, 0
	s_ashr_i32 s5, s4, 31
	s_lshl_b64 s[2:3], s[4:5], 3
	s_add_u32 s2, s0, s2
	s_addc_u32 s3, s1, s3
	s_load_dwordx2 s[2:3], s[2:3], 0xd0
	v_mov_b32_e32 v143, v4
	s_waitcnt lgkmcnt(0)
	s_add_u32 s2, s2, s80
	s_addc_u32 s3, s3, 0
	s_lshl_b32 s4, s46, 19
	s_add_u32 s2, s2, s4
	s_addc_u32 s3, s3, 0
	v_readlane_b32 s4, v253, 62
	v_readlane_b32 s5, v253, 63
	s_add_u32 s2, s2, s4
	s_addc_u32 s3, s3, s5
	s_add_u32 s4, s2, 0xe00000
	s_addc_u32 s5, s3, 0
	s_ashr_i32 s7, s6, 31
	s_lshl_b64 s[2:3], s[6:7], 3
	s_add_u32 s2, s0, s2
	s_addc_u32 s3, s1, s3
	s_load_dwordx2 s[2:3], s[2:3], 0xd8
	s_waitcnt lgkmcnt(0)
	s_add_u32 s2, s2, s81
	v_readfirstlane_b32 s6, v145
	s_addc_u32 s3, s3, 0
	s_ashr_i32 s9, s6, 6
	s_lshl_b32 s10, s9, 5
	s_lshl_b64 s[6:7], s[74:75], 8
	s_ashr_i32 s11, s10, 31
	s_add_u32 s19, s6, s10
	s_addc_u32 s20, s7, s11
	s_lshl_b32 s6, s78, 2
	s_ashr_i32 s7, s6, 31
	s_lshl_b64 s[10:11], s[6:7], 14
	s_add_u32 s10, s17, s10
	s_addc_u32 s11, s18, s11
	s_or_b32 s12, s6, 1
	s_ashr_i32 s13, s12, 31
	s_lshl_b64 s[12:13], s[12:13], 14
	s_add_u32 s12, s17, s12
	s_addc_u32 s13, s18, s13
	s_or_b32 s14, s6, 2
	s_ashr_i32 s15, s14, 31
	s_lshl_b64 s[14:15], s[14:15], 14
	s_add_u32 s14, s17, s14
	s_addc_u32 s15, s18, s15
	s_or_b32 s6, s6, 3
	v_and_b32_e32 v144, 15, v145
	s_ashr_i32 s7, s6, 31
	s_lshl_b64 s[6:7], s[6:7], 14
	v_or_b32_e32 v6, s19, v144
	s_add_u32 s6, s17, s6
	v_mov_b32_e32 v5, v6
	s_addc_u32 s7, s18, s7
	v_ashrrev_i64 v[2:3], 30, v[4:5]
	v_mov_b32_e32 v7, s20
	v_lshl_add_u64 v[8:9], s[10:11], 0, v[2:3]
	v_lshl_add_u64 v[10:11], s[12:13], 0, v[2:3]
	v_lshl_add_u64 v[12:13], s[14:15], 0, v[2:3]
	v_lshl_add_u64 v[2:3], s[6:7], 0, v[2:3]
	global_load_dword v14, v[8:9], off
	global_load_dword v16, v[10:11], off
	global_load_dword v15, v[12:13], off
	global_load_dword v17, v[2:3], off
	v_lshlrev_b64 v[2:3], 11, v[6:7]
	v_or_b32_e32 v6, 16, v6
	v_mov_b32_e32 v5, v6
	v_ashrrev_i64 v[8:9], 30, v[4:5]
	v_lshl_add_u64 v[10:11], s[10:11], 0, v[8:9]
	v_lshl_add_u64 v[12:13], s[12:13], 0, v[8:9]
	v_lshl_add_u64 v[18:19], s[14:15], 0, v[8:9]
	v_lshl_add_u64 v[8:9], s[6:7], 0, v[8:9]
	s_lshl_b32 s6, s78, 8
	s_ashr_i32 s7, s6, 31
	s_lshl_b64 s[6:7], s[6:7], 1
	s_add_u32 s10, s8, s6
	s_addc_u32 s11, s16, s7
	v_and_b32_e32 v142, 48, v145
	global_load_dword v20, v[10:11], off
	global_load_dword v22, v[12:13], off
	global_load_dword v21, v[18:19], off
	global_load_dword v23, v[8:9], off
	v_lshl_add_u64 v[8:9], s[10:11], 0, v[142:143]
	s_mov_b64 s[10:11], 0x9e00000
	v_lshl_add_u64 v[8:9], v[8:9], 0, s[10:11]
	v_lshlrev_b64 v[6:7], 11, v[6:7]
	v_lshl_add_u64 v[10:11], v[8:9], 0, v[2:3]
	v_lshl_add_u64 v[6:7], v[8:9], 0, v[6:7]
	global_load_dwordx4 v[66:69], v[10:11], off
	global_load_dwordx4 v[62:65], v[10:11], off offset:64
	global_load_dwordx4 v[58:61], v[10:11], off offset:128
	global_load_dwordx4 v[54:57], v[10:11], off offset:192
	global_load_dwordx4 v[50:53], v[10:11], off offset:256
	global_load_dwordx4 v[46:49], v[10:11], off offset:320
	global_load_dwordx4 v[42:45], v[10:11], off offset:384
	global_load_dwordx4 v[38:41], v[10:11], off offset:448
	global_load_dwordx4 v[98:101], v[6:7], off
	global_load_dwordx4 v[94:97], v[6:7], off offset:64
	global_load_dwordx4 v[90:93], v[6:7], off offset:128
	global_load_dwordx4 v[86:89], v[6:7], off offset:192
	global_load_dwordx4 v[82:85], v[6:7], off offset:256
	global_load_dwordx4 v[78:81], v[6:7], off offset:320
	global_load_dwordx4 v[74:77], v[6:7], off offset:384
	global_load_dwordx4 v[70:73], v[6:7], off offset:448
	v_bfe_u32 v5, v145, 4, 2
	v_bitop3_b32 v6, v5, v145, 15 bitop3:0x78
	v_bitop3_b32 v8, v5, v144, 8 bitop3:0x36
	v_bitop3_b32 v30, v5, v144, 24 bitop3:0x36
	v_lshl_add_u32 v134, v144, 9, 0
	v_bitop3_b32 v7, v5, v144, 4 bitop3:0x36
	v_bitop3_b32 v9, v5, v144, 12 bitop3:0x36
	v_lshlrev_b32_e32 v149, 4, v6
	v_lshlrev_b32_e32 v136, 4, v8
	v_lshlrev_b32_e32 v152, 4, v30
	v_lshlrev_b32_e32 v137, 4, v7
	v_lshlrev_b32_e32 v135, 4, v9
	v_add_u32_e32 v170, v134, v149
	v_add_u32_e32 v172, v134, v136
	v_add_u32_e32 v176, v134, v152
	v_add_u32_e32 v171, v134, v137
	v_add_u32_e32 v173, v134, v135
	s_waitcnt vmcnt(0)
	s_barrier
	ds_read_b128 v[6:9], v170
	ds_read_b128 v[10:13], v171
	v_lshrrev_b32_e32 v146, 1, v145
	s_lshl_b32 s8, s9, 3
	s_waitcnt vmcnt(20)
	v_pk_add_f32 v[14:15], v[14:15], v[16:17]
	s_nop 0
	v_add_f32_e32 v14, v14, v15
	v_fmamk_f32 v14, v14, 0x3b800000, v236
	v_rsq_f32_e32 v148, v14
	s_waitcnt vmcnt(16)
	v_pk_add_f32 v[16:17], v[20:21], v[22:23]
	v_bitop3_b32 v22, v5, v144, 16 bitop3:0x36
	v_lshlrev_b32_e32 v150, 4, v22
	v_bitop3_b32 v22, v5, v144, 20 bitop3:0x36
	v_bitop3_b32 v5, v5, v144, 28 bitop3:0x36
	v_add_f32_e32 v15, v16, v17
	v_add_u32_e32 v174, v134, v150
	v_lshlrev_b32_e32 v151, 4, v22
	v_lshlrev_b32_e32 v153, 4, v5
	v_fmamk_f32 v102, v15, 0x3b800000, v236
	ds_read_b128 v[14:17], v172
	ds_read_b128 v[18:21], v173
	v_add_u32_e32 v175, v134, v151
	ds_read_b128 v[22:25], v174
	ds_read_b128 v[26:29], v175
	v_add_u32_e32 v177, v134, v153
	ds_read_b128 v[30:33], v176
	ds_read_b128 v[34:37], v177
	v_rsq_f32_e32 v147, v102
	v_and_b32_e32 v5, 63, v145
	s_setprio 1
	s_waitcnt vmcnt(15) lgkmcnt(7)
	v_mfma_f32_16x16x32_bf16 v[102:105], v[6:9], v[66:69], 0
	s_waitcnt vmcnt(7)
	v_mfma_f32_16x16x32_bf16 v[6:9], v[6:9], v[98:101], 0
	s_waitcnt lgkmcnt(6)
	v_mfma_f32_16x16x32_bf16 v[102:105], v[10:13], v[62:65], v[102:105]
	s_waitcnt vmcnt(6)
	v_mfma_f32_16x16x32_bf16 v[6:9], v[10:13], v[94:97], v[6:9]
	s_waitcnt lgkmcnt(5)
	v_mfma_f32_16x16x32_bf16 v[10:13], v[14:17], v[58:61], v[102:105]
	s_waitcnt vmcnt(5)
	v_mfma_f32_16x16x32_bf16 v[6:9], v[14:17], v[90:93], v[6:9]
	s_waitcnt lgkmcnt(4)
	v_mfma_f32_16x16x32_bf16 v[10:13], v[18:21], v[54:57], v[10:13]
	s_waitcnt vmcnt(4)
	v_mfma_f32_16x16x32_bf16 v[6:9], v[18:21], v[86:89], v[6:9]
	s_setprio 0
	ds_read_b128 v[14:17], v170 offset:8192
	ds_read_b128 v[18:21], v171 offset:8192
	ds_read_b128 v[102:105], v172 offset:8192
	ds_read_b128 v[106:109], v173 offset:8192
	s_setprio 1
	s_waitcnt lgkmcnt(7)
	v_mfma_f32_16x16x32_bf16 v[10:13], v[22:25], v[50:53], v[10:13]
	s_waitcnt vmcnt(3)
	v_mfma_f32_16x16x32_bf16 v[6:9], v[22:25], v[82:85], v[6:9]
	s_waitcnt lgkmcnt(6)
	v_mfma_f32_16x16x32_bf16 v[10:13], v[26:29], v[46:49], v[10:13]
	s_waitcnt vmcnt(2)
	v_mfma_f32_16x16x32_bf16 v[6:9], v[26:29], v[78:81], v[6:9]
	s_waitcnt lgkmcnt(5)
	v_mfma_f32_16x16x32_bf16 v[10:13], v[30:33], v[42:45], v[10:13]
	s_waitcnt vmcnt(1)
	v_mfma_f32_16x16x32_bf16 v[6:9], v[30:33], v[74:77], v[6:9]
	s_waitcnt lgkmcnt(4)
	v_mfma_f32_16x16x32_bf16 v[10:13], v[34:37], v[38:41], v[10:13]
	s_waitcnt vmcnt(0)
	v_mfma_f32_16x16x32_bf16 v[22:25], v[34:37], v[70:73], v[6:9]
	s_setprio 0
	s_nop 2
	ds_read_b128 v[6:9], v174 offset:8192
	ds_read_b128 v[26:29], v175 offset:8192
	ds_read_b128 v[30:33], v176 offset:8192
	ds_read_b128 v[34:37], v177 offset:8192
	s_setprio 1
	s_waitcnt lgkmcnt(7)
	v_mfma_f32_16x16x32_bf16 v[110:113], v[14:17], v[66:69], 0
	v_mfma_f32_16x16x32_bf16 v[14:17], v[14:17], v[98:101], 0
	s_waitcnt lgkmcnt(6)
	v_mfma_f32_16x16x32_bf16 v[110:113], v[18:21], v[62:65], v[110:113]
	v_mfma_f32_16x16x32_bf16 v[14:17], v[18:21], v[94:97], v[14:17]
	s_waitcnt lgkmcnt(5)
	v_mfma_f32_16x16x32_bf16 v[18:21], v[102:105], v[58:61], v[110:113]
	v_mfma_f32_16x16x32_bf16 v[14:17], v[102:105], v[90:93], v[14:17]
	s_waitcnt lgkmcnt(4)
	v_mfma_f32_16x16x32_bf16 v[18:21], v[106:109], v[54:57], v[18:21]
	v_mfma_f32_16x16x32_bf16 v[14:17], v[106:109], v[86:89], v[14:17]
	s_setprio 0
	ds_read_b128 v[102:105], v170 offset:16384
	ds_read_b128 v[106:109], v171 offset:16384
	ds_read_b128 v[110:113], v172 offset:16384
	ds_read_b128 v[114:117], v173 offset:16384
	s_setprio 1
	s_waitcnt lgkmcnt(7)
	v_mfma_f32_16x16x32_bf16 v[18:21], v[6:9], v[50:53], v[18:21]
	v_mfma_f32_16x16x32_bf16 v[6:9], v[6:9], v[82:85], v[14:17]
	s_waitcnt lgkmcnt(6)
	v_mfma_f32_16x16x32_bf16 v[14:17], v[26:29], v[46:49], v[18:21]
	v_mfma_f32_16x16x32_bf16 v[6:9], v[26:29], v[78:81], v[6:9]
	s_waitcnt lgkmcnt(5)
	v_mfma_f32_16x16x32_bf16 v[14:17], v[30:33], v[42:45], v[14:17]
	v_mfma_f32_16x16x32_bf16 v[6:9], v[30:33], v[74:77], v[6:9]
	s_waitcnt lgkmcnt(4)
	v_mfma_f32_16x16x32_bf16 v[14:17], v[34:37], v[38:41], v[14:17]
	v_mfma_f32_16x16x32_bf16 v[26:29], v[34:37], v[70:73], v[6:9]
	s_setprio 0
	s_nop 3
	ds_read_b128 v[6:9], v174 offset:16384
	ds_read_b128 v[18:21], v175 offset:16384
	ds_read_b128 v[30:33], v176 offset:16384
	ds_read_b128 v[34:37], v177 offset:16384
	s_setprio 1
	s_waitcnt lgkmcnt(7)
	v_mfma_f32_16x16x32_bf16 v[118:121], v[102:105], v[66:69], 0
	v_mfma_f32_16x16x32_bf16 v[102:105], v[102:105], v[98:101], 0
	s_waitcnt lgkmcnt(6)
	v_mfma_f32_16x16x32_bf16 v[118:121], v[106:109], v[62:65], v[118:121]
	v_mfma_f32_16x16x32_bf16 v[102:105], v[106:109], v[94:97], v[102:105]
	s_waitcnt lgkmcnt(5)
	v_mfma_f32_16x16x32_bf16 v[106:109], v[110:113], v[58:61], v[118:121]
	v_mfma_f32_16x16x32_bf16 v[102:105], v[110:113], v[90:93], v[102:105]
	s_waitcnt lgkmcnt(4)
	v_mfma_f32_16x16x32_bf16 v[106:109], v[114:117], v[54:57], v[106:109]
	v_mfma_f32_16x16x32_bf16 v[102:105], v[114:117], v[86:89], v[102:105]
	s_setprio 0
	ds_read_b128 v[110:113], v170 offset:24576
	ds_read_b128 v[114:117], v171 offset:24576
	ds_read_b128 v[118:121], v172 offset:24576
	ds_read_b128 v[122:125], v173 offset:24576
	s_setprio 1
	s_waitcnt lgkmcnt(7)
	v_mfma_f32_16x16x32_bf16 v[106:109], v[6:9], v[50:53], v[106:109]
	v_mfma_f32_16x16x32_bf16 v[6:9], v[6:9], v[82:85], v[102:105]
	s_waitcnt lgkmcnt(6)
	v_mfma_f32_16x16x32_bf16 v[102:105], v[18:21], v[46:49], v[106:109]
	v_mfma_f32_16x16x32_bf16 v[6:9], v[18:21], v[78:81], v[6:9]
	s_waitcnt lgkmcnt(5)
	v_mfma_f32_16x16x32_bf16 v[18:21], v[30:33], v[42:45], v[102:105]
	v_mfma_f32_16x16x32_bf16 v[6:9], v[30:33], v[74:77], v[6:9]
	s_waitcnt lgkmcnt(4)
	v_mfma_f32_16x16x32_bf16 v[18:21], v[34:37], v[38:41], v[18:21]
	v_mfma_f32_16x16x32_bf16 v[30:33], v[34:37], v[70:73], v[6:9]
	s_setprio 0
	s_nop 3
	ds_read_b128 v[6:9], v174 offset:24576
	ds_read_b128 v[34:37], v175 offset:24576
	ds_read_b128 v[102:105], v176 offset:24576
	ds_read_b128 v[106:109], v177 offset:24576
	s_setprio 1
	s_waitcnt lgkmcnt(7)
	v_mfma_f32_16x16x32_bf16 v[126:129], v[110:113], v[66:69], 0
	v_mfma_f32_16x16x32_bf16 v[110:113], v[110:113], v[98:101], 0
	s_waitcnt lgkmcnt(6)
	v_mfma_f32_16x16x32_bf16 v[126:129], v[114:117], v[62:65], v[126:129]
	v_mfma_f32_16x16x32_bf16 v[110:113], v[114:117], v[94:97], v[110:113]
	s_waitcnt lgkmcnt(5)
	v_mfma_f32_16x16x32_bf16 v[114:117], v[118:121], v[58:61], v[126:129]
	v_mfma_f32_16x16x32_bf16 v[110:113], v[118:121], v[90:93], v[110:113]
	s_waitcnt lgkmcnt(4)
	v_mfma_f32_16x16x32_bf16 v[114:117], v[122:125], v[54:57], v[114:117]
	v_mfma_f32_16x16x32_bf16 v[110:113], v[122:125], v[86:89], v[110:113]
	s_setprio 0
	ds_read_b128 v[118:121], v170 offset:32768
	ds_read_b128 v[122:125], v171 offset:32768
	ds_read_b128 v[126:129], v172 offset:32768
	ds_read_b128 v[130:133], v173 offset:32768
	s_setprio 1
	s_waitcnt lgkmcnt(7)
	v_mfma_f32_16x16x32_bf16 v[114:117], v[6:9], v[50:53], v[114:117]
	v_mfma_f32_16x16x32_bf16 v[6:9], v[6:9], v[82:85], v[110:113]
	s_waitcnt lgkmcnt(6)
	v_mfma_f32_16x16x32_bf16 v[110:113], v[34:37], v[46:49], v[114:117]
	v_mfma_f32_16x16x32_bf16 v[6:9], v[34:37], v[78:81], v[6:9]
	s_waitcnt lgkmcnt(5)
	v_mfma_f32_16x16x32_bf16 v[34:37], v[102:105], v[42:45], v[110:113]
	v_mfma_f32_16x16x32_bf16 v[6:9], v[102:105], v[74:77], v[6:9]
	s_waitcnt lgkmcnt(4)
	v_mfma_f32_16x16x32_bf16 v[114:117], v[106:109], v[38:41], v[34:37]
	v_mfma_f32_16x16x32_bf16 v[34:37], v[106:109], v[70:73], v[6:9]
	s_setprio 0
	s_nop 3
	ds_read_b128 v[6:9], v174 offset:32768
	ds_read_b128 v[102:105], v175 offset:32768
	ds_read_b128 v[106:109], v176 offset:32768
	ds_read_b128 v[110:113], v177 offset:32768
	s_setprio 1
	s_waitcnt lgkmcnt(7)
	v_mfma_f32_16x16x32_bf16 v[138:141], v[118:121], v[66:69], 0
	v_mfma_f32_16x16x32_bf16 v[118:121], v[118:121], v[98:101], 0
	s_waitcnt lgkmcnt(6)
	v_mfma_f32_16x16x32_bf16 v[138:141], v[122:125], v[62:65], v[138:141]
	v_mfma_f32_16x16x32_bf16 v[118:121], v[122:125], v[94:97], v[118:121]
	s_waitcnt lgkmcnt(5)
	v_mfma_f32_16x16x32_bf16 v[122:125], v[126:129], v[58:61], v[138:141]
	v_mfma_f32_16x16x32_bf16 v[118:121], v[126:129], v[90:93], v[118:121]
	s_waitcnt lgkmcnt(4)
	v_mfma_f32_16x16x32_bf16 v[122:125], v[130:133], v[54:57], v[122:125]
	v_mfma_f32_16x16x32_bf16 v[118:121], v[130:133], v[86:89], v[118:121]
	s_setprio 0
	ds_read_b128 v[126:129], v170 offset:40960
	ds_read_b128 v[130:133], v171 offset:40960
	ds_read_b128 v[138:141], v172 offset:40960
	ds_read_b128 v[154:157], v173 offset:40960
	s_setprio 1
	s_waitcnt lgkmcnt(7)
	v_mfma_f32_16x16x32_bf16 v[122:125], v[6:9], v[50:53], v[122:125]
	v_mfma_f32_16x16x32_bf16 v[6:9], v[6:9], v[82:85], v[118:121]
	s_waitcnt lgkmcnt(6)
	v_mfma_f32_16x16x32_bf16 v[118:121], v[102:105], v[46:49], v[122:125]
	v_mfma_f32_16x16x32_bf16 v[6:9], v[102:105], v[78:81], v[6:9]
	s_waitcnt lgkmcnt(5)
	v_mfma_f32_16x16x32_bf16 v[102:105], v[106:109], v[42:45], v[118:121]
	v_mfma_f32_16x16x32_bf16 v[6:9], v[106:109], v[74:77], v[6:9]
	s_waitcnt lgkmcnt(4)
	v_mfma_f32_16x16x32_bf16 v[118:121], v[110:113], v[38:41], v[102:105]
	v_mfma_f32_16x16x32_bf16 v[102:105], v[110:113], v[70:73], v[6:9]
	s_setprio 0
	s_nop 3
	ds_read_b128 v[6:9], v174 offset:40960
	ds_read_b128 v[106:109], v175 offset:40960
	ds_read_b128 v[110:113], v176 offset:40960
	ds_read_b128 v[122:125], v177 offset:40960
	s_setprio 1
	s_waitcnt lgkmcnt(7)
	v_mfma_f32_16x16x32_bf16 v[158:161], v[126:129], v[66:69], 0
	v_mfma_f32_16x16x32_bf16 v[126:129], v[126:129], v[98:101], 0
	s_waitcnt lgkmcnt(6)
	v_mfma_f32_16x16x32_bf16 v[158:161], v[130:133], v[62:65], v[158:161]
	v_mfma_f32_16x16x32_bf16 v[126:129], v[130:133], v[94:97], v[126:129]
	s_waitcnt lgkmcnt(5)
	v_mfma_f32_16x16x32_bf16 v[130:133], v[138:141], v[58:61], v[158:161]
	v_mfma_f32_16x16x32_bf16 v[126:129], v[138:141], v[90:93], v[126:129]
	s_waitcnt lgkmcnt(4)
	v_mfma_f32_16x16x32_bf16 v[130:133], v[154:157], v[54:57], v[130:133]
	v_mfma_f32_16x16x32_bf16 v[126:129], v[154:157], v[86:89], v[126:129]
	s_setprio 0
	ds_read_b128 v[138:141], v170 offset:49152
	ds_read_b128 v[154:157], v171 offset:49152
	ds_read_b128 v[158:161], v172 offset:49152
	ds_read_b128 v[162:165], v173 offset:49152
	s_setprio 1
	s_waitcnt lgkmcnt(7)
	v_mfma_f32_16x16x32_bf16 v[130:133], v[6:9], v[50:53], v[130:133]
	v_mfma_f32_16x16x32_bf16 v[6:9], v[6:9], v[82:85], v[126:129]
	s_waitcnt lgkmcnt(6)
	v_mfma_f32_16x16x32_bf16 v[126:129], v[106:109], v[46:49], v[130:133]
	v_mfma_f32_16x16x32_bf16 v[6:9], v[106:109], v[78:81], v[6:9]
	s_waitcnt lgkmcnt(5)
	v_mfma_f32_16x16x32_bf16 v[106:109], v[110:113], v[42:45], v[126:129]
	v_mfma_f32_16x16x32_bf16 v[6:9], v[110:113], v[74:77], v[6:9]
	s_waitcnt lgkmcnt(4)
	v_mfma_f32_16x16x32_bf16 v[126:129], v[122:125], v[38:41], v[106:109]
	v_mfma_f32_16x16x32_bf16 v[106:109], v[122:125], v[70:73], v[6:9]
	s_setprio 0
	s_nop 3
	ds_read_b128 v[6:9], v174 offset:49152
	ds_read_b128 v[110:113], v175 offset:49152
	ds_read_b128 v[122:125], v176 offset:49152
	ds_read_b128 v[130:133], v177 offset:49152
	s_setprio 1
	s_waitcnt lgkmcnt(7)
	v_mfma_f32_16x16x32_bf16 v[166:169], v[138:141], v[66:69], 0
	v_mfma_f32_16x16x32_bf16 v[138:141], v[138:141], v[98:101], 0
	s_waitcnt lgkmcnt(6)
	v_mfma_f32_16x16x32_bf16 v[166:169], v[154:157], v[62:65], v[166:169]
	v_mfma_f32_16x16x32_bf16 v[138:141], v[154:157], v[94:97], v[138:141]
	s_waitcnt lgkmcnt(5)
	v_mfma_f32_16x16x32_bf16 v[154:157], v[158:161], v[58:61], v[166:169]
	v_mfma_f32_16x16x32_bf16 v[138:141], v[158:161], v[90:93], v[138:141]
	s_waitcnt lgkmcnt(4)
	v_mfma_f32_16x16x32_bf16 v[154:157], v[162:165], v[54:57], v[154:157]
	v_mfma_f32_16x16x32_bf16 v[138:141], v[162:165], v[86:89], v[138:141]
	s_setprio 0
	ds_read_b128 v[158:161], v170 offset:57344
	ds_read_b128 v[162:165], v171 offset:57344
	ds_read_b128 v[166:169], v172 offset:57344
	ds_read_b128 v[170:173], v173 offset:57344
	s_setprio 1
	s_waitcnt lgkmcnt(7)
	v_mfma_f32_16x16x32_bf16 v[154:157], v[6:9], v[50:53], v[154:157]
	v_mfma_f32_16x16x32_bf16 v[6:9], v[6:9], v[82:85], v[138:141]
	s_waitcnt lgkmcnt(6)
	v_mfma_f32_16x16x32_bf16 v[138:141], v[110:113], v[46:49], v[154:157]
	v_mfma_f32_16x16x32_bf16 v[6:9], v[110:113], v[78:81], v[6:9]
	s_waitcnt lgkmcnt(5)
	v_mfma_f32_16x16x32_bf16 v[110:113], v[122:125], v[42:45], v[138:141]
	v_mfma_f32_16x16x32_bf16 v[6:9], v[122:125], v[74:77], v[6:9]
	s_waitcnt lgkmcnt(4)
	v_mfma_f32_16x16x32_bf16 v[122:125], v[130:133], v[38:41], v[110:113]
	v_mfma_f32_16x16x32_bf16 v[110:113], v[130:133], v[70:73], v[6:9]
	s_setprio 0
	s_nop 3
	ds_read_b128 v[6:9], v174 offset:57344
	ds_read_b128 v[130:133], v175 offset:57344
	ds_read_b128 v[138:141], v176 offset:57344
	ds_read_b128 v[154:157], v177 offset:57344
	s_setprio 1
	s_waitcnt lgkmcnt(7)
	v_mfma_f32_16x16x32_bf16 v[174:177], v[158:161], v[66:69], 0
	v_mfma_f32_16x16x32_bf16 v[158:161], v[158:161], v[98:101], 0
	s_waitcnt lgkmcnt(6)
	v_mfma_f32_16x16x32_bf16 v[174:177], v[162:165], v[62:65], v[174:177]
	v_mfma_f32_16x16x32_bf16 v[158:161], v[162:165], v[94:97], v[158:161]
	s_waitcnt lgkmcnt(5)
	v_mfma_f32_16x16x32_bf16 v[162:165], v[166:169], v[58:61], v[174:177]
	v_mfma_f32_16x16x32_bf16 v[158:161], v[166:169], v[90:93], v[158:161]
	s_waitcnt lgkmcnt(4)
	v_mfma_f32_16x16x32_bf16 v[162:165], v[170:173], v[54:57], v[162:165]
	v_mfma_f32_16x16x32_bf16 v[158:161], v[170:173], v[86:89], v[158:161]
	s_setprio 0
	s_setprio 1
	s_waitcnt lgkmcnt(3)
	v_mfma_f32_16x16x32_bf16 v[162:165], v[6:9], v[50:53], v[162:165]
	v_mfma_f32_16x16x32_bf16 v[6:9], v[6:9], v[82:85], v[158:161]
	s_waitcnt lgkmcnt(2)
	v_mfma_f32_16x16x32_bf16 v[158:161], v[130:133], v[46:49], v[162:165]
	v_mfma_f32_16x16x32_bf16 v[6:9], v[130:133], v[78:81], v[6:9]
	s_waitcnt lgkmcnt(1)
	v_mfma_f32_16x16x32_bf16 v[130:133], v[138:141], v[42:45], v[158:161]
	v_mfma_f32_16x16x32_bf16 v[6:9], v[138:141], v[74:77], v[6:9]
	s_waitcnt lgkmcnt(0)
	v_mfma_f32_16x16x32_bf16 v[130:133], v[154:157], v[38:41], v[130:133]
	v_mfma_f32_16x16x32_bf16 v[138:141], v[154:157], v[70:73], v[6:9]
	s_setprio 0
	s_nop 3
	v_mul_f32_e32 v7, v148, v14
	v_mul_f32_e32 v6, v148, v10
	v_exp_f32_e32 v8, v7
	v_mul_f32_e32 v7, v148, v11
	v_mul_f32_e32 v10, v148, v12
	v_mul_f32_e32 v12, v148, v13
	v_exp_f32_e32 v6, v6
	v_exp_f32_e32 v7, v7
	v_mul_f32_e32 v9, v148, v15
	v_exp_f32_e32 v10, v10
	v_mul_f32_e32 v11, v148, v16
	v_exp_f32_e32 v12, v12
	v_mul_f32_e32 v13, v148, v17
	v_exp_f32_e32 v9, v9
	v_exp_f32_e32 v11, v11
	v_exp_f32_e32 v13, v13
	v_add_f32_e32 v14, v6, v7
	v_add_f32_e32 v15, v10, v12
	v_add_f32_e32 v14, v14, v15
	v_add_f32_e32 v15, v8, v9
	v_add_f32_e32 v16, v11, v13
	v_add_f32_e32 v15, v15, v16
	v_cvt_pk_bf16_f32 v8, v8, v9
	v_cvt_pk_bf16_f32 v9, v11, v13
	v_mul_f32_e32 v11, v148, v114
	v_add_f32_e32 v14, v14, v15
	v_cvt_pk_bf16_f32 v6, v6, v7
	v_cvt_pk_bf16_f32 v7, v10, v12
	v_mul_f32_e32 v10, v148, v18
	v_exp_f32_e32 v12, v11
	v_mul_f32_e32 v11, v148, v19
	v_mul_f32_e32 v15, v148, v20
	v_mul_f32_e32 v17, v148, v21
	v_exp_f32_e32 v10, v10
	v_exp_f32_e32 v11, v11
	v_mul_f32_e32 v13, v148, v115
	v_exp_f32_e32 v15, v15
	v_mul_f32_e32 v16, v148, v116
	v_exp_f32_e32 v17, v17
	v_mul_f32_e32 v18, v148, v117
	v_exp_f32_e32 v13, v13
	v_exp_f32_e32 v16, v16
	v_exp_f32_e32 v18, v18
	v_add_f32_e32 v19, v10, v11
	v_add_f32_e32 v20, v15, v17
	v_add_f32_e32 v19, v19, v20
	v_add_f32_e32 v20, v12, v13
	v_add_f32_e32 v21, v16, v18
	v_add_f32_e32 v20, v20, v21
	v_add_f32_e32 v14, 0, v14
	v_add_f32_e32 v19, v19, v20
	v_add_f32_e32 v14, v14, v19
	v_cvt_pk_bf16_f32 v10, v10, v11
	v_cvt_pk_bf16_f32 v11, v15, v17
	v_mul_f32_e32 v15, v148, v118
	v_mul_f32_e32 v17, v148, v119
	v_mul_f32_e32 v19, v148, v120
	v_mul_f32_e32 v21, v148, v121
	v_cvt_pk_bf16_f32 v12, v12, v13
	v_cvt_pk_bf16_f32 v13, v16, v18
	v_exp_f32_e32 v15, v15
	v_mul_f32_e32 v16, v148, v126
	v_exp_f32_e32 v17, v17
	v_mul_f32_e32 v18, v148, v127
	v_exp_f32_e32 v19, v19
	v_mul_f32_e32 v20, v148, v128
	v_exp_f32_e32 v21, v21
	v_mul_f32_e32 v114, v148, v129
	v_exp_f32_e32 v16, v16
	v_exp_f32_e32 v18, v18
	v_exp_f32_e32 v20, v20
	v_exp_f32_e32 v114, v114
	v_add_f32_e32 v115, v15, v17
	v_add_f32_e32 v116, v19, v21
	v_add_f32_e32 v115, v115, v116
	v_add_f32_e32 v116, v16, v18
	v_add_f32_e32 v117, v20, v114
	v_add_f32_e32 v116, v116, v117
	v_add_f32_e32 v115, v115, v116
	v_add_f32_e32 v115, v14, v115
	v_cvt_pk_bf16_f32 v14, v15, v17
	v_cvt_pk_bf16_f32 v15, v19, v21
	v_mul_f32_e32 v19, v148, v130
	v_cvt_pk_bf16_f32 v16, v16, v18
	v_cvt_pk_bf16_f32 v17, v20, v114
	v_mul_f32_e32 v18, v148, v122
	v_exp_f32_e32 v20, v19
	v_mul_f32_e32 v19, v148, v123
	v_mul_f32_e32 v114, v148, v124
	v_mul_f32_e32 v117, v148, v125
	v_exp_f32_e32 v18, v18
	v_exp_f32_e32 v19, v19
	v_mul_f32_e32 v21, v148, v131
	v_exp_f32_e32 v114, v114
	v_mul_f32_e32 v116, v148, v132
	v_exp_f32_e32 v117, v117
	v_mul_f32_e32 v118, v148, v133
	v_exp_f32_e32 v21, v21
	v_exp_f32_e32 v116, v116
	v_exp_f32_e32 v118, v118
	v_mul_f32_e32 v22, v147, v22
	v_mul_f32_e32 v23, v147, v23
	v_mul_f32_e32 v24, v147, v24
	v_mul_f32_e32 v25, v147, v25
	v_add_f32_e32 v119, v18, v19
	v_add_f32_e32 v120, v114, v117
	v_exp_f32_e32 v22, v22
	v_mul_f32_e32 v26, v147, v26
	v_exp_f32_e32 v23, v23
	v_mul_f32_e32 v27, v147, v27
	v_exp_f32_e32 v24, v24
	v_exp_f32_e32 v25, v25
	v_add_f32_e32 v119, v119, v120
	v_add_f32_e32 v120, v20, v21
	v_add_f32_e32 v121, v116, v118
	v_exp_f32_e32 v26, v26
	v_exp_f32_e32 v27, v27
	v_mul_f32_e32 v28, v147, v28
	v_mul_f32_e32 v29, v147, v29
	v_add_f32_e32 v120, v120, v121
	v_exp_f32_e32 v28, v28
	v_exp_f32_e32 v29, v29
	v_add_f32_e32 v119, v119, v120
	v_add_f32_e32 v155, v115, v119
	v_cvt_pk_bf16_f32 v18, v18, v19
	v_cvt_pk_bf16_f32 v19, v114, v117
	v_add_f32_e32 v114, v22, v23
	v_add_f32_e32 v115, v24, v25
	v_add_f32_e32 v114, v114, v115
	v_add_f32_e32 v115, v26, v27
	v_cvt_pk_bf16_f32 v22, v22, v23
	v_cvt_pk_bf16_f32 v23, v24, v25
	v_cvt_pk_bf16_f32 v24, v26, v27
	v_mul_f32_e32 v27, v147, v34
	v_cvt_pk_bf16_f32 v20, v20, v21
	v_cvt_pk_bf16_f32 v21, v116, v118
	v_add_f32_e32 v116, v28, v29
	v_cvt_pk_bf16_f32 v25, v28, v29
	v_mul_f32_e32 v26, v147, v30
	v_exp_f32_e32 v28, v27
	v_mul_f32_e32 v27, v147, v31
	v_mul_f32_e32 v30, v147, v32
	v_mul_f32_e32 v32, v147, v33
	v_exp_f32_e32 v26, v26
	v_exp_f32_e32 v27, v27
	v_mul_f32_e32 v29, v147, v35
	v_exp_f32_e32 v30, v30
	v_mul_f32_e32 v31, v147, v36
	v_exp_f32_e32 v32, v32
	v_mul_f32_e32 v33, v147, v37
	v_exp_f32_e32 v29, v29
	v_exp_f32_e32 v31, v31
	v_exp_f32_e32 v33, v33
	v_add_f32_e32 v34, v26, v27
	v_add_f32_e32 v35, v30, v32
	v_add_f32_e32 v34, v34, v35
	v_add_f32_e32 v35, v28, v29
	v_add_f32_e32 v36, v31, v33
	v_add_f32_e32 v35, v35, v36
	v_cvt_pk_bf16_f32 v28, v28, v29
	v_cvt_pk_bf16_f32 v29, v31, v33
	v_mul_f32_e32 v31, v147, v106
	v_add_f32_e32 v34, v34, v35
	v_cvt_pk_bf16_f32 v26, v26, v27
	v_cvt_pk_bf16_f32 v27, v30, v32
	v_mul_f32_e32 v30, v147, v102
	v_exp_f32_e32 v32, v31
	v_mul_f32_e32 v31, v147, v103
	v_mul_f32_e32 v35, v147, v104
	v_mul_f32_e32 v37, v147, v105
	v_exp_f32_e32 v30, v30
	v_exp_f32_e32 v31, v31
	v_mul_f32_e32 v33, v147, v107
	v_exp_f32_e32 v35, v35
	v_mul_f32_e32 v36, v147, v108
	v_exp_f32_e32 v37, v37
	v_mul_f32_e32 v102, v147, v109
	v_exp_f32_e32 v33, v33
	v_exp_f32_e32 v36, v36
	v_exp_f32_e32 v102, v102
	v_add_f32_e32 v115, v115, v116
	v_add_f32_e32 v103, v30, v31
	v_add_f32_e32 v104, v35, v37
	v_add_f32_e32 v114, v114, v115
	v_add_f32_e32 v103, v103, v104
	v_add_f32_e32 v104, v32, v33
	v_add_f32_e32 v105, v36, v102
	v_add_f32_e32 v114, 0, v114
	v_add_f32_e32 v104, v104, v105
	v_add_f32_e32 v34, v114, v34
	v_add_f32_e32 v103, v103, v104
	v_add_f32_e32 v34, v34, v103
	v_cvt_pk_bf16_f32 v30, v30, v31
	v_cvt_pk_bf16_f32 v31, v35, v37
	v_mul_f32_e32 v35, v147, v110
	v_mul_f32_e32 v37, v147, v111
	v_mul_f32_e32 v103, v147, v112
	v_mul_f32_e32 v105, v147, v113
	v_cvt_pk_bf16_f32 v32, v32, v33
	v_cvt_pk_bf16_f32 v33, v36, v102
	v_exp_f32_e32 v35, v35
	v_mul_f32_e32 v36, v147, v138
	v_exp_f32_e32 v37, v37
	v_mul_f32_e32 v102, v147, v139
	v_exp_f32_e32 v103, v103
	v_mul_f32_e32 v104, v147, v140
	v_exp_f32_e32 v105, v105
	v_mul_f32_e32 v106, v147, v141
	v_exp_f32_e32 v36, v36
	v_exp_f32_e32 v102, v102
	v_exp_f32_e32 v104, v104
	v_exp_f32_e32 v106, v106
	v_add_f32_e32 v107, v35, v37
	v_add_f32_e32 v108, v103, v105
	v_add_f32_e32 v107, v107, v108
	v_add_f32_e32 v108, v36, v102
	v_add_f32_e32 v109, v104, v106
	v_add_f32_e32 v108, v108, v109
	v_add_f32_e32 v107, v107, v108
	v_cvt_pk_bf16_f32 v36, v36, v102
	v_mov_b32_e32 v102, v5
	v_add_f32_e32 v154, v34, v107
	v_cvt_pk_bf16_f32 v34, v35, v37
	v_cvt_pk_bf16_f32 v37, v104, v106
	s_barrier
	v_cvt_pk_bf16_f32 v35, v103, v105
	v_mov_b32_e32 v105, v4
	v_ashrrev_i32_e32 v106, 5, v102
	v_and_b32_e32 v107, 31, v102
	v_lshl_add_u32 v102, s9, 4, v106
	v_lshrrev_b32_e32 v103, 1, v102
	v_and_b32_e32 v103, 12, v103
	v_and_b32_e32 v108, 3, v106
	v_bitop3_b32 v104, v103, v107, v108 bitop3:0x36
	v_ashrrev_i32_e32 v103, 31, v102
	v_lshlrev_b64 v[102:103], 9, v[102:103]
	v_lshl_add_u64 v[102:103], s[4:5], 0, v[102:103]
	v_lshlrev_b32_e32 v104, 4, v104
	s_lshl_b32 s9, s9, 13
	v_lshl_add_u64 v[102:103], v[102:103], 0, v[104:105]
	s_add_i32 m0, s9, 0
	s_or_b32 s9, s8, 1
	global_load_lds_dwordx4 v[102:103], off
	v_lshl_add_u32 v102, s9, 1, v106
	v_lshrrev_b32_e32 v103, 1, v102
	v_and_b32_e32 v103, 12, v103
	v_and_b32_e32 v104, 3, v102
	v_bitop3_b32 v104, v103, v107, v104 bitop3:0x36
	v_ashrrev_i32_e32 v103, 31, v102
	v_lshlrev_b64 v[102:103], 9, v[102:103]
	v_lshl_add_u64 v[102:103], s[4:5], 0, v[102:103]
	v_lshlrev_b32_e32 v104, 4, v104
	s_lshl_b32 s9, s9, 10
	v_lshl_add_u64 v[102:103], v[102:103], 0, v[104:105]
	s_add_i32 m0, s9, 0
	s_or_b32 s9, s8, 2
	global_load_lds_dwordx4 v[102:103], off
	v_lshl_add_u32 v102, s9, 1, v106
	v_lshrrev_b32_e32 v103, 1, v102
	v_and_b32_e32 v103, 12, v103
	v_bitop3_b32 v104, v103, v107, v108 bitop3:0x36
	v_ashrrev_i32_e32 v103, 31, v102
	v_lshlrev_b64 v[102:103], 9, v[102:103]
	v_lshl_add_u64 v[102:103], s[4:5], 0, v[102:103]
	v_lshlrev_b32_e32 v104, 4, v104
	s_lshl_b32 s9, s9, 10
	v_lshl_add_u64 v[102:103], v[102:103], 0, v[104:105]
	s_add_i32 m0, s9, 0
	s_or_b32 s9, s8, 3
	global_load_lds_dwordx4 v[102:103], off
	v_lshl_add_u32 v102, s9, 1, v106
	v_lshrrev_b32_e32 v103, 1, v102
	v_and_b32_e32 v103, 12, v103
	v_and_b32_e32 v104, 3, v102
	v_bitop3_b32 v104, v103, v107, v104 bitop3:0x36
	v_ashrrev_i32_e32 v103, 31, v102
	v_lshlrev_b64 v[102:103], 9, v[102:103]
	v_lshl_add_u64 v[102:103], s[4:5], 0, v[102:103]
	v_lshlrev_b32_e32 v104, 4, v104
	s_lshl_b32 s9, s9, 10
	v_lshl_add_u64 v[102:103], v[102:103], 0, v[104:105]
	s_add_i32 m0, s9, 0
	s_or_b32 s9, s8, 4
	global_load_lds_dwordx4 v[102:103], off
	v_lshl_add_u32 v102, s9, 1, v106
	v_lshrrev_b32_e32 v103, 1, v102
	v_and_b32_e32 v103, 12, v103
	v_bitop3_b32 v104, v103, v107, v108 bitop3:0x36
	v_ashrrev_i32_e32 v103, 31, v102
	v_lshlrev_b64 v[102:103], 9, v[102:103]
	v_lshl_add_u64 v[102:103], s[4:5], 0, v[102:103]
	v_lshlrev_b32_e32 v104, 4, v104
	s_lshl_b32 s9, s9, 10
	v_lshl_add_u64 v[102:103], v[102:103], 0, v[104:105]
	s_add_i32 m0, s9, 0
	s_or_b32 s9, s8, 5
	global_load_lds_dwordx4 v[102:103], off
	v_lshl_add_u32 v102, s9, 1, v106
	v_lshrrev_b32_e32 v103, 1, v102
	v_and_b32_e32 v103, 12, v103
	v_and_b32_e32 v104, 3, v102
	v_bitop3_b32 v104, v103, v107, v104 bitop3:0x36
	v_ashrrev_i32_e32 v103, 31, v102
	v_lshlrev_b64 v[102:103], 9, v[102:103]
	v_lshl_add_u64 v[102:103], s[4:5], 0, v[102:103]
	v_lshlrev_b32_e32 v104, 4, v104
	s_lshl_b32 s9, s9, 10
	v_lshl_add_u64 v[102:103], v[102:103], 0, v[104:105]
	s_add_i32 m0, s9, 0
	s_or_b32 s9, s8, 6
	global_load_lds_dwordx4 v[102:103], off
	v_lshl_add_u32 v102, s9, 1, v106
	v_lshrrev_b32_e32 v103, 1, v102
	v_and_b32_e32 v103, 12, v103
	v_bitop3_b32 v104, v103, v107, v108 bitop3:0x36
	v_ashrrev_i32_e32 v103, 31, v102
	v_lshlrev_b64 v[102:103], 9, v[102:103]
	v_lshl_add_u64 v[102:103], s[4:5], 0, v[102:103]
	v_lshlrev_b32_e32 v104, 4, v104
	s_lshl_b32 s9, s9, 10
	v_lshl_add_u64 v[102:103], v[102:103], 0, v[104:105]
	s_add_i32 m0, s9, 0
	s_or_b32 s9, s8, 7
	global_load_lds_dwordx4 v[102:103], off
	v_lshl_add_u32 v102, s9, 1, v106
	v_lshrrev_b32_e32 v103, 1, v102
	v_and_b32_e32 v103, 12, v103
	v_and_b32_e32 v104, 3, v102
	v_bitop3_b32 v104, v103, v107, v104 bitop3:0x36
	v_ashrrev_i32_e32 v103, 31, v102
	v_lshlrev_b64 v[102:103], 9, v[102:103]
	v_lshl_add_u64 v[102:103], s[4:5], 0, v[102:103]
	v_lshlrev_b32_e32 v104, 4, v104
	s_lshl_b32 s9, s9, 10
	v_lshl_add_u64 v[102:103], v[102:103], 0, v[104:105]
	s_add_i32 m0, s9, 0
	v_add_u32_e32 v130, 0x10000, v134
	global_load_lds_dwordx4 v[102:103], off
	v_add_u32_e32 v102, v130, v149
	v_add_u32_e32 v106, v130, v137
	v_add_u32_e32 v110, v130, v136
	v_add_u32_e32 v114, v130, v135
	v_add_u32_e32 v118, v130, v150
	v_add_u32_e32 v122, v130, v151
	v_add_u32_e32 v126, v130, v152
	v_add_u32_e32 v130, v130, v153
	ds_read_b128 v[102:105], v102
	ds_read_b128 v[106:109], v106
	ds_read_b128 v[110:113], v110
	ds_read_b128 v[114:117], v114
	ds_read_b128 v[118:121], v118
	ds_read_b128 v[122:125], v122
	ds_read_b128 v[126:129], v126
	ds_read_b128 v[130:133], v130
	s_setprio 1
	s_waitcnt lgkmcnt(0)
	v_mfma_f32_16x16x32_bf16 v[138:141], v[102:105], v[66:69], 0
	v_mfma_f32_16x16x32_bf16 v[102:105], v[102:105], v[98:101], 0
	v_mfma_f32_16x16x32_bf16 v[138:141], v[106:109], v[62:65], v[138:141]
	v_mfma_f32_16x16x32_bf16 v[102:105], v[106:109], v[94:97], v[102:105]
	v_mfma_f32_16x16x32_bf16 v[106:109], v[110:113], v[58:61], v[138:141]
	v_mfma_f32_16x16x32_bf16 v[102:105], v[110:113], v[90:93], v[102:105]
	v_mfma_f32_16x16x32_bf16 v[106:109], v[114:117], v[54:57], v[106:109]
	v_mfma_f32_16x16x32_bf16 v[102:105], v[114:117], v[86:89], v[102:105]
	s_setprio 0
	v_add_u32_e32 v160, 0x12000, v134
	v_add_u32_e32 v110, v160, v149
	v_add_u32_e32 v114, v160, v137
	v_add_u32_e32 v138, v160, v136
	v_add_u32_e32 v156, v160, v135
	ds_read_b128 v[110:113], v110
	ds_read_b128 v[114:117], v114
	ds_read_b128 v[138:141], v138
	ds_read_b128 v[156:159], v156
	s_setprio 1
	v_mfma_f32_16x16x32_bf16 v[106:109], v[118:121], v[50:53], v[106:109]
	v_mfma_f32_16x16x32_bf16 v[102:105], v[118:121], v[82:85], v[102:105]
	v_mfma_f32_16x16x32_bf16 v[106:109], v[122:125], v[46:49], v[106:109]
	v_mfma_f32_16x16x32_bf16 v[102:105], v[122:125], v[78:81], v[102:105]
	v_mfma_f32_16x16x32_bf16 v[106:109], v[126:129], v[42:45], v[106:109]
	v_mfma_f32_16x16x32_bf16 v[102:105], v[126:129], v[74:77], v[102:105]
	v_mfma_f32_16x16x32_bf16 v[122:125], v[130:133], v[38:41], v[106:109]
	v_mfma_f32_16x16x32_bf16 v[102:105], v[130:133], v[70:73], v[102:105]
	s_setprio 0
	s_nop 3
	v_add_u32_e32 v106, v160, v150
	v_add_u32_e32 v118, v160, v151
	v_add_u32_e32 v126, v160, v152
	ds_read_b128 v[106:109], v106
	ds_read_b128 v[118:121], v118
	v_add_u32_e32 v130, v160, v153
	ds_read_b128 v[126:129], v126
	ds_read_b128 v[160:163], v130
	s_setprio 1
	s_waitcnt lgkmcnt(0)
	v_mfma_f32_16x16x32_bf16 v[130:133], v[110:113], v[66:69], 0
	v_mfma_f32_16x16x32_bf16 v[110:113], v[110:113], v[98:101], 0
	v_mfma_f32_16x16x32_bf16 v[130:133], v[114:117], v[62:65], v[130:133]
	v_mfma_f32_16x16x32_bf16 v[110:113], v[114:117], v[94:97], v[110:113]
	v_mfma_f32_16x16x32_bf16 v[114:117], v[138:141], v[58:61], v[130:133]
	v_mfma_f32_16x16x32_bf16 v[110:113], v[138:141], v[90:93], v[110:113]
	v_mfma_f32_16x16x32_bf16 v[114:117], v[156:159], v[54:57], v[114:117]
	v_mfma_f32_16x16x32_bf16 v[110:113], v[156:159], v[86:89], v[110:113]
	s_setprio 0
	v_add_u32_e32 v172, 0x14000, v134
	s_nop 0
	v_add_u32_e32 v130, v172, v149
	v_add_u32_e32 v131, v172, v137
	ds_read_b128 v[138:141], v130
	ds_read_b128 v[156:159], v131
	v_add_u32_e32 v130, v172, v136
	v_add_u32_e32 v131, v172, v135
	ds_read_b128 v[164:167], v130
	ds_read_b128 v[168:171], v131
	s_setprio 1
	v_mfma_f32_16x16x32_bf16 v[114:117], v[106:109], v[50:53], v[114:117]
	v_mfma_f32_16x16x32_bf16 v[106:109], v[106:109], v[82:85], v[110:113]
	v_mfma_f32_16x16x32_bf16 v[110:113], v[118:121], v[46:49], v[114:117]
	v_mfma_f32_16x16x32_bf16 v[106:109], v[118:121], v[78:81], v[106:109]
	v_mfma_f32_16x16x32_bf16 v[110:113], v[126:129], v[42:45], v[110:113]
	v_mfma_f32_16x16x32_bf16 v[106:109], v[126:129], v[74:77], v[106:109]
	v_mfma_f32_16x16x32_bf16 v[130:133], v[160:163], v[38:41], v[110:113]
	v_mfma_f32_16x16x32_bf16 v[106:109], v[160:163], v[70:73], v[106:109]
	s_setprio 0
	s_nop 3
	v_add_u32_e32 v110, v172, v150
	v_add_u32_e32 v114, v172, v151
	v_add_u32_e32 v118, v172, v152
	v_add_u32_e32 v126, v172, v153
	ds_read_b128 v[110:113], v110
	ds_read_b128 v[114:117], v114
	ds_read_b128 v[118:121], v118
	ds_read_b128 v[126:129], v126
	s_setprio 1
	s_waitcnt lgkmcnt(0)
	v_mfma_f32_16x16x32_bf16 v[160:163], v[138:141], v[66:69], 0
	v_mfma_f32_16x16x32_bf16 v[138:141], v[138:141], v[98:101], 0
	v_mfma_f32_16x16x32_bf16 v[160:163], v[156:159], v[62:65], v[160:163]
	v_mfma_f32_16x16x32_bf16 v[138:141], v[156:159], v[94:97], v[138:141]
	v_mfma_f32_16x16x32_bf16 v[156:159], v[164:167], v[58:61], v[160:163]
	v_mfma_f32_16x16x32_bf16 v[138:141], v[164:167], v[90:93], v[138:141]
	v_mfma_f32_16x16x32_bf16 v[156:159], v[168:171], v[54:57], v[156:159]
	v_mfma_f32_16x16x32_bf16 v[138:141], v[168:171], v[86:89], v[138:141]
	s_setprio 0
	v_add_u32_e32 v176, 0x16000, v134
	s_nop 0
	v_add_u32_e32 v160, v176, v149
	v_add_u32_e32 v164, v176, v137
	v_add_u32_e32 v168, v176, v136
	v_add_u32_e32 v172, v176, v135
	ds_read_b128 v[160:163], v160
	ds_read_b128 v[164:167], v164
	ds_read_b128 v[168:171], v168
	ds_read_b128 v[172:175], v172
	s_setprio 1
	v_mfma_f32_16x16x32_bf16 v[156:159], v[110:113], v[50:53], v[156:159]
	v_mfma_f32_16x16x32_bf16 v[110:113], v[110:113], v[82:85], v[138:141]
	v_mfma_f32_16x16x32_bf16 v[138:141], v[114:117], v[46:49], v[156:159]
	v_mfma_f32_16x16x32_bf16 v[110:113], v[114:117], v[78:81], v[110:113]
	v_mfma_f32_16x16x32_bf16 v[114:117], v[118:121], v[42:45], v[138:141]
	v_mfma_f32_16x16x32_bf16 v[110:113], v[118:121], v[74:77], v[110:113]
	v_mfma_f32_16x16x32_bf16 v[138:141], v[126:129], v[38:41], v[114:117]
	v_mfma_f32_16x16x32_bf16 v[110:113], v[126:129], v[70:73], v[110:113]
	s_setprio 0
	s_nop 3
	v_add_u32_e32 v114, v176, v150
	v_add_u32_e32 v118, v176, v151
	v_add_u32_e32 v126, v176, v152
	v_add_u32_e32 v156, v176, v153
	ds_read_b128 v[114:117], v114
	ds_read_b128 v[118:121], v118
	ds_read_b128 v[126:129], v126
	ds_read_b128 v[156:159], v156
	s_setprio 1
	s_waitcnt lgkmcnt(0)
	v_mfma_f32_16x16x32_bf16 v[176:179], v[160:163], v[66:69], 0
	v_mfma_f32_16x16x32_bf16 v[160:163], v[160:163], v[98:101], 0
	v_mfma_f32_16x16x32_bf16 v[176:179], v[164:167], v[62:65], v[176:179]
	v_mfma_f32_16x16x32_bf16 v[160:163], v[164:167], v[94:97], v[160:163]
	v_mfma_f32_16x16x32_bf16 v[164:167], v[168:171], v[58:61], v[176:179]
	v_mfma_f32_16x16x32_bf16 v[160:163], v[168:171], v[90:93], v[160:163]
	v_mfma_f32_16x16x32_bf16 v[164:167], v[172:175], v[54:57], v[164:167]
	v_mfma_f32_16x16x32_bf16 v[160:163], v[172:175], v[86:89], v[160:163]
	s_setprio 0
	v_add_u32_e32 v184, 0x18000, v134
	v_add_u32_e32 v168, v184, v149
	v_add_u32_e32 v172, v184, v137
	v_add_u32_e32 v176, v184, v136
	v_add_u32_e32 v180, v184, v135
	ds_read_b128 v[168:171], v168
	ds_read_b128 v[172:175], v172
	ds_read_b128 v[176:179], v176
	ds_read_b128 v[180:183], v180
	s_setprio 1
	v_mfma_f32_16x16x32_bf16 v[164:167], v[114:117], v[50:53], v[164:167]
	v_mfma_f32_16x16x32_bf16 v[114:117], v[114:117], v[82:85], v[160:163]
	v_mfma_f32_16x16x32_bf16 v[160:163], v[118:121], v[46:49], v[164:167]
	v_mfma_f32_16x16x32_bf16 v[114:117], v[118:121], v[78:81], v[114:117]
	v_mfma_f32_16x16x32_bf16 v[118:121], v[126:129], v[42:45], v[160:163]
	v_mfma_f32_16x16x32_bf16 v[114:117], v[126:129], v[74:77], v[114:117]
	v_mfma_f32_16x16x32_bf16 v[160:163], v[156:159], v[38:41], v[118:121]
	v_mfma_f32_16x16x32_bf16 v[114:117], v[156:159], v[70:73], v[114:117]
	s_setprio 0
	s_nop 3
	v_add_u32_e32 v118, v184, v150
	v_add_u32_e32 v126, v184, v151
	v_add_u32_e32 v156, v184, v152
	v_add_u32_e32 v164, v184, v153
	ds_read_b128 v[118:121], v118
	ds_read_b128 v[126:129], v126
	ds_read_b128 v[156:159], v156
	ds_read_b128 v[164:167], v164
	s_setprio 1
	s_waitcnt lgkmcnt(0)
	v_mfma_f32_16x16x32_bf16 v[184:187], v[168:171], v[66:69], 0
	v_mfma_f32_16x16x32_bf16 v[168:171], v[168:171], v[98:101], 0
	v_mfma_f32_16x16x32_bf16 v[184:187], v[172:175], v[62:65], v[184:187]
	v_mfma_f32_16x16x32_bf16 v[168:171], v[172:175], v[94:97], v[168:171]
	v_mfma_f32_16x16x32_bf16 v[172:175], v[176:179], v[58:61], v[184:187]
	v_mfma_f32_16x16x32_bf16 v[168:171], v[176:179], v[90:93], v[168:171]
	v_mfma_f32_16x16x32_bf16 v[172:175], v[180:183], v[54:57], v[172:175]
	v_mfma_f32_16x16x32_bf16 v[168:171], v[180:183], v[86:89], v[168:171]
	s_setprio 0
	v_add_u32_e32 v192, 0x1a000, v134
	v_add_u32_e32 v176, v192, v149
	v_add_u32_e32 v180, v192, v137
	v_add_u32_e32 v184, v192, v136
	v_add_u32_e32 v188, v192, v135
	ds_read_b128 v[176:179], v176
	ds_read_b128 v[180:183], v180
	ds_read_b128 v[184:187], v184
	ds_read_b128 v[188:191], v188
	s_setprio 1
	v_mfma_f32_16x16x32_bf16 v[172:175], v[118:121], v[50:53], v[172:175]
	v_mfma_f32_16x16x32_bf16 v[118:121], v[118:121], v[82:85], v[168:171]
	v_mfma_f32_16x16x32_bf16 v[168:171], v[126:129], v[46:49], v[172:175]
	v_mfma_f32_16x16x32_bf16 v[118:121], v[126:129], v[78:81], v[118:121]
	v_mfma_f32_16x16x32_bf16 v[126:129], v[156:159], v[42:45], v[168:171]
	v_mfma_f32_16x16x32_bf16 v[118:121], v[156:159], v[74:77], v[118:121]
	v_mfma_f32_16x16x32_bf16 v[156:159], v[164:167], v[38:41], v[126:129]
	v_mfma_f32_16x16x32_bf16 v[118:121], v[164:167], v[70:73], v[118:121]
	s_setprio 0
	s_nop 3
	v_add_u32_e32 v126, v192, v150
	v_add_u32_e32 v164, v192, v151
	v_add_u32_e32 v168, v192, v152
	v_add_u32_e32 v172, v192, v153
	ds_read_b128 v[126:129], v126
	ds_read_b128 v[164:167], v164
	ds_read_b128 v[168:171], v168
	ds_read_b128 v[172:175], v172
	s_setprio 1
	s_waitcnt lgkmcnt(0)
	v_mfma_f32_16x16x32_bf16 v[192:195], v[176:179], v[66:69], 0
	v_mfma_f32_16x16x32_bf16 v[176:179], v[176:179], v[98:101], 0
	v_mfma_f32_16x16x32_bf16 v[192:195], v[180:183], v[62:65], v[192:195]
	v_mfma_f32_16x16x32_bf16 v[176:179], v[180:183], v[94:97], v[176:179]
	v_mfma_f32_16x16x32_bf16 v[180:183], v[184:187], v[58:61], v[192:195]
	v_mfma_f32_16x16x32_bf16 v[176:179], v[184:187], v[90:93], v[176:179]
	v_mfma_f32_16x16x32_bf16 v[180:183], v[188:191], v[54:57], v[180:183]
	v_mfma_f32_16x16x32_bf16 v[176:179], v[188:191], v[86:89], v[176:179]
	s_setprio 0
	v_add_u32_e32 v200, 0x1c000, v134
	v_add_u32_e32 v184, v200, v149
	v_add_u32_e32 v188, v200, v137
	v_add_u32_e32 v192, v200, v136
	v_add_u32_e32 v196, v200, v135
	ds_read_b128 v[184:187], v184
	ds_read_b128 v[188:191], v188
	ds_read_b128 v[192:195], v192
	ds_read_b128 v[196:199], v196
	s_setprio 1
	v_mfma_f32_16x16x32_bf16 v[180:183], v[126:129], v[50:53], v[180:183]
	v_mfma_f32_16x16x32_bf16 v[126:129], v[126:129], v[82:85], v[176:179]
	v_mfma_f32_16x16x32_bf16 v[176:179], v[164:167], v[46:49], v[180:183]
	v_mfma_f32_16x16x32_bf16 v[126:129], v[164:167], v[78:81], v[126:129]
	v_mfma_f32_16x16x32_bf16 v[164:167], v[168:171], v[42:45], v[176:179]
	v_mfma_f32_16x16x32_bf16 v[126:129], v[168:171], v[74:77], v[126:129]
	v_mfma_f32_16x16x32_bf16 v[164:167], v[172:175], v[38:41], v[164:167]
	v_mfma_f32_16x16x32_bf16 v[126:129], v[172:175], v[70:73], v[126:129]
	s_setprio 0
	v_add_u32_e32 v168, v200, v150
	v_add_u32_e32 v172, v200, v151
	v_add_u32_e32 v176, v200, v152
	v_add_u32_e32 v180, v200, v153
	ds_read_b128 v[168:171], v168
	ds_read_b128 v[172:175], v172
	ds_read_b128 v[176:179], v176
	ds_read_b128 v[180:183], v180
	s_setprio 1
	s_waitcnt lgkmcnt(0)
	v_mfma_f32_16x16x32_bf16 v[200:203], v[184:187], v[66:69], 0
	v_mfma_f32_16x16x32_bf16 v[184:187], v[184:187], v[98:101], 0
	v_mfma_f32_16x16x32_bf16 v[200:203], v[188:191], v[62:65], v[200:203]
	v_mfma_f32_16x16x32_bf16 v[184:187], v[188:191], v[94:97], v[184:187]
	v_mfma_f32_16x16x32_bf16 v[188:191], v[192:195], v[58:61], v[200:203]
	v_mfma_f32_16x16x32_bf16 v[184:187], v[192:195], v[90:93], v[184:187]
	v_mfma_f32_16x16x32_bf16 v[188:191], v[196:199], v[54:57], v[188:191]
	v_mfma_f32_16x16x32_bf16 v[184:187], v[196:199], v[86:89], v[184:187]
	s_setprio 0
	v_add_u32_e32 v208, 0x1e000, v134
	v_add_u32_e32 v134, v208, v149
	v_add_u32_e32 v137, v208, v137
	ds_read_b128 v[192:195], v134
	ds_read_b128 v[196:199], v137
	v_add_u32_e32 v134, v208, v136
	v_add_u32_e32 v135, v208, v135
	ds_read_b128 v[200:203], v134
	ds_read_b128 v[204:207], v135
	s_setprio 1
	v_mfma_f32_16x16x32_bf16 v[134:137], v[168:171], v[50:53], v[188:191]
	v_mfma_f32_16x16x32_bf16 v[168:171], v[168:171], v[82:85], v[184:187]
	v_mfma_f32_16x16x32_bf16 v[134:137], v[172:175], v[46:49], v[134:137]
	v_mfma_f32_16x16x32_bf16 v[168:171], v[172:175], v[78:81], v[168:171]
	v_mfma_f32_16x16x32_bf16 v[134:137], v[176:179], v[42:45], v[134:137]
	v_mfma_f32_16x16x32_bf16 v[168:171], v[176:179], v[74:77], v[168:171]
	v_mfma_f32_16x16x32_bf16 v[172:175], v[180:183], v[38:41], v[134:137]
	v_mfma_f32_16x16x32_bf16 v[134:137], v[180:183], v[70:73], v[168:171]
	s_setprio 0
	v_add_u32_e32 v149, v208, v150
	v_add_u32_e32 v150, v208, v151
	s_nop 2
	ds_read_b128 v[168:171], v149
	ds_read_b128 v[176:179], v150
	v_add_u32_e32 v149, v208, v152
	v_add_u32_e32 v180, v208, v153
	ds_read_b128 v[150:153], v149
	ds_read_b128 v[180:183], v180
	s_setprio 1
	s_waitcnt lgkmcnt(0)
	v_mfma_f32_16x16x32_bf16 v[66:69], v[192:195], v[66:69], 0
	v_mfma_f32_16x16x32_bf16 v[98:101], v[192:195], v[98:101], 0
	v_mfma_f32_16x16x32_bf16 v[62:65], v[196:199], v[62:65], v[66:69]
	v_mfma_f32_16x16x32_bf16 v[66:69], v[196:199], v[94:97], v[98:101]
	v_mfma_f32_16x16x32_bf16 v[58:61], v[200:203], v[58:61], v[62:65]
	v_mfma_f32_16x16x32_bf16 v[62:65], v[200:203], v[90:93], v[66:69]
	v_mfma_f32_16x16x32_bf16 v[54:57], v[204:207], v[54:57], v[58:61]
	v_mfma_f32_16x16x32_bf16 v[58:61], v[204:207], v[86:89], v[62:65]
	s_setprio 0
	s_setprio 1
	v_mfma_f32_16x16x32_bf16 v[50:53], v[168:171], v[50:53], v[54:57]
	v_mfma_f32_16x16x32_bf16 v[54:57], v[168:171], v[82:85], v[58:61]
	v_mfma_f32_16x16x32_bf16 v[46:49], v[176:179], v[46:49], v[50:53]
	v_mfma_f32_16x16x32_bf16 v[50:53], v[176:179], v[78:81], v[54:57]
	v_mfma_f32_16x16x32_bf16 v[42:45], v[150:153], v[42:45], v[46:49]
	v_mfma_f32_16x16x32_bf16 v[46:49], v[150:153], v[74:77], v[50:53]
	v_mfma_f32_16x16x32_bf16 v[50:53], v[180:183], v[38:41], v[42:45]
	v_mfma_f32_16x16x32_bf16 v[66:69], v[180:183], v[70:73], v[46:49]
	s_setprio 0
	v_mul_f32_e32 v39, v148, v130
	v_mul_f32_e32 v38, v148, v122
	v_exp_f32_e32 v40, v39
	v_mul_f32_e32 v39, v148, v123
	v_mul_f32_e32 v42, v148, v124
	v_mul_f32_e32 v44, v148, v125
	v_exp_f32_e32 v38, v38
	v_exp_f32_e32 v39, v39
	v_mul_f32_e32 v41, v148, v131
	v_exp_f32_e32 v42, v42
	v_mul_f32_e32 v43, v148, v132
	v_exp_f32_e32 v44, v44
	v_mul_f32_e32 v45, v148, v133
	v_exp_f32_e32 v41, v41
	v_exp_f32_e32 v43, v43
	v_exp_f32_e32 v45, v45
	v_add_f32_e32 v46, v38, v39
	v_add_f32_e32 v47, v42, v44
	v_add_f32_e32 v46, v46, v47
	v_add_f32_e32 v47, v40, v41
	v_add_f32_e32 v48, v43, v45
	v_add_f32_e32 v47, v47, v48
	v_cvt_pk_bf16_f32 v40, v40, v41
	v_cvt_pk_bf16_f32 v41, v43, v45
	v_mul_f32_e32 v43, v148, v160
	v_add_f32_e32 v46, v46, v47
	v_cvt_pk_bf16_f32 v38, v38, v39
	v_cvt_pk_bf16_f32 v39, v42, v44
	v_mul_f32_e32 v42, v148, v138
	v_exp_f32_e32 v44, v43
	v_mul_f32_e32 v43, v148, v139
	v_mul_f32_e32 v47, v148, v140
	v_mul_f32_e32 v49, v148, v141
	v_exp_f32_e32 v42, v42
	v_exp_f32_e32 v43, v43
	v_mul_f32_e32 v45, v148, v161
	v_exp_f32_e32 v47, v47
	v_mul_f32_e32 v48, v148, v162
	v_exp_f32_e32 v49, v49
	v_mul_f32_e32 v54, v148, v163
	v_exp_f32_e32 v45, v45
	v_exp_f32_e32 v48, v48
	v_exp_f32_e32 v54, v54
	v_add_f32_e32 v55, v42, v43
	v_add_f32_e32 v56, v47, v49
	v_add_f32_e32 v55, v55, v56
	v_add_f32_e32 v56, v44, v45
	v_add_f32_e32 v57, v48, v54
	v_add_f32_e32 v56, v56, v57
	v_add_f32_e32 v46, v155, v46
	v_add_f32_e32 v55, v55, v56
	v_add_f32_e32 v46, v46, v55
	v_cvt_pk_bf16_f32 v42, v42, v43
	v_cvt_pk_bf16_f32 v43, v47, v49
	v_mul_f32_e32 v47, v148, v156
	v_mul_f32_e32 v49, v148, v157
	v_mul_f32_e32 v55, v148, v158
	v_mul_f32_e32 v57, v148, v159
	v_cvt_pk_bf16_f32 v44, v44, v45
	v_cvt_pk_bf16_f32 v45, v48, v54
	v_exp_f32_e32 v47, v47
	v_mul_f32_e32 v48, v148, v164
	v_exp_f32_e32 v49, v49
	v_mul_f32_e32 v54, v148, v165
	v_exp_f32_e32 v55, v55
	v_mul_f32_e32 v56, v148, v166
	v_exp_f32_e32 v57, v57
	v_mul_f32_e32 v58, v148, v167
	v_exp_f32_e32 v48, v48
	v_exp_f32_e32 v54, v54
	v_exp_f32_e32 v56, v56
	v_exp_f32_e32 v58, v58
	v_add_f32_e32 v59, v47, v49
	v_add_f32_e32 v60, v55, v57
	v_add_f32_e32 v59, v59, v60
	v_add_f32_e32 v60, v48, v54
	v_add_f32_e32 v61, v56, v58
	v_add_f32_e32 v60, v60, v61
	v_add_f32_e32 v59, v59, v60
	v_mul_f32_e32 v50, v148, v50
	v_mul_f32_e32 v51, v148, v51
	v_mul_f32_e32 v52, v148, v52
	v_add_f32_e32 v59, v46, v59
	v_cvt_pk_bf16_f32 v46, v47, v49
	v_cvt_pk_bf16_f32 v47, v55, v57
	v_cvt_pk_bf16_f32 v48, v48, v54
	v_cvt_pk_bf16_f32 v49, v56, v58
	v_mul_f32_e32 v54, v148, v172
	v_exp_f32_e32 v55, v50
	v_mul_f32_e32 v50, v148, v173
	v_exp_f32_e32 v56, v51
	v_mul_f32_e32 v51, v148, v174
	v_exp_f32_e32 v57, v52
	v_mul_f32_e32 v52, v148, v175
	v_exp_f32_e32 v54, v54
	v_exp_f32_e32 v50, v50
	v_exp_f32_e32 v51, v51
	v_exp_f32_e32 v52, v52
	v_mul_f32_e32 v53, v148, v53
	v_exp_f32_e32 v53, v53
	v_add_f32_e32 v58, v54, v50
	v_add_f32_e32 v60, v51, v52
	v_add_f32_e32 v58, v58, v60
	v_add_f32_e32 v60, v55, v56
	v_add_f32_e32 v61, v57, v53
	v_add_f32_e32 v60, v60, v61
	v_add_f32_e32 v58, v58, v60
	v_cvt_pk_bf16_f32 v51, v51, v52
	v_cvt_pk_bf16_f32 v52, v55, v56
	v_mul_f32_e32 v55, v147, v106
	v_add_f32_e32 v74, v59, v58
	v_cvt_pk_bf16_f32 v50, v54, v50
	v_mul_f32_e32 v54, v147, v102
	v_exp_f32_e32 v56, v55
	v_mul_f32_e32 v55, v147, v103
	v_mul_f32_e32 v58, v147, v104
	v_mul_f32_e32 v60, v147, v105
	v_cvt_pk_bf16_f32 v53, v57, v53
	v_exp_f32_e32 v54, v54
	v_exp_f32_e32 v55, v55
	v_mul_f32_e32 v57, v147, v107
	v_exp_f32_e32 v58, v58
	v_mul_f32_e32 v59, v147, v108
	v_exp_f32_e32 v60, v60
	v_mul_f32_e32 v61, v147, v109
	v_exp_f32_e32 v57, v57
	v_exp_f32_e32 v59, v59
	v_exp_f32_e32 v61, v61
	v_add_f32_e32 v62, v54, v55
	v_add_f32_e32 v63, v58, v60
	v_add_f32_e32 v62, v62, v63
	v_add_f32_e32 v63, v56, v57
	v_add_f32_e32 v64, v59, v61
	v_add_f32_e32 v63, v63, v64
	v_cvt_pk_bf16_f32 v56, v56, v57
	v_cvt_pk_bf16_f32 v57, v59, v61
	v_mul_f32_e32 v59, v147, v114
	v_add_f32_e32 v62, v62, v63
	v_cvt_pk_bf16_f32 v54, v54, v55
	v_cvt_pk_bf16_f32 v55, v58, v60
	v_mul_f32_e32 v58, v147, v110
	v_exp_f32_e32 v60, v59
	v_mul_f32_e32 v59, v147, v111
	v_mul_f32_e32 v63, v147, v112
	v_mul_f32_e32 v65, v147, v113
	v_exp_f32_e32 v58, v58
	v_exp_f32_e32 v59, v59
	v_mul_f32_e32 v61, v147, v115
	v_exp_f32_e32 v63, v63
	v_mul_f32_e32 v64, v147, v116
	v_exp_f32_e32 v65, v65
	v_mul_f32_e32 v70, v147, v117
	v_exp_f32_e32 v61, v61
	v_exp_f32_e32 v64, v64
	v_exp_f32_e32 v70, v70
	v_add_f32_e32 v71, v58, v59
	v_add_f32_e32 v72, v63, v65
	v_add_f32_e32 v71, v71, v72
	v_add_f32_e32 v72, v60, v61
	v_add_f32_e32 v73, v64, v70
	v_add_f32_e32 v72, v72, v73
	v_add_f32_e32 v62, v154, v62
	v_add_f32_e32 v71, v71, v72
	v_add_f32_e32 v62, v62, v71
	v_cvt_pk_bf16_f32 v58, v58, v59
	v_cvt_pk_bf16_f32 v59, v63, v65
	v_mul_f32_e32 v63, v147, v118
	v_mul_f32_e32 v65, v147, v119
	v_mul_f32_e32 v71, v147, v120
	v_mul_f32_e32 v73, v147, v121
	v_cvt_pk_bf16_f32 v60, v60, v61
	v_cvt_pk_bf16_f32 v61, v64, v70
	v_exp_f32_e32 v63, v63
	v_mul_f32_e32 v64, v147, v126
	v_exp_f32_e32 v65, v65
	v_mul_f32_e32 v70, v147, v127
	v_exp_f32_e32 v71, v71
	v_mul_f32_e32 v72, v147, v128
	v_exp_f32_e32 v73, v73
	v_mul_f32_e32 v75, v147, v129
	v_exp_f32_e32 v64, v64
	v_exp_f32_e32 v70, v70
	v_exp_f32_e32 v72, v72
	v_exp_f32_e32 v75, v75
	v_add_f32_e32 v76, v63, v65
	v_add_f32_e32 v77, v71, v73
	v_add_f32_e32 v76, v76, v77
	v_add_f32_e32 v77, v64, v70
	v_add_f32_e32 v78, v72, v75
	v_add_f32_e32 v77, v77, v78
	v_add_f32_e32 v76, v76, v77
	v_mul_f32_e32 v66, v147, v66
	v_mul_f32_e32 v67, v147, v67
	v_mul_f32_e32 v68, v147, v68
	v_add_f32_e32 v76, v62, v76
	v_cvt_pk_bf16_f32 v62, v63, v65
	v_cvt_pk_bf16_f32 v63, v71, v73
	v_cvt_pk_bf16_f32 v64, v64, v70
	v_cvt_pk_bf16_f32 v65, v72, v75
	v_mul_f32_e32 v70, v147, v134
	v_exp_f32_e32 v71, v66
	v_mul_f32_e32 v66, v147, v135
	v_exp_f32_e32 v72, v67
	v_mul_f32_e32 v67, v147, v136
	v_exp_f32_e32 v73, v68
	v_mul_f32_e32 v68, v147, v137
	v_exp_f32_e32 v70, v70
	v_exp_f32_e32 v66, v66
	v_exp_f32_e32 v67, v67
	v_exp_f32_e32 v68, v68
	v_mul_f32_e32 v69, v147, v69
	v_exp_f32_e32 v69, v69
	v_add_f32_e32 v75, v70, v66
	v_add_f32_e32 v77, v67, v68
	v_add_f32_e32 v75, v75, v77
	v_add_f32_e32 v77, v71, v72
	v_add_f32_e32 v78, v73, v69
	v_add_f32_e32 v77, v77, v78
	v_add_f32_e32 v75, v75, v77
	v_add_f32_e32 v75, v76, v75
	s_waitcnt vmcnt(0)
	s_barrier
	s_add_i32 s9, s8, 64
	v_ashrrev_i32_e32 v76, 5, v5
	v_cvt_pk_bf16_f32 v66, v70, v66
	v_lshl_add_u32 v70, s9, 1, v76
	v_cvt_pk_bf16_f32 v67, v67, v68
	v_cvt_pk_bf16_f32 v68, v71, v72
	v_lshrrev_b32_e32 v71, 1, v70
	v_and_b32_e32 v5, 31, v5
	v_and_b32_e32 v71, 12, v71
	v_and_b32_e32 v77, 3, v76
	v_bitop3_b32 v72, v71, v5, v77 bitop3:0x36
	v_ashrrev_i32_e32 v71, 31, v70
	v_lshlrev_b64 v[70:71], 9, v[70:71]
	v_cvt_pk_bf16_f32 v69, v73, v69
	v_lshl_add_u64 v[70:71], s[4:5], 0, v[70:71]
	v_lshlrev_b32_e32 v72, 4, v72
	v_mov_b32_e32 v73, v4
	s_lshl_b32 s9, s9, 10
	v_lshl_add_u64 v[70:71], v[70:71], 0, v[72:73]
	s_add_i32 m0, s9, 0
	s_add_i32 s9, s8, 0x41
	global_load_lds_dwordx4 v[70:71], off
	v_lshl_add_u32 v70, s9, 1, v76
	v_lshrrev_b32_e32 v71, 1, v70
	v_and_b32_e32 v71, 12, v71
	v_and_b32_e32 v72, 3, v70
	v_bitop3_b32 v72, v71, v5, v72 bitop3:0x36
	v_ashrrev_i32_e32 v71, 31, v70
	v_lshlrev_b64 v[70:71], 9, v[70:71]
	v_lshl_add_u64 v[70:71], s[4:5], 0, v[70:71]
	v_lshlrev_b32_e32 v72, 4, v72
	s_lshl_b32 s9, s9, 10
	v_lshl_add_u64 v[70:71], v[70:71], 0, v[72:73]
	s_add_i32 m0, s9, 0
	s_add_i32 s9, s8, 0x42
	global_load_lds_dwordx4 v[70:71], off
	v_lshl_add_u32 v70, s9, 1, v76
	v_lshrrev_b32_e32 v71, 1, v70
	v_and_b32_e32 v71, 12, v71
	v_bitop3_b32 v72, v71, v5, v77 bitop3:0x36
	v_ashrrev_i32_e32 v71, 31, v70
	v_lshlrev_b64 v[70:71], 9, v[70:71]
	v_lshl_add_u64 v[70:71], s[4:5], 0, v[70:71]
	v_lshlrev_b32_e32 v72, 4, v72
	s_lshl_b32 s9, s9, 10
	v_lshl_add_u64 v[70:71], v[70:71], 0, v[72:73]
	s_add_i32 m0, s9, 0
	s_add_i32 s9, s8, 0x43
	global_load_lds_dwordx4 v[70:71], off
	v_lshl_add_u32 v70, s9, 1, v76
	v_lshrrev_b32_e32 v71, 1, v70
	v_and_b32_e32 v71, 12, v71
	v_and_b32_e32 v72, 3, v70
	v_bitop3_b32 v72, v71, v5, v72 bitop3:0x36
	v_ashrrev_i32_e32 v71, 31, v70
	v_lshlrev_b64 v[70:71], 9, v[70:71]
	v_lshl_add_u64 v[70:71], s[4:5], 0, v[70:71]
	v_lshlrev_b32_e32 v72, 4, v72
	s_lshl_b32 s9, s9, 10
	v_lshl_add_u64 v[70:71], v[70:71], 0, v[72:73]
	s_add_i32 m0, s9, 0
	s_add_i32 s9, s8, 0x44
	global_load_lds_dwordx4 v[70:71], off
	v_lshl_add_u32 v70, s9, 1, v76
	v_lshrrev_b32_e32 v71, 1, v70
	v_and_b32_e32 v71, 12, v71
	v_bitop3_b32 v72, v71, v5, v77 bitop3:0x36
	v_ashrrev_i32_e32 v71, 31, v70
	v_lshlrev_b64 v[70:71], 9, v[70:71]
	v_lshl_add_u64 v[70:71], s[4:5], 0, v[70:71]
	v_lshlrev_b32_e32 v72, 4, v72
	s_lshl_b32 s9, s9, 10
	v_lshl_add_u64 v[70:71], v[70:71], 0, v[72:73]
	s_add_i32 m0, s9, 0
	s_add_i32 s9, s8, 0x45
	global_load_lds_dwordx4 v[70:71], off
	v_lshl_add_u32 v70, s9, 1, v76
	v_lshrrev_b32_e32 v71, 1, v70
	v_and_b32_e32 v71, 12, v71
	v_and_b32_e32 v72, 3, v70
	v_bitop3_b32 v72, v71, v5, v72 bitop3:0x36
	v_ashrrev_i32_e32 v71, 31, v70
	v_lshlrev_b64 v[70:71], 9, v[70:71]
	v_lshl_add_u64 v[70:71], s[4:5], 0, v[70:71]
	v_lshlrev_b32_e32 v72, 4, v72
	s_lshl_b32 s9, s9, 10
	v_lshl_add_u64 v[70:71], v[70:71], 0, v[72:73]
	s_add_i32 m0, s9, 0
	s_add_i32 s9, s8, 0x46
	global_load_lds_dwordx4 v[70:71], off
	v_lshl_add_u32 v70, s9, 1, v76
	v_lshrrev_b32_e32 v71, 1, v70
	v_and_b32_e32 v71, 12, v71
	v_bitop3_b32 v72, v71, v5, v77 bitop3:0x36
	v_ashrrev_i32_e32 v71, 31, v70
	v_lshlrev_b64 v[70:71], 9, v[70:71]
	v_lshl_add_u64 v[70:71], s[4:5], 0, v[70:71]
	v_lshlrev_b32_e32 v72, 4, v72
	s_lshl_b32 s9, s9, 10
	v_lshl_add_u64 v[70:71], v[70:71], 0, v[72:73]
	s_add_i32 m0, s9, 0
	s_addk_i32 s8, 0x47
	global_load_lds_dwordx4 v[70:71], off
	v_lshl_add_u32 v70, s8, 1, v76
	v_lshrrev_b32_e32 v71, 1, v70
	v_and_b32_e32 v71, 12, v71
	v_and_b32_e32 v72, 3, v70
	v_bitop3_b32 v5, v71, v5, v72 bitop3:0x36
	v_ashrrev_i32_e32 v71, 31, v70
	v_lshlrev_b64 v[70:71], 9, v[70:71]
	v_lshl_add_u64 v[70:71], s[4:5], 0, v[70:71]
	v_lshlrev_b32_e32 v72, 4, v5
	s_lshl_b32 s4, s8, 10
	v_lshl_add_u64 v[70:71], v[70:71], 0, v[72:73]
	s_add_i32 m0, s4, 0
	v_mov_b32_e32 v5, v74
	global_load_lds_dwordx4 v[70:71], off
	s_nop 0
	v_permlane16_swap_b32_e32 v74, v5
	v_add_f32_e32 v5, v74, v5
	v_mov_b32_e32 v70, v5
	s_nop 1
	v_permlane32_swap_b32_e32 v5, v70
	v_add_f32_e32 v5, v5, v70
	v_div_scale_f32 v70, s[4:5], v5, v5, 1.0
	v_rcp_f32_e32 v71, v70
	v_lshl_add_u64 v[2:3], s[2:3], 0, v[2:3]
	v_bfe_u32 v87, v145, 5, 1
	v_lshl_add_u64 v[2:3], v[2:3], 0, s[6:7]
	v_fma_f32 v72, -v70, v71, 1.0
	v_fmac_f32_e32 v71, v72, v71
	v_div_scale_f32 v72, vcc, 1.0, v5, 1.0
	v_mul_f32_e32 v73, v72, v71
	v_fma_f32 v74, -v70, v73, v72
	v_fmac_f32_e32 v73, v74, v71
	v_fma_f32 v70, -v70, v73, v72
	v_div_fmas_f32 v70, v70, v71, v73
	v_div_fixup_f32 v5, v70, v5, 1.0
	v_mov_b32_e32 v70, v75
	s_nop 1
	v_permlane16_swap_b32_e32 v75, v70
	v_add_f32_e32 v70, v75, v70
	v_mov_b32_e32 v71, v70
	s_nop 1
	v_permlane32_swap_b32_e32 v70, v71
	v_add_f32_e32 v70, v70, v71
	v_div_scale_f32 v71, s[4:5], v70, v70, 1.0
	v_rcp_f32_e32 v72, v71
	v_bitop3_b32 v76, v87, v144, 8 bitop3:0x36
	v_bitop3_b32 v77, v87, v144, 10 bitop3:0x36
	v_bitop3_b32 v78, v87, v144, 12 bitop3:0x36
	v_fma_f32 v73, -v71, v72, 1.0
	v_fmac_f32_e32 v72, v73, v72
	v_div_scale_f32 v73, vcc, 1.0, v70, 1.0
	v_mul_f32_e32 v74, v73, v72
	v_fma_f32 v75, -v71, v74, v73
	v_fmac_f32_e32 v74, v75, v72
	v_fma_f32 v71, -v71, v74, v73
	v_div_fmas_f32 v71, v71, v72, v74
	v_lshlrev_b32_e32 v72, 1, v145
	v_and_b32_e32 v73, 3, v145
	v_and_or_b32 v72, v72, 24, v73
	v_and_b32_e32 v73, 8, v146
	v_lshlrev_b32_e32 v72, 9, v72
	v_add3_u32 v146, 0, v73, v72
	v_bitop3_b32 v72, v87, v145, 15 bitop3:0x78
	v_bitop3_b32 v73, v87, v144, 2 bitop3:0x36
	v_bitop3_b32 v74, v87, v144, 4 bitop3:0x36
	v_bitop3_b32 v75, v87, v144, 6 bitop3:0x36
	v_bitop3_b32 v79, v87, v144, 14 bitop3:0x36
	v_bitop3_b32 v80, v87, v144, 16 bitop3:0x36
	v_bitop3_b32 v81, v87, v144, 18 bitop3:0x36
	v_bitop3_b32 v82, v87, v144, 20 bitop3:0x36
	v_bitop3_b32 v83, v87, v144, 22 bitop3:0x36
	v_bitop3_b32 v84, v87, v144, 24 bitop3:0x36
	v_bitop3_b32 v85, v87, v144, 26 bitop3:0x36
	v_bitop3_b32 v86, v87, v144, 28 bitop3:0x36
	v_bitop3_b32 v87, v87, v144, 30 bitop3:0x36
	v_div_fixup_f32 v136, v71, v70, 1.0
	v_lshl_add_u64 v[70:71], v[2:3], 0, v[142:143]
	v_lshlrev_b32_e32 v149, 4, v72
	v_lshlrev_b32_e32 v151, 4, v73
	v_lshlrev_b32_e32 v153, 4, v74
	v_lshlrev_b32_e32 v154, 4, v75
	v_lshlrev_b32_e32 v143, 4, v76
	v_lshlrev_b32_e32 v147, 4, v77
	v_lshlrev_b32_e32 v150, 4, v78
	v_lshlrev_b32_e32 v152, 4, v79
	v_lshlrev_b32_e32 v139, 4, v80
	v_lshlrev_b32_e32 v141, 4, v81
	v_lshlrev_b32_e32 v145, 4, v82
	v_lshlrev_b32_e32 v148, 4, v83
	v_lshlrev_b32_e32 v137, 4, v84
	v_lshlrev_b32_e32 v138, 4, v85
	v_lshlrev_b32_e32 v140, 4, v86
	v_lshlrev_b32_e32 v142, 4, v87
	v_add_u32_e32 v72, v146, v149
	v_add_u32_e32 v73, v146, v151
	v_add_u32_e32 v74, v146, v153
	v_add_u32_e32 v75, v146, v154
	v_add_u32_e32 v76, v146, v143
	v_add_u32_e32 v77, v146, v147
	v_add_u32_e32 v78, v146, v150
	v_add_u32_e32 v79, v146, v152
	v_add_u32_e32 v80, v146, v139
	v_add_u32_e32 v81, v146, v141
	v_add_u32_e32 v82, v146, v145
	v_add_u32_e32 v83, v146, v148
	v_add_u32_e32 v84, v146, v137
	v_add_u32_e32 v85, v146, v138
	v_add_u32_e32 v86, v146, v140
	v_add_u32_e32 v87, v146, v142
	s_waitcnt vmcnt(8)
	s_waitcnt vmcnt(0) lgkmcnt(0)
	s_barrier
	ds_read2st64_b64 v[88:91], v72 offset1:4
	ds_read2st64_b64 v[92:95], v73 offset1:4
	ds_read2st64_b64 v[96:99], v74 offset1:4
	ds_read2st64_b64 v[100:103], v75 offset1:4
	ds_read2st64_b64 v[104:107], v76 offset1:4
	ds_read2st64_b64 v[108:111], v77 offset1:4
	ds_read2st64_b64 v[112:115], v78 offset1:4
	ds_read2st64_b64 v[116:119], v79 offset1:4
	ds_read2st64_b64 v[120:123], v80 offset1:4
	ds_read2st64_b64 v[124:127], v81 offset1:4
	ds_read2st64_b64 v[128:131], v82 offset1:4
	ds_read2st64_b64 v[132:135], v83 offset1:4
	ds_read2st64_b64 v[156:159], v84 offset1:4
	ds_read2st64_b64 v[160:163], v85 offset1:4
	ds_read2st64_b64 v[164:167], v86 offset1:4
	ds_read2st64_b64 v[168:171], v87 offset1:4
	s_mov_b64 s[2:3], 0xae00000
	v_lshl_add_u64 v[2:3], v[70:71], 0, s[2:3]
	s_setprio 1
	s_waitcnt lgkmcnt(14)
	v_mov_b32_e32 v172, v88
	v_mov_b32_e32 v173, v89
	v_mov_b32_e32 v174, v92
	v_mov_b32_e32 v175, v93
	s_waitcnt lgkmcnt(13)
	v_mov_b32_e32 v180, v96
	v_mov_b32_e32 v181, v97
	s_waitcnt lgkmcnt(12)
	v_mov_b32_e32 v182, v100
	v_mov_b32_e32 v183, v101
	v_mfma_f32_16x16x32_bf16 v[176:179], v[172:175], v[6:9], 0
	v_mfma_f32_16x16x32_bf16 v[172:175], v[172:175], v[22:25], 0
	v_mfma_f32_16x16x32_bf16 v[176:179], v[180:183], v[10:13], v[176:179]
	v_mfma_f32_16x16x32_bf16 v[172:175], v[180:183], v[26:29], v[172:175]
	s_waitcnt lgkmcnt(11)
	v_mov_b32_e32 v180, v104
	v_mov_b32_e32 v181, v105
	s_waitcnt lgkmcnt(10)
	v_mov_b32_e32 v182, v108
	v_mov_b32_e32 v183, v109
	s_nop 1
	v_mfma_f32_16x16x32_bf16 v[176:179], v[180:183], v[14:17], v[176:179]
	v_mfma_f32_16x16x32_bf16 v[172:175], v[180:183], v[30:33], v[172:175]
	s_waitcnt lgkmcnt(9)
	v_mov_b32_e32 v180, v112
	v_mov_b32_e32 v181, v113
	s_waitcnt lgkmcnt(8)
	v_mov_b32_e32 v182, v116
	v_mov_b32_e32 v183, v117
	s_nop 1
	v_mfma_f32_16x16x32_bf16 v[176:179], v[180:183], v[18:21], v[176:179]
	v_mfma_f32_16x16x32_bf16 v[172:175], v[180:183], v[34:37], v[172:175]
	s_waitcnt lgkmcnt(7)
	v_mov_b32_e32 v180, v120
	v_mov_b32_e32 v181, v121
	s_waitcnt lgkmcnt(6)
	v_mov_b32_e32 v182, v124
	v_mov_b32_e32 v183, v125
	s_nop 1
	v_mfma_f32_16x16x32_bf16 v[176:179], v[180:183], v[38:41], v[176:179]
	v_mfma_f32_16x16x32_bf16 v[172:175], v[180:183], v[54:57], v[172:175]
	s_waitcnt lgkmcnt(5)
	v_mov_b32_e32 v180, v128
	v_mov_b32_e32 v181, v129
	s_waitcnt lgkmcnt(4)
	v_mov_b32_e32 v182, v132
	v_mov_b32_e32 v183, v133
	s_nop 1
	v_mfma_f32_16x16x32_bf16 v[176:179], v[180:183], v[42:45], v[176:179]
	v_mfma_f32_16x16x32_bf16 v[172:175], v[180:183], v[58:61], v[172:175]
	s_waitcnt lgkmcnt(3)
	v_mov_b32_e32 v180, v156
	v_mov_b32_e32 v181, v157
	s_waitcnt lgkmcnt(2)
	v_mov_b32_e32 v182, v160
	v_mov_b32_e32 v183, v161
	s_nop 1
	v_mfma_f32_16x16x32_bf16 v[176:179], v[180:183], v[46:49], v[176:179]
	v_mfma_f32_16x16x32_bf16 v[172:175], v[180:183], v[62:65], v[172:175]
	s_waitcnt lgkmcnt(1)
	v_mov_b32_e32 v180, v164
	v_mov_b32_e32 v181, v165
	s_waitcnt lgkmcnt(0)
	v_mov_b32_e32 v182, v168
	v_mov_b32_e32 v183, v169
	s_nop 1
	v_mfma_f32_16x16x32_bf16 v[176:179], v[180:183], v[50:53], v[176:179]
	v_mfma_f32_16x16x32_bf16 v[172:175], v[180:183], v[66:69], v[172:175]
	s_setprio 0
	s_nop 5
	v_mul_f32_e32 v88, v5, v176
	v_mul_f32_e32 v89, v5, v177
	v_cvt_pk_bf16_f32 v88, v88, v89
	v_mul_f32_e32 v89, v5, v178
	v_mul_f32_e32 v92, v5, v179
	v_cvt_pk_bf16_f32 v89, v89, v92
	v_mul_f32_e32 v92, v136, v172
	v_mul_f32_e32 v93, v136, v173
	v_cvt_pk_bf16_f32 v96, v92, v93
	v_mul_f32_e32 v92, v136, v174
	v_mul_f32_e32 v93, v136, v175
	ds_read_b64 v[172:173], v72 offset:16384
	ds_read_b64 v[174:175], v73 offset:16384
	ds_read_b64 v[176:177], v74 offset:16384
	ds_read_b64 v[178:179], v75 offset:16384
	ds_read_b64 v[180:181], v76 offset:16384
	ds_read_b64 v[182:183], v77 offset:16384
	ds_read_b64 v[184:185], v78 offset:16384
	ds_read_b64 v[186:187], v79 offset:16384
	ds_read_b64 v[188:189], v80 offset:16384
	ds_read_b64 v[190:191], v81 offset:16384
	ds_read_b64 v[192:193], v82 offset:16384
	ds_read_b64 v[194:195], v83 offset:16384
	ds_read_b64 v[196:197], v84 offset:16384
	ds_read_b64 v[198:199], v85 offset:16384
	ds_read_b64 v[200:201], v86 offset:16384
	ds_read_b64 v[202:203], v87 offset:16384
	v_cvt_pk_bf16_f32 v97, v92, v93
	s_setprio 1
	v_mov_b32_e32 v92, v90
	v_mov_b32_e32 v93, v91
	v_mov_b32_e32 v100, v98
	v_mov_b32_e32 v101, v99
	v_mov_b32_e32 v108, v106
	v_mfma_f32_16x16x32_bf16 v[204:207], v[92:95], v[6:9], 0
	v_mov_b32_e32 v109, v107
	v_mov_b32_e32 v116, v114
	v_mov_b32_e32 v117, v115
	v_mfma_f32_16x16x32_bf16 v[90:93], v[92:95], v[22:25], 0
	v_mov_b32_e32 v124, v122
	v_mov_b32_e32 v125, v123
	v_mov_b32_e32 v132, v130
	v_mfma_f32_16x16x32_bf16 v[204:207], v[100:103], v[10:13], v[204:207]
	v_mov_b32_e32 v133, v131
	v_mov_b32_e32 v160, v158
	v_mov_b32_e32 v161, v159
	v_mfma_f32_16x16x32_bf16 v[90:93], v[100:103], v[26:29], v[90:93]
	v_mov_b32_e32 v168, v166
	v_mov_b32_e32 v169, v167
	v_mfma_f32_16x16x32_bf16 v[98:101], v[108:111], v[14:17], v[204:207]
	v_mfma_f32_16x16x32_bf16 v[90:93], v[108:111], v[30:33], v[90:93]
	v_mfma_f32_16x16x32_bf16 v[98:101], v[116:119], v[18:21], v[98:101]
	v_mfma_f32_16x16x32_bf16 v[90:93], v[116:119], v[34:37], v[90:93]
	v_mfma_f32_16x16x32_bf16 v[98:101], v[124:127], v[38:41], v[98:101]
	v_mfma_f32_16x16x32_bf16 v[90:93], v[124:127], v[54:57], v[90:93]
	v_mfma_f32_16x16x32_bf16 v[98:101], v[132:135], v[42:45], v[98:101]
	v_mfma_f32_16x16x32_bf16 v[90:93], v[132:135], v[58:61], v[90:93]
	v_mfma_f32_16x16x32_bf16 v[98:101], v[160:163], v[46:49], v[98:101]
	v_mfma_f32_16x16x32_bf16 v[90:93], v[160:163], v[62:65], v[90:93]
	v_mfma_f32_16x16x32_bf16 v[98:101], v[168:171], v[50:53], v[98:101]
	v_mfma_f32_16x16x32_bf16 v[92:95], v[168:171], v[66:69], v[90:93]
	s_setprio 0
	s_nop 5
	v_mul_f32_e32 v90, v5, v98
	v_mul_f32_e32 v91, v5, v99
	v_cvt_pk_bf16_f32 v90, v90, v91
	v_mul_f32_e32 v91, v5, v100
	v_mul_f32_e32 v98, v5, v101
	v_mul_f32_e32 v92, v136, v92
	v_cvt_pk_bf16_f32 v91, v91, v98
	v_mul_f32_e32 v93, v136, v93
	v_cvt_pk_bf16_f32 v98, v92, v93
	v_mul_f32_e32 v92, v136, v94
	s_mov_b32 s2, 0xae00000
	v_mul_f32_e32 v93, v136, v95
	v_cvt_pk_bf16_f32 v99, v92, v93
	v_add_co_u32_e32 v92, vcc, s2, v70
	s_mov_b32 s2, 0xae08000
	s_nop 0
	v_addc_co_u32_e32 v93, vcc, 0, v71, vcc
	v_add_co_u32_e32 v134, vcc, s2, v70
	global_store_dwordx4 v[92:93], v[88:91], off
	s_nop 0
	v_addc_co_u32_e32 v135, vcc, 0, v71, vcc
	global_store_dwordx4 v[134:135], v[96:99], off
	ds_read_b64 v[88:89], v72 offset:18432
	ds_read_b64 v[90:91], v73 offset:18432
	ds_read_b64 v[92:93], v74 offset:18432
	ds_read_b64 v[94:95], v75 offset:18432
	ds_read_b64 v[96:97], v76 offset:18432
	ds_read_b64 v[98:99], v77 offset:18432
	ds_read_b64 v[100:101], v78 offset:18432
	ds_read_b64 v[102:103], v79 offset:18432
	ds_read_b64 v[104:105], v80 offset:18432
	ds_read_b64 v[106:107], v81 offset:18432
	ds_read_b64 v[108:109], v82 offset:18432
	ds_read_b64 v[110:111], v83 offset:18432
	ds_read_b64 v[112:113], v84 offset:18432
	ds_read_b64 v[114:115], v85 offset:18432
	ds_read_b64 v[116:117], v86 offset:18432
	ds_read_b64 v[118:119], v87 offset:18432
	s_setprio 1
	s_waitcnt lgkmcnt(14)
	v_mfma_f32_16x16x32_bf16 v[120:123], v[172:175], v[6:9], 0
	v_mfma_f32_16x16x32_bf16 v[124:127], v[172:175], v[22:25], 0
	v_mfma_f32_16x16x32_bf16 v[120:123], v[176:179], v[10:13], v[120:123]
	v_mfma_f32_16x16x32_bf16 v[124:127], v[176:179], v[26:29], v[124:127]
	v_mfma_f32_16x16x32_bf16 v[120:123], v[180:183], v[14:17], v[120:123]
	v_mfma_f32_16x16x32_bf16 v[124:127], v[180:183], v[30:33], v[124:127]
	v_mfma_f32_16x16x32_bf16 v[120:123], v[184:187], v[18:21], v[120:123]
	v_mfma_f32_16x16x32_bf16 v[124:127], v[184:187], v[34:37], v[124:127]
	v_mfma_f32_16x16x32_bf16 v[120:123], v[188:191], v[38:41], v[120:123]
	v_mfma_f32_16x16x32_bf16 v[124:127], v[188:191], v[54:57], v[124:127]
	v_mfma_f32_16x16x32_bf16 v[120:123], v[192:195], v[42:45], v[120:123]
	v_mfma_f32_16x16x32_bf16 v[124:127], v[192:195], v[58:61], v[124:127]
	v_mfma_f32_16x16x32_bf16 v[120:123], v[196:199], v[46:49], v[120:123]
	v_mfma_f32_16x16x32_bf16 v[124:127], v[196:199], v[62:65], v[124:127]
	v_mfma_f32_16x16x32_bf16 v[120:123], v[200:203], v[50:53], v[120:123]
	v_mfma_f32_16x16x32_bf16 v[124:127], v[200:203], v[66:69], v[124:127]
	s_setprio 0
	ds_read_b64 v[128:129], v72 offset:32768
	ds_read_b64 v[130:131], v73 offset:32768
	ds_read_b64 v[156:157], v74 offset:32768
	ds_read_b64 v[158:159], v75 offset:32768
	ds_read_b64 v[160:161], v76 offset:32768
	ds_read_b64 v[162:163], v77 offset:32768
	ds_read_b64 v[164:165], v78 offset:32768
	ds_read_b64 v[166:167], v79 offset:32768
	ds_read_b64 v[168:169], v80 offset:32768
	ds_read_b64 v[170:171], v81 offset:32768
	ds_read_b64 v[172:173], v82 offset:32768
	ds_read_b64 v[174:175], v83 offset:32768
	ds_read_b64 v[176:177], v84 offset:32768
	ds_read_b64 v[178:179], v85 offset:32768
	ds_read_b64 v[180:181], v86 offset:32768
	ds_read_b64 v[182:183], v87 offset:32768
	v_mul_f32_e32 v70, v5, v120
	v_mul_f32_e32 v71, v5, v121
	v_cvt_pk_bf16_f32 v120, v70, v71
	v_mul_f32_e32 v70, v5, v122
	v_mul_f32_e32 v71, v5, v123
	v_cvt_pk_bf16_f32 v121, v70, v71
	v_mul_f32_e32 v70, v136, v124
	v_mul_f32_e32 v71, v136, v125
	v_cvt_pk_bf16_f32 v124, v70, v71
	v_mul_f32_e32 v70, v136, v126
	v_mul_f32_e32 v71, v136, v127
	v_cvt_pk_bf16_f32 v125, v70, v71
	s_setprio 1
	v_mfma_f32_16x16x32_bf16 v[184:187], v[88:91], v[6:9], 0
	v_mfma_f32_16x16x32_bf16 v[88:91], v[88:91], v[22:25], 0
	s_waitcnt lgkmcnt(14)
	v_mfma_f32_16x16x32_bf16 v[184:187], v[92:95], v[10:13], v[184:187]
	v_mfma_f32_16x16x32_bf16 v[88:91], v[92:95], v[26:29], v[88:91]
	v_mfma_f32_16x16x32_bf16 v[92:95], v[96:99], v[14:17], v[184:187]
	v_mfma_f32_16x16x32_bf16 v[88:91], v[96:99], v[30:33], v[88:91]
	v_mfma_f32_16x16x32_bf16 v[92:95], v[100:103], v[18:21], v[92:95]
	v_mfma_f32_16x16x32_bf16 v[88:91], v[100:103], v[34:37], v[88:91]
	v_mfma_f32_16x16x32_bf16 v[92:95], v[104:107], v[38:41], v[92:95]
	v_mfma_f32_16x16x32_bf16 v[88:91], v[104:107], v[54:57], v[88:91]
	v_mfma_f32_16x16x32_bf16 v[92:95], v[108:111], v[42:45], v[92:95]
	v_mfma_f32_16x16x32_bf16 v[88:91], v[108:111], v[58:61], v[88:91]
	v_mfma_f32_16x16x32_bf16 v[92:95], v[112:115], v[46:49], v[92:95]
	v_mfma_f32_16x16x32_bf16 v[88:91], v[112:115], v[62:65], v[88:91]
	v_mfma_f32_16x16x32_bf16 v[92:95], v[116:119], v[50:53], v[92:95]
	v_mfma_f32_16x16x32_bf16 v[88:91], v[116:119], v[66:69], v[88:91]
	s_setprio 0
	s_nop 5
	v_mul_f32_e32 v70, v5, v92
	v_mul_f32_e32 v71, v5, v93
	v_cvt_pk_bf16_f32 v122, v70, v71
	v_mul_f32_e32 v70, v5, v94
	v_mul_f32_e32 v71, v5, v95
	v_cvt_pk_bf16_f32 v123, v70, v71
	v_mul_f32_e32 v70, v136, v88
	v_mul_f32_e32 v71, v136, v89
	v_cvt_pk_bf16_f32 v126, v70, v71
	v_mul_f32_e32 v70, v136, v90
	v_mul_f32_e32 v71, v136, v91
	v_cvt_pk_bf16_f32 v127, v70, v71
	global_store_dwordx4 v[2:3], v[120:123], off offset:64
	global_store_dwordx4 v[134:135], v[124:127], off offset:64
	ds_read_b64 v[88:89], v72 offset:34816
	ds_read_b64 v[90:91], v73 offset:34816
	ds_read_b64 v[92:93], v74 offset:34816
	ds_read_b64 v[94:95], v75 offset:34816
	ds_read_b64 v[96:97], v76 offset:34816
	ds_read_b64 v[98:99], v77 offset:34816
	ds_read_b64 v[100:101], v78 offset:34816
	ds_read_b64 v[102:103], v79 offset:34816
	ds_read_b64 v[104:105], v80 offset:34816
	ds_read_b64 v[106:107], v81 offset:34816
	ds_read_b64 v[108:109], v82 offset:34816
	ds_read_b64 v[110:111], v83 offset:34816
	ds_read_b64 v[112:113], v84 offset:34816
	ds_read_b64 v[114:115], v85 offset:34816
	ds_read_b64 v[116:117], v86 offset:34816
	ds_read_b64 v[118:119], v87 offset:34816
	s_setprio 1
	v_mfma_f32_16x16x32_bf16 v[120:123], v[128:131], v[6:9], 0
	v_mfma_f32_16x16x32_bf16 v[124:127], v[128:131], v[22:25], 0
	s_waitcnt lgkmcnt(14)
	v_mfma_f32_16x16x32_bf16 v[120:123], v[156:159], v[10:13], v[120:123]
	v_mfma_f32_16x16x32_bf16 v[124:127], v[156:159], v[26:29], v[124:127]
	v_mfma_f32_16x16x32_bf16 v[120:123], v[160:163], v[14:17], v[120:123]
	v_mfma_f32_16x16x32_bf16 v[124:127], v[160:163], v[30:33], v[124:127]
	v_mfma_f32_16x16x32_bf16 v[120:123], v[164:167], v[18:21], v[120:123]
	v_mfma_f32_16x16x32_bf16 v[124:127], v[164:167], v[34:37], v[124:127]
	v_mfma_f32_16x16x32_bf16 v[120:123], v[168:171], v[38:41], v[120:123]
	v_mfma_f32_16x16x32_bf16 v[124:127], v[168:171], v[54:57], v[124:127]
	v_mfma_f32_16x16x32_bf16 v[120:123], v[172:175], v[42:45], v[120:123]
	v_mfma_f32_16x16x32_bf16 v[124:127], v[172:175], v[58:61], v[124:127]
	v_mfma_f32_16x16x32_bf16 v[120:123], v[176:179], v[46:49], v[120:123]
	v_mfma_f32_16x16x32_bf16 v[124:127], v[176:179], v[62:65], v[124:127]
	v_mfma_f32_16x16x32_bf16 v[120:123], v[180:183], v[50:53], v[120:123]
	v_mfma_f32_16x16x32_bf16 v[124:127], v[180:183], v[66:69], v[124:127]
	s_setprio 0
	ds_read_b64 v[128:129], v72 offset:49152
	ds_read_b64 v[130:131], v73 offset:49152
	ds_read_b64 v[156:157], v74 offset:49152
	ds_read_b64 v[158:159], v75 offset:49152
	ds_read_b64 v[160:161], v76 offset:49152
	ds_read_b64 v[162:163], v77 offset:49152
	ds_read_b64 v[164:165], v78 offset:49152
	ds_read_b64 v[166:167], v79 offset:49152
	ds_read_b64 v[168:169], v80 offset:49152
	ds_read_b64 v[170:171], v81 offset:49152
	ds_read_b64 v[172:173], v82 offset:49152
	ds_read_b64 v[174:175], v83 offset:49152
	ds_read_b64 v[176:177], v84 offset:49152
	ds_read_b64 v[178:179], v85 offset:49152
	ds_read_b64 v[180:181], v86 offset:49152
	ds_read_b64 v[182:183], v87 offset:49152
	v_mul_f32_e32 v70, v5, v120
	v_mul_f32_e32 v71, v5, v121
	v_cvt_pk_bf16_f32 v120, v70, v71
	v_mul_f32_e32 v70, v5, v122
	v_mul_f32_e32 v71, v5, v123
	v_cvt_pk_bf16_f32 v121, v70, v71
	v_mul_f32_e32 v70, v136, v124
	v_mul_f32_e32 v71, v136, v125
	v_cvt_pk_bf16_f32 v124, v70, v71
	v_mul_f32_e32 v70, v136, v126
	v_mul_f32_e32 v71, v136, v127
	v_cvt_pk_bf16_f32 v125, v70, v71
	s_setprio 1
	v_mfma_f32_16x16x32_bf16 v[184:187], v[88:91], v[6:9], 0
	v_mfma_f32_16x16x32_bf16 v[88:91], v[88:91], v[22:25], 0
	s_waitcnt lgkmcnt(14)
	v_mfma_f32_16x16x32_bf16 v[184:187], v[92:95], v[10:13], v[184:187]
	v_mfma_f32_16x16x32_bf16 v[88:91], v[92:95], v[26:29], v[88:91]
	v_mfma_f32_16x16x32_bf16 v[92:95], v[96:99], v[14:17], v[184:187]
	v_mfma_f32_16x16x32_bf16 v[88:91], v[96:99], v[30:33], v[88:91]
	v_mfma_f32_16x16x32_bf16 v[92:95], v[100:103], v[18:21], v[92:95]
	v_mfma_f32_16x16x32_bf16 v[88:91], v[100:103], v[34:37], v[88:91]
	v_mfma_f32_16x16x32_bf16 v[92:95], v[104:107], v[38:41], v[92:95]
	v_mfma_f32_16x16x32_bf16 v[88:91], v[104:107], v[54:57], v[88:91]
	v_mfma_f32_16x16x32_bf16 v[92:95], v[108:111], v[42:45], v[92:95]
	v_mfma_f32_16x16x32_bf16 v[88:91], v[108:111], v[58:61], v[88:91]
	v_mfma_f32_16x16x32_bf16 v[92:95], v[112:115], v[46:49], v[92:95]
	v_mfma_f32_16x16x32_bf16 v[88:91], v[112:115], v[62:65], v[88:91]
	v_mfma_f32_16x16x32_bf16 v[92:95], v[116:119], v[50:53], v[92:95]
	v_mfma_f32_16x16x32_bf16 v[88:91], v[116:119], v[66:69], v[88:91]
	s_setprio 0
	s_nop 5
	v_mul_f32_e32 v70, v5, v92
	v_mul_f32_e32 v71, v5, v93
	v_cvt_pk_bf16_f32 v122, v70, v71
	v_mul_f32_e32 v70, v5, v94
	v_mul_f32_e32 v71, v5, v95
	v_cvt_pk_bf16_f32 v123, v70, v71
	v_mul_f32_e32 v70, v136, v88
	v_mul_f32_e32 v71, v136, v89
	v_cvt_pk_bf16_f32 v126, v70, v71
	v_mul_f32_e32 v70, v136, v90
	v_mul_f32_e32 v71, v136, v91
	v_cvt_pk_bf16_f32 v127, v70, v71
	global_store_dwordx4 v[2:3], v[120:123], off offset:128
	global_store_dwordx4 v[134:135], v[124:127], off offset:128
	ds_read_b64 v[70:71], v72 offset:51200
	ds_read_b64 v[72:73], v73 offset:51200
	ds_read_b64 v[88:89], v74 offset:51200
	ds_read_b64 v[90:91], v75 offset:51200
	ds_read_b64 v[74:75], v76 offset:51200
	ds_read_b64 v[76:77], v77 offset:51200
	ds_read_b64 v[92:93], v78 offset:51200
	ds_read_b64 v[94:95], v79 offset:51200
	ds_read_b64 v[78:79], v80 offset:51200
	ds_read_b64 v[80:81], v81 offset:51200
	ds_read_b64 v[96:97], v82 offset:51200
	ds_read_b64 v[98:99], v83 offset:51200
	ds_read_b64 v[82:83], v84 offset:51200
	ds_read_b64 v[84:85], v85 offset:51200
	ds_read_b64 v[100:101], v86 offset:51200
	ds_read_b64 v[102:103], v87 offset:51200
	s_setprio 1
	v_mfma_f32_16x16x32_bf16 v[104:107], v[128:131], v[6:9], 0
	v_mfma_f32_16x16x32_bf16 v[108:111], v[128:131], v[22:25], 0
	s_waitcnt lgkmcnt(14)
	v_mfma_f32_16x16x32_bf16 v[104:107], v[156:159], v[10:13], v[104:107]
	v_mfma_f32_16x16x32_bf16 v[108:111], v[156:159], v[26:29], v[108:111]
	v_mfma_f32_16x16x32_bf16 v[104:107], v[160:163], v[14:17], v[104:107]
	v_mfma_f32_16x16x32_bf16 v[108:111], v[160:163], v[30:33], v[108:111]
	v_mfma_f32_16x16x32_bf16 v[104:107], v[164:167], v[18:21], v[104:107]
	v_mfma_f32_16x16x32_bf16 v[108:111], v[164:167], v[34:37], v[108:111]
	v_mfma_f32_16x16x32_bf16 v[104:107], v[168:171], v[38:41], v[104:107]
	v_mfma_f32_16x16x32_bf16 v[108:111], v[168:171], v[54:57], v[108:111]
	v_mfma_f32_16x16x32_bf16 v[104:107], v[172:175], v[42:45], v[104:107]
	v_mfma_f32_16x16x32_bf16 v[108:111], v[172:175], v[58:61], v[108:111]
	v_mfma_f32_16x16x32_bf16 v[104:107], v[176:179], v[46:49], v[104:107]
	v_mfma_f32_16x16x32_bf16 v[108:111], v[176:179], v[62:65], v[108:111]
	v_mfma_f32_16x16x32_bf16 v[104:107], v[180:183], v[50:53], v[104:107]
	v_mfma_f32_16x16x32_bf16 v[108:111], v[180:183], v[66:69], v[108:111]
	s_setprio 0
	s_nop 5
	v_mul_f32_e32 v86, v5, v104
	v_mul_f32_e32 v87, v5, v105
	v_cvt_pk_bf16_f32 v86, v86, v87
	v_mul_f32_e32 v87, v5, v106
	v_mul_f32_e32 v104, v5, v107
	v_cvt_pk_bf16_f32 v87, v87, v104
	v_mul_f32_e32 v104, v136, v108
	v_mul_f32_e32 v105, v136, v109
	v_cvt_pk_bf16_f32 v104, v104, v105
	v_mul_f32_e32 v105, v136, v110
	v_mul_f32_e32 v106, v136, v111
	v_cvt_pk_bf16_f32 v105, v105, v106
	s_setprio 1
	v_mfma_f32_16x16x32_bf16 v[106:109], v[70:73], v[6:9], 0
	v_mfma_f32_16x16x32_bf16 v[70:73], v[70:73], v[22:25], 0
	s_waitcnt lgkmcnt(12)
	v_mfma_f32_16x16x32_bf16 v[106:109], v[88:91], v[10:13], v[106:109]
	v_mfma_f32_16x16x32_bf16 v[70:73], v[88:91], v[26:29], v[70:73]
	s_waitcnt lgkmcnt(10)
	v_mfma_f32_16x16x32_bf16 v[88:91], v[74:77], v[14:17], v[106:109]
	v_mfma_f32_16x16x32_bf16 v[70:73], v[74:77], v[30:33], v[70:73]
	s_waitcnt lgkmcnt(8)
	v_mfma_f32_16x16x32_bf16 v[74:77], v[92:95], v[18:21], v[88:91]
	v_mfma_f32_16x16x32_bf16 v[70:73], v[92:95], v[34:37], v[70:73]
	s_waitcnt lgkmcnt(6)
	v_mfma_f32_16x16x32_bf16 v[74:77], v[78:81], v[38:41], v[74:77]
	v_mfma_f32_16x16x32_bf16 v[70:73], v[78:81], v[54:57], v[70:73]
	s_waitcnt lgkmcnt(4)
	v_mfma_f32_16x16x32_bf16 v[74:77], v[96:99], v[42:45], v[74:77]
	v_mfma_f32_16x16x32_bf16 v[70:73], v[96:99], v[58:61], v[70:73]
	s_waitcnt lgkmcnt(2)
	v_mfma_f32_16x16x32_bf16 v[74:77], v[82:85], v[46:49], v[74:77]
	v_mfma_f32_16x16x32_bf16 v[70:73], v[82:85], v[62:65], v[70:73]
	s_waitcnt lgkmcnt(0)
	v_mfma_f32_16x16x32_bf16 v[74:77], v[100:103], v[50:53], v[74:77]
	v_mfma_f32_16x16x32_bf16 v[70:73], v[100:103], v[66:69], v[70:73]
	s_setprio 0
	s_nop 5
	v_mul_f32_e32 v74, v5, v74
	v_mul_f32_e32 v75, v5, v75
	v_mul_f32_e32 v70, v136, v70
	v_cvt_pk_bf16_f32 v88, v74, v75
	v_mul_f32_e32 v74, v5, v76
	v_mul_f32_e32 v75, v5, v77
	v_cvt_pk_bf16_f32 v89, v74, v75
	v_mul_f32_e32 v71, v136, v71
	v_cvt_pk_bf16_f32 v106, v70, v71
	v_mul_f32_e32 v70, v136, v72
	v_add_u32_e32 v78, 0x10000, v146
	v_mul_f32_e32 v71, v136, v73
	v_cvt_pk_bf16_f32 v107, v70, v71
	global_store_dwordx4 v[2:3], v[86:89], off offset:192
	global_store_dwordx4 v[134:135], v[104:107], off offset:192
	v_add_u32_e32 v70, v78, v149
	v_add_u32_e32 v72, v78, v151
	v_add_u32_e32 v74, v78, v153
	v_add_u32_e32 v76, v78, v154
	v_add_u32_e32 v79, v78, v143
	v_add_u32_e32 v80, v78, v147
	v_add_u32_e32 v81, v78, v150
	s_waitcnt vmcnt(0)
	s_barrier
	ds_read_b64 v[70:71], v70
	ds_read_b64 v[72:73], v72
	ds_read_b64 v[74:75], v74
	ds_read_b64 v[76:77], v76
	v_add_u32_e32 v86, v78, v152
	ds_read_b64 v[82:83], v79
	ds_read_b64 v[84:85], v80
	ds_read_b64 v[90:91], v81
	ds_read_b64 v[92:93], v86
	v_add_u32_e32 v79, v78, v139
	v_add_u32_e32 v80, v78, v141
	v_add_u32_e32 v81, v78, v145
	v_add_u32_e32 v86, v78, v148
	ds_read_b64 v[94:95], v79
	ds_read_b64 v[96:97], v80
	ds_read_b64 v[98:99], v81
	ds_read_b64 v[100:101], v86
	v_add_u32_e32 v79, v78, v137
	v_add_u32_e32 v80, v78, v138
	v_add_u32_e32 v81, v78, v140
	v_add_u32_e32 v78, v78, v142
	ds_read_b64 v[102:103], v79
	ds_read_b64 v[104:105], v80
	ds_read_b64 v[106:107], v81
	ds_read_b64 v[108:109], v78
	v_add_u32_e32 v78, 0x10800, v146
	v_add_u32_e32 v79, v78, v149
	v_add_u32_e32 v80, v78, v151
	v_add_u32_e32 v81, v78, v153
	v_add_u32_e32 v86, v78, v154
	ds_read_b64 v[110:111], v79
	ds_read_b64 v[112:113], v80
	ds_read_b64 v[118:119], v81
	ds_read_b64 v[120:121], v86
	v_add_u32_e32 v79, v78, v143
	v_add_u32_e32 v80, v78, v147
	v_add_u32_e32 v81, v78, v150
	v_add_u32_e32 v86, v78, v152
	ds_read_b64 v[126:127], v79
	ds_read_b64 v[128:129], v80
	ds_read_b64 v[130:131], v81
	ds_read_b64 v[132:133], v86
	v_add_u32_e32 v79, v78, v139
	v_add_u32_e32 v80, v78, v141
	v_add_u32_e32 v81, v78, v145
	v_add_u32_e32 v88, v78, v148
	ds_read_b64 v[156:157], v79
	ds_read_b64 v[158:159], v80
	ds_read_b64 v[86:87], v81
	ds_read_b64 v[88:89], v88
	v_add_u32_e32 v79, v78, v137
	v_add_u32_e32 v80, v78, v138
	v_add_u32_e32 v81, v78, v140
	v_add_u32_e32 v114, v78, v142
	ds_read_b64 v[160:161], v79
	ds_read_b64 v[162:163], v80
	ds_read_b64 v[78:79], v81
	ds_read_b64 v[80:81], v114
	s_setprio 1
	s_waitcnt lgkmcnt(14)
	v_mfma_f32_16x16x32_bf16 v[114:117], v[70:73], v[6:9], 0
	v_mfma_f32_16x16x32_bf16 v[70:73], v[70:73], v[22:25], 0
	v_mfma_f32_16x16x32_bf16 v[114:117], v[74:77], v[10:13], v[114:117]
	v_mfma_f32_16x16x32_bf16 v[70:73], v[74:77], v[26:29], v[70:73]
	v_mfma_f32_16x16x32_bf16 v[74:77], v[82:85], v[14:17], v[114:117]
	v_mfma_f32_16x16x32_bf16 v[70:73], v[82:85], v[30:33], v[70:73]
	v_mfma_f32_16x16x32_bf16 v[74:77], v[90:93], v[18:21], v[74:77]
	v_mfma_f32_16x16x32_bf16 v[70:73], v[90:93], v[34:37], v[70:73]
	v_mfma_f32_16x16x32_bf16 v[74:77], v[94:97], v[38:41], v[74:77]
	v_mfma_f32_16x16x32_bf16 v[70:73], v[94:97], v[54:57], v[70:73]
	v_mfma_f32_16x16x32_bf16 v[74:77], v[98:101], v[42:45], v[74:77]
	v_mfma_f32_16x16x32_bf16 v[70:73], v[98:101], v[58:61], v[70:73]
	v_mfma_f32_16x16x32_bf16 v[74:77], v[102:105], v[46:49], v[74:77]
	v_mfma_f32_16x16x32_bf16 v[70:73], v[102:105], v[62:65], v[70:73]
	v_mfma_f32_16x16x32_bf16 v[74:77], v[106:109], v[50:53], v[74:77]
	v_mfma_f32_16x16x32_bf16 v[70:73], v[106:109], v[66:69], v[70:73]
	s_setprio 0
	v_add_u32_e32 v96, 0x14000, v146
	v_add_u32_e32 v97, v96, v139
	ds_read_b64 v[98:99], v97
	v_add_u32_e32 v97, v96, v141
	ds_read_b64 v[100:101], v97
	v_add_u32_e32 v97, v96, v145
	ds_read_b64 v[106:107], v97
	v_add_u32_e32 v97, v96, v148
	v_mul_f32_e32 v74, v5, v74
	v_mul_f32_e32 v70, v136, v70
	ds_read_b64 v[108:109], v97
	v_add_u32_e32 v97, v96, v137
	v_mul_f32_e32 v75, v5, v75
	v_cvt_pk_bf16_f32 v94, v74, v75
	v_mul_f32_e32 v74, v5, v76
	v_mul_f32_e32 v71, v136, v71
	v_cvt_pk_bf16_f32 v102, v70, v71
	v_mul_f32_e32 v70, v136, v72
	ds_read_b64 v[114:115], v97
	v_add_u32_e32 v97, v96, v138
	v_mul_f32_e32 v75, v5, v77
	v_cvt_pk_bf16_f32 v95, v74, v75
	v_mul_f32_e32 v71, v136, v73
	v_cvt_pk_bf16_f32 v103, v70, v71
	v_add_u32_e32 v70, v96, v149
	v_add_u32_e32 v72, v96, v151
	v_add_u32_e32 v74, v96, v153
	v_add_u32_e32 v76, v96, v154
	v_add_u32_e32 v82, v96, v143
	v_add_u32_e32 v84, v96, v147
	v_add_u32_e32 v90, v96, v150
	v_add_u32_e32 v92, v96, v152
	ds_read_b64 v[116:117], v97
	v_add_u32_e32 v97, v96, v140
	v_add_u32_e32 v96, v96, v142
	ds_read_b64 v[70:71], v70
	ds_read_b64 v[72:73], v72
	ds_read_b64 v[74:75], v74
	ds_read_b64 v[76:77], v76
	ds_read_b64 v[82:83], v82
	ds_read_b64 v[84:85], v84
	ds_read_b64 v[90:91], v90
	ds_read_b64 v[92:93], v92
	ds_read_b64 v[122:123], v97
	ds_read_b64 v[124:125], v96
	s_setprio 1
	v_mfma_f32_16x16x32_bf16 v[164:167], v[110:113], v[6:9], 0
	v_mfma_f32_16x16x32_bf16 v[110:113], v[110:113], v[22:25], 0
	s_waitcnt lgkmcnt(14)
	v_mfma_f32_16x16x32_bf16 v[164:167], v[118:121], v[10:13], v[164:167]
	v_mfma_f32_16x16x32_bf16 v[110:113], v[118:121], v[26:29], v[110:113]
	v_mfma_f32_16x16x32_bf16 v[118:121], v[126:129], v[14:17], v[164:167]
	v_mfma_f32_16x16x32_bf16 v[110:113], v[126:129], v[30:33], v[110:113]
	v_mfma_f32_16x16x32_bf16 v[118:121], v[130:133], v[18:21], v[118:121]
	v_mfma_f32_16x16x32_bf16 v[110:113], v[130:133], v[34:37], v[110:113]
	v_mfma_f32_16x16x32_bf16 v[118:121], v[156:159], v[38:41], v[118:121]
	v_mfma_f32_16x16x32_bf16 v[110:113], v[156:159], v[54:57], v[110:113]
	v_mfma_f32_16x16x32_bf16 v[118:121], v[86:89], v[42:45], v[118:121]
	v_mfma_f32_16x16x32_bf16 v[86:89], v[86:89], v[58:61], v[110:113]
	v_mfma_f32_16x16x32_bf16 v[110:113], v[160:163], v[46:49], v[118:121]
	v_mfma_f32_16x16x32_bf16 v[86:89], v[160:163], v[62:65], v[86:89]
	v_mfma_f32_16x16x32_bf16 v[110:113], v[78:81], v[50:53], v[110:113]
	v_mfma_f32_16x16x32_bf16 v[78:81], v[78:81], v[66:69], v[86:89]
	s_setprio 0
	s_nop 5
	v_mul_f32_e32 v86, v5, v110
	v_mul_f32_e32 v87, v5, v111
	v_mul_f32_e32 v78, v136, v78
	v_cvt_pk_bf16_f32 v96, v86, v87
	v_mul_f32_e32 v86, v5, v112
	v_mul_f32_e32 v87, v5, v113
	v_cvt_pk_bf16_f32 v97, v86, v87
	v_mul_f32_e32 v79, v136, v79
	v_cvt_pk_bf16_f32 v104, v78, v79
	v_mul_f32_e32 v78, v136, v80
	v_add_u32_e32 v132, 0x14800, v146
	v_mul_f32_e32 v79, v136, v81
	v_cvt_pk_bf16_f32 v105, v78, v79
	global_store_dwordx4 v[2:3], v[94:97], off offset:256
	global_store_dwordx4 v[134:135], v[102:105], off offset:256
	v_add_u32_e32 v78, v132, v149
	v_add_u32_e32 v80, v132, v151
	v_add_u32_e32 v86, v132, v153
	v_add_u32_e32 v88, v132, v154
	v_add_u32_e32 v94, v132, v143
	v_add_u32_e32 v96, v132, v147
	v_add_u32_e32 v102, v132, v150
	v_add_u32_e32 v104, v132, v152
	v_add_u32_e32 v110, v132, v139
	v_add_u32_e32 v112, v132, v141
	v_add_u32_e32 v118, v132, v145
	v_add_u32_e32 v120, v132, v148
	v_add_u32_e32 v126, v132, v137
	v_add_u32_e32 v128, v132, v138
	v_add_u32_e32 v130, v132, v140
	v_add_u32_e32 v132, v132, v142
	ds_read_b64 v[78:79], v78
	ds_read_b64 v[80:81], v80
	ds_read_b64 v[86:87], v86
	ds_read_b64 v[88:89], v88
	ds_read_b64 v[94:95], v94
	ds_read_b64 v[96:97], v96
	ds_read_b64 v[102:103], v102
	ds_read_b64 v[104:105], v104
	ds_read_b64 v[110:111], v110
	ds_read_b64 v[112:113], v112
	ds_read_b64 v[118:119], v118
	ds_read_b64 v[120:121], v120
	ds_read_b64 v[126:127], v126
	ds_read_b64 v[128:129], v128
	ds_read_b64 v[130:131], v130
	ds_read_b64 v[132:133], v132
	s_setprio 1
	s_waitcnt lgkmcnt(14)
	v_mfma_f32_16x16x32_bf16 v[156:159], v[70:73], v[6:9], 0
	v_mfma_f32_16x16x32_bf16 v[70:73], v[70:73], v[22:25], 0
	v_mfma_f32_16x16x32_bf16 v[156:159], v[74:77], v[10:13], v[156:159]
	v_mfma_f32_16x16x32_bf16 v[70:73], v[74:77], v[26:29], v[70:73]
	v_mfma_f32_16x16x32_bf16 v[74:77], v[82:85], v[14:17], v[156:159]
	v_mfma_f32_16x16x32_bf16 v[70:73], v[82:85], v[30:33], v[70:73]
	v_mfma_f32_16x16x32_bf16 v[74:77], v[90:93], v[18:21], v[74:77]
	v_mfma_f32_16x16x32_bf16 v[70:73], v[90:93], v[34:37], v[70:73]
	v_mfma_f32_16x16x32_bf16 v[74:77], v[98:101], v[38:41], v[74:77]
	v_mfma_f32_16x16x32_bf16 v[70:73], v[98:101], v[54:57], v[70:73]
	v_mfma_f32_16x16x32_bf16 v[74:77], v[106:109], v[42:45], v[74:77]
	v_mfma_f32_16x16x32_bf16 v[70:73], v[106:109], v[58:61], v[70:73]
	v_mfma_f32_16x16x32_bf16 v[74:77], v[114:117], v[46:49], v[74:77]
	v_mfma_f32_16x16x32_bf16 v[70:73], v[114:117], v[62:65], v[70:73]
	v_mfma_f32_16x16x32_bf16 v[74:77], v[122:125], v[50:53], v[74:77]
	v_mfma_f32_16x16x32_bf16 v[70:73], v[122:125], v[66:69], v[70:73]
	s_setprio 0
	s_nop 5
	v_mul_f32_e32 v74, v5, v74
	v_mul_f32_e32 v70, v136, v70
	v_mul_f32_e32 v75, v5, v75
	v_cvt_pk_bf16_f32 v156, v74, v75
	v_mul_f32_e32 v74, v5, v76
	v_mul_f32_e32 v71, v136, v71
	v_cvt_pk_bf16_f32 v160, v70, v71
	v_mul_f32_e32 v70, v136, v72
	v_add_u32_e32 v124, 0x18000, v146
	v_mul_f32_e32 v75, v5, v77
	v_cvt_pk_bf16_f32 v157, v74, v75
	v_mul_f32_e32 v71, v136, v73
	v_cvt_pk_bf16_f32 v161, v70, v71
	v_add_u32_e32 v70, v124, v149
	v_add_u32_e32 v72, v124, v151
	v_add_u32_e32 v74, v124, v153
	v_add_u32_e32 v76, v124, v154
	v_add_u32_e32 v82, v124, v143
	v_add_u32_e32 v84, v124, v147
	v_add_u32_e32 v90, v124, v150
	v_add_u32_e32 v92, v124, v152
	v_add_u32_e32 v98, v124, v139
	v_add_u32_e32 v100, v124, v141
	v_add_u32_e32 v106, v124, v145
	v_add_u32_e32 v108, v124, v148
	v_add_u32_e32 v114, v124, v137
	v_add_u32_e32 v116, v124, v138
	v_add_u32_e32 v122, v124, v140
	v_add_u32_e32 v124, v124, v142
	ds_read_b64 v[70:71], v70
	ds_read_b64 v[72:73], v72
	ds_read_b64 v[74:75], v74
	ds_read_b64 v[76:77], v76
	ds_read_b64 v[82:83], v82
	ds_read_b64 v[84:85], v84
	ds_read_b64 v[90:91], v90
	ds_read_b64 v[92:93], v92
	ds_read_b64 v[98:99], v98
	ds_read_b64 v[100:101], v100
	ds_read_b64 v[106:107], v106
	ds_read_b64 v[108:109], v108
	ds_read_b64 v[114:115], v114
	ds_read_b64 v[116:117], v116
	ds_read_b64 v[122:123], v122
	ds_read_b64 v[124:125], v124
	s_setprio 1
	v_mfma_f32_16x16x32_bf16 v[162:165], v[78:81], v[6:9], 0
	v_mfma_f32_16x16x32_bf16 v[78:81], v[78:81], v[22:25], 0
	s_waitcnt lgkmcnt(14)
	v_mfma_f32_16x16x32_bf16 v[162:165], v[86:89], v[10:13], v[162:165]
	v_mfma_f32_16x16x32_bf16 v[78:81], v[86:89], v[26:29], v[78:81]
	v_mfma_f32_16x16x32_bf16 v[86:89], v[94:97], v[14:17], v[162:165]
	v_mfma_f32_16x16x32_bf16 v[78:81], v[94:97], v[30:33], v[78:81]
	v_mfma_f32_16x16x32_bf16 v[86:89], v[102:105], v[18:21], v[86:89]
	v_mfma_f32_16x16x32_bf16 v[78:81], v[102:105], v[34:37], v[78:81]
	v_mfma_f32_16x16x32_bf16 v[86:89], v[110:113], v[38:41], v[86:89]
	v_mfma_f32_16x16x32_bf16 v[78:81], v[110:113], v[54:57], v[78:81]
	v_mfma_f32_16x16x32_bf16 v[86:89], v[118:121], v[42:45], v[86:89]
	v_mfma_f32_16x16x32_bf16 v[78:81], v[118:121], v[58:61], v[78:81]
	v_mfma_f32_16x16x32_bf16 v[86:89], v[126:129], v[46:49], v[86:89]
	v_mfma_f32_16x16x32_bf16 v[78:81], v[126:129], v[62:65], v[78:81]
	v_mfma_f32_16x16x32_bf16 v[86:89], v[130:133], v[50:53], v[86:89]
	v_mfma_f32_16x16x32_bf16 v[78:81], v[130:133], v[66:69], v[78:81]
	s_setprio 0
	s_nop 5
	v_mul_f32_e32 v86, v5, v86
	v_mul_f32_e32 v87, v5, v87
	v_mul_f32_e32 v78, v136, v78
	v_cvt_pk_bf16_f32 v158, v86, v87
	v_mul_f32_e32 v86, v5, v88
	v_mul_f32_e32 v87, v5, v89
	v_cvt_pk_bf16_f32 v159, v86, v87
	v_mul_f32_e32 v79, v136, v79
	v_cvt_pk_bf16_f32 v162, v78, v79
	v_mul_f32_e32 v78, v136, v80
	v_add_u32_e32 v132, 0x18800, v146
	v_mul_f32_e32 v79, v136, v81
	v_cvt_pk_bf16_f32 v163, v78, v79
	global_store_dwordx4 v[2:3], v[156:159], off offset:320
	global_store_dwordx4 v[134:135], v[160:163], off offset:320
	v_add_u32_e32 v78, v132, v149
	v_add_u32_e32 v80, v132, v151
	v_add_u32_e32 v86, v132, v153
	v_add_u32_e32 v88, v132, v154
	v_add_u32_e32 v94, v132, v143
	v_add_u32_e32 v96, v132, v147
	v_add_u32_e32 v102, v132, v150
	v_add_u32_e32 v104, v132, v152
	v_add_u32_e32 v110, v132, v139
	v_add_u32_e32 v112, v132, v141
	v_add_u32_e32 v118, v132, v145
	v_add_u32_e32 v120, v132, v148
	v_add_u32_e32 v126, v132, v137
	v_add_u32_e32 v128, v132, v138
	v_add_u32_e32 v130, v132, v140
	v_add_u32_e32 v132, v132, v142
	ds_read_b64 v[78:79], v78
	ds_read_b64 v[80:81], v80
	ds_read_b64 v[86:87], v86
	ds_read_b64 v[88:89], v88
	ds_read_b64 v[94:95], v94
	ds_read_b64 v[96:97], v96
	ds_read_b64 v[102:103], v102
	ds_read_b64 v[104:105], v104
	ds_read_b64 v[110:111], v110
	ds_read_b64 v[112:113], v112
	ds_read_b64 v[118:119], v118
	ds_read_b64 v[120:121], v120
	ds_read_b64 v[126:127], v126
	ds_read_b64 v[128:129], v128
	ds_read_b64 v[130:131], v130
	ds_read_b64 v[132:133], v132
	s_setprio 1
	v_mfma_f32_16x16x32_bf16 v[156:159], v[70:73], v[6:9], 0
	v_mfma_f32_16x16x32_bf16 v[70:73], v[70:73], v[22:25], 0
	s_waitcnt lgkmcnt(14)
	v_mfma_f32_16x16x32_bf16 v[156:159], v[74:77], v[10:13], v[156:159]
	v_mfma_f32_16x16x32_bf16 v[70:73], v[74:77], v[26:29], v[70:73]
	v_mfma_f32_16x16x32_bf16 v[74:77], v[82:85], v[14:17], v[156:159]
	v_mfma_f32_16x16x32_bf16 v[70:73], v[82:85], v[30:33], v[70:73]
	v_mfma_f32_16x16x32_bf16 v[74:77], v[90:93], v[18:21], v[74:77]
	v_mfma_f32_16x16x32_bf16 v[70:73], v[90:93], v[34:37], v[70:73]
	v_mfma_f32_16x16x32_bf16 v[74:77], v[98:101], v[38:41], v[74:77]
	v_mfma_f32_16x16x32_bf16 v[70:73], v[98:101], v[54:57], v[70:73]
	v_mfma_f32_16x16x32_bf16 v[74:77], v[106:109], v[42:45], v[74:77]
	v_mfma_f32_16x16x32_bf16 v[70:73], v[106:109], v[58:61], v[70:73]
	v_mfma_f32_16x16x32_bf16 v[74:77], v[114:117], v[46:49], v[74:77]
	v_mfma_f32_16x16x32_bf16 v[70:73], v[114:117], v[62:65], v[70:73]
	v_mfma_f32_16x16x32_bf16 v[74:77], v[122:125], v[50:53], v[74:77]
	v_mfma_f32_16x16x32_bf16 v[70:73], v[122:125], v[66:69], v[70:73]
	s_setprio 0
	s_nop 5
	v_mul_f32_e32 v74, v5, v74
	v_mul_f32_e32 v70, v136, v70
	v_mul_f32_e32 v75, v5, v75
	v_cvt_pk_bf16_f32 v156, v74, v75
	v_mul_f32_e32 v74, v5, v76
	v_mul_f32_e32 v71, v136, v71
	v_cvt_pk_bf16_f32 v160, v70, v71
	v_mul_f32_e32 v70, v136, v72
	v_add_u32_e32 v124, 0x1c000, v146
	v_mul_f32_e32 v75, v5, v77
	v_cvt_pk_bf16_f32 v157, v74, v75
	v_mul_f32_e32 v71, v136, v73
	v_cvt_pk_bf16_f32 v161, v70, v71
	v_add_u32_e32 v70, v124, v149
	v_add_u32_e32 v72, v124, v151
	v_add_u32_e32 v74, v124, v153
	v_add_u32_e32 v76, v124, v154
	v_add_u32_e32 v82, v124, v143
	v_add_u32_e32 v84, v124, v147
	v_add_u32_e32 v90, v124, v150
	v_add_u32_e32 v92, v124, v152
	v_add_u32_e32 v98, v124, v139
	v_add_u32_e32 v100, v124, v141
	v_add_u32_e32 v106, v124, v145
	v_add_u32_e32 v108, v124, v148
	v_add_u32_e32 v114, v124, v137
	v_add_u32_e32 v116, v124, v138
	v_add_u32_e32 v122, v124, v140
	v_add_u32_e32 v124, v124, v142
	ds_read_b64 v[70:71], v70
	ds_read_b64 v[72:73], v72
	ds_read_b64 v[74:75], v74
	ds_read_b64 v[76:77], v76
	ds_read_b64 v[82:83], v82
	ds_read_b64 v[84:85], v84
	ds_read_b64 v[90:91], v90
	ds_read_b64 v[92:93], v92
	ds_read_b64 v[98:99], v98
	ds_read_b64 v[100:101], v100
	ds_read_b64 v[106:107], v106
	ds_read_b64 v[108:109], v108
	ds_read_b64 v[114:115], v114
	ds_read_b64 v[116:117], v116
	ds_read_b64 v[122:123], v122
	ds_read_b64 v[124:125], v124
	s_setprio 1
	v_mfma_f32_16x16x32_bf16 v[162:165], v[78:81], v[6:9], 0
	v_mfma_f32_16x16x32_bf16 v[78:81], v[78:81], v[22:25], 0
	s_waitcnt lgkmcnt(14)
	v_mfma_f32_16x16x32_bf16 v[162:165], v[86:89], v[10:13], v[162:165]
	v_mfma_f32_16x16x32_bf16 v[78:81], v[86:89], v[26:29], v[78:81]
	v_mfma_f32_16x16x32_bf16 v[86:89], v[94:97], v[14:17], v[162:165]
	v_mfma_f32_16x16x32_bf16 v[78:81], v[94:97], v[30:33], v[78:81]
	v_mfma_f32_16x16x32_bf16 v[86:89], v[102:105], v[18:21], v[86:89]
	v_mfma_f32_16x16x32_bf16 v[78:81], v[102:105], v[34:37], v[78:81]
	v_mfma_f32_16x16x32_bf16 v[86:89], v[110:113], v[38:41], v[86:89]
	v_mfma_f32_16x16x32_bf16 v[78:81], v[110:113], v[54:57], v[78:81]
	v_mfma_f32_16x16x32_bf16 v[86:89], v[118:121], v[42:45], v[86:89]
	v_mfma_f32_16x16x32_bf16 v[78:81], v[118:121], v[58:61], v[78:81]
	v_mfma_f32_16x16x32_bf16 v[86:89], v[126:129], v[46:49], v[86:89]
	v_mfma_f32_16x16x32_bf16 v[78:81], v[126:129], v[62:65], v[78:81]
	v_mfma_f32_16x16x32_bf16 v[86:89], v[130:133], v[50:53], v[86:89]
	v_mfma_f32_16x16x32_bf16 v[78:81], v[130:133], v[66:69], v[78:81]
	s_setprio 0
	s_nop 5
	v_mul_f32_e32 v86, v5, v86
	v_mul_f32_e32 v87, v5, v87
	v_mul_f32_e32 v78, v136, v78
	v_cvt_pk_bf16_f32 v158, v86, v87
	v_mul_f32_e32 v86, v5, v88
	v_mul_f32_e32 v87, v5, v89
	v_cvt_pk_bf16_f32 v159, v86, v87
	v_mul_f32_e32 v79, v136, v79
	v_cvt_pk_bf16_f32 v162, v78, v79
	v_mul_f32_e32 v78, v136, v80
	v_add_u32_e32 v132, 0x1c800, v146
	v_mul_f32_e32 v79, v136, v81
	v_cvt_pk_bf16_f32 v163, v78, v79
	global_store_dwordx4 v[2:3], v[156:159], off offset:384
	global_store_dwordx4 v[134:135], v[160:163], off offset:384
	v_add_u32_e32 v78, v132, v149
	v_add_u32_e32 v80, v132, v151
	v_add_u32_e32 v86, v132, v153
	v_add_u32_e32 v88, v132, v154
	v_add_u32_e32 v94, v132, v143
	v_add_u32_e32 v96, v132, v147
	v_add_u32_e32 v102, v132, v150
	v_add_u32_e32 v104, v132, v152
	v_add_u32_e32 v110, v132, v139
	v_add_u32_e32 v112, v132, v141
	v_add_u32_e32 v118, v132, v145
	v_add_u32_e32 v120, v132, v148
	v_add_u32_e32 v126, v132, v137
	v_add_u32_e32 v128, v132, v138
	v_add_u32_e32 v130, v132, v140
	v_add_u32_e32 v132, v132, v142
	ds_read_b64 v[78:79], v78
	ds_read_b64 v[80:81], v80
	ds_read_b64 v[86:87], v86
	ds_read_b64 v[88:89], v88
	ds_read_b64 v[94:95], v94
	ds_read_b64 v[96:97], v96
	ds_read_b64 v[102:103], v102
	ds_read_b64 v[104:105], v104
	ds_read_b64 v[110:111], v110
	ds_read_b64 v[112:113], v112
	ds_read_b64 v[118:119], v118
	ds_read_b64 v[120:121], v120
	ds_read_b64 v[126:127], v126
	ds_read_b64 v[128:129], v128
	ds_read_b64 v[130:131], v130
	ds_read_b64 v[132:133], v132
	s_setprio 1
	v_mfma_f32_16x16x32_bf16 v[138:141], v[70:73], v[6:9], 0
	v_mfma_f32_16x16x32_bf16 v[70:73], v[70:73], v[22:25], 0
	s_waitcnt lgkmcnt(14)
	v_mfma_f32_16x16x32_bf16 v[138:141], v[74:77], v[10:13], v[138:141]
	v_mfma_f32_16x16x32_bf16 v[70:73], v[74:77], v[26:29], v[70:73]
	v_mfma_f32_16x16x32_bf16 v[74:77], v[82:85], v[14:17], v[138:141]
	v_mfma_f32_16x16x32_bf16 v[70:73], v[82:85], v[30:33], v[70:73]
	v_mfma_f32_16x16x32_bf16 v[74:77], v[90:93], v[18:21], v[74:77]
	v_mfma_f32_16x16x32_bf16 v[70:73], v[90:93], v[34:37], v[70:73]
	v_mfma_f32_16x16x32_bf16 v[74:77], v[98:101], v[38:41], v[74:77]
	v_mfma_f32_16x16x32_bf16 v[70:73], v[98:101], v[54:57], v[70:73]
	v_mfma_f32_16x16x32_bf16 v[74:77], v[106:109], v[42:45], v[74:77]
	v_mfma_f32_16x16x32_bf16 v[70:73], v[106:109], v[58:61], v[70:73]
	v_mfma_f32_16x16x32_bf16 v[74:77], v[114:117], v[46:49], v[74:77]
	v_mfma_f32_16x16x32_bf16 v[70:73], v[114:117], v[62:65], v[70:73]
	v_mfma_f32_16x16x32_bf16 v[74:77], v[122:125], v[50:53], v[74:77]
	v_mfma_f32_16x16x32_bf16 v[70:73], v[122:125], v[66:69], v[70:73]
	s_setprio 0
	s_nop 5
	v_mul_f32_e32 v74, v5, v74
	v_mul_f32_e32 v75, v5, v75
	v_mul_f32_e32 v70, v136, v70
	v_mul_f32_e32 v71, v136, v71
	v_cvt_pk_bf16_f32 v74, v74, v75
	v_mul_f32_e32 v75, v5, v76
	v_cvt_pk_bf16_f32 v70, v70, v71
	v_mul_f32_e32 v71, v136, v72
	v_mul_f32_e32 v76, v5, v77
	v_cvt_pk_bf16_f32 v75, v75, v76
	v_mul_f32_e32 v72, v136, v73
	v_cvt_pk_bf16_f32 v71, v71, v72
	s_setprio 1
	v_mfma_f32_16x16x32_bf16 v[6:9], v[78:81], v[6:9], 0
	v_mfma_f32_16x16x32_bf16 v[22:25], v[78:81], v[22:25], 0
	s_waitcnt lgkmcnt(12)
	v_mfma_f32_16x16x32_bf16 v[6:9], v[86:89], v[10:13], v[6:9]
	v_mfma_f32_16x16x32_bf16 v[10:13], v[86:89], v[26:29], v[22:25]
	s_waitcnt lgkmcnt(10)
	v_mfma_f32_16x16x32_bf16 v[6:9], v[94:97], v[14:17], v[6:9]
	v_mfma_f32_16x16x32_bf16 v[10:13], v[94:97], v[30:33], v[10:13]
	s_waitcnt lgkmcnt(8)
	v_mfma_f32_16x16x32_bf16 v[6:9], v[102:105], v[18:21], v[6:9]
	v_mfma_f32_16x16x32_bf16 v[10:13], v[102:105], v[34:37], v[10:13]
	s_waitcnt lgkmcnt(6)
	v_mfma_f32_16x16x32_bf16 v[6:9], v[110:113], v[38:41], v[6:9]
	v_mfma_f32_16x16x32_bf16 v[10:13], v[110:113], v[54:57], v[10:13]
	s_waitcnt lgkmcnt(4)
	v_mfma_f32_16x16x32_bf16 v[6:9], v[118:121], v[42:45], v[6:9]
	v_mfma_f32_16x16x32_bf16 v[10:13], v[118:121], v[58:61], v[10:13]
	s_waitcnt lgkmcnt(2)
	v_mfma_f32_16x16x32_bf16 v[6:9], v[126:129], v[46:49], v[6:9]
	v_mfma_f32_16x16x32_bf16 v[10:13], v[126:129], v[62:65], v[10:13]
	s_waitcnt lgkmcnt(0)
	v_mfma_f32_16x16x32_bf16 v[6:9], v[130:133], v[50:53], v[6:9]
	v_mfma_f32_16x16x32_bf16 v[10:13], v[130:133], v[66:69], v[10:13]
	s_setprio 0
	s_nop 5
	v_mul_f32_e32 v6, v5, v6
	v_mul_f32_e32 v7, v5, v7
	v_cvt_pk_bf16_f32 v76, v6, v7
	v_mul_f32_e32 v6, v5, v8
	v_mul_f32_e32 v5, v5, v9
	v_cvt_pk_bf16_f32 v77, v6, v5
	v_mul_f32_e32 v5, v136, v10
	v_mul_f32_e32 v6, v136, v11
	v_cvt_pk_bf16_f32 v72, v5, v6
	v_mul_f32_e32 v5, v136, v12
	v_mul_f32_e32 v6, v136, v13
	v_cvt_pk_bf16_f32 v73, v5, v6
	global_store_dwordx4 v[2:3], v[74:77], off offset:448
	global_store_dwordx4 v[134:135], v[70:73], off offset:448
	s_barrier

.LBB0_958:
	v_pk_mul_f32 v[126:127], v[126:127], v[140:141] op_sel_hi:[1,0]
	v_lshl_or_b32 v2, s59, 8, v226
	v_pk_mul_f32 v[130:131], v[130:131], v[140:141] op_sel_hi:[1,0]
	v_pk_mul_f32 v[128:129], v[128:129], v[140:141] op_sel_hi:[1,0]
	v_max_f32_e32 v126, 0, v126
	v_ashrrev_i32_e32 v3, 31, v2
	v_lshlrev_b64 v[138:139], 13, v[146:147]
	v_pk_mul_f32 v[132:133], v[132:133], v[140:141] op_sel_hi:[1,0]
	v_mul_f32_e32 v141, v126, v126
	v_max_f32_e32 v126, 0, v131
	v_max_f32_e32 v127, 0, v127
	v_max_f32_e32 v128, 0, v128
	v_lshl_add_u64 v[138:139], s[4:5], 0, v[138:139]
	v_lshlrev_b64 v[2:3], 1, v[2:3]
	v_max_f32_e32 v130, 0, v130
	v_mul_f32_e32 v126, v126, v126
	v_mul_f32_e32 v131, v127, v127
	v_max_f32_e32 v127, 0, v132
	v_mul_f32_e32 v132, v128, v128
	v_max_f32_e32 v128, 0, v133
	v_max_f32_e32 v129, 0, v129
	v_pk_mul_f32 v[118:119], v[118:119], v[140:141] op_sel_hi:[1,0]
	v_lshl_add_u64 v[138:139], v[138:139], 0, v[2:3]
	v_mul_f32_e32 v130, v130, v130
	v_mul_f32_e32 v127, v127, v127
	v_mul_f32_e32 v128, v128, v128
	v_mul_f32_e32 v129, v129, v129
	v_cvt_pk_bf16_f32 v126, v130, v126
	v_pk_mul_f32 v[122:123], v[122:123], v[140:141] op_sel_hi:[1,0]
	v_pk_mul_f32 v[120:121], v[120:121], v[140:141] op_sel_hi:[1,0]
	v_max_f32_e32 v118, 0, v118
	v_cvt_pk_bf16_f32 v127, v127, v128
	v_cvt_pk_bf16_f32 v128, v141, v131
	v_cvt_pk_bf16_f32 v129, v132, v129
	global_store_dwordx4 v[138:139], v[126:129], off
	v_pk_mul_f32 v[124:125], v[124:125], v[140:141] op_sel_hi:[1,0]
	v_max_f32_e32 v119, 0, v119
	v_mul_f32_e32 v126, v118, v118
	v_max_f32_e32 v118, 0, v123
	v_max_f32_e32 v120, 0, v120
	v_max_f32_e32 v122, 0, v122
	v_mul_f32_e32 v118, v118, v118
	v_mul_f32_e32 v123, v119, v119
	v_max_f32_e32 v119, 0, v124
	v_mul_f32_e32 v124, v120, v120
	v_max_f32_e32 v120, 0, v125
	v_max_f32_e32 v121, 0, v121
	v_mul_f32_e32 v122, v122, v122
	v_mul_f32_e32 v119, v119, v119
	v_mul_f32_e32 v120, v120, v120
	v_mul_f32_e32 v121, v121, v121
	v_cvt_pk_bf16_f32 v118, v122, v118
	v_cvt_pk_bf16_f32 v119, v119, v120
	v_cvt_pk_bf16_f32 v120, v126, v123
	v_cvt_pk_bf16_f32 v121, v124, v121
	global_store_dwordx4 v[138:139], v[118:121], off offset:64
	v_pk_mul_f32 v[110:111], v[110:111], v[144:145] op_sel_hi:[1,0]
	v_pk_mul_f32 v[114:115], v[114:115], v[144:145] op_sel_hi:[1,0]
	v_or_b32_e32 v118, 16, v146
	v_ashrrev_i32_e32 v119, 31, v118
	v_pk_mul_f32 v[112:113], v[112:113], v[144:145] op_sel_hi:[1,0]
	v_max_f32_e32 v110, 0, v110
	v_lshlrev_b64 v[118:119], 13, v[118:119]
	v_pk_mul_f32 v[116:117], v[116:117], v[144:145] op_sel_hi:[1,0]
	v_mul_f32_e32 v120, v110, v110
	v_max_f32_e32 v110, 0, v115
	v_max_f32_e32 v111, 0, v111
	v_max_f32_e32 v112, 0, v112
	v_lshl_add_u64 v[118:119], s[4:5], 0, v[118:119]
	v_max_f32_e32 v114, 0, v114
	v_mul_f32_e32 v110, v110, v110
	v_mul_f32_e32 v115, v111, v111
	v_max_f32_e32 v111, 0, v116
	v_mul_f32_e32 v116, v112, v112
	v_max_f32_e32 v112, 0, v117
	v_max_f32_e32 v113, 0, v113
	v_pk_mul_f32 v[102:103], v[102:103], v[144:145] op_sel_hi:[1,0]
	v_lshl_add_u64 v[118:119], v[118:119], 0, v[2:3]
	v_mul_f32_e32 v114, v114, v114
	v_mul_f32_e32 v111, v111, v111
	v_mul_f32_e32 v112, v112, v112
	v_mul_f32_e32 v113, v113, v113
	v_cvt_pk_bf16_f32 v110, v114, v110
	v_pk_mul_f32 v[106:107], v[106:107], v[144:145] op_sel_hi:[1,0]
	v_pk_mul_f32 v[104:105], v[104:105], v[144:145] op_sel_hi:[1,0]
	v_max_f32_e32 v102, 0, v102
	v_cvt_pk_bf16_f32 v111, v111, v112
	v_cvt_pk_bf16_f32 v112, v120, v115
	v_cvt_pk_bf16_f32 v113, v116, v113
	global_store_dwordx4 v[118:119], v[110:113], off
	v_pk_mul_f32 v[108:109], v[108:109], v[144:145] op_sel_hi:[1,0]
	v_max_f32_e32 v103, 0, v103
	v_mul_f32_e32 v110, v102, v102
	v_max_f32_e32 v102, 0, v107
	v_max_f32_e32 v104, 0, v104
	v_max_f32_e32 v106, 0, v106
	v_mul_f32_e32 v102, v102, v102
	v_mul_f32_e32 v107, v103, v103
	v_max_f32_e32 v103, 0, v108
	v_mul_f32_e32 v108, v104, v104
	v_max_f32_e32 v104, 0, v109
	v_max_f32_e32 v105, 0, v105
	v_mul_f32_e32 v106, v106, v106
	v_mul_f32_e32 v103, v103, v103
	v_mul_f32_e32 v104, v104, v104
	v_mul_f32_e32 v105, v105, v105
	v_cvt_pk_bf16_f32 v102, v106, v102
	v_cvt_pk_bf16_f32 v103, v103, v104
	v_cvt_pk_bf16_f32 v104, v110, v107
	v_cvt_pk_bf16_f32 v105, v108, v105
	global_store_dwordx4 v[118:119], v[102:105], off offset:64
	v_pk_mul_f32 v[94:95], v[94:95], v[148:149] op_sel_hi:[1,0]
	v_pk_mul_f32 v[98:99], v[98:99], v[148:149] op_sel_hi:[1,0]
	v_or_b32_e32 v102, 32, v146
	v_ashrrev_i32_e32 v103, 31, v102
	v_pk_mul_f32 v[96:97], v[96:97], v[148:149] op_sel_hi:[1,0]
	v_max_f32_e32 v94, 0, v94
	v_lshlrev_b64 v[102:103], 13, v[102:103]
	v_pk_mul_f32 v[100:101], v[100:101], v[148:149] op_sel_hi:[1,0]
	v_mul_f32_e32 v104, v94, v94
	v_max_f32_e32 v94, 0, v99
	v_max_f32_e32 v95, 0, v95
	v_max_f32_e32 v96, 0, v96
	v_lshl_add_u64 v[102:103], s[4:5], 0, v[102:103]
	v_max_f32_e32 v98, 0, v98
	v_mul_f32_e32 v94, v94, v94
	v_mul_f32_e32 v99, v95, v95
	v_max_f32_e32 v95, 0, v100
	v_mul_f32_e32 v100, v96, v96
	v_max_f32_e32 v96, 0, v101
	v_max_f32_e32 v97, 0, v97
	v_pk_mul_f32 v[86:87], v[86:87], v[148:149] op_sel_hi:[1,0]
	v_lshl_add_u64 v[102:103], v[102:103], 0, v[2:3]
	v_mul_f32_e32 v98, v98, v98
	v_mul_f32_e32 v95, v95, v95
	v_mul_f32_e32 v96, v96, v96
	v_mul_f32_e32 v97, v97, v97
	v_cvt_pk_bf16_f32 v94, v98, v94
	v_pk_mul_f32 v[90:91], v[90:91], v[148:149] op_sel_hi:[1,0]
	v_pk_mul_f32 v[88:89], v[88:89], v[148:149] op_sel_hi:[1,0]
	v_max_f32_e32 v86, 0, v86
	v_cvt_pk_bf16_f32 v95, v95, v96
	v_cvt_pk_bf16_f32 v96, v104, v99
	v_cvt_pk_bf16_f32 v97, v100, v97
	global_store_dwordx4 v[102:103], v[94:97], off
	v_pk_mul_f32 v[92:93], v[92:93], v[148:149] op_sel_hi:[1,0]
	v_max_f32_e32 v87, 0, v87
	v_mul_f32_e32 v94, v86, v86
	v_max_f32_e32 v86, 0, v91
	v_max_f32_e32 v88, 0, v88
	v_max_f32_e32 v90, 0, v90
	v_mul_f32_e32 v86, v86, v86
	v_mul_f32_e32 v91, v87, v87
	v_max_f32_e32 v87, 0, v92
	v_mul_f32_e32 v92, v88, v88
	v_max_f32_e32 v88, 0, v93
	v_max_f32_e32 v89, 0, v89
	v_mul_f32_e32 v90, v90, v90
	v_mul_f32_e32 v87, v87, v87
	v_mul_f32_e32 v88, v88, v88
	v_mul_f32_e32 v89, v89, v89
	v_cvt_pk_bf16_f32 v86, v90, v86
	v_cvt_pk_bf16_f32 v87, v87, v88
	v_cvt_pk_bf16_f32 v88, v94, v91
	v_cvt_pk_bf16_f32 v89, v92, v89
	global_store_dwordx4 v[102:103], v[86:89], off offset:64
	v_pk_mul_f32 v[78:79], v[78:79], v[150:151] op_sel_hi:[1,0]
	v_pk_mul_f32 v[82:83], v[82:83], v[150:151] op_sel_hi:[1,0]
	v_or_b32_e32 v86, 48, v146
	v_ashrrev_i32_e32 v87, 31, v86
	v_pk_mul_f32 v[80:81], v[80:81], v[150:151] op_sel_hi:[1,0]
	v_max_f32_e32 v78, 0, v78
	v_lshlrev_b64 v[86:87], 13, v[86:87]
	v_pk_mul_f32 v[84:85], v[84:85], v[150:151] op_sel_hi:[1,0]
	v_mul_f32_e32 v88, v78, v78
	v_max_f32_e32 v78, 0, v83
	v_max_f32_e32 v79, 0, v79
	v_max_f32_e32 v80, 0, v80
	v_lshl_add_u64 v[86:87], s[4:5], 0, v[86:87]
	v_max_f32_e32 v82, 0, v82
	v_mul_f32_e32 v78, v78, v78
	v_mul_f32_e32 v83, v79, v79
	v_max_f32_e32 v79, 0, v84
	v_mul_f32_e32 v84, v80, v80
	v_max_f32_e32 v80, 0, v85
	v_max_f32_e32 v81, 0, v81
	v_pk_mul_f32 v[72:73], v[72:73], v[150:151] op_sel_hi:[1,0]
	v_pk_mul_f32 v[70:71], v[70:71], v[150:151] op_sel_hi:[1,0]
	v_lshl_add_u64 v[86:87], v[86:87], 0, v[2:3]
	v_mul_f32_e32 v82, v82, v82
	v_mul_f32_e32 v79, v79, v79
	v_mul_f32_e32 v80, v80, v80
	v_mul_f32_e32 v81, v81, v81
	v_cvt_pk_bf16_f32 v78, v82, v78
	v_pk_mul_f32 v[76:77], v[76:77], v[150:151] op_sel_hi:[1,0]
	v_pk_mul_f32 v[74:75], v[74:75], v[150:151] op_sel_hi:[1,0]
	v_max_f32_e32 v70, 0, v70
	v_max_f32_e32 v71, 0, v71
	v_max_f32_e32 v72, 0, v72
	v_cvt_pk_bf16_f32 v79, v79, v80
	v_cvt_pk_bf16_f32 v80, v88, v83
	v_cvt_pk_bf16_f32 v81, v84, v81
	global_store_dwordx4 v[86:87], v[78:81], off
	v_max_f32_e32 v74, 0, v74
	v_max_f32_e32 v73, 0, v73
	v_mul_f32_e32 v78, v70, v70
	v_max_f32_e32 v70, 0, v75
	v_mul_f32_e32 v75, v71, v71
	v_max_f32_e32 v71, 0, v76
	v_mul_f32_e32 v76, v72, v72
	v_max_f32_e32 v72, 0, v77
	v_mul_f32_e32 v70, v70, v70
	v_mul_f32_e32 v71, v71, v71
	v_mul_f32_e32 v72, v72, v72
	v_pk_mul_f32 v[62:63], v[62:63], v[136:137] op_sel_hi:[1,0]
	v_mul_f32_e32 v74, v74, v74
	v_mul_f32_e32 v73, v73, v73
	v_cvt_pk_bf16_f32 v70, v74, v70
	v_cvt_pk_bf16_f32 v71, v71, v72
	v_cvt_pk_bf16_f32 v72, v78, v75
	v_pk_mul_f32 v[66:67], v[66:67], v[136:137] op_sel_hi:[1,0]
	v_pk_mul_f32 v[64:65], v[64:65], v[136:137] op_sel_hi:[1,0]
	v_max_f32_e32 v62, 0, v62
	v_cvt_pk_bf16_f32 v73, v76, v73
	global_store_dwordx4 v[86:87], v[70:73], off offset:64
	v_pk_mul_f32 v[68:69], v[68:69], v[136:137] op_sel_hi:[1,0]
	v_max_f32_e32 v63, 0, v63
	v_lshlrev_b64 v[70:71], 13, v[158:159]
	v_mul_f32_e32 v72, v62, v62
	v_max_f32_e32 v62, 0, v67
	v_max_f32_e32 v64, 0, v64
	v_lshl_add_u64 v[70:71], s[4:5], 0, v[70:71]
	v_max_f32_e32 v66, 0, v66
	v_mul_f32_e32 v62, v62, v62
	v_mul_f32_e32 v67, v63, v63
	v_max_f32_e32 v63, 0, v68
	v_mul_f32_e32 v68, v64, v64
	v_max_f32_e32 v64, 0, v69
	v_max_f32_e32 v65, 0, v65
	v_pk_mul_f32 v[54:55], v[54:55], v[136:137] op_sel_hi:[1,0]
	v_lshl_add_u64 v[70:71], v[70:71], 0, v[2:3]
	v_mul_f32_e32 v66, v66, v66
	v_mul_f32_e32 v63, v63, v63
	v_mul_f32_e32 v64, v64, v64
	v_mul_f32_e32 v65, v65, v65
	v_cvt_pk_bf16_f32 v62, v66, v62
	v_pk_mul_f32 v[60:61], v[60:61], v[136:137] op_sel_hi:[1,0]
	v_pk_mul_f32 v[58:59], v[58:59], v[136:137] op_sel_hi:[1,0]
	v_pk_mul_f32 v[56:57], v[56:57], v[136:137] op_sel_hi:[1,0]
	v_max_f32_e32 v54, 0, v54
	v_max_f32_e32 v55, 0, v55
	v_cvt_pk_bf16_f32 v63, v63, v64
	v_cvt_pk_bf16_f32 v64, v72, v67
	v_cvt_pk_bf16_f32 v65, v68, v65
	global_store_dwordx4 v[70:71], v[62:65], off
	v_max_f32_e32 v56, 0, v56
	v_max_f32_e32 v58, 0, v58
	v_mul_f32_e32 v62, v54, v54
	v_max_f32_e32 v54, 0, v59
	v_mul_f32_e32 v59, v55, v55
	v_max_f32_e32 v55, 0, v60
	v_mul_f32_e32 v54, v54, v54
	v_mul_f32_e32 v55, v55, v55
	v_mul_f32_e32 v60, v56, v56
	v_max_f32_e32 v56, 0, v61
	v_max_f32_e32 v57, 0, v57
	v_mul_f32_e32 v58, v58, v58
	v_mul_f32_e32 v56, v56, v56
	v_mul_f32_e32 v57, v57, v57
	v_cvt_pk_bf16_f32 v54, v58, v54
	v_cvt_pk_bf16_f32 v55, v55, v56
	v_ashrrev_i32_e32 v143, 31, v142
	v_pk_mul_f32 v[46:47], v[46:47], v[136:137] op_sel:[0,1]
	v_cvt_pk_bf16_f32 v56, v62, v59
	v_cvt_pk_bf16_f32 v57, v60, v57
	global_store_dwordx4 v[70:71], v[54:57], off offset:64
	v_pk_mul_f32 v[50:51], v[50:51], v[136:137] op_sel:[0,1]
	v_pk_mul_f32 v[48:49], v[48:49], v[136:137] op_sel:[0,1]
	v_lshlrev_b64 v[54:55], 13, v[142:143]
	v_max_f32_e32 v46, 0, v46
	v_lshl_add_u64 v[54:55], s[4:5], 0, v[54:55]
	v_pk_mul_f32 v[52:53], v[52:53], v[136:137] op_sel:[0,1]
	v_max_f32_e32 v50, 0, v50
	v_mul_f32_e32 v56, v46, v46
	v_max_f32_e32 v46, 0, v51
	v_max_f32_e32 v47, 0, v47
	v_max_f32_e32 v48, 0, v48
	v_lshl_add_u64 v[2:3], v[54:55], 0, v[2:3]
	v_mul_f32_e32 v50, v50, v50
	v_mul_f32_e32 v46, v46, v46
	v_mul_f32_e32 v51, v47, v47
	v_max_f32_e32 v47, 0, v52
	v_mul_f32_e32 v52, v48, v48
	v_max_f32_e32 v48, 0, v53
	s_mov_b32 s13, 0x20000
	v_mul_f32_e32 v47, v47, v47
	v_max_f32_e32 v49, 0, v49
	v_mul_f32_e32 v48, v48, v48
	v_cvt_pk_bf16_f32 v46, v50, v46
	v_add_co_u32_e32 v50, vcc, s13, v2
	v_pk_mul_f32 v[40:41], v[40:41], v[136:137] op_sel:[0,1]
	v_pk_mul_f32 v[38:39], v[38:39], v[136:137] op_sel:[0,1]
	v_mul_f32_e32 v49, v49, v49
	v_cvt_pk_bf16_f32 v47, v47, v48
	v_cvt_pk_bf16_f32 v48, v56, v51
	v_addc_co_u32_e32 v51, vcc, 0, v3, vcc
	v_pk_mul_f32 v[44:45], v[44:45], v[136:137] op_sel:[0,1]
	v_pk_mul_f32 v[42:43], v[42:43], v[136:137] op_sel:[0,1]
	v_max_f32_e32 v38, 0, v38
	v_max_f32_e32 v39, 0, v39
	v_max_f32_e32 v40, 0, v40
	v_cvt_pk_bf16_f32 v49, v52, v49
	global_store_dwordx4 v[50:51], v[46:49], off
	s_mov_b64 s[22:23], 0x20000
	v_max_f32_e32 v41, 0, v41
	v_mul_f32_e32 v46, v38, v38
	v_max_f32_e32 v38, 0, v43
	v_mul_f32_e32 v43, v39, v39
	v_max_f32_e32 v39, 0, v44
	v_mul_f32_e32 v44, v40, v40
	v_max_f32_e32 v40, 0, v45
	v_mul_f32_e32 v39, v39, v39
	v_mul_f32_e32 v40, v40, v40
	v_pk_mul_f32 v[30:31], v[30:31], v[152:153] op_sel_hi:[1,0]
	v_lshl_add_u64 v[54:55], v[2:3], 0, s[22:23]
	v_max_f32_e32 v42, 0, v42
	v_mul_f32_e32 v38, v38, v38
	v_mul_f32_e32 v41, v41, v41
	v_cvt_pk_bf16_f32 v39, v39, v40
	v_cvt_pk_bf16_f32 v40, v46, v43
	v_pk_mul_f32 v[34:35], v[34:35], v[152:153] op_sel_hi:[1,0]
	v_pk_mul_f32 v[32:33], v[32:33], v[152:153] op_sel_hi:[1,0]
	v_max_f32_e32 v30, 0, v30
	v_mul_f32_e32 v42, v42, v42
	v_cvt_pk_bf16_f32 v38, v42, v38
	v_cvt_pk_bf16_f32 v41, v44, v41
	global_store_dwordx4 v[54:55], v[38:41], off offset:64
	v_pk_mul_f32 v[36:37], v[36:37], v[152:153] op_sel_hi:[1,0]
	v_max_f32_e32 v34, 0, v34
	v_mul_f32_e32 v40, v30, v30
	v_max_f32_e32 v30, 0, v35
	v_max_f32_e32 v31, 0, v31
	v_max_f32_e32 v32, 0, v32
	v_mul_f32_e32 v34, v34, v34
	v_mul_f32_e32 v30, v30, v30
	v_mul_f32_e32 v35, v31, v31
	v_max_f32_e32 v31, 0, v36
	v_mul_f32_e32 v36, v32, v32
	v_max_f32_e32 v32, 0, v37
	v_mul_f32_e32 v31, v31, v31
	v_max_f32_e32 v33, 0, v33
	v_mul_f32_e32 v32, v32, v32
	v_cvt_pk_bf16_f32 v30, v34, v30
	v_add_co_u32_e32 v34, vcc, s72, v2
	v_pk_mul_f32 v[24:25], v[24:25], v[152:153] op_sel_hi:[1,0]
	v_pk_mul_f32 v[22:23], v[22:23], v[152:153] op_sel_hi:[1,0]
	v_mul_f32_e32 v33, v33, v33
	v_cvt_pk_bf16_f32 v31, v31, v32
	v_cvt_pk_bf16_f32 v32, v40, v35
	v_addc_co_u32_e32 v35, vcc, 0, v3, vcc
	v_pk_mul_f32 v[28:29], v[28:29], v[152:153] op_sel_hi:[1,0]
	v_pk_mul_f32 v[26:27], v[26:27], v[152:153] op_sel_hi:[1,0]
	v_max_f32_e32 v22, 0, v22
	v_max_f32_e32 v23, 0, v23
	v_max_f32_e32 v24, 0, v24
	v_cvt_pk_bf16_f32 v33, v36, v33
	global_store_dwordx4 v[34:35], v[30:33], off
	s_mov_b64 s[22:23], 0x40000
	v_max_f32_e32 v26, 0, v26
	v_mul_f32_e32 v30, v22, v22
	v_max_f32_e32 v22, 0, v27
	v_mul_f32_e32 v27, v23, v23
	v_max_f32_e32 v23, 0, v28
	v_mul_f32_e32 v28, v24, v24
	v_max_f32_e32 v24, 0, v29
	v_mul_f32_e32 v22, v22, v22
	v_mul_f32_e32 v23, v23, v23
	v_max_f32_e32 v25, 0, v25
	v_mul_f32_e32 v24, v24, v24
	v_pk_mul_f32 v[16:17], v[16:17], v[154:155] op_sel_hi:[1,0]
	v_pk_mul_f32 v[14:15], v[14:15], v[154:155] op_sel_hi:[1,0]
	v_lshl_add_u64 v[38:39], v[2:3], 0, s[22:23]
	v_mul_f32_e32 v26, v26, v26
	v_mul_f32_e32 v25, v25, v25
	v_cvt_pk_bf16_f32 v22, v26, v22
	v_cvt_pk_bf16_f32 v23, v23, v24
	v_cvt_pk_bf16_f32 v24, v30, v27
	s_mov_b64 s[22:23], 0x60000
	v_pk_mul_f32 v[20:21], v[20:21], v[154:155] op_sel_hi:[1,0]
	v_pk_mul_f32 v[18:19], v[18:19], v[154:155] op_sel_hi:[1,0]
	v_max_f32_e32 v14, 0, v14
	v_max_f32_e32 v15, 0, v15
	v_max_f32_e32 v16, 0, v16
	s_mov_b32 s13, 0x60000
	v_cvt_pk_bf16_f32 v25, v28, v25
	global_store_dwordx4 v[38:39], v[22:25], off offset:64
	v_max_f32_e32 v17, 0, v17
	v_pk_mul_f32 v[6:7], v[6:7], v[154:155] op_sel_hi:[1,0]
	v_lshl_add_u64 v[22:23], v[2:3], 0, s[22:23]
	v_mul_f32_e32 v24, v14, v14
	v_max_f32_e32 v14, 0, v19
	v_mul_f32_e32 v19, v15, v15
	v_max_f32_e32 v15, 0, v20
	v_mul_f32_e32 v20, v16, v16
	v_max_f32_e32 v16, 0, v21
	v_add_co_u32_e32 v2, vcc, s13, v2
	v_max_f32_e32 v18, 0, v18
	v_mul_f32_e32 v14, v14, v14
	v_mul_f32_e32 v15, v15, v15
	v_mul_f32_e32 v16, v16, v16
	v_mul_f32_e32 v17, v17, v17
	v_addc_co_u32_e32 v3, vcc, 0, v3, vcc
	v_pk_mul_f32 v[10:11], v[10:11], v[154:155] op_sel_hi:[1,0]
	v_pk_mul_f32 v[8:9], v[8:9], v[154:155] op_sel_hi:[1,0]
	v_max_f32_e32 v6, 0, v6
	v_max_f32_e32 v7, 0, v7
	v_mul_f32_e32 v18, v18, v18
	v_cvt_pk_bf16_f32 v14, v18, v14
	v_cvt_pk_bf16_f32 v15, v15, v16
	v_cvt_pk_bf16_f32 v16, v24, v19
	v_cvt_pk_bf16_f32 v17, v20, v17
	global_store_dwordx4 v[2:3], v[14:17], off
	v_pk_mul_f32 v[2:3], v[12:13], v[154:155] op_sel_hi:[1,0]
	v_mul_f32_e32 v12, v6, v6
	v_max_f32_e32 v6, 0, v11
	v_mul_f32_e32 v11, v7, v7
	v_max_f32_e32 v7, 0, v8
	v_mul_f32_e32 v13, v7, v7
	v_max_f32_e32 v7, 0, v9
	v_max_f32_e32 v10, 0, v10
	v_mul_f32_e32 v6, v6, v6
	v_max_f32_e32 v2, 0, v2
	v_max_f32_e32 v3, 0, v3
	v_mul_f32_e32 v9, v7, v7
	s_andn2_b64 vcc, exec, s[20:21]
	s_mov_b64 s[20:21], -1
	v_mul_f32_e32 v10, v10, v10
	v_mul_f32_e32 v2, v2, v2
	v_mul_f32_e32 v3, v3, v3
	v_cvt_pk_bf16_f32 v6, v10, v6
	v_cvt_pk_bf16_f32 v7, v2, v3
	v_cvt_pk_bf16_f32 v8, v12, v11
	v_cvt_pk_bf16_f32 v9, v13, v9
	global_store_dwordx4 v[22:23], v[6:9], off offset:64
	s_cbranch_vccnz .LBB0_936
	s_andn2_b64 vcc, exec, s[2:3]
	s_cbranch_vccnz .LBB0_935
	s_barrier
	s_branch .LBB0_935

.LBB0_1027:
	v_lshl_add_u32 v198, s78, 8, v5
	v_lshl_or_b32 v200, s79, 8, v242
	v_ashrrev_i32_e32 v201, 31, v200
	v_ashrrev_i32_e32 v199, 31, v198
	v_lshl_add_u64 v[202:203], v[200:201], 1, s[16:17]
	v_lshlrev_b64 v[90:91], 11, v[198:199]
	v_or_b32_e32 v228, 16, v198
	v_lshl_add_u64 v[90:91], v[202:203], 0, v[90:91]
	v_ashrrev_i32_e32 v229, 31, v228
	global_load_dwordx4 v[194:197], v[90:91], off
	global_load_dwordx4 v[190:193], v[90:91], off offset:64
	v_lshlrev_b64 v[90:91], 11, v[228:229]
	v_or_b32_e32 v226, 32, v198
	v_lshl_add_u64 v[90:91], v[202:203], 0, v[90:91]
	v_ashrrev_i32_e32 v227, 31, v226
	global_load_dwordx4 v[186:189], v[90:91], off
	global_load_dwordx4 v[182:185], v[90:91], off offset:64
	v_lshlrev_b64 v[90:91], 11, v[226:227]
	v_or_b32_e32 v212, 48, v198
	v_lshl_add_u64 v[90:91], v[202:203], 0, v[90:91]
	v_ashrrev_i32_e32 v213, 31, v212
	global_load_dwordx4 v[178:181], v[90:91], off
	global_load_dwordx4 v[174:177], v[90:91], off offset:64
	v_lshlrev_b64 v[90:91], 11, v[212:213]
	v_add_u32_e32 v210, 0x80, v198
	v_lshl_add_u64 v[90:91], v[202:203], 0, v[90:91]
	v_ashrrev_i32_e32 v211, 31, v210
	global_load_dwordx4 v[170:173], v[90:91], off
	global_load_dwordx4 v[166:169], v[90:91], off offset:64
	v_lshlrev_b64 v[90:91], 11, v[210:211]
	v_add_u32_e32 v208, 0x90, v198
	v_lshl_add_u64 v[90:91], v[202:203], 0, v[90:91]
	v_ashrrev_i32_e32 v209, 31, v208
	global_load_dwordx4 v[162:165], v[90:91], off
	global_load_dwordx4 v[158:161], v[90:91], off offset:64
	v_lshlrev_b64 v[90:91], 11, v[208:209]
	v_add_u32_e32 v206, 0xa0, v198
	v_lshl_add_u64 v[90:91], v[202:203], 0, v[90:91]
	v_ashrrev_i32_e32 v207, 31, v206
	global_load_dwordx4 v[146:149], v[90:91], off
	global_load_dwordx4 v[134:137], v[90:91], off offset:64
	v_lshlrev_b64 v[90:91], 11, v[206:207]
	v_add_u32_e32 v204, 0xb0, v198
	v_lshl_add_u64 v[90:91], v[202:203], 0, v[90:91]
	v_ashrrev_i32_e32 v205, 31, v204
	global_load_dwordx4 v[126:129], v[90:91], off
	global_load_dwordx4 v[114:117], v[90:91], off offset:64
	v_lshlrev_b64 v[90:91], 11, v[204:205]
	v_lshl_add_u64 v[90:91], v[202:203], 0, v[90:91]
	global_load_dwordx4 v[106:109], v[90:91], off
	s_nop 0
	global_load_dwordx4 v[90:93], v[90:91], off offset:64
	v_cndmask_b32_e64 v230, 0, 1, s[24:25]
	v_cmp_ne_u32_e64 s[6:7], 1, v230
	v_lshlrev_b64 v[230:231], 10, v[198:199]
	v_lshl_add_u64 v[232:233], v[230:231], 0, v[200:201]
	s_mov_b64 s[8:9], -1
	s_andn2_b64 vcc, exec, s[24:25]
	s_waitcnt vmcnt(0)
	v_lshlrev_b32_e32 v246, 16, v194
	v_and_b32_e32 v247, 0xffff0000, v194
	v_lshlrev_b32_e32 v194, 16, v195
	v_and_b32_e32 v195, 0xffff0000, v195
	v_lshlrev_b32_e32 v248, 16, v196
	v_and_b32_e32 v249, 0xffff0000, v196
	v_lshlrev_b32_e32 v250, 16, v197
	v_and_b32_e32 v251, 0xffff0000, v197
	v_pk_add_f32 v[196:197], v[152:153], v[194:195]
	v_pk_add_f32 v[194:195], v[150:151], v[246:247]
	v_pk_add_f32 v[152:153], v[156:157], v[250:251]
	v_pk_add_f32 v[150:151], v[154:155], v[248:249]
	v_lshl_add_u64 v[156:157], v[232:233], 2, s[12:13]
	s_cbranch_vccnz .LBB0_1029
	s_mov_b64 s[8:9], 0
	global_store_dwordx4 v[156:157], v[194:197], off
	global_store_dwordx4 v[156:157], v[150:153], off offset:16
.LBB0_1029:
	v_mov_b32_e32 v232, 0
	s_andn2_b64 vcc, exec, s[8:9]
	v_lshl_add_u64 v[154:155], v[230:231], 1, v[202:203]
	s_cbranch_vccnz .LBB0_1031
	v_mov_b32_e32 v232, v195
	v_mov_b32_e32 v233, v151
	v_mov_b32_e32 v230, v194
	v_mov_b32_e32 v231, v150
	v_pk_mul_f32 v[232:233], v[232:233], v[232:233]
	v_mov_b32_e32 v246, v197
	v_mov_b32_e32 v247, v153
	v_pk_fma_f32 v[230:231], v[230:231], v[230:231], v[232:233]
	v_mov_b32_e32 v232, v196
	v_mov_b32_e32 v233, v152
	v_pk_mul_f32 v[246:247], v[246:247], v[246:247]
	v_cvt_pk_bf16_f32 v194, v194, v195
	v_cvt_pk_bf16_f32 v195, v196, v197
	v_cvt_pk_bf16_f32 v196, v150, v151
	v_cvt_pk_bf16_f32 v197, v152, v153
	global_store_dwordx4 v[154:155], v[194:197], off
	v_pk_fma_f32 v[232:233], v[232:233], v[232:233], v[246:247]
	s_nop 0
	v_pk_add_f32 v[230:231], v[230:231], v[232:233]
	s_nop 0
	v_add_f32_e32 v232, v230, v231
.LBB0_1031:
	v_lshlrev_b32_e32 v150, 16, v190
	v_and_b32_e32 v151, 0xffff0000, v190
	v_lshlrev_b32_e32 v152, 16, v191
	v_and_b32_e32 v153, 0xffff0000, v191
	v_lshlrev_b32_e32 v190, 16, v192
	v_and_b32_e32 v191, 0xffff0000, v192
	v_lshlrev_b32_e32 v192, 16, v193
	v_and_b32_e32 v193, 0xffff0000, v193
	v_pk_add_f32 v[144:145], v[144:145], v[152:153]
	v_pk_add_f32 v[142:143], v[142:143], v[150:151]
	v_pk_add_f32 v[140:141], v[140:141], v[192:193]
	v_pk_add_f32 v[138:139], v[138:139], v[190:191]
	s_and_b64 vcc, exec, s[6:7]
	s_mov_b64 s[8:9], -1
	s_cbranch_vccnz .LBB0_1033
	s_mov_b64 s[8:9], 0
	global_store_dwordx4 v[156:157], v[142:145], off offset:128
	global_store_dwordx4 v[156:157], v[138:141], off offset:144
.LBB0_1033:
	s_andn2_b64 vcc, exec, s[8:9]
	s_cbranch_vccnz .LBB0_1035
	v_mov_b32_e32 v152, v143
	v_mov_b32_e32 v153, v139
	v_mov_b32_e32 v150, v142
	v_mov_b32_e32 v151, v138
	v_pk_mul_f32 v[152:153], v[152:153], v[152:153]
	v_mov_b32_e32 v156, v145
	v_mov_b32_e32 v157, v141
	v_pk_fma_f32 v[150:151], v[150:151], v[150:151], v[152:153]
	v_mov_b32_e32 v152, v144
	v_mov_b32_e32 v153, v140
	v_pk_mul_f32 v[156:157], v[156:157], v[156:157]
	v_cvt_pk_bf16_f32 v142, v142, v143
	v_cvt_pk_bf16_f32 v143, v144, v145
	v_cvt_pk_bf16_f32 v144, v138, v139
	v_cvt_pk_bf16_f32 v145, v140, v141
	global_store_dwordx4 v[154:155], v[142:145], off offset:64
	v_pk_fma_f32 v[152:153], v[152:153], v[152:153], v[156:157]
	s_nop 0
	v_pk_add_f32 v[150:151], v[150:151], v[152:153]
	s_nop 0
	v_add_f32_e32 v150, v150, v151
	v_add_f32_e32 v232, v150, v232

.LBB0_1039:
	v_lshlrev_b64 v[138:139], 10, v[228:229]
	v_lshl_add_u64 v[140:141], v[138:139], 0, v[200:201]
	v_lshlrev_b32_e32 v142, 16, v186
	v_and_b32_e32 v143, 0xffff0000, v186
	v_lshlrev_b32_e32 v144, 16, v187
	v_and_b32_e32 v145, 0xffff0000, v187
	v_lshlrev_b32_e32 v150, 16, v188
	v_and_b32_e32 v151, 0xffff0000, v188
	v_lshlrev_b32_e32 v152, 16, v189
	v_and_b32_e32 v153, 0xffff0000, v189
	v_pk_add_f32 v[132:133], v[132:133], v[144:145]
	v_pk_add_f32 v[130:131], v[130:131], v[142:143]
	v_pk_add_f32 v[124:125], v[124:125], v[152:153]
	v_pk_add_f32 v[122:123], v[122:123], v[150:151]
	s_mov_b64 s[42:43], -1
	s_and_b64 vcc, exec, s[6:7]
	v_lshl_add_u64 v[140:141], v[140:141], 2, s[12:13]
	s_cbranch_vccnz .LBB0_1041
	s_mov_b64 s[42:43], 0
	global_store_dwordx4 v[140:141], v[130:133], off
	global_store_dwordx4 v[140:141], v[122:125], off offset:16
.LBB0_1041:
	v_mov_b32_e32 v142, 0
	s_andn2_b64 vcc, exec, s[42:43]
	v_lshl_add_u64 v[138:139], v[138:139], 1, v[202:203]
	s_cbranch_vccnz .LBB0_1043
	v_mov_b32_e32 v144, v131
	v_mov_b32_e32 v145, v123
	v_mov_b32_e32 v142, v130
	v_mov_b32_e32 v143, v122
	v_pk_mul_f32 v[144:145], v[144:145], v[144:145]
	v_mov_b32_e32 v150, v133
	v_mov_b32_e32 v151, v125
	v_pk_fma_f32 v[142:143], v[142:143], v[142:143], v[144:145]
	v_mov_b32_e32 v144, v132
	v_mov_b32_e32 v145, v124
	v_pk_mul_f32 v[150:151], v[150:151], v[150:151]
	v_cvt_pk_bf16_f32 v130, v130, v131
	v_cvt_pk_bf16_f32 v131, v132, v133
	v_cvt_pk_bf16_f32 v132, v122, v123
	v_cvt_pk_bf16_f32 v133, v124, v125
	global_store_dwordx4 v[138:139], v[130:133], off
	v_pk_fma_f32 v[144:145], v[144:145], v[144:145], v[150:151]
	s_nop 0
	v_pk_add_f32 v[142:143], v[142:143], v[144:145]
	s_nop 0
	v_add_f32_e32 v142, v142, v143

.LBB0_1046:
	global_store_dwordx4 v[140:141], v[118:121], off offset:128
	global_store_dwordx4 v[140:141], v[110:113], off offset:144
	s_cbranch_execnz .LBB0_1045
.LBB0_1047:
	v_mov_b32_e32 v124, v119
	v_mov_b32_e32 v125, v111
	v_mov_b32_e32 v122, v118
	v_mov_b32_e32 v123, v110
	v_pk_mul_f32 v[124:125], v[124:125], v[124:125]
	v_mov_b32_e32 v130, v121
	v_mov_b32_e32 v131, v113
	v_pk_fma_f32 v[122:123], v[122:123], v[122:123], v[124:125]
	v_mov_b32_e32 v124, v120
	v_mov_b32_e32 v125, v112
	v_pk_mul_f32 v[130:131], v[130:131], v[130:131]
	v_cvt_pk_bf16_f32 v118, v118, v119
	v_cvt_pk_bf16_f32 v119, v120, v121
	v_cvt_pk_bf16_f32 v120, v110, v111
	v_cvt_pk_bf16_f32 v121, v112, v113
	global_store_dwordx4 v[138:139], v[118:121], off offset:64
	v_pk_fma_f32 v[124:125], v[124:125], v[124:125], v[130:131]
	s_nop 0
	v_pk_add_f32 v[122:123], v[122:123], v[124:125]
	s_nop 0
	v_add_f32_e32 v122, v122, v123
	v_add_f32_e32 v142, v122, v142
	s_and_b64 vcc, exec, s[8:9]
	s_cbranch_vccnz .LBB0_1051

.LBB0_1051:
	v_lshlrev_b64 v[110:111], 10, v[226:227]
	v_lshl_add_u64 v[112:113], v[110:111], 0, v[200:201]
	v_lshlrev_b32_e32 v118, 16, v178
	v_and_b32_e32 v119, 0xffff0000, v178
	v_lshlrev_b32_e32 v120, 16, v179
	v_and_b32_e32 v121, 0xffff0000, v179
	v_lshlrev_b32_e32 v122, 16, v180
	v_and_b32_e32 v123, 0xffff0000, v180
	v_lshlrev_b32_e32 v124, 16, v181
	v_and_b32_e32 v125, 0xffff0000, v181
	v_pk_add_f32 v[104:105], v[104:105], v[120:121]
	v_pk_add_f32 v[102:103], v[102:103], v[118:119]
	v_pk_add_f32 v[100:101], v[100:101], v[124:125]
	v_pk_add_f32 v[98:99], v[98:99], v[122:123]
	s_mov_b64 s[42:43], -1
	s_and_b64 vcc, exec, s[6:7]
	v_lshl_add_u64 v[112:113], v[112:113], 2, s[12:13]
	s_cbranch_vccnz .LBB0_1053
	s_mov_b64 s[42:43], 0
	global_store_dwordx4 v[112:113], v[102:105], off
	global_store_dwordx4 v[112:113], v[98:101], off offset:16
.LBB0_1053:
	v_mov_b32_e32 v118, 0
	s_andn2_b64 vcc, exec, s[42:43]
	v_lshl_add_u64 v[110:111], v[110:111], 1, v[202:203]
	s_cbranch_vccnz .LBB0_1055
	v_mov_b32_e32 v120, v103
	v_mov_b32_e32 v121, v99
	v_mov_b32_e32 v118, v102
	v_mov_b32_e32 v119, v98
	v_pk_mul_f32 v[120:121], v[120:121], v[120:121]
	v_mov_b32_e32 v122, v105
	v_mov_b32_e32 v123, v101
	v_pk_fma_f32 v[118:119], v[118:119], v[118:119], v[120:121]
	v_mov_b32_e32 v120, v104
	v_mov_b32_e32 v121, v100
	v_pk_mul_f32 v[122:123], v[122:123], v[122:123]
	v_cvt_pk_bf16_f32 v102, v102, v103
	v_cvt_pk_bf16_f32 v103, v104, v105
	v_cvt_pk_bf16_f32 v104, v98, v99
	v_cvt_pk_bf16_f32 v105, v100, v101
	global_store_dwordx4 v[110:111], v[102:105], off
	v_pk_fma_f32 v[120:121], v[120:121], v[120:121], v[122:123]
	s_nop 0
	v_pk_add_f32 v[118:119], v[118:119], v[120:121]
	s_nop 0
	v_add_f32_e32 v118, v118, v119

.LBB0_1058:
	global_store_dwordx4 v[112:113], v[94:97], off offset:128
	global_store_dwordx4 v[112:113], v[86:89], off offset:144
	s_cbranch_execnz .LBB0_1057
.LBB0_1059:
	v_mov_b32_e32 v100, v95
	v_mov_b32_e32 v101, v87
	v_mov_b32_e32 v98, v94
	v_mov_b32_e32 v99, v86
	v_pk_mul_f32 v[100:101], v[100:101], v[100:101]
	v_mov_b32_e32 v102, v97
	v_mov_b32_e32 v103, v89
	v_pk_fma_f32 v[98:99], v[98:99], v[98:99], v[100:101]
	v_mov_b32_e32 v100, v96
	v_mov_b32_e32 v101, v88
	v_pk_mul_f32 v[102:103], v[102:103], v[102:103]
	v_cvt_pk_bf16_f32 v94, v94, v95
	v_cvt_pk_bf16_f32 v95, v96, v97
	v_cvt_pk_bf16_f32 v96, v86, v87
	v_cvt_pk_bf16_f32 v97, v88, v89
	global_store_dwordx4 v[110:111], v[94:97], off offset:64
	v_pk_fma_f32 v[100:101], v[100:101], v[100:101], v[102:103]
	s_nop 0
	v_pk_add_f32 v[98:99], v[98:99], v[100:101]
	s_nop 0
	v_add_f32_e32 v98, v98, v99
	v_add_f32_e32 v118, v98, v118
	s_and_b64 vcc, exec, s[8:9]
	s_cbranch_vccnz .LBB0_1063

.LBB0_1063:
	v_lshlrev_b64 v[86:87], 10, v[212:213]
	v_lshl_add_u64 v[88:89], v[86:87], 0, v[200:201]
	v_lshlrev_b32_e32 v94, 16, v170
	v_and_b32_e32 v95, 0xffff0000, v170
	v_lshlrev_b32_e32 v96, 16, v171
	v_and_b32_e32 v97, 0xffff0000, v171
	v_lshlrev_b32_e32 v98, 16, v172
	v_and_b32_e32 v99, 0xffff0000, v172
	v_lshlrev_b32_e32 v100, 16, v173
	v_and_b32_e32 v101, 0xffff0000, v173
	v_pk_add_f32 v[84:85], v[84:85], v[96:97]
	v_pk_add_f32 v[82:83], v[82:83], v[94:95]
	v_pk_add_f32 v[80:81], v[80:81], v[100:101]
	v_pk_add_f32 v[78:79], v[78:79], v[98:99]
	s_mov_b64 s[42:43], -1
	s_and_b64 vcc, exec, s[6:7]
	v_lshl_add_u64 v[88:89], v[88:89], 2, s[12:13]
	s_cbranch_vccnz .LBB0_1065
	s_mov_b64 s[42:43], 0
	global_store_dwordx4 v[88:89], v[82:85], off
	global_store_dwordx4 v[88:89], v[78:81], off offset:16
.LBB0_1065:
	v_mov_b32_e32 v94, 0
	s_andn2_b64 vcc, exec, s[42:43]
	v_lshl_add_u64 v[86:87], v[86:87], 1, v[202:203]
	s_cbranch_vccnz .LBB0_1067
	v_mov_b32_e32 v96, v83
	v_mov_b32_e32 v97, v79
	v_mov_b32_e32 v94, v82
	v_mov_b32_e32 v95, v78
	v_pk_mul_f32 v[96:97], v[96:97], v[96:97]
	v_mov_b32_e32 v98, v85
	v_mov_b32_e32 v99, v81
	v_pk_fma_f32 v[94:95], v[94:95], v[94:95], v[96:97]
	v_mov_b32_e32 v96, v84
	v_mov_b32_e32 v97, v80
	v_pk_mul_f32 v[98:99], v[98:99], v[98:99]
	v_cvt_pk_bf16_f32 v82, v82, v83
	v_cvt_pk_bf16_f32 v83, v84, v85
	v_cvt_pk_bf16_f32 v84, v78, v79
	v_cvt_pk_bf16_f32 v85, v80, v81
	global_store_dwordx4 v[86:87], v[82:85], off
	v_pk_fma_f32 v[96:97], v[96:97], v[96:97], v[98:99]
	s_nop 0
	v_pk_add_f32 v[94:95], v[94:95], v[96:97]
	s_nop 0
	v_add_f32_e32 v94, v94, v95

.LBB0_1070:
	global_store_dwordx4 v[88:89], v[74:77], off offset:128
	global_store_dwordx4 v[88:89], v[70:73], off offset:144
	s_cbranch_execnz .LBB0_1069
.LBB0_1071:
	v_mov_b32_e32 v80, v75
	v_mov_b32_e32 v81, v71
	v_mov_b32_e32 v78, v74
	v_mov_b32_e32 v79, v70
	v_pk_mul_f32 v[80:81], v[80:81], v[80:81]
	v_mov_b32_e32 v82, v77
	v_mov_b32_e32 v83, v73
	v_pk_fma_f32 v[78:79], v[78:79], v[78:79], v[80:81]
	v_mov_b32_e32 v80, v76
	v_mov_b32_e32 v81, v72
	v_pk_mul_f32 v[82:83], v[82:83], v[82:83]
	v_cvt_pk_bf16_f32 v74, v74, v75
	v_cvt_pk_bf16_f32 v75, v76, v77
	v_cvt_pk_bf16_f32 v76, v70, v71
	v_cvt_pk_bf16_f32 v77, v72, v73
	global_store_dwordx4 v[86:87], v[74:77], off offset:64
	v_pk_fma_f32 v[80:81], v[80:81], v[80:81], v[82:83]
	s_nop 0
	v_pk_add_f32 v[78:79], v[78:79], v[80:81]
	s_nop 0
	v_add_f32_e32 v78, v78, v79
	v_add_f32_e32 v94, v78, v94
	s_and_b64 vcc, exec, s[8:9]
	s_cbranch_vccnz .LBB0_1075

.LBB0_1075:
	v_lshlrev_b64 v[70:71], 10, v[210:211]
	v_lshl_add_u64 v[72:73], v[70:71], 0, v[200:201]
	v_lshlrev_b32_e32 v74, 16, v162
	v_and_b32_e32 v75, 0xffff0000, v162
	v_lshlrev_b32_e32 v76, 16, v163
	v_and_b32_e32 v77, 0xffff0000, v163
	v_lshlrev_b32_e32 v78, 16, v164
	v_and_b32_e32 v79, 0xffff0000, v164
	v_lshlrev_b32_e32 v80, 16, v165
	v_and_b32_e32 v81, 0xffff0000, v165
	v_pk_add_f32 v[68:69], v[68:69], v[76:77]
	v_pk_add_f32 v[66:67], v[66:67], v[74:75]
	v_pk_add_f32 v[64:65], v[64:65], v[80:81]
	v_pk_add_f32 v[62:63], v[62:63], v[78:79]
	s_mov_b64 s[42:43], -1
	s_and_b64 vcc, exec, s[6:7]
	v_lshl_add_u64 v[72:73], v[72:73], 2, s[12:13]
	s_cbranch_vccnz .LBB0_1077
	s_mov_b64 s[42:43], 0
	global_store_dwordx4 v[72:73], v[66:69], off
	global_store_dwordx4 v[72:73], v[62:65], off offset:16
.LBB0_1077:
	v_mov_b32_e32 v74, 0
	s_andn2_b64 vcc, exec, s[42:43]
	v_lshl_add_u64 v[70:71], v[70:71], 1, v[202:203]
	s_cbranch_vccnz .LBB0_1079
	v_mov_b32_e32 v76, v67
	v_mov_b32_e32 v77, v63
	v_mov_b32_e32 v74, v66
	v_mov_b32_e32 v75, v62
	v_pk_mul_f32 v[76:77], v[76:77], v[76:77]
	v_mov_b32_e32 v78, v69
	v_mov_b32_e32 v79, v65
	v_pk_fma_f32 v[74:75], v[74:75], v[74:75], v[76:77]
	v_mov_b32_e32 v76, v68
	v_mov_b32_e32 v77, v64
	v_pk_mul_f32 v[78:79], v[78:79], v[78:79]
	v_cvt_pk_bf16_f32 v66, v66, v67
	v_cvt_pk_bf16_f32 v67, v68, v69
	v_cvt_pk_bf16_f32 v68, v62, v63
	v_cvt_pk_bf16_f32 v69, v64, v65
	global_store_dwordx4 v[70:71], v[66:69], off
	v_pk_fma_f32 v[76:77], v[76:77], v[76:77], v[78:79]
	s_nop 0
	v_pk_add_f32 v[74:75], v[74:75], v[76:77]
	s_nop 0
	v_add_f32_e32 v74, v74, v75

.LBB0_1082:
	global_store_dwordx4 v[72:73], v[58:61], off offset:128
	global_store_dwordx4 v[72:73], v[54:57], off offset:144
	s_cbranch_execnz .LBB0_1081
.LBB0_1083:
	v_mov_b32_e32 v64, v59
	v_mov_b32_e32 v65, v55
	v_mov_b32_e32 v62, v58
	v_mov_b32_e32 v63, v54
	v_pk_mul_f32 v[64:65], v[64:65], v[64:65]
	v_mov_b32_e32 v66, v61
	v_mov_b32_e32 v67, v57
	v_pk_fma_f32 v[62:63], v[62:63], v[62:63], v[64:65]
	v_mov_b32_e32 v64, v60
	v_mov_b32_e32 v65, v56
	v_pk_mul_f32 v[66:67], v[66:67], v[66:67]
	v_cvt_pk_bf16_f32 v58, v58, v59
	v_cvt_pk_bf16_f32 v59, v60, v61
	v_cvt_pk_bf16_f32 v60, v54, v55
	v_cvt_pk_bf16_f32 v61, v56, v57
	global_store_dwordx4 v[70:71], v[58:61], off offset:64
	v_pk_fma_f32 v[64:65], v[64:65], v[64:65], v[66:67]
	s_nop 0
	v_pk_add_f32 v[62:63], v[62:63], v[64:65]
	s_nop 0
	v_add_f32_e32 v62, v62, v63
	v_add_f32_e32 v74, v62, v74
	s_and_b64 vcc, exec, s[8:9]
	s_cbranch_vccnz .LBB0_1087

.LBB0_1087:
	v_lshlrev_b64 v[54:55], 10, v[208:209]
	v_lshl_add_u64 v[56:57], v[54:55], 0, v[200:201]
	v_lshlrev_b32_e32 v58, 16, v146
	v_and_b32_e32 v59, 0xffff0000, v146
	v_lshlrev_b32_e32 v60, 16, v147
	v_and_b32_e32 v61, 0xffff0000, v147
	v_lshlrev_b32_e32 v62, 16, v148
	v_and_b32_e32 v63, 0xffff0000, v148
	v_lshlrev_b32_e32 v64, 16, v149
	v_and_b32_e32 v65, 0xffff0000, v149
	v_pk_add_f32 v[52:53], v[52:53], v[60:61]
	v_pk_add_f32 v[50:51], v[50:51], v[58:59]
	v_pk_add_f32 v[48:49], v[48:49], v[64:65]
	v_pk_add_f32 v[46:47], v[46:47], v[62:63]
	s_mov_b64 s[42:43], -1
	s_and_b64 vcc, exec, s[6:7]
	v_lshl_add_u64 v[56:57], v[56:57], 2, s[12:13]
	s_cbranch_vccnz .LBB0_1089
	s_mov_b64 s[42:43], 0
	global_store_dwordx4 v[56:57], v[50:53], off
	global_store_dwordx4 v[56:57], v[46:49], off offset:16
.LBB0_1089:
	v_mov_b32_e32 v58, 0
	s_andn2_b64 vcc, exec, s[42:43]
	v_lshl_add_u64 v[54:55], v[54:55], 1, v[202:203]
	s_cbranch_vccnz .LBB0_1091
	v_mov_b32_e32 v60, v51
	v_mov_b32_e32 v61, v47
	v_mov_b32_e32 v58, v50
	v_mov_b32_e32 v59, v46
	v_pk_mul_f32 v[60:61], v[60:61], v[60:61]
	v_mov_b32_e32 v62, v53
	v_mov_b32_e32 v63, v49
	v_pk_fma_f32 v[58:59], v[58:59], v[58:59], v[60:61]
	v_mov_b32_e32 v60, v52
	v_mov_b32_e32 v61, v48
	v_pk_mul_f32 v[62:63], v[62:63], v[62:63]
	v_cvt_pk_bf16_f32 v50, v50, v51
	v_cvt_pk_bf16_f32 v51, v52, v53
	v_cvt_pk_bf16_f32 v52, v46, v47
	v_cvt_pk_bf16_f32 v53, v48, v49
	global_store_dwordx4 v[54:55], v[50:53], off
	v_pk_fma_f32 v[60:61], v[60:61], v[60:61], v[62:63]
	s_nop 0
	v_pk_add_f32 v[58:59], v[58:59], v[60:61]
	s_nop 0
	v_add_f32_e32 v58, v58, v59

.LBB0_1094:
	global_store_dwordx4 v[56:57], v[42:45], off offset:128
	global_store_dwordx4 v[56:57], v[38:41], off offset:144
	s_cbranch_execnz .LBB0_1093
.LBB0_1095:
	v_mov_b32_e32 v48, v43
	v_mov_b32_e32 v49, v39
	v_mov_b32_e32 v46, v42
	v_mov_b32_e32 v47, v38
	v_pk_mul_f32 v[48:49], v[48:49], v[48:49]
	v_mov_b32_e32 v50, v45
	v_mov_b32_e32 v51, v41
	v_pk_fma_f32 v[46:47], v[46:47], v[46:47], v[48:49]
	v_mov_b32_e32 v48, v44
	v_mov_b32_e32 v49, v40
	v_pk_mul_f32 v[50:51], v[50:51], v[50:51]
	v_cvt_pk_bf16_f32 v42, v42, v43
	v_cvt_pk_bf16_f32 v43, v44, v45
	v_cvt_pk_bf16_f32 v44, v38, v39
	v_cvt_pk_bf16_f32 v45, v40, v41
	global_store_dwordx4 v[54:55], v[42:45], off offset:64
	v_pk_fma_f32 v[48:49], v[48:49], v[48:49], v[50:51]
	s_nop 0
	v_pk_add_f32 v[46:47], v[46:47], v[48:49]
	s_nop 0
	v_add_f32_e32 v46, v46, v47
	v_add_f32_e32 v58, v46, v58
	s_and_b64 vcc, exec, s[8:9]
	s_cbranch_vccnz .LBB0_1099

.LBB0_1099:
	v_lshlrev_b64 v[38:39], 10, v[206:207]
	v_lshl_add_u64 v[40:41], v[38:39], 0, v[200:201]
	v_lshlrev_b32_e32 v42, 16, v126
	v_and_b32_e32 v43, 0xffff0000, v126
	v_lshlrev_b32_e32 v44, 16, v127
	v_and_b32_e32 v45, 0xffff0000, v127
	v_lshlrev_b32_e32 v46, 16, v128
	v_and_b32_e32 v47, 0xffff0000, v128
	v_lshlrev_b32_e32 v48, 16, v129
	v_and_b32_e32 v49, 0xffff0000, v129
	v_pk_add_f32 v[36:37], v[36:37], v[44:45]
	v_pk_add_f32 v[34:35], v[34:35], v[42:43]
	v_pk_add_f32 v[32:33], v[32:33], v[48:49]
	v_pk_add_f32 v[30:31], v[30:31], v[46:47]
	s_mov_b64 s[42:43], -1
	s_and_b64 vcc, exec, s[6:7]
	v_lshl_add_u64 v[40:41], v[40:41], 2, s[12:13]
	s_cbranch_vccnz .LBB0_1101
	s_mov_b64 s[42:43], 0
	global_store_dwordx4 v[40:41], v[34:37], off
	global_store_dwordx4 v[40:41], v[30:33], off offset:16
.LBB0_1101:
	v_mov_b32_e32 v42, 0
	s_andn2_b64 vcc, exec, s[42:43]
	v_lshl_add_u64 v[38:39], v[38:39], 1, v[202:203]
	s_cbranch_vccnz .LBB0_1103
	v_mov_b32_e32 v44, v35
	v_mov_b32_e32 v45, v31
	v_mov_b32_e32 v42, v34
	v_mov_b32_e32 v43, v30
	v_pk_mul_f32 v[44:45], v[44:45], v[44:45]
	v_mov_b32_e32 v46, v37
	v_mov_b32_e32 v47, v33
	v_pk_fma_f32 v[42:43], v[42:43], v[42:43], v[44:45]
	v_mov_b32_e32 v44, v36
	v_mov_b32_e32 v45, v32
	v_pk_mul_f32 v[46:47], v[46:47], v[46:47]
	v_cvt_pk_bf16_f32 v34, v34, v35
	v_cvt_pk_bf16_f32 v35, v36, v37
	v_cvt_pk_bf16_f32 v36, v30, v31
	v_cvt_pk_bf16_f32 v37, v32, v33
	global_store_dwordx4 v[38:39], v[34:37], off
	v_pk_fma_f32 v[44:45], v[44:45], v[44:45], v[46:47]
	s_nop 0
	v_pk_add_f32 v[42:43], v[42:43], v[44:45]
	s_nop 0
	v_add_f32_e32 v42, v42, v43

.LBB0_1106:
	global_store_dwordx4 v[40:41], v[26:29], off offset:128
	global_store_dwordx4 v[40:41], v[22:25], off offset:144
	s_cbranch_execnz .LBB0_1105
.LBB0_1107:
	v_mov_b32_e32 v32, v27
	v_mov_b32_e32 v33, v23
	v_mov_b32_e32 v30, v26
	v_mov_b32_e32 v31, v22
	v_pk_mul_f32 v[32:33], v[32:33], v[32:33]
	v_mov_b32_e32 v34, v29
	v_mov_b32_e32 v35, v25
	v_pk_fma_f32 v[30:31], v[30:31], v[30:31], v[32:33]
	v_mov_b32_e32 v32, v28
	v_mov_b32_e32 v33, v24
	v_pk_mul_f32 v[34:35], v[34:35], v[34:35]
	v_cvt_pk_bf16_f32 v26, v26, v27
	v_cvt_pk_bf16_f32 v27, v28, v29
	v_cvt_pk_bf16_f32 v28, v22, v23
	v_cvt_pk_bf16_f32 v29, v24, v25
	global_store_dwordx4 v[38:39], v[26:29], off offset:64
	v_pk_fma_f32 v[32:33], v[32:33], v[32:33], v[34:35]
	s_nop 0
	v_pk_add_f32 v[30:31], v[30:31], v[32:33]
	s_nop 0
	v_add_f32_e32 v30, v30, v31
	v_add_f32_e32 v42, v30, v42
	s_and_b64 vcc, exec, s[8:9]
	s_cbranch_vccnz .LBB0_1111

.LBB0_1111:
	v_lshlrev_b64 v[22:23], 10, v[204:205]
	v_lshl_add_u64 v[24:25], v[22:23], 0, v[200:201]
	v_lshlrev_b32_e32 v26, 16, v106
	v_and_b32_e32 v27, 0xffff0000, v106
	v_lshlrev_b32_e32 v28, 16, v107
	v_and_b32_e32 v29, 0xffff0000, v107
	v_lshlrev_b32_e32 v30, 16, v108
	v_and_b32_e32 v31, 0xffff0000, v108
	v_lshlrev_b32_e32 v32, 16, v109
	v_and_b32_e32 v33, 0xffff0000, v109
	v_pk_add_f32 v[20:21], v[20:21], v[28:29]
	v_pk_add_f32 v[18:19], v[18:19], v[26:27]
	v_pk_add_f32 v[16:17], v[16:17], v[32:33]
	v_pk_add_f32 v[14:15], v[14:15], v[30:31]
	s_mov_b64 s[42:43], -1
	s_and_b64 vcc, exec, s[6:7]
	v_lshl_add_u64 v[30:31], v[24:25], 2, s[12:13]
	s_cbranch_vccnz .LBB0_1113
	s_mov_b64 s[42:43], 0
	global_store_dwordx4 v[30:31], v[18:21], off
	global_store_dwordx4 v[30:31], v[14:17], off offset:16
.LBB0_1113:
	v_mad_i64_i32 v[24:25], s[44:45], s78, 15, v[220:221]
	v_lshlrev_b64 v[26:27], 11, v[24:25]
	v_mov_b32_e32 v24, 0
	s_andn2_b64 vcc, exec, s[42:43]
	v_lshl_add_u64 v[28:29], v[22:23], 1, v[202:203]
	s_cbranch_vccnz .LBB0_1117
	v_cvt_pk_bf16_f32 v22, v18, v19
	v_cvt_pk_bf16_f32 v23, v20, v21
	v_cvt_pk_bf16_f32 v24, v14, v15
	v_cvt_pk_bf16_f32 v25, v16, v17
	global_store_dwordx4 v[28:29], v[22:25], off
	s_and_saveexec_b64 s[42:43], s[26:27]
	s_cbranch_execz .LBB0_1116
	v_lshl_add_u64 v[32:33], s[10:11], 0, v[26:27]
	v_lshl_add_u64 v[32:33], v[200:201], 1, v[32:33]
	global_store_dwordx4 v[32:33], v[22:25], off

.LBB0_1120:
	global_store_dwordx4 v[30:31], v[10:13], off offset:128
	global_store_dwordx4 v[30:31], v[6:9], off offset:144
	s_cbranch_execnz .LBB0_1119
.LBB0_1121:
	v_cvt_pk_bf16_f32 v14, v10, v11
	v_cvt_pk_bf16_f32 v15, v12, v13
	v_cvt_pk_bf16_f32 v16, v6, v7
	v_cvt_pk_bf16_f32 v17, v8, v9
	global_store_dwordx4 v[28:29], v[14:17], off offset:64
	s_and_saveexec_b64 s[6:7], s[26:27]
	s_cbranch_execz .LBB0_1123
	v_lshl_add_u64 v[18:19], s[10:11], 0, v[26:27]
	v_lshl_add_u64 v[18:19], v[200:201], 1, v[18:19]
	global_store_dwordx4 v[18:19], v[14:17], off offset:64

.LBB0_1149:
	s_mov_b64 s[4:5], exec
	buffer_wbl2 sc1
	s_waitcnt lgkmcnt(0)
	s_waitcnt vmcnt(0)
	buffer_inv sc1
	v_mbcnt_lo_u32_b32 v3, s4, 0
	v_mbcnt_hi_u32_b32 v3, s5, v3
	v_cmp_eq_u32_e32 vcc, 0, v3
	s_and_saveexec_b64 s[6:7], vcc
	s_cbranch_execz .LBB0_1151
	s_bcnt1_i32_b64 s4, s[4:5]
	v_mov_b32_e32 v5, s4
	v_readlane_b32 s4, v253, 9
	v_readlane_b32 s5, v253, 10
	s_nop 4
	global_atomic_add v5, v4, v5, s[4:5] sc0
